# K-loop LDS-DMAs use saddr form (SGPR base + 32-bit VGPR offset): removes 16 v_lshl_add_u64 per trip, K-advanced bases kept in s98-s101
# speedup vs baseline: 1.0318x; 1.0064x over previous
; #define PG8_STAGE(bufoff, gbase, voff) do { _Pragma("unroll") for (int _i = 0; _i < 2; ++_i) \
;         __builtin_amdgcn_global_load_lds((const unsigned*)((const char*)(gbase) + (voff)[_i]), (PG8_LAS unsigned*)(lds + (bufoff) + ldsw + _i * 8192), 16, 0, 0); } while (0)
; #define PG8_LDA(dst, b, h) do { _Pragma("unroll") for (int m = 0; m < 4; ++m) _Pragma("unroll") for (int k = 0; k < 2; ++k) dst[m][k] = *(const PG8_LAS bf16x8*)(lds + PG8_SA(b, h) + aoff + m * 2048 + k * 1024); } while (0)
; #define PG8_LDB(dst, b, h) do { _Pragma("unroll") for (int n = 0; n < 2; ++n) _Pragma("unroll") for (int k = 0; k < 2; ++k) dst[n][k] = *(const PG8_LAS bf16x8*)(lds + PG8_SB(b, h) + boff + n * 2048 + k * 1024); } while (0)
; #define PG8_WAIT_V(n) asm volatile("s_waitcnt vmcnt(" #n ")" ::: "memory")
; #define PG8_WAIT_L(n) asm volatile("s_waitcnt lgkmcnt(" #n ")" ::: "memory")
; #define PG8_BAR __builtin_amdgcn_s_barrier()
; #define PG8_SCHED __builtin_amdgcn_sched_barrier(0)
; template <class Epi, class Sched>
; __device__ __forceinline__ void gemm_phase(PG8_LAS unsigned char* lds, const Gemm g, const Sched& S, const Epi& E) {
;     ...
;         const bool has_next = S.next(ui + 1, nxt);
;         const char* nA = has_next ? (const char*)g.A + (size_t)nxt.pm * tstep : cA; const char* nB = has_next ? (const char*)g.Bt + (size_t)nxt.pn * tstep : cB;
;         for (int t = 0; t < nt; t += 2) {
;             const bool last = (t == nt - 2);
;             const char* a1 = cA + (size_t)(t + 1) * kstep;
;             const char* a2 = last ? nA : cA + (size_t)(t + 2) * kstep; const char* b2 = last ? nB : cB + (size_t)(t + 2) * kstep;
;             const char* a3 = a2 + kstep; const char* b3 = b2 + kstep;
;             if (last && has_next) S.a_ready(nxt);
;             PG8_LDB(B0, 0, 0); PG8_SCHED; PG8_LDA(At, 0, 0); PG8_STAGE(PG8_SA(1, 1), a1 + hstep, voffA);
;             PG8_WAIT_L(8); PG8_BAR; PG8_WAIT_L(0); PG8_MMA(0, 0, At, B0); PG8_BAR; PG8_SCHED;
;             PG8_LDB(B1, 0, 1); PG8_STAGE(PG8_SB(0, 0), b2, voffB);
;             PG8_BAR; PG8_WAIT_L(0); PG8_MMA(0, 1, At, B1); PG8_BAR;
;             PG8_LDA(At, 0, 1); PG8_STAGE(PG8_SA(0, 0), a2, voffA);
;             PG8_BAR; PG8_WAIT_L(0); PG8_MMA(1, 0, At, B0); PG8_BAR; PG8_SCHED;
;             PG8_STAGE(PG8_SB(0, 1), b2 + hstep, voffB);
;             PG8_WAIT_V(6); PG8_BAR; PG8_MMA(1, 1, At, B1); PG8_BAR;
.LBB0_194:
	s_ashr_i32 s17, s16, 31
	v_cmp_lt_i64_e32 vcc, s[18:19], v[140:141]
	s_lshl_b64 s[18:19], s[16:17], 19
	s_add_u32 s18, s38, s18
	s_addc_u32 s19, s39, s19
	s_and_b64 s[24:25], vcc, exec
	s_cselect_b32 s17, s19, s29
	s_cselect_b32 s54, s18, s28
	s_ashr_i32 s15, s14, 31
	s_lshl_b64 s[24:25], s[14:15], 19
	s_add_u32 s24, s90, s24
	s_addc_u32 s25, s91, s25
	s_and_b64 s[34:35], vcc, exec
	s_cselect_b32 s15, s25, s31
	s_cselect_b32 s55, s24, s30
	s_add_u32 s28, s28, 0x40080
	s_addc_u32 s29, s29, 0
	s_add_u32 s56, s30, 0x100
	s_addc_u32 s57, s31, 0
	s_mov_b32 s58, -2
	ds_read_b128 v[144:147], v151
	ds_read_b128 v[156:159], v151 offset:1024
	ds_read_b128 v[160:163], v151 offset:2048
	ds_read_b128 v[166:169], v151 offset:3072
	s_add_u32 s30, s28, 0xfffc0080
	s_addc_u32 s31, s29, -1
	s_cmp_eq_u32 s58, 12
	s_cselect_b32 s35, s17, s31
	s_cselect_b32 s34, s54, s30
	s_cselect_b32 s31, s15, s57
	s_cselect_b32 s30, s55, s56
	s_add_i32 m0, s27, 0xc000
	ds_read_b128 v[170:173], v153
	ds_read_b128 v[182:185], v153 offset:1024
	ds_read_b128 v[190:193], v153 offset:2048
	ds_read_b128 v[194:197], v153 offset:3072
	ds_read_b128 v[198:201], v153 offset:4096
	ds_read_b128 v[202:205], v153 offset:5120
	ds_read_b128 v[206:209], v153 offset:6144
	ds_read_b128 v[210:213], v153 offset:7168
	global_load_lds_dwordx4 v136, s[28:29]
	s_nop 1
	s_add_i32 m0, s27, 0xe000
	s_nop 0
	global_load_lds_dwordx4 v138, s[28:29]
	s_waitcnt lgkmcnt(8)
	ds_read_b128 v[214:217], v154
	ds_read_b128 v[218:221], v154 offset:1024
	ds_read_b128 v[222:225], v154 offset:2048
	ds_read_b128 v[226:229], v154 offset:3072
	s_waitcnt vmcnt(8) lgkmcnt(0)
	s_barrier
	v_mfma_f32_16x16x32_bf16 v[124:127], v[144:147], v[170:173], 0
	v_mfma_f32_16x16x32_bf16 v[120:123], v[160:163], v[170:173], 0
	v_mfma_f32_16x16x32_bf16 v[108:111], v[144:147], v[190:193], 0
	v_mfma_f32_16x16x32_bf16 v[104:107], v[160:163], v[190:193], 0
	v_mfma_f32_16x16x32_bf16 v[92:95], v[144:147], v[198:201], 0
	v_mfma_f32_16x16x32_bf16 v[88:91], v[160:163], v[198:201], 0
	v_mfma_f32_16x16x32_bf16 v[76:79], v[144:147], v[206:209], 0
	v_mfma_f32_16x16x32_bf16 v[72:75], v[160:163], v[206:209], 0
	v_mfma_f32_16x16x32_bf16 v[124:127], v[156:159], v[182:185], v[124:127]
	v_mfma_f32_16x16x32_bf16 v[120:123], v[166:169], v[182:185], v[120:123]
	v_mfma_f32_16x16x32_bf16 v[108:111], v[156:159], v[194:197], v[108:111]
	v_mfma_f32_16x16x32_bf16 v[104:107], v[166:169], v[194:197], v[104:107]
	v_mfma_f32_16x16x32_bf16 v[92:95], v[156:159], v[202:205], v[92:95]
	v_mfma_f32_16x16x32_bf16 v[88:91], v[166:169], v[202:205], v[88:91]
	v_mfma_f32_16x16x32_bf16 v[76:79], v[156:159], v[210:213], v[76:79]
	v_mfma_f32_16x16x32_bf16 v[72:75], v[166:169], v[210:213], v[72:75]
	v_mfma_f32_16x16x32_bf16 v[116:119], v[214:217], v[170:173], 0
	v_mfma_f32_16x16x32_bf16 v[112:115], v[222:225], v[170:173], 0
	v_mfma_f32_16x16x32_bf16 v[100:103], v[214:217], v[190:193], 0
	v_mfma_f32_16x16x32_bf16 v[96:99], v[222:225], v[190:193], 0
	v_mfma_f32_16x16x32_bf16 v[84:87], v[214:217], v[198:201], 0
	v_mfma_f32_16x16x32_bf16 v[80:83], v[222:225], v[198:201], 0
	v_mfma_f32_16x16x32_bf16 v[68:71], v[214:217], v[206:209], 0
	v_mfma_f32_16x16x32_bf16 v[64:67], v[222:225], v[206:209], 0
	v_mfma_f32_16x16x32_bf16 v[116:119], v[218:221], v[182:185], v[116:119]
	v_mfma_f32_16x16x32_bf16 v[112:115], v[226:229], v[182:185], v[112:115]
	v_mfma_f32_16x16x32_bf16 v[100:103], v[218:221], v[194:197], v[100:103]
	v_mfma_f32_16x16x32_bf16 v[96:99], v[226:229], v[194:197], v[96:99]
	v_mfma_f32_16x16x32_bf16 v[84:87], v[218:221], v[202:205], v[84:87]
	v_mfma_f32_16x16x32_bf16 v[80:83], v[226:229], v[202:205], v[80:83]
	v_mfma_f32_16x16x32_bf16 v[68:71], v[218:221], v[210:213], v[68:71]
	v_mfma_f32_16x16x32_bf16 v[64:67], v[226:229], v[210:213], v[64:67]
	s_barrier
	ds_read_b128 v[170:173], v153 offset:16384
	ds_read_b128 v[182:185], v153 offset:17408
	ds_read_b128 v[190:193], v153 offset:18432
	ds_read_b128 v[194:197], v153 offset:19456
	ds_read_b128 v[198:201], v153 offset:20480
	ds_read_b128 v[202:205], v153 offset:21504
	ds_read_b128 v[206:209], v153 offset:22528
	ds_read_b128 v[210:213], v153 offset:23552
	s_add_i32 s59, s50, s40
	s_add_u32 s98, s30, s10
	s_addc_u32 s99, s31, s11
	s_mov_b32 m0, s59
	s_nop 0
	global_load_lds_dwordx4 v132, s[30:31]
	s_nop 1
	s_add_i32 m0, s59, 0x2000
	s_nop 0
	global_load_lds_dwordx4 v128, s[30:31]
	s_nop 1
	s_mov_b32 m0, s27
	s_add_u32 s100, s34, s10
	s_addc_u32 s101, s35, s11
	global_load_lds_dwordx4 v134, s[34:35]
	s_nop 1
	s_mov_b32 m0, s43
	s_nop 0
	global_load_lds_dwordx4 v130, s[34:35]
	s_add_u32 s60, s30, 0x40000
	s_addc_u32 s61, s31, 0
	s_add_i32 s59, s51, s40
	s_mov_b32 m0, s59
	s_nop 0
	global_load_lds_dwordx4 v132, s[60:61]
	s_nop 1
	s_add_i32 m0, s59, 0x2000
	s_nop 0
	global_load_lds_dwordx4 v128, s[60:61]
	s_waitcnt vmcnt(8) lgkmcnt(0)
	s_barrier
; #define PG8_STAGE(bufoff, gbase, voff) do { _Pragma("unroll") for (int _i = 0; _i < 2; ++_i) \
;         __builtin_amdgcn_global_load_lds((const unsigned*)((const char*)(gbase) + (voff)[_i]), (PG8_LAS unsigned*)(lds + (bufoff) + ldsw + _i * 8192), 16, 0, 0); } while (0)
; #define PG8_LDA(dst, b, h) do { _Pragma("unroll") for (int m = 0; m < 4; ++m) _Pragma("unroll") for (int k = 0; k < 2; ++k) dst[m][k] = *(const PG8_LAS bf16x8*)(lds + PG8_SA(b, h) + aoff + m * 2048 + k * 1024); } while (0)
; #define PG8_LDB(dst, b, h) do { _Pragma("unroll") for (int n = 0; n < 2; ++n) _Pragma("unroll") for (int k = 0; k < 2; ++k) dst[n][k] = *(const PG8_LAS bf16x8*)(lds + PG8_SB(b, h) + boff + n * 2048 + k * 1024); } while (0)
; #define PG8_MMA(ai, bj, At, Bt) do { __builtin_amdgcn_s_setprio(1); _Pragma("unroll") for (int m = 0; m < 4; ++m) _Pragma("unroll") for (int n = 0; n < 2; ++n) _Pragma("unroll") for (int k = 0; k < 2; ++k) \
;         acc[ai][bj][m][n] = __builtin_amdgcn_mfma_f32_16x16x32_bf16(Bt[n][k], At[m][k], acc[ai][bj][m][n], 0, 0, 0); __builtin_amdgcn_s_setprio(0); } while (0)
; #define PG8_WAIT_V(n) asm volatile("s_waitcnt vmcnt(" #n ")" ::: "memory")
; #define PG8_WAIT_L(n) asm volatile("s_waitcnt lgkmcnt(" #n ")" ::: "memory")
; #define PG8_BAR __builtin_amdgcn_s_barrier()
; #define PG8_SCHED __builtin_amdgcn_sched_barrier(0)
; template <class Epi, class Sched>
; __device__ __forceinline__ void gemm_phase(PG8_LAS unsigned char* lds, const Gemm g, const Sched& S, const Epi& E) {
;     ...
;             PG8_BAR; PG8_WAIT_L(0); PG8_MMA(1, 0, At, B0); PG8_BAR; PG8_SCHED;
;             PG8_STAGE(PG8_SB(0, 1), b2 + hstep, voffB);
;             PG8_WAIT_V(6); PG8_BAR; PG8_MMA(1, 1, At, B1); PG8_BAR;
;             PG8_LDB(B0, 1, 0); PG8_SCHED; PG8_LDA(At, 1, 0); PG8_STAGE(PG8_SA(0, 1), a2 + hstep, voffA);
;             PG8_WAIT_L(8); PG8_BAR; PG8_WAIT_L(0); PG8_MMA(0, 0, At, B0); PG8_BAR; PG8_SCHED;
;             PG8_LDB(B1, 1, 1); PG8_STAGE(PG8_SB(1, 0), b3, voffB);
;             PG8_BAR; PG8_WAIT_L(0); PG8_MMA(0, 1, At, B1); PG8_BAR;
	v_mfma_f32_16x16x32_bf16 v[60:63], v[144:147], v[170:173], 0
	v_mfma_f32_16x16x32_bf16 v[56:59], v[160:163], v[170:173], 0
	v_mfma_f32_16x16x32_bf16 v[44:47], v[144:147], v[190:193], 0
	v_mfma_f32_16x16x32_bf16 v[40:43], v[160:163], v[190:193], 0
	v_mfma_f32_16x16x32_bf16 v[28:31], v[144:147], v[198:201], 0
	v_mfma_f32_16x16x32_bf16 v[24:27], v[160:163], v[198:201], 0
	v_mfma_f32_16x16x32_bf16 v[12:15], v[144:147], v[206:209], 0
	v_mfma_f32_16x16x32_bf16 v[8:11], v[160:163], v[206:209], 0
	v_mfma_f32_16x16x32_bf16 v[60:63], v[156:159], v[182:185], v[60:63]
	v_mfma_f32_16x16x32_bf16 v[56:59], v[166:169], v[182:185], v[56:59]
	v_mfma_f32_16x16x32_bf16 v[44:47], v[156:159], v[194:197], v[44:47]
	v_mfma_f32_16x16x32_bf16 v[40:43], v[166:169], v[194:197], v[40:43]
	v_mfma_f32_16x16x32_bf16 v[28:31], v[156:159], v[202:205], v[28:31]
	v_mfma_f32_16x16x32_bf16 v[24:27], v[166:169], v[202:205], v[24:27]
	v_mfma_f32_16x16x32_bf16 v[12:15], v[156:159], v[210:213], v[12:15]
	v_mfma_f32_16x16x32_bf16 v[8:11], v[166:169], v[210:213], v[8:11]
	v_mfma_f32_16x16x32_bf16 v[52:55], v[214:217], v[170:173], 0
	v_mfma_f32_16x16x32_bf16 v[48:51], v[222:225], v[170:173], 0
	v_mfma_f32_16x16x32_bf16 v[36:39], v[214:217], v[190:193], 0
	v_mfma_f32_16x16x32_bf16 v[32:35], v[222:225], v[190:193], 0
	v_mfma_f32_16x16x32_bf16 v[20:23], v[214:217], v[198:201], 0
	v_mfma_f32_16x16x32_bf16 v[16:19], v[222:225], v[198:201], 0
	v_mfma_f32_16x16x32_bf16 v[4:7], v[214:217], v[206:209], 0
	v_mfma_f32_16x16x32_bf16 v[0:3], v[222:225], v[206:209], 0
	v_mfma_f32_16x16x32_bf16 v[52:55], v[218:221], v[182:185], v[52:55]
	v_mfma_f32_16x16x32_bf16 v[48:51], v[226:229], v[182:185], v[48:51]
	v_mfma_f32_16x16x32_bf16 v[36:39], v[218:221], v[194:197], v[36:39]
	v_mfma_f32_16x16x32_bf16 v[32:35], v[226:229], v[194:197], v[32:35]
	v_mfma_f32_16x16x32_bf16 v[20:23], v[218:221], v[202:205], v[20:23]
	v_mfma_f32_16x16x32_bf16 v[16:19], v[226:229], v[202:205], v[16:19]
	v_mfma_f32_16x16x32_bf16 v[4:7], v[218:221], v[210:213], v[4:7]
	v_mfma_f32_16x16x32_bf16 v[0:3], v[226:229], v[210:213], v[0:3]
	s_barrier
	s_add_i32 s59, 0, 0x18000
	v_add_u32_e32 v155, s59, v149
	ds_read_b128 v[144:147], v155
	ds_read_b128 v[156:159], v155 offset:1024
	ds_read_b128 v[160:163], v155 offset:2048
	ds_read_b128 v[166:169], v155 offset:3072
	s_add_u32 s34, s34, 0x40000
	s_addc_u32 s35, s35, 0
	s_mov_b32 m0, s44
	ds_read_b128 v[170:173], v153 offset:32768
	ds_read_b128 v[182:185], v153 offset:33792
	ds_read_b128 v[190:193], v153 offset:34816
	ds_read_b128 v[194:197], v153 offset:35840
	ds_read_b128 v[198:201], v153 offset:36864
	ds_read_b128 v[202:205], v153 offset:37888
	ds_read_b128 v[206:209], v153 offset:38912
	ds_read_b128 v[210:213], v153 offset:39936
	global_load_lds_dwordx4 v134, s[34:35]
	s_nop 1
	s_mov_b32 m0, s45
	s_nop 0
	global_load_lds_dwordx4 v130, s[34:35]
	s_add_i32 s34, 0, 0x1c000
	v_add_u32_e32 v155, s34, v149
	s_waitcnt lgkmcnt(8)
	ds_read_b128 v[214:217], v155
	ds_read_b128 v[218:221], v155 offset:1024
	ds_read_b128 v[222:225], v155 offset:2048
	ds_read_b128 v[226:229], v155 offset:3072
	s_waitcnt vmcnt(8) lgkmcnt(0)
	s_barrier
	v_mfma_f32_16x16x32_bf16 v[124:127], v[144:147], v[170:173], v[124:127]
	v_mfma_f32_16x16x32_bf16 v[120:123], v[160:163], v[170:173], v[120:123]
	v_mfma_f32_16x16x32_bf16 v[108:111], v[144:147], v[190:193], v[108:111]
	v_mfma_f32_16x16x32_bf16 v[104:107], v[160:163], v[190:193], v[104:107]
	v_mfma_f32_16x16x32_bf16 v[92:95], v[144:147], v[198:201], v[92:95]
	v_mfma_f32_16x16x32_bf16 v[88:91], v[160:163], v[198:201], v[88:91]
	v_mfma_f32_16x16x32_bf16 v[76:79], v[144:147], v[206:209], v[76:79]
	v_mfma_f32_16x16x32_bf16 v[72:75], v[160:163], v[206:209], v[72:75]
	v_mfma_f32_16x16x32_bf16 v[124:127], v[156:159], v[182:185], v[124:127]
	v_mfma_f32_16x16x32_bf16 v[120:123], v[166:169], v[182:185], v[120:123]
	v_mfma_f32_16x16x32_bf16 v[108:111], v[156:159], v[194:197], v[108:111]
	v_mfma_f32_16x16x32_bf16 v[104:107], v[166:169], v[194:197], v[104:107]
	v_mfma_f32_16x16x32_bf16 v[92:95], v[156:159], v[202:205], v[92:95]
	v_mfma_f32_16x16x32_bf16 v[88:91], v[166:169], v[202:205], v[88:91]
	v_mfma_f32_16x16x32_bf16 v[76:79], v[156:159], v[210:213], v[76:79]
	v_mfma_f32_16x16x32_bf16 v[72:75], v[166:169], v[210:213], v[72:75]
	v_mfma_f32_16x16x32_bf16 v[116:119], v[214:217], v[170:173], v[116:119]
	v_mfma_f32_16x16x32_bf16 v[112:115], v[222:225], v[170:173], v[112:115]
	v_mfma_f32_16x16x32_bf16 v[100:103], v[214:217], v[190:193], v[100:103]
	v_mfma_f32_16x16x32_bf16 v[96:99], v[222:225], v[190:193], v[96:99]
	v_mfma_f32_16x16x32_bf16 v[84:87], v[214:217], v[198:201], v[84:87]
	v_mfma_f32_16x16x32_bf16 v[80:83], v[222:225], v[198:201], v[80:83]
	v_mfma_f32_16x16x32_bf16 v[68:71], v[214:217], v[206:209], v[68:71]
	v_mfma_f32_16x16x32_bf16 v[64:67], v[222:225], v[206:209], v[64:67]
	v_mfma_f32_16x16x32_bf16 v[116:119], v[218:221], v[182:185], v[116:119]
	v_mfma_f32_16x16x32_bf16 v[112:115], v[226:229], v[182:185], v[112:115]
	v_mfma_f32_16x16x32_bf16 v[100:103], v[218:221], v[194:197], v[100:103]
	v_mfma_f32_16x16x32_bf16 v[96:99], v[226:229], v[194:197], v[96:99]
	v_mfma_f32_16x16x32_bf16 v[84:87], v[218:221], v[202:205], v[84:87]
	v_mfma_f32_16x16x32_bf16 v[80:83], v[226:229], v[202:205], v[80:83]
	v_mfma_f32_16x16x32_bf16 v[68:71], v[218:221], v[210:213], v[68:71]
	v_mfma_f32_16x16x32_bf16 v[64:67], v[226:229], v[210:213], v[64:67]
	s_barrier
; #define PG8_STAGE(bufoff, gbase, voff) do { _Pragma("unroll") for (int _i = 0; _i < 2; ++_i) \
;         __builtin_amdgcn_global_load_lds((const unsigned*)((const char*)(gbase) + (voff)[_i]), (PG8_LAS unsigned*)(lds + (bufoff) + ldsw + _i * 8192), 16, 0, 0); } while (0)
; #define PG8_LDA(dst, b, h) do { _Pragma("unroll") for (int m = 0; m < 4; ++m) _Pragma("unroll") for (int k = 0; k < 2; ++k) dst[m][k] = *(const PG8_LAS bf16x8*)(lds + PG8_SA(b, h) + aoff + m * 2048 + k * 1024); } while (0)
; #define PG8_LDB(dst, b, h) do { _Pragma("unroll") for (int n = 0; n < 2; ++n) _Pragma("unroll") for (int k = 0; k < 2; ++k) dst[n][k] = *(const PG8_LAS bf16x8*)(lds + PG8_SB(b, h) + boff + n * 2048 + k * 1024); } while (0)
; #define PG8_WAIT_V(n) asm volatile("s_waitcnt vmcnt(" #n ")" ::: "memory")
; #define PG8_WAIT_L(n) asm volatile("s_waitcnt lgkmcnt(" #n ")" ::: "memory")
; #define PG8_BAR __builtin_amdgcn_s_barrier()
; #define PG8_SCHED __builtin_amdgcn_sched_barrier(0)
; template <class Epi, class Sched>
; __device__ __forceinline__ void gemm_phase(PG8_LAS unsigned char* lds, const Gemm g, const Sched& S, const Epi& E) {
;     ...
;             PG8_LDB(B0, 0, 0); PG8_SCHED; PG8_LDA(At, 0, 0); PG8_STAGE(PG8_SA(1, 1), a1 + hstep, voffA);
;             PG8_WAIT_L(8); PG8_BAR; PG8_WAIT_L(0); PG8_MMA(0, 0, At, B0); PG8_BAR; PG8_SCHED;
;             PG8_LDB(B1, 0, 1); PG8_STAGE(PG8_SB(0, 0), b2, voffB);
;             PG8_BAR; PG8_WAIT_L(0); PG8_MMA(0, 1, At, B1); PG8_BAR;
;             PG8_LDA(At, 0, 1); PG8_STAGE(PG8_SA(0, 0), a2, voffA);
;             PG8_BAR; PG8_WAIT_L(0); PG8_MMA(1, 0, At, B0); PG8_BAR; PG8_SCHED;
;             PG8_STAGE(PG8_SB(0, 1), b2 + hstep, voffB);
;             PG8_WAIT_V(6); PG8_BAR; PG8_MMA(1, 1, At, B1); PG8_BAR;
;             PG8_LDB(B0, 1, 0); PG8_SCHED; PG8_LDA(At, 1, 0); PG8_STAGE(PG8_SA(0, 1), a2 + hstep, voffA);
;             PG8_WAIT_L(8); PG8_BAR; PG8_WAIT_L(0); PG8_MMA(0, 0, At, B0); PG8_BAR; PG8_SCHED;
;             PG8_LDB(B1, 1, 1); PG8_STAGE(PG8_SB(1, 0), b3, voffB);
;             PG8_BAR; PG8_WAIT_L(0); PG8_MMA(0, 1, At, B1); PG8_BAR;
;             PG8_LDA(At, 1, 1); PG8_STAGE(PG8_SA(1, 0), a3, voffA);
;             PG8_BAR; PG8_WAIT_L(0); PG8_MMA(1, 0, At, B0); PG8_BAR; PG8_SCHED;
;             PG8_STAGE(PG8_SB(1, 1), b3 + hstep, voffB);
;             PG8_WAIT_V(6); PG8_BAR; PG8_MMA(1, 1, At, B1); PG8_BAR;
	ds_read_b128 v[170:173], v153 offset:49152
	ds_read_b128 v[182:185], v153 offset:50176
	ds_read_b128 v[190:193], v153 offset:51200
	ds_read_b128 v[194:197], v153 offset:52224
	ds_read_b128 v[198:201], v153 offset:53248
	ds_read_b128 v[202:205], v153 offset:54272
	ds_read_b128 v[206:209], v153 offset:55296
	ds_read_b128 v[210:213], v153 offset:56320
	s_add_i32 s35, s59, s40
	s_mov_b32 m0, s35
	s_nop 0
	global_load_lds_dwordx4 v132, s[98:99]
	s_nop 1
	s_add_i32 m0, s35, 0x2000
	s_nop 0
	global_load_lds_dwordx4 v128, s[98:99]
	s_nop 1
	s_mov_b32 m0, s47
	s_nop 0
	global_load_lds_dwordx4 v134, s[100:101]
	s_nop 1
	s_mov_b32 m0, s48
	s_nop 0
	global_load_lds_dwordx4 v130, s[100:101]
	s_add_u32 s30, s30, 0x40080
	s_addc_u32 s31, s31, 0
	s_add_i32 s34, s34, s40
	s_mov_b32 m0, s34
	s_nop 0
	global_load_lds_dwordx4 v132, s[30:31]
	s_nop 1
	s_add_i32 m0, s34, 0x2000
	s_nop 0
	global_load_lds_dwordx4 v128, s[30:31]
	s_waitcnt vmcnt(8) lgkmcnt(0)
	s_barrier
	v_mfma_f32_16x16x32_bf16 v[60:63], v[144:147], v[170:173], v[60:63]
	v_mfma_f32_16x16x32_bf16 v[56:59], v[160:163], v[170:173], v[56:59]
	v_mfma_f32_16x16x32_bf16 v[44:47], v[144:147], v[190:193], v[44:47]
	v_mfma_f32_16x16x32_bf16 v[40:43], v[160:163], v[190:193], v[40:43]
	v_mfma_f32_16x16x32_bf16 v[28:31], v[144:147], v[198:201], v[28:31]
	v_mfma_f32_16x16x32_bf16 v[24:27], v[160:163], v[198:201], v[24:27]
	v_mfma_f32_16x16x32_bf16 v[12:15], v[144:147], v[206:209], v[12:15]
	v_mfma_f32_16x16x32_bf16 v[8:11], v[160:163], v[206:209], v[8:11]
	v_mfma_f32_16x16x32_bf16 v[60:63], v[156:159], v[182:185], v[60:63]
	v_mfma_f32_16x16x32_bf16 v[56:59], v[166:169], v[182:185], v[56:59]
	v_mfma_f32_16x16x32_bf16 v[44:47], v[156:159], v[194:197], v[44:47]
	v_mfma_f32_16x16x32_bf16 v[40:43], v[166:169], v[194:197], v[40:43]
	v_mfma_f32_16x16x32_bf16 v[28:31], v[156:159], v[202:205], v[28:31]
	v_mfma_f32_16x16x32_bf16 v[24:27], v[166:169], v[202:205], v[24:27]
	v_mfma_f32_16x16x32_bf16 v[12:15], v[156:159], v[210:213], v[12:15]
	v_mfma_f32_16x16x32_bf16 v[8:11], v[166:169], v[210:213], v[8:11]
	v_mfma_f32_16x16x32_bf16 v[52:55], v[214:217], v[170:173], v[52:55]
	v_mfma_f32_16x16x32_bf16 v[48:51], v[222:225], v[170:173], v[48:51]
	v_mfma_f32_16x16x32_bf16 v[36:39], v[214:217], v[190:193], v[36:39]
	v_mfma_f32_16x16x32_bf16 v[32:35], v[222:225], v[190:193], v[32:35]
	v_mfma_f32_16x16x32_bf16 v[20:23], v[214:217], v[198:201], v[20:23]
	v_mfma_f32_16x16x32_bf16 v[16:19], v[222:225], v[198:201], v[16:19]
	v_mfma_f32_16x16x32_bf16 v[4:7], v[214:217], v[206:209], v[4:7]
	v_mfma_f32_16x16x32_bf16 v[0:3], v[222:225], v[206:209], v[0:3]
	v_mfma_f32_16x16x32_bf16 v[52:55], v[218:221], v[182:185], v[52:55]
	v_mfma_f32_16x16x32_bf16 v[48:51], v[226:229], v[182:185], v[48:51]
	v_mfma_f32_16x16x32_bf16 v[36:39], v[218:221], v[194:197], v[36:39]
	v_mfma_f32_16x16x32_bf16 v[32:35], v[226:229], v[194:197], v[32:35]
	v_mfma_f32_16x16x32_bf16 v[20:23], v[218:221], v[202:205], v[20:23]
	v_mfma_f32_16x16x32_bf16 v[16:19], v[226:229], v[202:205], v[16:19]
	v_mfma_f32_16x16x32_bf16 v[4:7], v[218:221], v[210:213], v[4:7]
	v_mfma_f32_16x16x32_bf16 v[0:3], v[226:229], v[210:213], v[0:3]
	s_barrier
	s_add_i32 s58, s58, 2
	s_add_u32 s28, s28, 0x100
	s_addc_u32 s29, s29, 0
	s_add_u32 s56, s56, 0x100
	s_addc_u32 s57, s57, 0
	s_cmp_gt_u32 s58, 13
.LBB0_195:
	ds_read_b128 v[144:147], v151
	ds_read_b128 v[156:159], v151 offset:1024
	ds_read_b128 v[160:163], v151 offset:2048
	ds_read_b128 v[166:169], v151 offset:3072
	s_add_u32 s30, s28, 0xfffc0080
	s_addc_u32 s31, s29, -1
	s_cmp_eq_u32 s58, 12
	s_cselect_b32 s35, s17, s31
	s_cselect_b32 s34, s54, s30
	s_cselect_b32 s31, s15, s57
	s_cselect_b32 s30, s55, s56
	s_add_i32 m0, s27, 0xc000
	ds_read_b128 v[170:173], v153
	ds_read_b128 v[182:185], v153 offset:1024
	ds_read_b128 v[190:193], v153 offset:2048
	ds_read_b128 v[194:197], v153 offset:3072
	ds_read_b128 v[198:201], v153 offset:4096
	ds_read_b128 v[202:205], v153 offset:5120
	ds_read_b128 v[206:209], v153 offset:6144
	ds_read_b128 v[210:213], v153 offset:7168
	global_load_lds_dwordx4 v136, s[28:29]
	s_nop 1
	s_add_i32 m0, s27, 0xe000
	s_nop 0
	global_load_lds_dwordx4 v138, s[28:29]
	s_waitcnt lgkmcnt(8)
	ds_read_b128 v[214:217], v154
	ds_read_b128 v[218:221], v154 offset:1024
	ds_read_b128 v[222:225], v154 offset:2048
	ds_read_b128 v[226:229], v154 offset:3072
	s_waitcnt vmcnt(8) lgkmcnt(0)
	s_barrier
	v_mfma_f32_16x16x32_bf16 v[124:127], v[144:147], v[170:173], v[124:127]
	v_mfma_f32_16x16x32_bf16 v[120:123], v[160:163], v[170:173], v[120:123]
	v_mfma_f32_16x16x32_bf16 v[108:111], v[144:147], v[190:193], v[108:111]
	v_mfma_f32_16x16x32_bf16 v[104:107], v[160:163], v[190:193], v[104:107]
	v_mfma_f32_16x16x32_bf16 v[92:95], v[144:147], v[198:201], v[92:95]
	v_mfma_f32_16x16x32_bf16 v[88:91], v[160:163], v[198:201], v[88:91]
	v_mfma_f32_16x16x32_bf16 v[76:79], v[144:147], v[206:209], v[76:79]
	v_mfma_f32_16x16x32_bf16 v[72:75], v[160:163], v[206:209], v[72:75]
	v_mfma_f32_16x16x32_bf16 v[124:127], v[156:159], v[182:185], v[124:127]
	v_mfma_f32_16x16x32_bf16 v[120:123], v[166:169], v[182:185], v[120:123]
	v_mfma_f32_16x16x32_bf16 v[108:111], v[156:159], v[194:197], v[108:111]
	v_mfma_f32_16x16x32_bf16 v[104:107], v[166:169], v[194:197], v[104:107]
	v_mfma_f32_16x16x32_bf16 v[92:95], v[156:159], v[202:205], v[92:95]
	v_mfma_f32_16x16x32_bf16 v[88:91], v[166:169], v[202:205], v[88:91]
	v_mfma_f32_16x16x32_bf16 v[76:79], v[156:159], v[210:213], v[76:79]
	v_mfma_f32_16x16x32_bf16 v[72:75], v[166:169], v[210:213], v[72:75]
	v_mfma_f32_16x16x32_bf16 v[116:119], v[214:217], v[170:173], v[116:119]
	v_mfma_f32_16x16x32_bf16 v[112:115], v[222:225], v[170:173], v[112:115]
	v_mfma_f32_16x16x32_bf16 v[100:103], v[214:217], v[190:193], v[100:103]
	v_mfma_f32_16x16x32_bf16 v[96:99], v[222:225], v[190:193], v[96:99]
	v_mfma_f32_16x16x32_bf16 v[84:87], v[214:217], v[198:201], v[84:87]
	v_mfma_f32_16x16x32_bf16 v[80:83], v[222:225], v[198:201], v[80:83]
	v_mfma_f32_16x16x32_bf16 v[68:71], v[214:217], v[206:209], v[68:71]
	v_mfma_f32_16x16x32_bf16 v[64:67], v[222:225], v[206:209], v[64:67]
	v_mfma_f32_16x16x32_bf16 v[116:119], v[218:221], v[182:185], v[116:119]
	v_mfma_f32_16x16x32_bf16 v[112:115], v[226:229], v[182:185], v[112:115]
	v_mfma_f32_16x16x32_bf16 v[100:103], v[218:221], v[194:197], v[100:103]
	v_mfma_f32_16x16x32_bf16 v[96:99], v[226:229], v[194:197], v[96:99]
	v_mfma_f32_16x16x32_bf16 v[84:87], v[218:221], v[202:205], v[84:87]
	v_mfma_f32_16x16x32_bf16 v[80:83], v[226:229], v[202:205], v[80:83]
	v_mfma_f32_16x16x32_bf16 v[68:71], v[218:221], v[210:213], v[68:71]
	v_mfma_f32_16x16x32_bf16 v[64:67], v[226:229], v[210:213], v[64:67]
	s_barrier
; #define PG8_STAGE(bufoff, gbase, voff) do { _Pragma("unroll") for (int _i = 0; _i < 2; ++_i) \
;         __builtin_amdgcn_global_load_lds((const unsigned*)((const char*)(gbase) + (voff)[_i]), (PG8_LAS unsigned*)(lds + (bufoff) + ldsw + _i * 8192), 16, 0, 0); } while (0)
; #define PG8_LDA(dst, b, h) do { _Pragma("unroll") for (int m = 0; m < 4; ++m) _Pragma("unroll") for (int k = 0; k < 2; ++k) dst[m][k] = *(const PG8_LAS bf16x8*)(lds + PG8_SA(b, h) + aoff + m * 2048 + k * 1024); } while (0)
; #define PG8_LDB(dst, b, h) do { _Pragma("unroll") for (int n = 0; n < 2; ++n) _Pragma("unroll") for (int k = 0; k < 2; ++k) dst[n][k] = *(const PG8_LAS bf16x8*)(lds + PG8_SB(b, h) + boff + n * 2048 + k * 1024); } while (0)
; #define PG8_MMA(ai, bj, At, Bt) do { __builtin_amdgcn_s_setprio(1); _Pragma("unroll") for (int m = 0; m < 4; ++m) _Pragma("unroll") for (int n = 0; n < 2; ++n) _Pragma("unroll") for (int k = 0; k < 2; ++k) \
;         acc[ai][bj][m][n] = __builtin_amdgcn_mfma_f32_16x16x32_bf16(Bt[n][k], At[m][k], acc[ai][bj][m][n], 0, 0, 0); __builtin_amdgcn_s_setprio(0); } while (0)
; #define PG8_WAIT_V(n) asm volatile("s_waitcnt vmcnt(" #n ")" ::: "memory")
; #define PG8_WAIT_L(n) asm volatile("s_waitcnt lgkmcnt(" #n ")" ::: "memory")
; template <class Epi, class Sched>
; __device__ __forceinline__ void gemm_phase(PG8_LAS unsigned char* lds, const Gemm g, const Sched& S, const Epi& E) {
;     ...
;             PG8_LDB(B0, 0, 0); PG8_SCHED; PG8_LDA(At, 0, 0); PG8_STAGE(PG8_SA(1, 1), a1 + hstep, voffA);
;             PG8_WAIT_L(8); PG8_BAR; PG8_WAIT_L(0); PG8_MMA(0, 0, At, B0); PG8_BAR; PG8_SCHED;
;             PG8_LDB(B1, 0, 1); PG8_STAGE(PG8_SB(0, 0), b2, voffB);
;             PG8_BAR; PG8_WAIT_L(0); PG8_MMA(0, 1, At, B1); PG8_BAR;
;             PG8_LDA(At, 0, 1); PG8_STAGE(PG8_SA(0, 0), a2, voffA);
;             PG8_BAR; PG8_WAIT_L(0); PG8_MMA(1, 0, At, B0); PG8_BAR; PG8_SCHED;
;             PG8_STAGE(PG8_SB(0, 1), b2 + hstep, voffB);
;             PG8_WAIT_V(6); PG8_BAR; PG8_MMA(1, 1, At, B1); PG8_BAR;
;             PG8_LDB(B0, 1, 0); PG8_SCHED; PG8_LDA(At, 1, 0); PG8_STAGE(PG8_SA(0, 1), a2 + hstep, voffA);
;             PG8_WAIT_L(8); PG8_BAR; PG8_WAIT_L(0); PG8_MMA(0, 0, At, B0); PG8_BAR; PG8_SCHED;
;             PG8_LDB(B1, 1, 1); PG8_STAGE(PG8_SB(1, 0), b3, voffB);
;             PG8_BAR; PG8_WAIT_L(0); PG8_MMA(0, 1, At, B1); PG8_BAR;
	ds_read_b128 v[170:173], v153 offset:16384
	ds_read_b128 v[182:185], v153 offset:17408
	ds_read_b128 v[190:193], v153 offset:18432
	ds_read_b128 v[194:197], v153 offset:19456
	ds_read_b128 v[198:201], v153 offset:20480
	ds_read_b128 v[202:205], v153 offset:21504
	ds_read_b128 v[206:209], v153 offset:22528
	ds_read_b128 v[210:213], v153 offset:23552
	s_add_i32 s59, s50, s40
	s_add_u32 s98, s30, s10
	s_addc_u32 s99, s31, s11
	s_mov_b32 m0, s59
	s_nop 0
	global_load_lds_dwordx4 v132, s[30:31]
	s_nop 1
	s_add_i32 m0, s59, 0x2000
	s_nop 0
	global_load_lds_dwordx4 v128, s[30:31]
	s_nop 1
	s_mov_b32 m0, s27
	s_add_u32 s100, s34, s10
	s_addc_u32 s101, s35, s11
	global_load_lds_dwordx4 v134, s[34:35]
	s_nop 1
	s_mov_b32 m0, s43
	s_nop 0
	global_load_lds_dwordx4 v130, s[34:35]
	s_add_u32 s60, s30, 0x40000
	s_addc_u32 s61, s31, 0
	s_add_i32 s59, s51, s40
	s_mov_b32 m0, s59
	s_nop 0
	global_load_lds_dwordx4 v132, s[60:61]
	s_nop 1
	s_add_i32 m0, s59, 0x2000
	s_nop 0
	global_load_lds_dwordx4 v128, s[60:61]
	s_waitcnt vmcnt(8) lgkmcnt(0)
	s_barrier
	v_mfma_f32_16x16x32_bf16 v[60:63], v[144:147], v[170:173], v[60:63]
	v_mfma_f32_16x16x32_bf16 v[56:59], v[160:163], v[170:173], v[56:59]
	v_mfma_f32_16x16x32_bf16 v[44:47], v[144:147], v[190:193], v[44:47]
	v_mfma_f32_16x16x32_bf16 v[40:43], v[160:163], v[190:193], v[40:43]
	v_mfma_f32_16x16x32_bf16 v[28:31], v[144:147], v[198:201], v[28:31]
	v_mfma_f32_16x16x32_bf16 v[24:27], v[160:163], v[198:201], v[24:27]
	v_mfma_f32_16x16x32_bf16 v[12:15], v[144:147], v[206:209], v[12:15]
	v_mfma_f32_16x16x32_bf16 v[8:11], v[160:163], v[206:209], v[8:11]
	v_mfma_f32_16x16x32_bf16 v[60:63], v[156:159], v[182:185], v[60:63]
	v_mfma_f32_16x16x32_bf16 v[56:59], v[166:169], v[182:185], v[56:59]
	v_mfma_f32_16x16x32_bf16 v[44:47], v[156:159], v[194:197], v[44:47]
	v_mfma_f32_16x16x32_bf16 v[40:43], v[166:169], v[194:197], v[40:43]
	v_mfma_f32_16x16x32_bf16 v[28:31], v[156:159], v[202:205], v[28:31]
	v_mfma_f32_16x16x32_bf16 v[24:27], v[166:169], v[202:205], v[24:27]
	v_mfma_f32_16x16x32_bf16 v[12:15], v[156:159], v[210:213], v[12:15]
	v_mfma_f32_16x16x32_bf16 v[8:11], v[166:169], v[210:213], v[8:11]
	v_mfma_f32_16x16x32_bf16 v[52:55], v[214:217], v[170:173], v[52:55]
	v_mfma_f32_16x16x32_bf16 v[48:51], v[222:225], v[170:173], v[48:51]
	v_mfma_f32_16x16x32_bf16 v[36:39], v[214:217], v[190:193], v[36:39]
	v_mfma_f32_16x16x32_bf16 v[32:35], v[222:225], v[190:193], v[32:35]
	v_mfma_f32_16x16x32_bf16 v[20:23], v[214:217], v[198:201], v[20:23]
	v_mfma_f32_16x16x32_bf16 v[16:19], v[222:225], v[198:201], v[16:19]
	v_mfma_f32_16x16x32_bf16 v[4:7], v[214:217], v[206:209], v[4:7]
	v_mfma_f32_16x16x32_bf16 v[0:3], v[222:225], v[206:209], v[0:3]
	v_mfma_f32_16x16x32_bf16 v[52:55], v[218:221], v[182:185], v[52:55]
	v_mfma_f32_16x16x32_bf16 v[48:51], v[226:229], v[182:185], v[48:51]
	v_mfma_f32_16x16x32_bf16 v[36:39], v[218:221], v[194:197], v[36:39]
	v_mfma_f32_16x16x32_bf16 v[32:35], v[226:229], v[194:197], v[32:35]
	v_mfma_f32_16x16x32_bf16 v[20:23], v[218:221], v[202:205], v[20:23]
	v_mfma_f32_16x16x32_bf16 v[16:19], v[226:229], v[202:205], v[16:19]
	v_mfma_f32_16x16x32_bf16 v[4:7], v[218:221], v[210:213], v[4:7]
	v_mfma_f32_16x16x32_bf16 v[0:3], v[226:229], v[210:213], v[0:3]
	s_barrier
	s_add_i32 s59, 0, 0x18000
	v_add_u32_e32 v155, s59, v149
	ds_read_b128 v[144:147], v155
	ds_read_b128 v[156:159], v155 offset:1024
	ds_read_b128 v[160:163], v155 offset:2048
	ds_read_b128 v[166:169], v155 offset:3072
	s_add_u32 s34, s34, 0x40000
	s_addc_u32 s35, s35, 0
	s_mov_b32 m0, s44
	ds_read_b128 v[170:173], v153 offset:32768
	ds_read_b128 v[182:185], v153 offset:33792
	ds_read_b128 v[190:193], v153 offset:34816
	ds_read_b128 v[194:197], v153 offset:35840
	ds_read_b128 v[198:201], v153 offset:36864
	ds_read_b128 v[202:205], v153 offset:37888
	ds_read_b128 v[206:209], v153 offset:38912
	ds_read_b128 v[210:213], v153 offset:39936
	global_load_lds_dwordx4 v134, s[34:35]
	s_nop 1
	s_mov_b32 m0, s45
	s_nop 0
	global_load_lds_dwordx4 v130, s[34:35]
	s_add_i32 s34, 0, 0x1c000
	v_add_u32_e32 v155, s34, v149
	s_waitcnt lgkmcnt(8)
	ds_read_b128 v[214:217], v155
	ds_read_b128 v[218:221], v155 offset:1024
	ds_read_b128 v[222:225], v155 offset:2048
	ds_read_b128 v[226:229], v155 offset:3072
	s_waitcnt vmcnt(8) lgkmcnt(0)
	s_barrier
	v_mfma_f32_16x16x32_bf16 v[124:127], v[144:147], v[170:173], v[124:127]
	v_mfma_f32_16x16x32_bf16 v[120:123], v[160:163], v[170:173], v[120:123]
	v_mfma_f32_16x16x32_bf16 v[108:111], v[144:147], v[190:193], v[108:111]
	v_mfma_f32_16x16x32_bf16 v[104:107], v[160:163], v[190:193], v[104:107]
	v_mfma_f32_16x16x32_bf16 v[92:95], v[144:147], v[198:201], v[92:95]
	v_mfma_f32_16x16x32_bf16 v[88:91], v[160:163], v[198:201], v[88:91]
	v_mfma_f32_16x16x32_bf16 v[76:79], v[144:147], v[206:209], v[76:79]
	v_mfma_f32_16x16x32_bf16 v[72:75], v[160:163], v[206:209], v[72:75]
	v_mfma_f32_16x16x32_bf16 v[124:127], v[156:159], v[182:185], v[124:127]
	v_mfma_f32_16x16x32_bf16 v[120:123], v[166:169], v[182:185], v[120:123]
	v_mfma_f32_16x16x32_bf16 v[108:111], v[156:159], v[194:197], v[108:111]
	v_mfma_f32_16x16x32_bf16 v[104:107], v[166:169], v[194:197], v[104:107]
	v_mfma_f32_16x16x32_bf16 v[92:95], v[156:159], v[202:205], v[92:95]
	v_mfma_f32_16x16x32_bf16 v[88:91], v[166:169], v[202:205], v[88:91]
	v_mfma_f32_16x16x32_bf16 v[76:79], v[156:159], v[210:213], v[76:79]
	v_mfma_f32_16x16x32_bf16 v[72:75], v[166:169], v[210:213], v[72:75]
	v_mfma_f32_16x16x32_bf16 v[116:119], v[214:217], v[170:173], v[116:119]
	v_mfma_f32_16x16x32_bf16 v[112:115], v[222:225], v[170:173], v[112:115]
	v_mfma_f32_16x16x32_bf16 v[100:103], v[214:217], v[190:193], v[100:103]
	v_mfma_f32_16x16x32_bf16 v[96:99], v[222:225], v[190:193], v[96:99]
	v_mfma_f32_16x16x32_bf16 v[84:87], v[214:217], v[198:201], v[84:87]
	v_mfma_f32_16x16x32_bf16 v[80:83], v[222:225], v[198:201], v[80:83]
	v_mfma_f32_16x16x32_bf16 v[68:71], v[214:217], v[206:209], v[68:71]
	v_mfma_f32_16x16x32_bf16 v[64:67], v[222:225], v[206:209], v[64:67]
	v_mfma_f32_16x16x32_bf16 v[116:119], v[218:221], v[182:185], v[116:119]
	v_mfma_f32_16x16x32_bf16 v[112:115], v[226:229], v[182:185], v[112:115]
	v_mfma_f32_16x16x32_bf16 v[100:103], v[218:221], v[194:197], v[100:103]
	v_mfma_f32_16x16x32_bf16 v[96:99], v[226:229], v[194:197], v[96:99]
	v_mfma_f32_16x16x32_bf16 v[84:87], v[218:221], v[202:205], v[84:87]
	v_mfma_f32_16x16x32_bf16 v[80:83], v[226:229], v[202:205], v[80:83]
	v_mfma_f32_16x16x32_bf16 v[68:71], v[218:221], v[210:213], v[68:71]
	v_mfma_f32_16x16x32_bf16 v[64:67], v[226:229], v[210:213], v[64:67]
	s_barrier
; #define PG8_STAGE(bufoff, gbase, voff) do { _Pragma("unroll") for (int _i = 0; _i < 2; ++_i) \
;         __builtin_amdgcn_global_load_lds((const unsigned*)((const char*)(gbase) + (voff)[_i]), (PG8_LAS unsigned*)(lds + (bufoff) + ldsw + _i * 8192), 16, 0, 0); } while (0)
; #define PG8_LDA(dst, b, h) do { _Pragma("unroll") for (int m = 0; m < 4; ++m) _Pragma("unroll") for (int k = 0; k < 2; ++k) dst[m][k] = *(const PG8_LAS bf16x8*)(lds + PG8_SA(b, h) + aoff + m * 2048 + k * 1024); } while (0)
; #define PG8_LDB(dst, b, h) do { _Pragma("unroll") for (int n = 0; n < 2; ++n) _Pragma("unroll") for (int k = 0; k < 2; ++k) dst[n][k] = *(const PG8_LAS bf16x8*)(lds + PG8_SB(b, h) + boff + n * 2048 + k * 1024); } while (0)
; #define PG8_WAIT_V(n) asm volatile("s_waitcnt vmcnt(" #n ")" ::: "memory")
; #define PG8_WAIT_L(n) asm volatile("s_waitcnt lgkmcnt(" #n ")" ::: "memory")
; #define PG8_BAR __builtin_amdgcn_s_barrier()
;     __device__ __forceinline__ void operator()(const f32x4 (&acc)[2][2][4][2], const Unit& u, int wr, int wc, int fr, int fq) const {
;         const int row0 = u.pm * BM + wr * 64 + fr, col0 = u.pn * HALF + wc * 32 + 8 * fq;
; #pragma unroll
;         for (int ai = 0; ai < 2; ++ai)
; #pragma unroll
;             for (int m = 0; m < 4; ++m) { bf16_t* rowp = O + (size_t)(row0 + ai * HALF + m * 16) * ldc + col0;
;                 f32x4 v0, v1;
; #pragma unroll
;                 for (int j = 0; j < 1; ++j) { v0 = acc[ai][0][m][0] * sigmoid4(acc[ai][0][m][0]) * acc[ai][1][m][0]; v1 = acc[ai][0][m][1] * sigmoid4(acc[ai][0][m][1]) * acc[ai][1][m][1]; }
; template <class Epi, class Sched>
; __device__ __forceinline__ void gemm_phase(PG8_LAS unsigned char* lds, const Gemm g, const Sched& S, const Epi& E) {
;     ...
;             PG8_LDB(B0, 1, 0); PG8_SCHED; PG8_LDA(At, 1, 0); PG8_STAGE(PG8_SA(0, 1), a2 + hstep, voffA);
;             PG8_WAIT_L(8); PG8_BAR; PG8_WAIT_L(0); PG8_MMA(0, 0, At, B0); PG8_BAR; PG8_SCHED;
;             PG8_LDB(B1, 1, 1); PG8_STAGE(PG8_SB(1, 0), b3, voffB);
;             PG8_BAR; PG8_WAIT_L(0); PG8_MMA(0, 1, At, B1); PG8_BAR;
;             PG8_LDA(At, 1, 1); PG8_STAGE(PG8_SA(1, 0), a3, voffA);
;             PG8_BAR; PG8_WAIT_L(0); PG8_MMA(1, 0, At, B0); PG8_BAR; PG8_SCHED;
;             PG8_STAGE(PG8_SB(1, 1), b3 + hstep, voffB);
;             PG8_WAIT_V(6); PG8_BAR; PG8_MMA(1, 1, At, B1); PG8_BAR;
	ds_read_b128 v[170:173], v153 offset:49152
	ds_read_b128 v[182:185], v153 offset:50176
	ds_read_b128 v[190:193], v153 offset:51200
	ds_read_b128 v[194:197], v153 offset:52224
	ds_read_b128 v[198:201], v153 offset:53248
	ds_read_b128 v[202:205], v153 offset:54272
	ds_read_b128 v[206:209], v153 offset:55296
	ds_read_b128 v[210:213], v153 offset:56320
	s_add_i32 s35, s59, s40
	s_mov_b32 m0, s35
	s_nop 0
	global_load_lds_dwordx4 v132, s[98:99]
	s_nop 1
	s_add_i32 m0, s35, 0x2000
	s_nop 0
	global_load_lds_dwordx4 v128, s[98:99]
	s_nop 1
	s_mov_b32 m0, s47
	s_nop 0
	global_load_lds_dwordx4 v134, s[100:101]
	s_nop 1
	s_mov_b32 m0, s48
	s_nop 0
	global_load_lds_dwordx4 v130, s[100:101]
	s_add_u32 s30, s30, 0x40080
	s_addc_u32 s31, s31, 0
	s_add_i32 s34, s34, s40
	s_mov_b32 m0, s34
	s_nop 0
	global_load_lds_dwordx4 v132, s[30:31]
	s_nop 1
	s_add_i32 m0, s34, 0x2000
	s_nop 0
	global_load_lds_dwordx4 v128, s[30:31]
	s_waitcnt vmcnt(8) lgkmcnt(0)
	s_barrier
	v_mfma_f32_16x16x32_bf16 v[60:63], v[144:147], v[170:173], v[60:63]
	v_mfma_f32_16x16x32_bf16 v[56:59], v[160:163], v[170:173], v[56:59]
	v_mfma_f32_16x16x32_bf16 v[44:47], v[144:147], v[190:193], v[44:47]
	v_mfma_f32_16x16x32_bf16 v[40:43], v[160:163], v[190:193], v[40:43]
	v_mfma_f32_16x16x32_bf16 v[28:31], v[144:147], v[198:201], v[28:31]
	v_mfma_f32_16x16x32_bf16 v[24:27], v[160:163], v[198:201], v[24:27]
	v_mfma_f32_16x16x32_bf16 v[12:15], v[144:147], v[206:209], v[12:15]
	v_mfma_f32_16x16x32_bf16 v[8:11], v[160:163], v[206:209], v[8:11]
	v_mfma_f32_16x16x32_bf16 v[60:63], v[156:159], v[182:185], v[60:63]
	v_mfma_f32_16x16x32_bf16 v[56:59], v[166:169], v[182:185], v[56:59]
	v_mfma_f32_16x16x32_bf16 v[44:47], v[156:159], v[194:197], v[44:47]
	v_mfma_f32_16x16x32_bf16 v[40:43], v[166:169], v[194:197], v[40:43]
	v_mfma_f32_16x16x32_bf16 v[28:31], v[156:159], v[202:205], v[28:31]
	v_mfma_f32_16x16x32_bf16 v[24:27], v[166:169], v[202:205], v[24:27]
	v_mfma_f32_16x16x32_bf16 v[12:15], v[156:159], v[210:213], v[12:15]
	v_mfma_f32_16x16x32_bf16 v[8:11], v[166:169], v[210:213], v[8:11]
	v_mfma_f32_16x16x32_bf16 v[52:55], v[214:217], v[170:173], v[52:55]
	v_mfma_f32_16x16x32_bf16 v[48:51], v[222:225], v[170:173], v[48:51]
	v_mfma_f32_16x16x32_bf16 v[36:39], v[214:217], v[190:193], v[36:39]
	v_mfma_f32_16x16x32_bf16 v[32:35], v[222:225], v[190:193], v[32:35]
	v_mfma_f32_16x16x32_bf16 v[20:23], v[214:217], v[198:201], v[20:23]
	v_mfma_f32_16x16x32_bf16 v[16:19], v[222:225], v[198:201], v[16:19]
	v_mfma_f32_16x16x32_bf16 v[4:7], v[214:217], v[206:209], v[4:7]
	v_mfma_f32_16x16x32_bf16 v[0:3], v[222:225], v[206:209], v[0:3]
	v_mfma_f32_16x16x32_bf16 v[52:55], v[218:221], v[182:185], v[52:55]
	v_mfma_f32_16x16x32_bf16 v[48:51], v[226:229], v[182:185], v[48:51]
	v_mfma_f32_16x16x32_bf16 v[36:39], v[218:221], v[194:197], v[36:39]
	v_mfma_f32_16x16x32_bf16 v[32:35], v[226:229], v[194:197], v[32:35]
	v_mfma_f32_16x16x32_bf16 v[20:23], v[218:221], v[202:205], v[20:23]
	v_mfma_f32_16x16x32_bf16 v[16:19], v[226:229], v[202:205], v[16:19]
	v_mfma_f32_16x16x32_bf16 v[4:7], v[218:221], v[210:213], v[4:7]
	v_mfma_f32_16x16x32_bf16 v[0:3], v[226:229], v[210:213], v[0:3]
	s_barrier
	s_add_i32 s58, s58, 2
	s_add_u32 s28, s28, 0x100
	s_addc_u32 s29, s29, 0
	s_add_u32 s56, s56, 0x100
	s_addc_u32 s57, s57, 0
	s_cmp_gt_u32 s58, 13
	s_cbranch_scc0 .LBB0_195
	v_max_f32_e32 v144, 0xc1a00000, v124
	v_mul_f32_e32 v144, 0xbfb8aa3b, v144
	v_exp_f32_e32 v157, v144
	v_max_f32_e32 v144, 0xc1a00000, v125
	v_mul_f32_e32 v144, 0xbfb8aa3b, v144
	v_exp_f32_e32 v156, v144
	v_max_f32_e32 v144, 0xc1a00000, v126
	v_mul_f32_e32 v144, 0xbfb8aa3b, v144
	v_exp_f32_e32 v159, v144
	v_max_f32_e32 v144, 0xc1a00000, v127
	v_mul_f32_e32 v144, 0xbfb8aa3b, v144
	v_exp_f32_e32 v158, v144
	v_pk_add_f32 v[156:157], v[156:157], 1.0 op_sel_hi:[1,0]
	v_lshl_or_b32 v146, s53, 7, v150
	v_mov_b32_e32 v160, v157
	v_pk_add_f32 v[158:159], v[158:159], 1.0 op_sel_hi:[1,0]
	v_mov_b32_e32 v162, v156
	v_mov_b32_e32 v161, v159
	v_mov_b32_e32 v163, v158
	v_pk_mul_f32 v[160:161], v[160:161], v[162:163]
	v_lshl_add_u32 v155, s26, 8, v148
	v_mul_f32_e32 v162, v160, v161
	v_rcp_f32_e32 v166, v162
	v_ashrrev_i32_e32 v147, 31, v146
	v_mov_b64_e32 v[144:145], s[4:5]
	v_mad_i64_i32 v[162:163], s[28:29], v155, s52, v[144:145]
	v_mul_f32_e32 v160, v160, v166
	v_mul_f32_e32 v164, v161, v166
	v_pk_mul_f32 v[158:159], v[158:159], v[160:161] op_sel_hi:[1,0]
	v_max_f32_e32 v160, 0xc1a00000, v120
	v_max_f32_e32 v166, 0xc1a00000, v122
	v_mul_f32_e32 v160, 0xbfb8aa3b, v160
	v_mul_f32_e32 v166, 0xbfb8aa3b, v166
	v_exp_f32_e32 v161, v160
	v_exp_f32_e32 v167, v166
	v_max_f32_e32 v160, 0xc1a00000, v121
	v_max_f32_e32 v166, 0xc1a00000, v123
	v_mul_f32_e32 v160, 0xbfb8aa3b, v160
	v_mul_f32_e32 v166, 0xbfb8aa3b, v166
	v_exp_f32_e32 v160, v160
	v_exp_f32_e32 v166, v166
	v_pk_mul_f32 v[156:157], v[156:157], v[164:165] op_sel_hi:[1,0]
	v_pk_mul_f32 v[126:127], v[126:127], v[158:159]
	v_pk_mul_f32 v[124:125], v[124:125], v[156:157]
	v_pk_add_f32 v[156:157], v[160:161], 1.0 op_sel_hi:[1,0]
	v_pk_add_f32 v[160:161], v[166:167], 1.0 op_sel_hi:[1,0]
	v_mov_b32_e32 v166, v157
	v_mov_b32_e32 v167, v161
	v_mov_b32_e32 v168, v156
	v_mov_b32_e32 v169, v160
	v_pk_mul_f32 v[166:167], v[166:167], v[168:169]
	v_pk_mul_f32 v[118:119], v[126:127], v[118:119]
	v_mul_f32_e32 v164, v166, v167
	v_rcp_f32_e32 v164, v164
	v_pk_mul_f32 v[116:117], v[124:125], v[116:117]
	v_lshlrev_b64 v[146:147], 1, v[146:147]
	v_lshl_add_u64 v[162:163], v[162:163], 0, v[146:147]
	v_mul_f32_e32 v124, v167, v164
	v_mul_f32_e32 v126, v166, v164
	v_pk_mul_f32 v[126:127], v[160:161], v[126:127] op_sel_hi:[1,0]
; __device__ __forceinline__ unsigned cvt_pk_bf16(float lo, float hi) { unsigned r; asm volatile("v_cvt_pk_bf16_f32 %0, %1, %2" : "=v"(r) : "v"(lo), "v"(hi)); return r; }
; __device__ __forceinline__ f32x4 sigmoid4(f32x4 x) {
;     f32x4 d;
; #pragma unroll
;     for (int j = 0; j < 4; ++j) d[j] = 1.0f + __expf(-fmaxf(x[j], -20.0f));
;     const float p01 = d[0] * d[1], p23 = d[2] * d[3], r = __builtin_amdgcn_rcpf(p01 * p23), r01 = r * p23, r23 = r * p01;
;     return (f32x4){r01 * d[1], r01 * d[0], r23 * d[3], r23 * d[2]};
; }
;     __device__ __forceinline__ void operator()(const f32x4 (&acc)[2][2][4][2], const Unit& u, int wr, int wc, int fr, int fq) const {
;         const int row0 = u.pm * BM + wr * 64 + fr, col0 = u.pn * HALF + wc * 32 + 8 * fq;
; #pragma unroll
;         for (int ai = 0; ai < 2; ++ai)
; #pragma unroll
;             for (int m = 0; m < 4; ++m) { bf16_t* rowp = O + (size_t)(row0 + ai * HALF + m * 16) * ldc + col0;
;                 f32x4 v0, v1;
; #pragma unroll
;                 for (int j = 0; j < 1; ++j) { v0 = acc[ai][0][m][0] * sigmoid4(acc[ai][0][m][0]) * acc[ai][1][m][0]; v1 = acc[ai][0][m][1] * sigmoid4(acc[ai][0][m][1]) * acc[ai][1][m][1]; }
;                 u32x4 w; w.x = cvt_pk_bf16(v0[0], v0[1]); w.y = cvt_pk_bf16(v0[2], v0[3]); w.z = cvt_pk_bf16(v1[0], v1[1]); w.w = cvt_pk_bf16(v1[2], v1[3]);
;                 *(u32x4*)rowp = w; }
	v_pk_mul_f32 v[124:125], v[156:157], v[124:125] op_sel_hi:[1,0]
	v_pk_mul_f32 v[122:123], v[122:123], v[126:127]
	v_pk_mul_f32 v[120:121], v[120:121], v[124:125]
	v_pk_mul_f32 v[122:123], v[122:123], v[114:115]
	v_pk_mul_f32 v[114:115], v[120:121], v[112:113]
	v_cvt_pk_bf16_f32 v112, v116, v117
	v_cvt_pk_bf16_f32 v113, v118, v119
	v_max_f32_e32 v116, 0xc1a00000, v108
	v_max_f32_e32 v118, 0xc1a00000, v110
	v_mul_f32_e32 v116, 0xbfb8aa3b, v116
	v_mul_f32_e32 v118, 0xbfb8aa3b, v118
	v_exp_f32_e32 v117, v116
	v_exp_f32_e32 v119, v118
	v_max_f32_e32 v116, 0xc1a00000, v109
	v_max_f32_e32 v118, 0xc1a00000, v111
	v_mul_f32_e32 v116, 0xbfb8aa3b, v116
	v_mul_f32_e32 v118, 0xbfb8aa3b, v118
	v_exp_f32_e32 v116, v116
	v_exp_f32_e32 v118, v118
	v_cvt_pk_bf16_f32 v114, v114, v115
	v_cvt_pk_bf16_f32 v115, v122, v123
	global_store_dwordx4 v[162:163], v[112:115], off
	v_or_b32_e32 v120, 16, v155
	s_and_b64 vcc, exec, s[2:3]
	v_pk_add_f32 v[112:113], v[116:117], 1.0 op_sel_hi:[1,0]
	v_pk_add_f32 v[114:115], v[118:119], 1.0 op_sel_hi:[1,0]
	v_mov_b32_e32 v116, v113
	v_mov_b32_e32 v117, v115
	v_mov_b32_e32 v118, v112
	v_mov_b32_e32 v119, v114
	v_pk_mul_f32 v[116:117], v[116:117], v[118:119]
	s_mov_b32 s53, s14
	v_mul_f32_e32 v118, v116, v117
	v_rcp_f32_e32 v121, v118
	v_mad_i64_i32 v[118:119], s[28:29], v120, s52, v[144:145]
	v_lshl_add_u64 v[118:119], v[118:119], 0, v[146:147]
	v_mul_f32_e32 v116, v116, v121
	v_mul_f32_e32 v120, v117, v121
	v_pk_mul_f32 v[114:115], v[114:115], v[116:117] op_sel_hi:[1,0]
	v_max_f32_e32 v116, 0xc1a00000, v104
	v_max_f32_e32 v121, 0xc1a00000, v106
	v_mul_f32_e32 v116, 0xbfb8aa3b, v116
	v_mul_f32_e32 v121, 0xbfb8aa3b, v121
	v_exp_f32_e32 v117, v116
	v_exp_f32_e32 v123, v121
	v_max_f32_e32 v116, 0xc1a00000, v105
	v_max_f32_e32 v121, 0xc1a00000, v107
	v_mul_f32_e32 v116, 0xbfb8aa3b, v116
	v_mul_f32_e32 v121, 0xbfb8aa3b, v121
	v_exp_f32_e32 v116, v116
	v_exp_f32_e32 v122, v121
	v_pk_mul_f32 v[112:113], v[112:113], v[120:121] op_sel_hi:[1,0]
	v_pk_mul_f32 v[110:111], v[110:111], v[114:115]
	v_pk_mul_f32 v[108:109], v[108:109], v[112:113]
	v_pk_add_f32 v[112:113], v[116:117], 1.0 op_sel_hi:[1,0]
	v_pk_add_f32 v[116:117], v[122:123], 1.0 op_sel_hi:[1,0]
	v_mov_b32_e32 v120, v113
	v_mov_b32_e32 v121, v117
	v_mov_b32_e32 v122, v112
	v_mov_b32_e32 v123, v116
	v_pk_mul_f32 v[120:121], v[120:121], v[122:123]
	v_pk_mul_f32 v[102:103], v[110:111], v[102:103]
	v_mul_f32_e32 v122, v120, v121
	v_rcp_f32_e32 v122, v122
	v_pk_mul_f32 v[100:101], v[108:109], v[100:101]
	s_mov_b32 s26, s16
	s_mov_b64 s[30:31], s[24:25]
	v_mul_f32_e32 v108, v121, v122
	v_mul_f32_e32 v110, v120, v122
	v_pk_mul_f32 v[110:111], v[116:117], v[110:111] op_sel_hi:[1,0]
	v_pk_mul_f32 v[108:109], v[112:113], v[108:109] op_sel_hi:[1,0]
	v_pk_mul_f32 v[106:107], v[106:107], v[110:111]
	v_pk_mul_f32 v[104:105], v[104:105], v[108:109]
	v_pk_mul_f32 v[106:107], v[106:107], v[98:99]
	v_pk_mul_f32 v[98:99], v[104:105], v[96:97]
	v_cvt_pk_bf16_f32 v96, v100, v101
	v_cvt_pk_bf16_f32 v97, v102, v103
	v_max_f32_e32 v100, 0xc1a00000, v92
	v_max_f32_e32 v102, 0xc1a00000, v94
	v_mul_f32_e32 v100, 0xbfb8aa3b, v100
	v_mul_f32_e32 v102, 0xbfb8aa3b, v102
	v_exp_f32_e32 v101, v100
	v_exp_f32_e32 v103, v102
	v_max_f32_e32 v100, 0xc1a00000, v93
	v_max_f32_e32 v102, 0xc1a00000, v95
	v_mul_f32_e32 v100, 0xbfb8aa3b, v100
	v_mul_f32_e32 v102, 0xbfb8aa3b, v102
	v_exp_f32_e32 v100, v100
	v_exp_f32_e32 v102, v102
	v_cvt_pk_bf16_f32 v98, v98, v99
	v_cvt_pk_bf16_f32 v99, v106, v107
	global_store_dwordx4 v[118:119], v[96:99], off
	v_or_b32_e32 v104, 32, v155
	s_nop 0
	v_pk_add_f32 v[96:97], v[100:101], 1.0 op_sel_hi:[1,0]
	v_pk_add_f32 v[98:99], v[102:103], 1.0 op_sel_hi:[1,0]
	v_mov_b32_e32 v100, v97
	v_mov_b32_e32 v101, v99
	v_mov_b32_e32 v102, v96
	v_mov_b32_e32 v103, v98
	v_pk_mul_f32 v[100:101], v[100:101], v[102:103]
	s_nop 0
	v_mul_f32_e32 v102, v100, v101
	v_rcp_f32_e32 v105, v102
	v_mad_i64_i32 v[102:103], s[28:29], v104, s52, v[144:145]
	v_lshl_add_u64 v[102:103], v[102:103], 0, v[146:147]
	v_mul_f32_e32 v100, v100, v105
	v_mul_f32_e32 v104, v101, v105
	v_pk_mul_f32 v[98:99], v[98:99], v[100:101] op_sel_hi:[1,0]
	v_max_f32_e32 v100, 0xc1a00000, v88
	v_max_f32_e32 v105, 0xc1a00000, v90
	v_mul_f32_e32 v100, 0xbfb8aa3b, v100
	v_mul_f32_e32 v105, 0xbfb8aa3b, v105
	v_exp_f32_e32 v101, v100
	v_exp_f32_e32 v107, v105
	v_max_f32_e32 v100, 0xc1a00000, v89
	v_max_f32_e32 v105, 0xc1a00000, v91
	v_mul_f32_e32 v100, 0xbfb8aa3b, v100
	v_mul_f32_e32 v105, 0xbfb8aa3b, v105
	v_exp_f32_e32 v100, v100
	v_exp_f32_e32 v106, v105
	v_pk_mul_f32 v[96:97], v[96:97], v[104:105] op_sel_hi:[1,0]
	v_pk_mul_f32 v[94:95], v[94:95], v[98:99]
	v_pk_mul_f32 v[92:93], v[92:93], v[96:97]
	v_pk_add_f32 v[96:97], v[100:101], 1.0 op_sel_hi:[1,0]
	v_pk_add_f32 v[100:101], v[106:107], 1.0 op_sel_hi:[1,0]
	v_mov_b32_e32 v104, v97
	v_mov_b32_e32 v105, v101
	v_mov_b32_e32 v106, v96
	v_mov_b32_e32 v107, v100
	v_pk_mul_f32 v[104:105], v[104:105], v[106:107]
	v_pk_mul_f32 v[86:87], v[94:95], v[86:87]
	v_mul_f32_e32 v106, v104, v105
	v_rcp_f32_e32 v106, v106
	v_pk_mul_f32 v[84:85], v[92:93], v[84:85]
	v_mul_f32_e32 v92, v105, v106
	v_mul_f32_e32 v94, v104, v106
	v_pk_mul_f32 v[94:95], v[100:101], v[94:95] op_sel_hi:[1,0]
	v_pk_mul_f32 v[92:93], v[96:97], v[92:93] op_sel_hi:[1,0]
	v_pk_mul_f32 v[90:91], v[90:91], v[94:95]
	v_pk_mul_f32 v[88:89], v[88:89], v[92:93]
	v_pk_mul_f32 v[90:91], v[90:91], v[82:83]
	v_pk_mul_f32 v[82:83], v[88:89], v[80:81]
	v_cvt_pk_bf16_f32 v80, v84, v85
	v_cvt_pk_bf16_f32 v81, v86, v87
	v_max_f32_e32 v84, 0xc1a00000, v76
	v_max_f32_e32 v86, 0xc1a00000, v78
	v_mul_f32_e32 v84, 0xbfb8aa3b, v84
; __device__ __forceinline__ unsigned cvt_pk_bf16(float lo, float hi) { unsigned r; asm volatile("v_cvt_pk_bf16_f32 %0, %1, %2" : "=v"(r) : "v"(lo), "v"(hi)); return r; }
; __device__ __forceinline__ f32x4 sigmoid4(f32x4 x) {
;     f32x4 d;
; #pragma unroll
;     for (int j = 0; j < 4; ++j) d[j] = 1.0f + __expf(-fmaxf(x[j], -20.0f));
;     const float p01 = d[0] * d[1], p23 = d[2] * d[3], r = __builtin_amdgcn_rcpf(p01 * p23), r01 = r * p23, r23 = r * p01;
;     return (f32x4){r01 * d[1], r01 * d[0], r23 * d[3], r23 * d[2]};
; }
;     __device__ __forceinline__ void operator()(const f32x4 (&acc)[2][2][4][2], const Unit& u, int wr, int wc, int fr, int fq) const {
;         const int row0 = u.pm * BM + wr * 64 + fr, col0 = u.pn * HALF + wc * 32 + 8 * fq;
; #pragma unroll
;         for (int ai = 0; ai < 2; ++ai)
; #pragma unroll
;             for (int m = 0; m < 4; ++m) { bf16_t* rowp = O + (size_t)(row0 + ai * HALF + m * 16) * ldc + col0;
;                 f32x4 v0, v1;
; #pragma unroll
;                 for (int j = 0; j < 1; ++j) { v0 = acc[ai][0][m][0] * sigmoid4(acc[ai][0][m][0]) * acc[ai][1][m][0]; v1 = acc[ai][0][m][1] * sigmoid4(acc[ai][0][m][1]) * acc[ai][1][m][1]; }
;                 u32x4 w; w.x = cvt_pk_bf16(v0[0], v0[1]); w.y = cvt_pk_bf16(v0[2], v0[3]); w.z = cvt_pk_bf16(v1[0], v1[1]); w.w = cvt_pk_bf16(v1[2], v1[3]);
;                 *(u32x4*)rowp = w; }
	v_mul_f32_e32 v86, 0xbfb8aa3b, v86
	v_exp_f32_e32 v85, v84
	v_exp_f32_e32 v87, v86
	v_max_f32_e32 v84, 0xc1a00000, v77
	v_max_f32_e32 v86, 0xc1a00000, v79
	v_mul_f32_e32 v84, 0xbfb8aa3b, v84
	v_mul_f32_e32 v86, 0xbfb8aa3b, v86
	v_exp_f32_e32 v84, v84
	v_exp_f32_e32 v86, v86
	v_cvt_pk_bf16_f32 v82, v82, v83
	v_cvt_pk_bf16_f32 v83, v90, v91
	global_store_dwordx4 v[102:103], v[80:83], off
	v_or_b32_e32 v88, 48, v155
	s_nop 0
	v_pk_add_f32 v[80:81], v[84:85], 1.0 op_sel_hi:[1,0]
	v_pk_add_f32 v[82:83], v[86:87], 1.0 op_sel_hi:[1,0]
	v_mov_b32_e32 v84, v81
	v_mov_b32_e32 v85, v83
	v_mov_b32_e32 v86, v80
	v_mov_b32_e32 v87, v82
	v_pk_mul_f32 v[84:85], v[84:85], v[86:87]
	s_nop 0
	v_mul_f32_e32 v86, v84, v85
	v_rcp_f32_e32 v89, v86
	v_mad_i64_i32 v[86:87], s[28:29], v88, s52, v[144:145]
	v_lshl_add_u64 v[86:87], v[86:87], 0, v[146:147]
	v_mul_f32_e32 v84, v84, v89
	v_mul_f32_e32 v88, v85, v89
	v_pk_mul_f32 v[82:83], v[82:83], v[84:85] op_sel_hi:[1,0]
	v_max_f32_e32 v84, 0xc1a00000, v72
	v_max_f32_e32 v89, 0xc1a00000, v74
	v_mul_f32_e32 v84, 0xbfb8aa3b, v84
	v_mul_f32_e32 v89, 0xbfb8aa3b, v89
	v_exp_f32_e32 v85, v84
	v_exp_f32_e32 v91, v89
	v_max_f32_e32 v84, 0xc1a00000, v73
	v_max_f32_e32 v89, 0xc1a00000, v75
	v_mul_f32_e32 v84, 0xbfb8aa3b, v84
	v_mul_f32_e32 v89, 0xbfb8aa3b, v89
	v_exp_f32_e32 v84, v84
	v_exp_f32_e32 v90, v89
	v_pk_mul_f32 v[80:81], v[80:81], v[88:89] op_sel_hi:[1,0]
	v_pk_mul_f32 v[78:79], v[78:79], v[82:83]
	v_pk_mul_f32 v[76:77], v[76:77], v[80:81]
	v_pk_add_f32 v[80:81], v[84:85], 1.0 op_sel_hi:[1,0]
	v_pk_add_f32 v[84:85], v[90:91], 1.0 op_sel_hi:[1,0]
	v_mov_b32_e32 v88, v81
	v_mov_b32_e32 v89, v85
	v_mov_b32_e32 v90, v80
	v_mov_b32_e32 v91, v84
	v_pk_mul_f32 v[88:89], v[88:89], v[90:91]
	v_pk_mul_f32 v[70:71], v[78:79], v[70:71]
	v_mul_f32_e32 v90, v88, v89
	v_rcp_f32_e32 v90, v90
	v_pk_mul_f32 v[68:69], v[76:77], v[68:69]
	v_mul_f32_e32 v76, v89, v90
	v_mul_f32_e32 v78, v88, v90
	v_pk_mul_f32 v[78:79], v[84:85], v[78:79] op_sel_hi:[1,0]
	v_pk_mul_f32 v[76:77], v[80:81], v[76:77] op_sel_hi:[1,0]
	v_pk_mul_f32 v[74:75], v[74:75], v[78:79]
	v_pk_mul_f32 v[72:73], v[72:73], v[76:77]
	v_pk_mul_f32 v[74:75], v[74:75], v[66:67]
	v_pk_mul_f32 v[66:67], v[72:73], v[64:65]
	v_cvt_pk_bf16_f32 v64, v68, v69
	v_cvt_pk_bf16_f32 v65, v70, v71
	v_max_f32_e32 v68, 0xc1a00000, v60
	v_max_f32_e32 v70, 0xc1a00000, v62
	v_mul_f32_e32 v68, 0xbfb8aa3b, v68
	v_mul_f32_e32 v70, 0xbfb8aa3b, v70
	v_exp_f32_e32 v69, v68
	v_exp_f32_e32 v71, v70
	v_max_f32_e32 v68, 0xc1a00000, v61
	v_max_f32_e32 v70, 0xc1a00000, v63
	v_mul_f32_e32 v68, 0xbfb8aa3b, v68
	v_mul_f32_e32 v70, 0xbfb8aa3b, v70
	v_exp_f32_e32 v68, v68
	v_exp_f32_e32 v70, v70
	v_cvt_pk_bf16_f32 v66, v66, v67
	v_cvt_pk_bf16_f32 v67, v74, v75
	global_store_dwordx4 v[86:87], v[64:67], off
	v_add_u32_e32 v72, 0x80, v155
	s_nop 0
	v_pk_add_f32 v[64:65], v[68:69], 1.0 op_sel_hi:[1,0]
	v_pk_add_f32 v[66:67], v[70:71], 1.0 op_sel_hi:[1,0]
	v_mov_b32_e32 v68, v65
	v_mov_b32_e32 v69, v67
	v_mov_b32_e32 v70, v64
	v_mov_b32_e32 v71, v66
	v_pk_mul_f32 v[68:69], v[68:69], v[70:71]
	s_nop 0
	v_mul_f32_e32 v70, v68, v69
	v_rcp_f32_e32 v73, v70
	v_mad_i64_i32 v[70:71], s[28:29], v72, s52, v[144:145]
	v_lshl_add_u64 v[70:71], v[70:71], 0, v[146:147]
	v_mul_f32_e32 v68, v68, v73
	v_mul_f32_e32 v72, v69, v73
	v_pk_mul_f32 v[66:67], v[66:67], v[68:69] op_sel_hi:[1,0]
	v_max_f32_e32 v68, 0xc1a00000, v56
	v_max_f32_e32 v73, 0xc1a00000, v58
	v_mul_f32_e32 v68, 0xbfb8aa3b, v68
	v_mul_f32_e32 v73, 0xbfb8aa3b, v73
	v_exp_f32_e32 v69, v68
	v_exp_f32_e32 v75, v73
	v_max_f32_e32 v68, 0xc1a00000, v57
	v_max_f32_e32 v73, 0xc1a00000, v59
	v_mul_f32_e32 v68, 0xbfb8aa3b, v68
	v_mul_f32_e32 v73, 0xbfb8aa3b, v73
	v_exp_f32_e32 v68, v68
	v_exp_f32_e32 v74, v73
	v_pk_mul_f32 v[64:65], v[64:65], v[72:73] op_sel_hi:[1,0]
	v_pk_mul_f32 v[62:63], v[62:63], v[66:67]
	v_pk_mul_f32 v[60:61], v[60:61], v[64:65]
	v_pk_add_f32 v[64:65], v[68:69], 1.0 op_sel_hi:[1,0]
	v_pk_add_f32 v[68:69], v[74:75], 1.0 op_sel_hi:[1,0]
	v_mov_b32_e32 v72, v65
	v_mov_b32_e32 v73, v69
	v_mov_b32_e32 v74, v64
	v_mov_b32_e32 v75, v68
	v_pk_mul_f32 v[72:73], v[72:73], v[74:75]
	v_pk_mul_f32 v[54:55], v[62:63], v[54:55]
	v_mul_f32_e32 v74, v72, v73
	v_rcp_f32_e32 v74, v74
	v_pk_mul_f32 v[52:53], v[60:61], v[52:53]
	v_mul_f32_e32 v60, v73, v74
	v_mul_f32_e32 v62, v72, v74
	v_pk_mul_f32 v[62:63], v[68:69], v[62:63] op_sel_hi:[1,0]
	v_pk_mul_f32 v[60:61], v[64:65], v[60:61] op_sel_hi:[1,0]
	v_pk_mul_f32 v[58:59], v[58:59], v[62:63]
	v_pk_mul_f32 v[56:57], v[56:57], v[60:61]
	v_pk_mul_f32 v[58:59], v[58:59], v[50:51]
	v_pk_mul_f32 v[50:51], v[56:57], v[48:49]
	v_cvt_pk_bf16_f32 v48, v52, v53
	v_cvt_pk_bf16_f32 v49, v54, v55
	v_max_f32_e32 v52, 0xc1a00000, v44
	v_max_f32_e32 v54, 0xc1a00000, v46
	v_mul_f32_e32 v52, 0xbfb8aa3b, v52
	v_mul_f32_e32 v54, 0xbfb8aa3b, v54
	v_exp_f32_e32 v53, v52
	v_exp_f32_e32 v55, v54
	v_max_f32_e32 v52, 0xc1a00000, v45
	v_max_f32_e32 v54, 0xc1a00000, v47
	v_mul_f32_e32 v52, 0xbfb8aa3b, v52
	v_mul_f32_e32 v54, 0xbfb8aa3b, v54
	v_exp_f32_e32 v52, v52
	v_exp_f32_e32 v54, v54
	v_cvt_pk_bf16_f32 v50, v50, v51
	v_cvt_pk_bf16_f32 v51, v58, v59
	global_store_dwordx4 v[70:71], v[48:51], off
	v_add_u32_e32 v56, 0x90, v155
	s_nop 0
	v_pk_add_f32 v[48:49], v[52:53], 1.0 op_sel_hi:[1,0]
	v_pk_add_f32 v[50:51], v[54:55], 1.0 op_sel_hi:[1,0]
	v_mov_b32_e32 v52, v49
	v_mov_b32_e32 v53, v51
	v_mov_b32_e32 v54, v48
	v_mov_b32_e32 v55, v50
	v_pk_mul_f32 v[52:53], v[52:53], v[54:55]
	s_nop 0
	v_mul_f32_e32 v54, v52, v53
	v_rcp_f32_e32 v57, v54
	v_mad_i64_i32 v[54:55], s[28:29], v56, s52, v[144:145]
	v_lshl_add_u64 v[54:55], v[54:55], 0, v[146:147]
; __device__ __forceinline__ unsigned cvt_pk_bf16(float lo, float hi) { unsigned r; asm volatile("v_cvt_pk_bf16_f32 %0, %1, %2" : "=v"(r) : "v"(lo), "v"(hi)); return r; }
; #define PG8_WAIT_V(n) asm volatile("s_waitcnt vmcnt(" #n ")" ::: "memory")
; #define PG8_BAR __builtin_amdgcn_s_barrier()
;     __device__ __forceinline__ void operator()(const f32x4 (&acc)[2][2][4][2], const Unit& u, int wr, int wc, int fr, int fq) const {
;         const int row0 = u.pm * BM + wr * 64 + fr, col0 = u.pn * HALF + wc * 32 + 8 * fq;
; #pragma unroll
;         for (int ai = 0; ai < 2; ++ai)
; #pragma unroll
;             for (int m = 0; m < 4; ++m) { bf16_t* rowp = O + (size_t)(row0 + ai * HALF + m * 16) * ldc + col0;
;                 f32x4 v0, v1;
; #pragma unroll
;                 for (int j = 0; j < 1; ++j) { v0 = acc[ai][0][m][0] * sigmoid4(acc[ai][0][m][0]) * acc[ai][1][m][0]; v1 = acc[ai][0][m][1] * sigmoid4(acc[ai][0][m][1]) * acc[ai][1][m][1]; }
;                 u32x4 w; w.x = cvt_pk_bf16(v0[0], v0[1]); w.y = cvt_pk_bf16(v0[2], v0[3]); w.z = cvt_pk_bf16(v1[0], v1[1]); w.w = cvt_pk_bf16(v1[2], v1[3]);
;                 *(u32x4*)rowp = w; }
; template <class Epi, class Sched>
; __device__ __forceinline__ void gemm_phase(PG8_LAS unsigned char* lds, const Gemm g, const Sched& S, const Epi& E) {
;     ...
;         if constexpr (!Epi::AFTER_DRAIN) { E(acc, cur, wr, wc, fr, fq); S.done(cur); }
;         if (!has_next) break;
; #pragma unroll
;         for (int a = 0; a < 2; ++a)
; #pragma unroll
;             for (int b = 0; b < 2; ++b)
; #pragma unroll
;                 for (int m = 0; m < 4; ++m)
; #pragma unroll
;                     for (int n = 0; n < 2; ++n) acc[a][b][m][n] = (f32x4){0.f, 0.f, 0.f, 0.f};
;         cur = nxt; cA = nA; cB = nB; ++ui;
;     }
;     PG8_WAIT_V(0);
;     if (wr == 0) PG8_BAR;
;     PG8_BAR;
	v_mul_f32_e32 v52, v52, v57
	v_mul_f32_e32 v56, v53, v57
	v_pk_mul_f32 v[50:51], v[50:51], v[52:53] op_sel_hi:[1,0]
	v_max_f32_e32 v52, 0xc1a00000, v40
	v_max_f32_e32 v57, 0xc1a00000, v42
	v_mul_f32_e32 v52, 0xbfb8aa3b, v52
	v_mul_f32_e32 v57, 0xbfb8aa3b, v57
	v_exp_f32_e32 v53, v52
	v_exp_f32_e32 v59, v57
	v_max_f32_e32 v52, 0xc1a00000, v41
	v_max_f32_e32 v57, 0xc1a00000, v43
	v_mul_f32_e32 v52, 0xbfb8aa3b, v52
	v_mul_f32_e32 v57, 0xbfb8aa3b, v57
	v_exp_f32_e32 v52, v52
	v_exp_f32_e32 v58, v57
	v_pk_mul_f32 v[48:49], v[48:49], v[56:57] op_sel_hi:[1,0]
	v_pk_mul_f32 v[46:47], v[46:47], v[50:51]
	v_pk_mul_f32 v[44:45], v[44:45], v[48:49]
	v_pk_add_f32 v[48:49], v[52:53], 1.0 op_sel_hi:[1,0]
	v_pk_add_f32 v[52:53], v[58:59], 1.0 op_sel_hi:[1,0]
	v_mov_b32_e32 v56, v49
	v_mov_b32_e32 v57, v53
	v_mov_b32_e32 v58, v48
	v_mov_b32_e32 v59, v52
	v_pk_mul_f32 v[56:57], v[56:57], v[58:59]
	v_pk_mul_f32 v[38:39], v[46:47], v[38:39]
	v_mul_f32_e32 v58, v56, v57
	v_rcp_f32_e32 v58, v58
	v_pk_mul_f32 v[36:37], v[44:45], v[36:37]
	v_mul_f32_e32 v44, v57, v58
	v_mul_f32_e32 v46, v56, v58
	v_pk_mul_f32 v[46:47], v[52:53], v[46:47] op_sel_hi:[1,0]
	v_pk_mul_f32 v[44:45], v[48:49], v[44:45] op_sel_hi:[1,0]
	v_pk_mul_f32 v[42:43], v[42:43], v[46:47]
	v_pk_mul_f32 v[40:41], v[40:41], v[44:45]
	v_pk_mul_f32 v[42:43], v[42:43], v[34:35]
	v_pk_mul_f32 v[34:35], v[40:41], v[32:33]
	v_cvt_pk_bf16_f32 v32, v36, v37
	v_cvt_pk_bf16_f32 v33, v38, v39
	v_max_f32_e32 v36, 0xc1a00000, v28
	v_max_f32_e32 v38, 0xc1a00000, v30
	v_mul_f32_e32 v36, 0xbfb8aa3b, v36
	v_mul_f32_e32 v38, 0xbfb8aa3b, v38
	v_exp_f32_e32 v37, v36
	v_exp_f32_e32 v39, v38
	v_max_f32_e32 v36, 0xc1a00000, v29
	v_max_f32_e32 v38, 0xc1a00000, v31
	v_mul_f32_e32 v36, 0xbfb8aa3b, v36
	v_mul_f32_e32 v38, 0xbfb8aa3b, v38
	v_exp_f32_e32 v36, v36
	v_exp_f32_e32 v38, v38
	v_cvt_pk_bf16_f32 v34, v34, v35
	v_cvt_pk_bf16_f32 v35, v42, v43
	global_store_dwordx4 v[54:55], v[32:35], off
	v_add_u32_e32 v40, 0xa0, v155
	s_nop 0
	v_pk_add_f32 v[32:33], v[36:37], 1.0 op_sel_hi:[1,0]
	v_pk_add_f32 v[34:35], v[38:39], 1.0 op_sel_hi:[1,0]
	v_mov_b32_e32 v36, v33
	v_mov_b32_e32 v37, v35
	v_mov_b32_e32 v38, v32
	v_mov_b32_e32 v39, v34
	v_pk_mul_f32 v[36:37], v[36:37], v[38:39]
	s_nop 0
	v_mul_f32_e32 v38, v36, v37
	v_rcp_f32_e32 v41, v38
	v_mad_i64_i32 v[38:39], s[28:29], v40, s52, v[144:145]
	v_lshl_add_u64 v[38:39], v[38:39], 0, v[146:147]
	v_mul_f32_e32 v36, v36, v41
	v_mul_f32_e32 v40, v37, v41
	v_pk_mul_f32 v[34:35], v[34:35], v[36:37] op_sel_hi:[1,0]
	v_max_f32_e32 v36, 0xc1a00000, v24
	v_max_f32_e32 v41, 0xc1a00000, v26
	v_mul_f32_e32 v36, 0xbfb8aa3b, v36
	v_mul_f32_e32 v41, 0xbfb8aa3b, v41
	v_exp_f32_e32 v37, v36
	v_exp_f32_e32 v43, v41
	v_max_f32_e32 v36, 0xc1a00000, v25
	v_max_f32_e32 v41, 0xc1a00000, v27
	v_mul_f32_e32 v36, 0xbfb8aa3b, v36
	v_mul_f32_e32 v41, 0xbfb8aa3b, v41
	v_exp_f32_e32 v36, v36
	v_exp_f32_e32 v42, v41
	v_pk_mul_f32 v[32:33], v[32:33], v[40:41] op_sel_hi:[1,0]
	v_pk_mul_f32 v[30:31], v[30:31], v[34:35]
	v_pk_mul_f32 v[28:29], v[28:29], v[32:33]
	v_pk_add_f32 v[32:33], v[36:37], 1.0 op_sel_hi:[1,0]
	v_pk_add_f32 v[36:37], v[42:43], 1.0 op_sel_hi:[1,0]
	v_mov_b32_e32 v40, v33
	v_mov_b32_e32 v41, v37
	v_mov_b32_e32 v42, v32
	v_mov_b32_e32 v43, v36
	v_pk_mul_f32 v[40:41], v[40:41], v[42:43]
	v_pk_mul_f32 v[22:23], v[30:31], v[22:23]
	v_mul_f32_e32 v42, v40, v41
	v_rcp_f32_e32 v42, v42
	v_pk_mul_f32 v[20:21], v[28:29], v[20:21]
	v_mul_f32_e32 v28, v41, v42
	v_mul_f32_e32 v30, v40, v42
	v_pk_mul_f32 v[30:31], v[36:37], v[30:31] op_sel_hi:[1,0]
	v_pk_mul_f32 v[28:29], v[32:33], v[28:29] op_sel_hi:[1,0]
	v_pk_mul_f32 v[26:27], v[26:27], v[30:31]
	v_pk_mul_f32 v[24:25], v[24:25], v[28:29]
	v_pk_mul_f32 v[26:27], v[26:27], v[18:19]
	v_pk_mul_f32 v[18:19], v[24:25], v[16:17]
	v_cvt_pk_bf16_f32 v16, v20, v21
	v_cvt_pk_bf16_f32 v17, v22, v23
	v_max_f32_e32 v20, 0xc1a00000, v12
	v_max_f32_e32 v22, 0xc1a00000, v14
	v_mul_f32_e32 v20, 0xbfb8aa3b, v20
	v_mul_f32_e32 v22, 0xbfb8aa3b, v22
	v_exp_f32_e32 v21, v20
	v_exp_f32_e32 v23, v22
	v_max_f32_e32 v20, 0xc1a00000, v13
	v_max_f32_e32 v22, 0xc1a00000, v15
	v_mul_f32_e32 v20, 0xbfb8aa3b, v20
	v_mul_f32_e32 v22, 0xbfb8aa3b, v22
	v_exp_f32_e32 v20, v20
	v_exp_f32_e32 v22, v22
	v_cvt_pk_bf16_f32 v18, v18, v19
	v_cvt_pk_bf16_f32 v19, v26, v27
	global_store_dwordx4 v[38:39], v[16:19], off
	v_add_u32_e32 v24, 0xb0, v155
	s_nop 0
	v_pk_add_f32 v[16:17], v[20:21], 1.0 op_sel_hi:[1,0]
	v_pk_add_f32 v[18:19], v[22:23], 1.0 op_sel_hi:[1,0]
	v_mov_b32_e32 v20, v17
	v_mov_b32_e32 v21, v19
	v_mov_b32_e32 v22, v16
	v_mov_b32_e32 v23, v18
	v_pk_mul_f32 v[20:21], v[20:21], v[22:23]
	s_nop 0
	v_mul_f32_e32 v22, v20, v21
	v_rcp_f32_e32 v25, v22
	v_mad_i64_i32 v[22:23], s[28:29], v24, s52, v[144:145]
	v_lshl_add_u64 v[22:23], v[22:23], 0, v[146:147]
	v_mul_f32_e32 v20, v20, v25
	v_mul_f32_e32 v24, v21, v25
	v_pk_mul_f32 v[18:19], v[18:19], v[20:21] op_sel_hi:[1,0]
	v_max_f32_e32 v20, 0xc1a00000, v8
	v_max_f32_e32 v25, 0xc1a00000, v10
	v_mul_f32_e32 v20, 0xbfb8aa3b, v20
	v_mul_f32_e32 v25, 0xbfb8aa3b, v25
	v_exp_f32_e32 v21, v20
	v_exp_f32_e32 v27, v25
	v_max_f32_e32 v20, 0xc1a00000, v9
	v_max_f32_e32 v25, 0xc1a00000, v11
	v_mul_f32_e32 v20, 0xbfb8aa3b, v20
	v_mul_f32_e32 v25, 0xbfb8aa3b, v25
	v_exp_f32_e32 v20, v20
	v_exp_f32_e32 v26, v25
	v_pk_mul_f32 v[16:17], v[16:17], v[24:25] op_sel_hi:[1,0]
	v_pk_mul_f32 v[14:15], v[14:15], v[18:19]
	v_pk_mul_f32 v[12:13], v[12:13], v[16:17]
	v_pk_add_f32 v[16:17], v[20:21], 1.0 op_sel_hi:[1,0]
	v_pk_add_f32 v[20:21], v[26:27], 1.0 op_sel_hi:[1,0]
	v_mov_b32_e32 v24, v17
	v_mov_b32_e32 v25, v21
	v_mov_b32_e32 v26, v16
	v_mov_b32_e32 v27, v20
	v_pk_mul_f32 v[24:25], v[24:25], v[26:27]
	v_pk_mul_f32 v[6:7], v[14:15], v[6:7]
	v_mul_f32_e32 v26, v24, v25
	v_rcp_f32_e32 v26, v26
	v_pk_mul_f32 v[4:5], v[12:13], v[4:5]
	s_mov_b64 s[28:29], s[18:19]
	v_mul_f32_e32 v12, v25, v26
	v_mul_f32_e32 v14, v24, v26
	v_pk_mul_f32 v[14:15], v[20:21], v[14:15] op_sel_hi:[1,0]
	v_pk_mul_f32 v[12:13], v[16:17], v[12:13] op_sel_hi:[1,0]
	v_pk_mul_f32 v[10:11], v[10:11], v[14:15]
	v_pk_mul_f32 v[8:9], v[8:9], v[12:13]
	v_pk_mul_f32 v[10:11], v[10:11], v[2:3]
	v_pk_mul_f32 v[2:3], v[8:9], v[0:1]
	v_cvt_pk_bf16_f32 v0, v4, v5
	v_cvt_pk_bf16_f32 v1, v6, v7
	s_nop 0
	v_cvt_pk_bf16_f32 v2, v2, v3
	v_cvt_pk_bf16_f32 v3, v10, v11
	global_store_dwordx4 v[22:23], v[0:3], off
	s_cbranch_vccz .LBB0_192
	s_waitcnt vmcnt(0)
	s_cmpk_gt_u32 s37, 0xff
	s_cbranch_scc1 .LBB0_199
	s_barrier

; #define PG8_STAGE(bufoff, gbase, voff) do { _Pragma("unroll") for (int _i = 0; _i < 2; ++_i) \
;         __builtin_amdgcn_global_load_lds((const unsigned*)((const char*)(gbase) + (voff)[_i]), (PG8_LAS unsigned*)(lds + (bufoff) + ldsw + _i * 8192), 16, 0, 0); } while (0)
; #define PG8_LDA(dst, b, h) do { _Pragma("unroll") for (int m = 0; m < 4; ++m) _Pragma("unroll") for (int k = 0; k < 2; ++k) dst[m][k] = *(const PG8_LAS bf16x8*)(lds + PG8_SA(b, h) + aoff + m * 2048 + k * 1024); } while (0)
; #define PG8_LDB(dst, b, h) do { _Pragma("unroll") for (int n = 0; n < 2; ++n) _Pragma("unroll") for (int k = 0; k < 2; ++k) dst[n][k] = *(const PG8_LAS bf16x8*)(lds + PG8_SB(b, h) + boff + n * 2048 + k * 1024); } while (0)
; #define PG8_WAIT_V(n) asm volatile("s_waitcnt vmcnt(" #n ")" ::: "memory")
; #define PG8_BAR __builtin_amdgcn_s_barrier()
; template <class Epi, class Sched>
; __device__ __forceinline__ void gemm_phase(PG8_LAS unsigned char* lds, const Gemm g, const Sched& S, const Epi& E) {
;     ...
;         for (int t = 0; t < nt; t += 2) {
;             const bool last = (t == nt - 2);
;             const char* a1 = cA + (size_t)(t + 1) * kstep;
;             const char* a2 = last ? nA : cA + (size_t)(t + 2) * kstep; const char* b2 = last ? nB : cB + (size_t)(t + 2) * kstep;
;             const char* a3 = a2 + kstep; const char* b3 = b2 + kstep;
;             if (last && has_next) S.a_ready(nxt);
;             PG8_LDB(B0, 0, 0); PG8_SCHED; PG8_LDA(At, 0, 0); PG8_STAGE(PG8_SA(1, 1), a1 + hstep, voffA);
;             PG8_WAIT_L(8); PG8_BAR; PG8_WAIT_L(0); PG8_MMA(0, 0, At, B0); PG8_BAR; PG8_SCHED;
;             PG8_LDB(B1, 0, 1); PG8_STAGE(PG8_SB(0, 0), b2, voffB);
;             PG8_BAR; PG8_WAIT_L(0); PG8_MMA(0, 1, At, B1); PG8_BAR;
;             PG8_LDA(At, 0, 1); PG8_STAGE(PG8_SA(0, 0), a2, voffA);
;             PG8_BAR; PG8_WAIT_L(0); PG8_MMA(1, 0, At, B0); PG8_BAR; PG8_SCHED;
;             PG8_STAGE(PG8_SB(0, 1), b2 + hstep, voffB);
;             PG8_WAIT_V(6); PG8_BAR; PG8_MMA(1, 1, At, B1); PG8_BAR;
;             PG8_LDB(B0, 1, 0); PG8_SCHED; PG8_LDA(At, 1, 0); PG8_STAGE(PG8_SA(0, 1), a2 + hstep, voffA);
;             PG8_WAIT_L(8); PG8_BAR; PG8_WAIT_L(0); PG8_MMA(0, 0, At, B0); PG8_BAR; PG8_SCHED;
;             PG8_LDB(B1, 1, 1); PG8_STAGE(PG8_SB(1, 0), b3, voffB);
;             PG8_BAR; PG8_WAIT_L(0); PG8_MMA(0, 1, At, B1); PG8_BAR;
.LBB0_285:
	s_add_u32 s55, s24, 0x100
	s_addc_u32 s56, s25, 0
	s_mov_b32 s57, -2
	ds_read_b128 v[154:157], v149
	ds_read_b128 v[158:161], v149 offset:1024
	ds_read_b128 v[166:169], v149 offset:2048
	ds_read_b128 v[170:173], v149 offset:3072
	s_add_u32 s24, s22, 0x100
	s_addc_u32 s25, s23, 0
	s_cmp_eq_u32 s57, 40
	s_cselect_b32 s29, s1, s25
	s_cselect_b32 s28, s0, s24
	s_cselect_b32 s27, s5, s56
	s_cselect_b32 s26, s4, s55
	s_add_i32 m0, s38, 0xc000
	ds_read_b128 v[182:185], v150
	ds_read_b128 v[190:193], v150 offset:1024
	ds_read_b128 v[194:197], v150 offset:2048
	ds_read_b128 v[198:201], v150 offset:3072
	ds_read_b128 v[202:205], v150 offset:4096
	ds_read_b128 v[206:209], v150 offset:5120
	ds_read_b128 v[210:213], v150 offset:6144
	ds_read_b128 v[214:217], v150 offset:7168
	global_load_lds_dwordx4 v136, s[22:23]
	s_nop 1
	s_add_i32 m0, s38, 0xe000
	s_nop 0
	global_load_lds_dwordx4 v138, s[22:23]
	s_waitcnt lgkmcnt(8)
	ds_read_b128 v[218:221], v151
	ds_read_b128 v[222:225], v151 offset:1024
	ds_read_b128 v[226:229], v151 offset:2048
	ds_read_b128 v[230:233], v151 offset:3072
	s_waitcnt vmcnt(8) lgkmcnt(0)
	s_barrier
	v_mfma_f32_16x16x32_bf16 v[124:127], v[154:157], v[182:185], 0
	v_mfma_f32_16x16x32_bf16 v[120:123], v[166:169], v[182:185], 0
	v_mfma_f32_16x16x32_bf16 v[108:111], v[154:157], v[194:197], 0
	v_mfma_f32_16x16x32_bf16 v[104:107], v[166:169], v[194:197], 0
	v_mfma_f32_16x16x32_bf16 v[92:95], v[154:157], v[202:205], 0
	v_mfma_f32_16x16x32_bf16 v[88:91], v[166:169], v[202:205], 0
	v_mfma_f32_16x16x32_bf16 v[76:79], v[154:157], v[210:213], 0
	v_mfma_f32_16x16x32_bf16 v[72:75], v[166:169], v[210:213], 0
	v_mfma_f32_16x16x32_bf16 v[124:127], v[158:161], v[190:193], v[124:127]
	v_mfma_f32_16x16x32_bf16 v[120:123], v[170:173], v[190:193], v[120:123]
	v_mfma_f32_16x16x32_bf16 v[108:111], v[158:161], v[198:201], v[108:111]
	v_mfma_f32_16x16x32_bf16 v[104:107], v[170:173], v[198:201], v[104:107]
	v_mfma_f32_16x16x32_bf16 v[92:95], v[158:161], v[206:209], v[92:95]
	v_mfma_f32_16x16x32_bf16 v[88:91], v[170:173], v[206:209], v[88:91]
	v_mfma_f32_16x16x32_bf16 v[76:79], v[158:161], v[214:217], v[76:79]
	v_mfma_f32_16x16x32_bf16 v[72:75], v[170:173], v[214:217], v[72:75]
	v_mfma_f32_16x16x32_bf16 v[116:119], v[218:221], v[182:185], 0
	v_mfma_f32_16x16x32_bf16 v[112:115], v[226:229], v[182:185], 0
	v_mfma_f32_16x16x32_bf16 v[100:103], v[218:221], v[194:197], 0
	v_mfma_f32_16x16x32_bf16 v[96:99], v[226:229], v[194:197], 0
	v_mfma_f32_16x16x32_bf16 v[84:87], v[218:221], v[202:205], 0
	v_mfma_f32_16x16x32_bf16 v[80:83], v[226:229], v[202:205], 0
	v_mfma_f32_16x16x32_bf16 v[68:71], v[218:221], v[210:213], 0
	v_mfma_f32_16x16x32_bf16 v[64:67], v[226:229], v[210:213], 0
	v_mfma_f32_16x16x32_bf16 v[116:119], v[222:225], v[190:193], v[116:119]
	v_mfma_f32_16x16x32_bf16 v[112:115], v[230:233], v[190:193], v[112:115]
	v_mfma_f32_16x16x32_bf16 v[100:103], v[222:225], v[198:201], v[100:103]
	v_mfma_f32_16x16x32_bf16 v[96:99], v[230:233], v[198:201], v[96:99]
	v_mfma_f32_16x16x32_bf16 v[84:87], v[222:225], v[206:209], v[84:87]
	v_mfma_f32_16x16x32_bf16 v[80:83], v[230:233], v[206:209], v[80:83]
	v_mfma_f32_16x16x32_bf16 v[68:71], v[222:225], v[214:217], v[68:71]
	v_mfma_f32_16x16x32_bf16 v[64:67], v[230:233], v[214:217], v[64:67]
	s_barrier
	ds_read_b128 v[182:185], v150 offset:16384
	ds_read_b128 v[190:193], v150 offset:17408
	ds_read_b128 v[194:197], v150 offset:18432
	ds_read_b128 v[198:201], v150 offset:19456
	ds_read_b128 v[202:205], v150 offset:20480
	ds_read_b128 v[206:209], v150 offset:21504
	ds_read_b128 v[210:213], v150 offset:22528
	ds_read_b128 v[214:217], v150 offset:23552
	s_add_i32 s22, s46, s37
	s_add_u32 s98, s26, s14
	s_addc_u32 s99, s27, s15
	s_mov_b32 m0, s22
	s_nop 0
	global_load_lds_dwordx4 v130, s[26:27]
	s_nop 1
	s_add_i32 m0, s22, 0x2000
	s_nop 0
	global_load_lds_dwordx4 v134, s[26:27]
	s_nop 1
	s_mov_b32 m0, s38
	s_add_u32 s100, s28, s14
	s_addc_u32 s101, s29, s15
	global_load_lds_dwordx4 v128, s[28:29]
	s_nop 1
	s_mov_b32 m0, s39
	s_nop 0
	global_load_lds_dwordx4 v132, s[28:29]
	s_add_u32 s22, s26, 0xb0000
	s_addc_u32 s23, s27, 0
	s_add_i32 s58, s47, s37
	s_mov_b32 m0, s58
	s_nop 0
	global_load_lds_dwordx4 v130, s[22:23]
	s_nop 1
	s_add_i32 m0, s58, 0x2000
	s_nop 0
	global_load_lds_dwordx4 v134, s[22:23]
	s_waitcnt vmcnt(8) lgkmcnt(0)
	s_barrier
	v_mfma_f32_16x16x32_bf16 v[60:63], v[154:157], v[182:185], 0
	v_mfma_f32_16x16x32_bf16 v[56:59], v[166:169], v[182:185], 0
	v_mfma_f32_16x16x32_bf16 v[48:51], v[154:157], v[194:197], 0
	v_mfma_f32_16x16x32_bf16 v[40:43], v[166:169], v[194:197], 0
	v_mfma_f32_16x16x32_bf16 v[32:35], v[154:157], v[202:205], 0
	v_mfma_f32_16x16x32_bf16 v[24:27], v[166:169], v[202:205], 0
	v_mfma_f32_16x16x32_bf16 v[16:19], v[154:157], v[210:213], 0
	v_mfma_f32_16x16x32_bf16 v[8:11], v[166:169], v[210:213], 0
	v_mfma_f32_16x16x32_bf16 v[60:63], v[158:161], v[190:193], v[60:63]
	v_mfma_f32_16x16x32_bf16 v[56:59], v[170:173], v[190:193], v[56:59]
	v_mfma_f32_16x16x32_bf16 v[48:51], v[158:161], v[198:201], v[48:51]
	v_mfma_f32_16x16x32_bf16 v[40:43], v[170:173], v[198:201], v[40:43]
	v_mfma_f32_16x16x32_bf16 v[32:35], v[158:161], v[206:209], v[32:35]
	v_mfma_f32_16x16x32_bf16 v[24:27], v[170:173], v[206:209], v[24:27]
	v_mfma_f32_16x16x32_bf16 v[16:19], v[158:161], v[214:217], v[16:19]
	v_mfma_f32_16x16x32_bf16 v[8:11], v[170:173], v[214:217], v[8:11]
	v_mfma_f32_16x16x32_bf16 v[52:55], v[218:221], v[182:185], 0
	v_mfma_f32_16x16x32_bf16 v[44:47], v[226:229], v[182:185], 0
	v_mfma_f32_16x16x32_bf16 v[36:39], v[218:221], v[194:197], 0
	v_mfma_f32_16x16x32_bf16 v[28:31], v[226:229], v[194:197], 0
	v_mfma_f32_16x16x32_bf16 v[20:23], v[218:221], v[202:205], 0
	v_mfma_f32_16x16x32_bf16 v[12:15], v[226:229], v[202:205], 0
	v_mfma_f32_16x16x32_bf16 v[4:7], v[218:221], v[210:213], 0
	v_mfma_f32_16x16x32_bf16 v[0:3], v[226:229], v[210:213], 0
	v_mfma_f32_16x16x32_bf16 v[52:55], v[222:225], v[190:193], v[52:55]
	v_mfma_f32_16x16x32_bf16 v[44:47], v[230:233], v[190:193], v[44:47]
	v_mfma_f32_16x16x32_bf16 v[36:39], v[222:225], v[198:201], v[36:39]
	v_mfma_f32_16x16x32_bf16 v[28:31], v[230:233], v[198:201], v[28:31]
	v_mfma_f32_16x16x32_bf16 v[20:23], v[222:225], v[206:209], v[20:23]
	v_mfma_f32_16x16x32_bf16 v[12:15], v[230:233], v[206:209], v[12:15]
	v_mfma_f32_16x16x32_bf16 v[4:7], v[222:225], v[214:217], v[4:7]
	v_mfma_f32_16x16x32_bf16 v[0:3], v[230:233], v[214:217], v[0:3]
	s_barrier
; #define PG8_STAGE(bufoff, gbase, voff) do { _Pragma("unroll") for (int _i = 0; _i < 2; ++_i) \
;         __builtin_amdgcn_global_load_lds((const unsigned*)((const char*)(gbase) + (voff)[_i]), (PG8_LAS unsigned*)(lds + (bufoff) + ldsw + _i * 8192), 16, 0, 0); } while (0)
; #define PG8_LDA(dst, b, h) do { _Pragma("unroll") for (int m = 0; m < 4; ++m) _Pragma("unroll") for (int k = 0; k < 2; ++k) dst[m][k] = *(const PG8_LAS bf16x8*)(lds + PG8_SA(b, h) + aoff + m * 2048 + k * 1024); } while (0)
; #define PG8_LDB(dst, b, h) do { _Pragma("unroll") for (int n = 0; n < 2; ++n) _Pragma("unroll") for (int k = 0; k < 2; ++k) dst[n][k] = *(const PG8_LAS bf16x8*)(lds + PG8_SB(b, h) + boff + n * 2048 + k * 1024); } while (0)
; #define PG8_MMA(ai, bj, At, Bt) do { __builtin_amdgcn_s_setprio(1); _Pragma("unroll") for (int m = 0; m < 4; ++m) _Pragma("unroll") for (int n = 0; n < 2; ++n) _Pragma("unroll") for (int k = 0; k < 2; ++k) \
;         acc[ai][bj][m][n] = __builtin_amdgcn_mfma_f32_16x16x32_bf16(Bt[n][k], At[m][k], acc[ai][bj][m][n], 0, 0, 0); __builtin_amdgcn_s_setprio(0); } while (0)
; #define PG8_WAIT_V(n) asm volatile("s_waitcnt vmcnt(" #n ")" ::: "memory")
; #define PG8_WAIT_L(n) asm volatile("s_waitcnt lgkmcnt(" #n ")" ::: "memory")
; #define PG8_BAR __builtin_amdgcn_s_barrier()
; #define PG8_SCHED __builtin_amdgcn_sched_barrier(0)
; template <class Epi, class Sched>
; __device__ __forceinline__ void gemm_phase(PG8_LAS unsigned char* lds, const Gemm g, const Sched& S, const Epi& E) {
;     ...
;             PG8_BAR; PG8_WAIT_L(0); PG8_MMA(1, 0, At, B0); PG8_BAR; PG8_SCHED;
;             PG8_STAGE(PG8_SB(0, 1), b2 + hstep, voffB);
;             PG8_WAIT_V(6); PG8_BAR; PG8_MMA(1, 1, At, B1); PG8_BAR;
;             PG8_LDB(B0, 1, 0); PG8_SCHED; PG8_LDA(At, 1, 0); PG8_STAGE(PG8_SA(0, 1), a2 + hstep, voffA);
;             PG8_WAIT_L(8); PG8_BAR; PG8_WAIT_L(0); PG8_MMA(0, 0, At, B0); PG8_BAR; PG8_SCHED;
;             PG8_LDB(B1, 1, 1); PG8_STAGE(PG8_SB(1, 0), b3, voffB);
;             PG8_BAR; PG8_WAIT_L(0); PG8_MMA(0, 1, At, B1); PG8_BAR;
;             PG8_LDA(At, 1, 1); PG8_STAGE(PG8_SA(1, 0), a3, voffA);
;             PG8_BAR; PG8_WAIT_L(0); PG8_MMA(1, 0, At, B0); PG8_BAR; PG8_SCHED;
;             PG8_STAGE(PG8_SB(1, 1), b3 + hstep, voffB);
;             PG8_WAIT_V(6); PG8_BAR; PG8_MMA(1, 1, At, B1); PG8_BAR;
	s_add_i32 s58, 0, 0x18000
	v_add_u32_e32 v153, s58, v147
	ds_read_b128 v[154:157], v153
	ds_read_b128 v[158:161], v153 offset:1024
	ds_read_b128 v[166:169], v153 offset:2048
	ds_read_b128 v[170:173], v153 offset:3072
	s_add_u32 s22, s28, 0xb0000
	s_addc_u32 s23, s29, 0
	s_mov_b32 m0, s40
	ds_read_b128 v[182:185], v150 offset:32768
	ds_read_b128 v[190:193], v150 offset:33792
	ds_read_b128 v[194:197], v150 offset:34816
	ds_read_b128 v[198:201], v150 offset:35840
	ds_read_b128 v[202:205], v150 offset:36864
	ds_read_b128 v[206:209], v150 offset:37888
	ds_read_b128 v[210:213], v150 offset:38912
	ds_read_b128 v[214:217], v150 offset:39936
	global_load_lds_dwordx4 v128, s[22:23]
	s_nop 1
	s_mov_b32 m0, s41
	s_nop 0
	global_load_lds_dwordx4 v132, s[22:23]
	s_add_i32 s28, 0, 0x1c000
	v_add_u32_e32 v153, s28, v147
	s_waitcnt lgkmcnt(8)
	ds_read_b128 v[218:221], v153
	ds_read_b128 v[222:225], v153 offset:1024
	ds_read_b128 v[226:229], v153 offset:2048
	ds_read_b128 v[230:233], v153 offset:3072
	s_waitcnt vmcnt(8) lgkmcnt(0)
	s_barrier
	v_mfma_f32_16x16x32_bf16 v[124:127], v[154:157], v[182:185], v[124:127]
	v_mfma_f32_16x16x32_bf16 v[120:123], v[166:169], v[182:185], v[120:123]
	v_mfma_f32_16x16x32_bf16 v[108:111], v[154:157], v[194:197], v[108:111]
	v_mfma_f32_16x16x32_bf16 v[104:107], v[166:169], v[194:197], v[104:107]
	v_mfma_f32_16x16x32_bf16 v[92:95], v[154:157], v[202:205], v[92:95]
	v_mfma_f32_16x16x32_bf16 v[88:91], v[166:169], v[202:205], v[88:91]
	v_mfma_f32_16x16x32_bf16 v[76:79], v[154:157], v[210:213], v[76:79]
	v_mfma_f32_16x16x32_bf16 v[72:75], v[166:169], v[210:213], v[72:75]
	v_mfma_f32_16x16x32_bf16 v[124:127], v[158:161], v[190:193], v[124:127]
	v_mfma_f32_16x16x32_bf16 v[120:123], v[170:173], v[190:193], v[120:123]
	v_mfma_f32_16x16x32_bf16 v[108:111], v[158:161], v[198:201], v[108:111]
	v_mfma_f32_16x16x32_bf16 v[104:107], v[170:173], v[198:201], v[104:107]
	v_mfma_f32_16x16x32_bf16 v[92:95], v[158:161], v[206:209], v[92:95]
	v_mfma_f32_16x16x32_bf16 v[88:91], v[170:173], v[206:209], v[88:91]
	v_mfma_f32_16x16x32_bf16 v[76:79], v[158:161], v[214:217], v[76:79]
	v_mfma_f32_16x16x32_bf16 v[72:75], v[170:173], v[214:217], v[72:75]
	v_mfma_f32_16x16x32_bf16 v[116:119], v[218:221], v[182:185], v[116:119]
	v_mfma_f32_16x16x32_bf16 v[112:115], v[226:229], v[182:185], v[112:115]
	v_mfma_f32_16x16x32_bf16 v[100:103], v[218:221], v[194:197], v[100:103]
	v_mfma_f32_16x16x32_bf16 v[96:99], v[226:229], v[194:197], v[96:99]
	v_mfma_f32_16x16x32_bf16 v[84:87], v[218:221], v[202:205], v[84:87]
	v_mfma_f32_16x16x32_bf16 v[80:83], v[226:229], v[202:205], v[80:83]
	v_mfma_f32_16x16x32_bf16 v[68:71], v[218:221], v[210:213], v[68:71]
	v_mfma_f32_16x16x32_bf16 v[64:67], v[226:229], v[210:213], v[64:67]
	v_mfma_f32_16x16x32_bf16 v[116:119], v[222:225], v[190:193], v[116:119]
	v_mfma_f32_16x16x32_bf16 v[112:115], v[230:233], v[190:193], v[112:115]
	v_mfma_f32_16x16x32_bf16 v[100:103], v[222:225], v[198:201], v[100:103]
	v_mfma_f32_16x16x32_bf16 v[96:99], v[230:233], v[198:201], v[96:99]
	v_mfma_f32_16x16x32_bf16 v[84:87], v[222:225], v[206:209], v[84:87]
	v_mfma_f32_16x16x32_bf16 v[80:83], v[230:233], v[206:209], v[80:83]
	v_mfma_f32_16x16x32_bf16 v[68:71], v[222:225], v[214:217], v[68:71]
	v_mfma_f32_16x16x32_bf16 v[64:67], v[230:233], v[214:217], v[64:67]
	s_barrier
	ds_read_b128 v[182:185], v150 offset:49152
	ds_read_b128 v[190:193], v150 offset:50176
	ds_read_b128 v[194:197], v150 offset:51200
	ds_read_b128 v[198:201], v150 offset:52224
	ds_read_b128 v[202:205], v150 offset:53248
	ds_read_b128 v[206:209], v150 offset:54272
	ds_read_b128 v[210:213], v150 offset:55296
	ds_read_b128 v[214:217], v150 offset:56320
	s_add_i32 s22, s58, s37
	s_mov_b32 m0, s22
	s_nop 0
	global_load_lds_dwordx4 v130, s[98:99]
	s_nop 1
	s_add_i32 m0, s22, 0x2000
	s_nop 0
	global_load_lds_dwordx4 v134, s[98:99]
	s_nop 1
	s_mov_b32 m0, s43
	s_nop 0
	global_load_lds_dwordx4 v128, s[100:101]
	s_nop 1
	s_mov_b32 m0, s44
	s_nop 0
	global_load_lds_dwordx4 v132, s[100:101]
	s_add_u32 s22, s26, 0xb0080
	s_addc_u32 s23, s27, 0
	s_add_i32 s26, s28, s37
	s_mov_b32 m0, s26
	s_nop 0
	global_load_lds_dwordx4 v130, s[22:23]
	s_nop 1
	s_add_i32 m0, s26, 0x2000
	s_nop 0
	global_load_lds_dwordx4 v134, s[22:23]
	s_waitcnt vmcnt(8) lgkmcnt(0)
	s_barrier
	v_mfma_f32_16x16x32_bf16 v[60:63], v[154:157], v[182:185], v[60:63]
	v_mfma_f32_16x16x32_bf16 v[56:59], v[166:169], v[182:185], v[56:59]
	v_mfma_f32_16x16x32_bf16 v[48:51], v[154:157], v[194:197], v[48:51]
	v_mfma_f32_16x16x32_bf16 v[40:43], v[166:169], v[194:197], v[40:43]
	v_mfma_f32_16x16x32_bf16 v[32:35], v[154:157], v[202:205], v[32:35]
	v_mfma_f32_16x16x32_bf16 v[24:27], v[166:169], v[202:205], v[24:27]
	v_mfma_f32_16x16x32_bf16 v[16:19], v[154:157], v[210:213], v[16:19]
	v_mfma_f32_16x16x32_bf16 v[8:11], v[166:169], v[210:213], v[8:11]
	v_mfma_f32_16x16x32_bf16 v[60:63], v[158:161], v[190:193], v[60:63]
	v_mfma_f32_16x16x32_bf16 v[56:59], v[170:173], v[190:193], v[56:59]
	v_mfma_f32_16x16x32_bf16 v[48:51], v[158:161], v[198:201], v[48:51]
	v_mfma_f32_16x16x32_bf16 v[40:43], v[170:173], v[198:201], v[40:43]
	v_mfma_f32_16x16x32_bf16 v[32:35], v[158:161], v[206:209], v[32:35]
	v_mfma_f32_16x16x32_bf16 v[24:27], v[170:173], v[206:209], v[24:27]
	v_mfma_f32_16x16x32_bf16 v[16:19], v[158:161], v[214:217], v[16:19]
	v_mfma_f32_16x16x32_bf16 v[8:11], v[170:173], v[214:217], v[8:11]
	v_mfma_f32_16x16x32_bf16 v[52:55], v[218:221], v[182:185], v[52:55]
	v_mfma_f32_16x16x32_bf16 v[44:47], v[226:229], v[182:185], v[44:47]
	v_mfma_f32_16x16x32_bf16 v[36:39], v[218:221], v[194:197], v[36:39]
	v_mfma_f32_16x16x32_bf16 v[28:31], v[226:229], v[194:197], v[28:31]
	v_mfma_f32_16x16x32_bf16 v[20:23], v[218:221], v[202:205], v[20:23]
	v_mfma_f32_16x16x32_bf16 v[12:15], v[226:229], v[202:205], v[12:15]
	v_mfma_f32_16x16x32_bf16 v[4:7], v[218:221], v[210:213], v[4:7]
	v_mfma_f32_16x16x32_bf16 v[0:3], v[226:229], v[210:213], v[0:3]
	v_mfma_f32_16x16x32_bf16 v[52:55], v[222:225], v[190:193], v[52:55]
	v_mfma_f32_16x16x32_bf16 v[44:47], v[230:233], v[190:193], v[44:47]
	v_mfma_f32_16x16x32_bf16 v[36:39], v[222:225], v[198:201], v[36:39]
	v_mfma_f32_16x16x32_bf16 v[28:31], v[230:233], v[198:201], v[28:31]
	v_mfma_f32_16x16x32_bf16 v[20:23], v[222:225], v[206:209], v[20:23]
	v_mfma_f32_16x16x32_bf16 v[12:15], v[230:233], v[206:209], v[12:15]
	v_mfma_f32_16x16x32_bf16 v[4:7], v[222:225], v[214:217], v[4:7]
	v_mfma_f32_16x16x32_bf16 v[0:3], v[230:233], v[214:217], v[0:3]
	s_barrier
	s_add_i32 s57, s57, 2
	s_add_u32 s55, s55, 0x100
	s_addc_u32 s56, s56, 0
	s_cmp_gt_u32 s57, 41
	s_mov_b64 s[22:23], s[24:25]
; #define PG8_STAGE(bufoff, gbase, voff) do { _Pragma("unroll") for (int _i = 0; _i < 2; ++_i) \
;         __builtin_amdgcn_global_load_lds((const unsigned*)((const char*)(gbase) + (voff)[_i]), (PG8_LAS unsigned*)(lds + (bufoff) + ldsw + _i * 8192), 16, 0, 0); } while (0)
; #define PG8_LDA(dst, b, h) do { _Pragma("unroll") for (int m = 0; m < 4; ++m) _Pragma("unroll") for (int k = 0; k < 2; ++k) dst[m][k] = *(const PG8_LAS bf16x8*)(lds + PG8_SA(b, h) + aoff + m * 2048 + k * 1024); } while (0)
; #define PG8_LDB(dst, b, h) do { _Pragma("unroll") for (int n = 0; n < 2; ++n) _Pragma("unroll") for (int k = 0; k < 2; ++k) dst[n][k] = *(const PG8_LAS bf16x8*)(lds + PG8_SB(b, h) + boff + n * 2048 + k * 1024); } while (0)
; #define PG8_MMA(ai, bj, At, Bt) do { __builtin_amdgcn_s_setprio(1); _Pragma("unroll") for (int m = 0; m < 4; ++m) _Pragma("unroll") for (int n = 0; n < 2; ++n) _Pragma("unroll") for (int k = 0; k < 2; ++k) \
;         acc[ai][bj][m][n] = __builtin_amdgcn_mfma_f32_16x16x32_bf16(Bt[n][k], At[m][k], acc[ai][bj][m][n], 0, 0, 0); __builtin_amdgcn_s_setprio(0); } while (0)
; #define PG8_WAIT_V(n) asm volatile("s_waitcnt vmcnt(" #n ")" ::: "memory")
; #define PG8_WAIT_L(n) asm volatile("s_waitcnt lgkmcnt(" #n ")" ::: "memory")
; template <class Epi, class Sched>
; __device__ __forceinline__ void gemm_phase(PG8_LAS unsigned char* lds, const Gemm g, const Sched& S, const Epi& E) {
;     ...
;             PG8_LDB(B0, 0, 0); PG8_SCHED; PG8_LDA(At, 0, 0); PG8_STAGE(PG8_SA(1, 1), a1 + hstep, voffA);
;             PG8_WAIT_L(8); PG8_BAR; PG8_WAIT_L(0); PG8_MMA(0, 0, At, B0); PG8_BAR; PG8_SCHED;
;             PG8_LDB(B1, 0, 1); PG8_STAGE(PG8_SB(0, 0), b2, voffB);
;             PG8_BAR; PG8_WAIT_L(0); PG8_MMA(0, 1, At, B1); PG8_BAR;
;             PG8_LDA(At, 0, 1); PG8_STAGE(PG8_SA(0, 0), a2, voffA);
;             PG8_BAR; PG8_WAIT_L(0); PG8_MMA(1, 0, At, B0); PG8_BAR; PG8_SCHED;
;             PG8_STAGE(PG8_SB(0, 1), b2 + hstep, voffB);
;             PG8_WAIT_V(6); PG8_BAR; PG8_MMA(1, 1, At, B1); PG8_BAR;
;             PG8_LDB(B0, 1, 0); PG8_SCHED; PG8_LDA(At, 1, 0); PG8_STAGE(PG8_SA(0, 1), a2 + hstep, voffA);
;             PG8_WAIT_L(8); PG8_BAR; PG8_WAIT_L(0); PG8_MMA(0, 0, At, B0); PG8_BAR; PG8_SCHED;
;             PG8_LDB(B1, 1, 1); PG8_STAGE(PG8_SB(1, 0), b3, voffB);
;             PG8_BAR; PG8_WAIT_L(0); PG8_MMA(0, 1, At, B1); PG8_BAR;
.LBB0_286:
	ds_read_b128 v[154:157], v149
	ds_read_b128 v[158:161], v149 offset:1024
	ds_read_b128 v[166:169], v149 offset:2048
	ds_read_b128 v[170:173], v149 offset:3072
	s_add_u32 s24, s22, 0x100
	s_addc_u32 s25, s23, 0
	s_cmp_eq_u32 s57, 40
	s_cselect_b32 s29, s1, s25
	s_cselect_b32 s28, s0, s24
	s_cselect_b32 s27, s5, s56
	s_cselect_b32 s26, s4, s55
	s_add_i32 m0, s38, 0xc000
	ds_read_b128 v[182:185], v150
	ds_read_b128 v[190:193], v150 offset:1024
	ds_read_b128 v[194:197], v150 offset:2048
	ds_read_b128 v[198:201], v150 offset:3072
	ds_read_b128 v[202:205], v150 offset:4096
	ds_read_b128 v[206:209], v150 offset:5120
	ds_read_b128 v[210:213], v150 offset:6144
	ds_read_b128 v[214:217], v150 offset:7168
	global_load_lds_dwordx4 v136, s[22:23]
	s_nop 1
	s_add_i32 m0, s38, 0xe000
	s_nop 0
	global_load_lds_dwordx4 v138, s[22:23]
	s_waitcnt lgkmcnt(8)
	ds_read_b128 v[218:221], v151
	ds_read_b128 v[222:225], v151 offset:1024
	ds_read_b128 v[226:229], v151 offset:2048
	ds_read_b128 v[230:233], v151 offset:3072
	s_waitcnt vmcnt(8) lgkmcnt(0)
	s_barrier
	v_mfma_f32_16x16x32_bf16 v[124:127], v[154:157], v[182:185], v[124:127]
	v_mfma_f32_16x16x32_bf16 v[120:123], v[166:169], v[182:185], v[120:123]
	v_mfma_f32_16x16x32_bf16 v[108:111], v[154:157], v[194:197], v[108:111]
	v_mfma_f32_16x16x32_bf16 v[104:107], v[166:169], v[194:197], v[104:107]
	v_mfma_f32_16x16x32_bf16 v[92:95], v[154:157], v[202:205], v[92:95]
	v_mfma_f32_16x16x32_bf16 v[88:91], v[166:169], v[202:205], v[88:91]
	v_mfma_f32_16x16x32_bf16 v[76:79], v[154:157], v[210:213], v[76:79]
	v_mfma_f32_16x16x32_bf16 v[72:75], v[166:169], v[210:213], v[72:75]
	v_mfma_f32_16x16x32_bf16 v[124:127], v[158:161], v[190:193], v[124:127]
	v_mfma_f32_16x16x32_bf16 v[120:123], v[170:173], v[190:193], v[120:123]
	v_mfma_f32_16x16x32_bf16 v[108:111], v[158:161], v[198:201], v[108:111]
	v_mfma_f32_16x16x32_bf16 v[104:107], v[170:173], v[198:201], v[104:107]
	v_mfma_f32_16x16x32_bf16 v[92:95], v[158:161], v[206:209], v[92:95]
	v_mfma_f32_16x16x32_bf16 v[88:91], v[170:173], v[206:209], v[88:91]
	v_mfma_f32_16x16x32_bf16 v[76:79], v[158:161], v[214:217], v[76:79]
	v_mfma_f32_16x16x32_bf16 v[72:75], v[170:173], v[214:217], v[72:75]
	v_mfma_f32_16x16x32_bf16 v[116:119], v[218:221], v[182:185], v[116:119]
	v_mfma_f32_16x16x32_bf16 v[112:115], v[226:229], v[182:185], v[112:115]
	v_mfma_f32_16x16x32_bf16 v[100:103], v[218:221], v[194:197], v[100:103]
	v_mfma_f32_16x16x32_bf16 v[96:99], v[226:229], v[194:197], v[96:99]
	v_mfma_f32_16x16x32_bf16 v[84:87], v[218:221], v[202:205], v[84:87]
	v_mfma_f32_16x16x32_bf16 v[80:83], v[226:229], v[202:205], v[80:83]
	v_mfma_f32_16x16x32_bf16 v[68:71], v[218:221], v[210:213], v[68:71]
	v_mfma_f32_16x16x32_bf16 v[64:67], v[226:229], v[210:213], v[64:67]
	v_mfma_f32_16x16x32_bf16 v[116:119], v[222:225], v[190:193], v[116:119]
	v_mfma_f32_16x16x32_bf16 v[112:115], v[230:233], v[190:193], v[112:115]
	v_mfma_f32_16x16x32_bf16 v[100:103], v[222:225], v[198:201], v[100:103]
	v_mfma_f32_16x16x32_bf16 v[96:99], v[230:233], v[198:201], v[96:99]
	v_mfma_f32_16x16x32_bf16 v[84:87], v[222:225], v[206:209], v[84:87]
	v_mfma_f32_16x16x32_bf16 v[80:83], v[230:233], v[206:209], v[80:83]
	v_mfma_f32_16x16x32_bf16 v[68:71], v[222:225], v[214:217], v[68:71]
	v_mfma_f32_16x16x32_bf16 v[64:67], v[230:233], v[214:217], v[64:67]
	s_barrier
	ds_read_b128 v[182:185], v150 offset:16384
	ds_read_b128 v[190:193], v150 offset:17408
	ds_read_b128 v[194:197], v150 offset:18432
	ds_read_b128 v[198:201], v150 offset:19456
	ds_read_b128 v[202:205], v150 offset:20480
	ds_read_b128 v[206:209], v150 offset:21504
	ds_read_b128 v[210:213], v150 offset:22528
	ds_read_b128 v[214:217], v150 offset:23552
	s_add_i32 s22, s46, s37
	s_add_u32 s98, s26, s14
	s_addc_u32 s99, s27, s15
	s_mov_b32 m0, s22
	s_nop 0
	global_load_lds_dwordx4 v130, s[26:27]
	s_nop 1
	s_add_i32 m0, s22, 0x2000
	s_nop 0
	global_load_lds_dwordx4 v134, s[26:27]
	s_nop 1
	s_mov_b32 m0, s38
	s_add_u32 s100, s28, s14
	s_addc_u32 s101, s29, s15
	global_load_lds_dwordx4 v128, s[28:29]
	s_nop 1
	s_mov_b32 m0, s39
	s_nop 0
	global_load_lds_dwordx4 v132, s[28:29]
	s_add_u32 s22, s26, 0xb0000
	s_addc_u32 s23, s27, 0
	s_add_i32 s58, s47, s37
	s_mov_b32 m0, s58
	s_nop 0
	global_load_lds_dwordx4 v130, s[22:23]
	s_nop 1
	s_add_i32 m0, s58, 0x2000
	s_nop 0
	global_load_lds_dwordx4 v134, s[22:23]
	s_waitcnt vmcnt(8) lgkmcnt(0)
	s_barrier
	v_mfma_f32_16x16x32_bf16 v[60:63], v[154:157], v[182:185], v[60:63]
	v_mfma_f32_16x16x32_bf16 v[56:59], v[166:169], v[182:185], v[56:59]
	v_mfma_f32_16x16x32_bf16 v[48:51], v[154:157], v[194:197], v[48:51]
	v_mfma_f32_16x16x32_bf16 v[40:43], v[166:169], v[194:197], v[40:43]
	v_mfma_f32_16x16x32_bf16 v[32:35], v[154:157], v[202:205], v[32:35]
	v_mfma_f32_16x16x32_bf16 v[24:27], v[166:169], v[202:205], v[24:27]
	v_mfma_f32_16x16x32_bf16 v[16:19], v[154:157], v[210:213], v[16:19]
	v_mfma_f32_16x16x32_bf16 v[8:11], v[166:169], v[210:213], v[8:11]
	v_mfma_f32_16x16x32_bf16 v[60:63], v[158:161], v[190:193], v[60:63]
	v_mfma_f32_16x16x32_bf16 v[56:59], v[170:173], v[190:193], v[56:59]
	v_mfma_f32_16x16x32_bf16 v[48:51], v[158:161], v[198:201], v[48:51]
	v_mfma_f32_16x16x32_bf16 v[40:43], v[170:173], v[198:201], v[40:43]
	v_mfma_f32_16x16x32_bf16 v[32:35], v[158:161], v[206:209], v[32:35]
	v_mfma_f32_16x16x32_bf16 v[24:27], v[170:173], v[206:209], v[24:27]
	v_mfma_f32_16x16x32_bf16 v[16:19], v[158:161], v[214:217], v[16:19]
	v_mfma_f32_16x16x32_bf16 v[8:11], v[170:173], v[214:217], v[8:11]
	v_mfma_f32_16x16x32_bf16 v[52:55], v[218:221], v[182:185], v[52:55]
	v_mfma_f32_16x16x32_bf16 v[44:47], v[226:229], v[182:185], v[44:47]
	v_mfma_f32_16x16x32_bf16 v[36:39], v[218:221], v[194:197], v[36:39]
	v_mfma_f32_16x16x32_bf16 v[28:31], v[226:229], v[194:197], v[28:31]
	v_mfma_f32_16x16x32_bf16 v[20:23], v[218:221], v[202:205], v[20:23]
	v_mfma_f32_16x16x32_bf16 v[12:15], v[226:229], v[202:205], v[12:15]
	v_mfma_f32_16x16x32_bf16 v[4:7], v[218:221], v[210:213], v[4:7]
	v_mfma_f32_16x16x32_bf16 v[0:3], v[226:229], v[210:213], v[0:3]
	v_mfma_f32_16x16x32_bf16 v[52:55], v[222:225], v[190:193], v[52:55]
	v_mfma_f32_16x16x32_bf16 v[44:47], v[230:233], v[190:193], v[44:47]
	v_mfma_f32_16x16x32_bf16 v[36:39], v[222:225], v[198:201], v[36:39]
	v_mfma_f32_16x16x32_bf16 v[28:31], v[230:233], v[198:201], v[28:31]
	v_mfma_f32_16x16x32_bf16 v[20:23], v[222:225], v[206:209], v[20:23]
	v_mfma_f32_16x16x32_bf16 v[12:15], v[230:233], v[206:209], v[12:15]
	v_mfma_f32_16x16x32_bf16 v[4:7], v[222:225], v[214:217], v[4:7]
	v_mfma_f32_16x16x32_bf16 v[0:3], v[230:233], v[214:217], v[0:3]
	s_barrier
; #define PG8_STAGE(bufoff, gbase, voff) do { _Pragma("unroll") for (int _i = 0; _i < 2; ++_i) \
;         __builtin_amdgcn_global_load_lds((const unsigned*)((const char*)(gbase) + (voff)[_i]), (PG8_LAS unsigned*)(lds + (bufoff) + ldsw + _i * 8192), 16, 0, 0); } while (0)
; #define PG8_LDA(dst, b, h) do { _Pragma("unroll") for (int m = 0; m < 4; ++m) _Pragma("unroll") for (int k = 0; k < 2; ++k) dst[m][k] = *(const PG8_LAS bf16x8*)(lds + PG8_SA(b, h) + aoff + m * 2048 + k * 1024); } while (0)
; #define PG8_LDB(dst, b, h) do { _Pragma("unroll") for (int n = 0; n < 2; ++n) _Pragma("unroll") for (int k = 0; k < 2; ++k) dst[n][k] = *(const PG8_LAS bf16x8*)(lds + PG8_SB(b, h) + boff + n * 2048 + k * 1024); } while (0)
; #define PG8_MMA(ai, bj, At, Bt) do { __builtin_amdgcn_s_setprio(1); _Pragma("unroll") for (int m = 0; m < 4; ++m) _Pragma("unroll") for (int n = 0; n < 2; ++n) _Pragma("unroll") for (int k = 0; k < 2; ++k) \
;         acc[ai][bj][m][n] = __builtin_amdgcn_mfma_f32_16x16x32_bf16(Bt[n][k], At[m][k], acc[ai][bj][m][n], 0, 0, 0); __builtin_amdgcn_s_setprio(0); } while (0)
; #define PG8_WAIT_V(n) asm volatile("s_waitcnt vmcnt(" #n ")" ::: "memory")
; #define PG8_WAIT_L(n) asm volatile("s_waitcnt lgkmcnt(" #n ")" ::: "memory")
; #define PG8_BAR __builtin_amdgcn_s_barrier()
; #define PG8_SCHED __builtin_amdgcn_sched_barrier(0)
; template <class Epi, class Sched>
; __device__ __forceinline__ void gemm_phase(PG8_LAS unsigned char* lds, const Gemm g, const Sched& S, const Epi& E) {
;     ...
;             PG8_LDB(B0, 1, 0); PG8_SCHED; PG8_LDA(At, 1, 0); PG8_STAGE(PG8_SA(0, 1), a2 + hstep, voffA);
;             PG8_WAIT_L(8); PG8_BAR; PG8_WAIT_L(0); PG8_MMA(0, 0, At, B0); PG8_BAR; PG8_SCHED;
;             PG8_LDB(B1, 1, 1); PG8_STAGE(PG8_SB(1, 0), b3, voffB);
;             PG8_BAR; PG8_WAIT_L(0); PG8_MMA(0, 1, At, B1); PG8_BAR;
;             PG8_LDA(At, 1, 1); PG8_STAGE(PG8_SA(1, 0), a3, voffA);
;             PG8_BAR; PG8_WAIT_L(0); PG8_MMA(1, 0, At, B0); PG8_BAR; PG8_SCHED;
;             PG8_STAGE(PG8_SB(1, 1), b3 + hstep, voffB);
;             PG8_WAIT_V(6); PG8_BAR; PG8_MMA(1, 1, At, B1); PG8_BAR;
	s_add_i32 s58, 0, 0x18000
	v_add_u32_e32 v153, s58, v147
	ds_read_b128 v[154:157], v153
	ds_read_b128 v[158:161], v153 offset:1024
	ds_read_b128 v[166:169], v153 offset:2048
	ds_read_b128 v[170:173], v153 offset:3072
	s_add_u32 s22, s28, 0xb0000
	s_addc_u32 s23, s29, 0
	s_mov_b32 m0, s40
	ds_read_b128 v[182:185], v150 offset:32768
	ds_read_b128 v[190:193], v150 offset:33792
	ds_read_b128 v[194:197], v150 offset:34816
	ds_read_b128 v[198:201], v150 offset:35840
	ds_read_b128 v[202:205], v150 offset:36864
	ds_read_b128 v[206:209], v150 offset:37888
	ds_read_b128 v[210:213], v150 offset:38912
	ds_read_b128 v[214:217], v150 offset:39936
	global_load_lds_dwordx4 v128, s[22:23]
	s_nop 1
	s_mov_b32 m0, s41
	s_nop 0
	global_load_lds_dwordx4 v132, s[22:23]
	s_add_i32 s28, 0, 0x1c000
	v_add_u32_e32 v153, s28, v147
	s_waitcnt lgkmcnt(8)
	ds_read_b128 v[218:221], v153
	ds_read_b128 v[222:225], v153 offset:1024
	ds_read_b128 v[226:229], v153 offset:2048
	ds_read_b128 v[230:233], v153 offset:3072
	s_waitcnt vmcnt(8) lgkmcnt(0)
	s_barrier
	v_mfma_f32_16x16x32_bf16 v[124:127], v[154:157], v[182:185], v[124:127]
	v_mfma_f32_16x16x32_bf16 v[120:123], v[166:169], v[182:185], v[120:123]
	v_mfma_f32_16x16x32_bf16 v[108:111], v[154:157], v[194:197], v[108:111]
	v_mfma_f32_16x16x32_bf16 v[104:107], v[166:169], v[194:197], v[104:107]
	v_mfma_f32_16x16x32_bf16 v[92:95], v[154:157], v[202:205], v[92:95]
	v_mfma_f32_16x16x32_bf16 v[88:91], v[166:169], v[202:205], v[88:91]
	v_mfma_f32_16x16x32_bf16 v[76:79], v[154:157], v[210:213], v[76:79]
	v_mfma_f32_16x16x32_bf16 v[72:75], v[166:169], v[210:213], v[72:75]
	v_mfma_f32_16x16x32_bf16 v[124:127], v[158:161], v[190:193], v[124:127]
	v_mfma_f32_16x16x32_bf16 v[120:123], v[170:173], v[190:193], v[120:123]
	v_mfma_f32_16x16x32_bf16 v[108:111], v[158:161], v[198:201], v[108:111]
	v_mfma_f32_16x16x32_bf16 v[104:107], v[170:173], v[198:201], v[104:107]
	v_mfma_f32_16x16x32_bf16 v[92:95], v[158:161], v[206:209], v[92:95]
	v_mfma_f32_16x16x32_bf16 v[88:91], v[170:173], v[206:209], v[88:91]
	v_mfma_f32_16x16x32_bf16 v[76:79], v[158:161], v[214:217], v[76:79]
	v_mfma_f32_16x16x32_bf16 v[72:75], v[170:173], v[214:217], v[72:75]
	v_mfma_f32_16x16x32_bf16 v[116:119], v[218:221], v[182:185], v[116:119]
	v_mfma_f32_16x16x32_bf16 v[112:115], v[226:229], v[182:185], v[112:115]
	v_mfma_f32_16x16x32_bf16 v[100:103], v[218:221], v[194:197], v[100:103]
	v_mfma_f32_16x16x32_bf16 v[96:99], v[226:229], v[194:197], v[96:99]
	v_mfma_f32_16x16x32_bf16 v[84:87], v[218:221], v[202:205], v[84:87]
	v_mfma_f32_16x16x32_bf16 v[80:83], v[226:229], v[202:205], v[80:83]
	v_mfma_f32_16x16x32_bf16 v[68:71], v[218:221], v[210:213], v[68:71]
	v_mfma_f32_16x16x32_bf16 v[64:67], v[226:229], v[210:213], v[64:67]
	v_mfma_f32_16x16x32_bf16 v[116:119], v[222:225], v[190:193], v[116:119]
	v_mfma_f32_16x16x32_bf16 v[112:115], v[230:233], v[190:193], v[112:115]
	v_mfma_f32_16x16x32_bf16 v[100:103], v[222:225], v[198:201], v[100:103]
	v_mfma_f32_16x16x32_bf16 v[96:99], v[230:233], v[198:201], v[96:99]
	v_mfma_f32_16x16x32_bf16 v[84:87], v[222:225], v[206:209], v[84:87]
	v_mfma_f32_16x16x32_bf16 v[80:83], v[230:233], v[206:209], v[80:83]
	v_mfma_f32_16x16x32_bf16 v[68:71], v[222:225], v[214:217], v[68:71]
	v_mfma_f32_16x16x32_bf16 v[64:67], v[230:233], v[214:217], v[64:67]
	s_barrier
	ds_read_b128 v[182:185], v150 offset:49152
	ds_read_b128 v[190:193], v150 offset:50176
	ds_read_b128 v[194:197], v150 offset:51200
	ds_read_b128 v[198:201], v150 offset:52224
	ds_read_b128 v[202:205], v150 offset:53248
	ds_read_b128 v[206:209], v150 offset:54272
	ds_read_b128 v[210:213], v150 offset:55296
	ds_read_b128 v[214:217], v150 offset:56320
	s_add_i32 s22, s58, s37
	s_mov_b32 m0, s22
	s_nop 0
	global_load_lds_dwordx4 v130, s[98:99]
	s_nop 1
	s_add_i32 m0, s22, 0x2000
	s_nop 0
	global_load_lds_dwordx4 v134, s[98:99]
	s_nop 1
	s_mov_b32 m0, s43
	s_nop 0
	global_load_lds_dwordx4 v128, s[100:101]
	s_nop 1
	s_mov_b32 m0, s44
	s_nop 0
	global_load_lds_dwordx4 v132, s[100:101]
	s_add_u32 s22, s26, 0xb0080
	s_addc_u32 s23, s27, 0
	s_add_i32 s26, s28, s37
	s_mov_b32 m0, s26
	s_nop 0
	global_load_lds_dwordx4 v130, s[22:23]
	s_nop 1
	s_add_i32 m0, s26, 0x2000
	s_nop 0
	global_load_lds_dwordx4 v134, s[22:23]
	s_waitcnt vmcnt(8) lgkmcnt(0)
	s_barrier
	v_mfma_f32_16x16x32_bf16 v[60:63], v[154:157], v[182:185], v[60:63]
	v_mfma_f32_16x16x32_bf16 v[56:59], v[166:169], v[182:185], v[56:59]
	v_mfma_f32_16x16x32_bf16 v[48:51], v[154:157], v[194:197], v[48:51]
	v_mfma_f32_16x16x32_bf16 v[40:43], v[166:169], v[194:197], v[40:43]
	v_mfma_f32_16x16x32_bf16 v[32:35], v[154:157], v[202:205], v[32:35]
	v_mfma_f32_16x16x32_bf16 v[24:27], v[166:169], v[202:205], v[24:27]
	v_mfma_f32_16x16x32_bf16 v[16:19], v[154:157], v[210:213], v[16:19]
	v_mfma_f32_16x16x32_bf16 v[8:11], v[166:169], v[210:213], v[8:11]
	v_mfma_f32_16x16x32_bf16 v[60:63], v[158:161], v[190:193], v[60:63]
	v_mfma_f32_16x16x32_bf16 v[56:59], v[170:173], v[190:193], v[56:59]
	v_mfma_f32_16x16x32_bf16 v[48:51], v[158:161], v[198:201], v[48:51]
	v_mfma_f32_16x16x32_bf16 v[40:43], v[170:173], v[198:201], v[40:43]
	v_mfma_f32_16x16x32_bf16 v[32:35], v[158:161], v[206:209], v[32:35]
	v_mfma_f32_16x16x32_bf16 v[24:27], v[170:173], v[206:209], v[24:27]
	v_mfma_f32_16x16x32_bf16 v[16:19], v[158:161], v[214:217], v[16:19]
	v_mfma_f32_16x16x32_bf16 v[8:11], v[170:173], v[214:217], v[8:11]
	v_mfma_f32_16x16x32_bf16 v[52:55], v[218:221], v[182:185], v[52:55]
	v_mfma_f32_16x16x32_bf16 v[44:47], v[226:229], v[182:185], v[44:47]
	v_mfma_f32_16x16x32_bf16 v[36:39], v[218:221], v[194:197], v[36:39]
	v_mfma_f32_16x16x32_bf16 v[28:31], v[226:229], v[194:197], v[28:31]
	v_mfma_f32_16x16x32_bf16 v[20:23], v[218:221], v[202:205], v[20:23]
	v_mfma_f32_16x16x32_bf16 v[12:15], v[226:229], v[202:205], v[12:15]
	v_mfma_f32_16x16x32_bf16 v[4:7], v[218:221], v[210:213], v[4:7]
	v_mfma_f32_16x16x32_bf16 v[0:3], v[226:229], v[210:213], v[0:3]
	v_mfma_f32_16x16x32_bf16 v[52:55], v[222:225], v[190:193], v[52:55]
	v_mfma_f32_16x16x32_bf16 v[44:47], v[230:233], v[190:193], v[44:47]
	v_mfma_f32_16x16x32_bf16 v[36:39], v[222:225], v[198:201], v[36:39]
	v_mfma_f32_16x16x32_bf16 v[28:31], v[230:233], v[198:201], v[28:31]
	v_mfma_f32_16x16x32_bf16 v[20:23], v[222:225], v[206:209], v[20:23]
	v_mfma_f32_16x16x32_bf16 v[12:15], v[230:233], v[206:209], v[12:15]
	v_mfma_f32_16x16x32_bf16 v[4:7], v[222:225], v[214:217], v[4:7]
	v_mfma_f32_16x16x32_bf16 v[0:3], v[230:233], v[214:217], v[0:3]
	s_barrier
; __device__ __forceinline__ unsigned cvt_pk_bf16(float lo, float hi) { unsigned r; asm volatile("v_cvt_pk_bf16_f32 %0, %1, %2" : "=v"(r) : "v"(lo), "v"(hi)); return r; }
; __device__ __forceinline__ float flogsig16(float x) { return (fminf(x, 0.f) - __logf(1.0f + __expf(-fabsf(x)))) * 0.0625f; }
;     __device__ __forceinline__ void operator()(const f32x4 (&acc)[2][2][4][2], const Unit& u, int wr, int wc, int fr, int fq) const {
;     ...
;         const int row0 = u.pm * BM + wr * 64 + fr, col0 = u.pn * BM + wc * 32 + 8 * fq, bcol0 = wc * 32 + 8 * fq;
;         f32x4 bv[2][2];
; #pragma unroll
;         for (int bj = 0; bj < 2; ++bj)
; #pragma unroll
;             for (int n = 0; n < 2; ++n) bv[bj][n] = bias ? *(const f32x4*)(bias + bcol0 + bj * HALF + 4 * n) : (f32x4){0.f, 0.f, 0.f, 0.f};
; #pragma unroll
;         for (int ai = 0; ai < 2; ++ai)
; #pragma unroll
;             for (int m = 0; m < 4; ++m) { bf16_t* rowp = O + (size_t)(row0 + ai * HALF + m * 16) * ldc + col0;
; #pragma unroll
;                 for (int bj = 0; bj < 2; ++bj) { f32x4 v0 = acc[ai][bj][m][0] + bv[bj][0], v1 = acc[ai][bj][m][1] + bv[bj][1];
;                     if (act == 1) {
; #pragma unroll
;                         for (int j = 0; j < 1; ++j) { v0 = v0 * sigmoid4(v0); v1 = v1 * sigmoid4(v1); } }
;                     else if (act == 2) {
; #pragma unroll
;                         for (int j = 0; j < 1; ++j) { v0 = sigmoid4(v0); v1 = sigmoid4(v1); } }
;                     else if (act == 3) {
; #pragma unroll
;                         for (int j = 0; j < 4; ++j) { v0[j] = flogsig16(v0[j]); v1[j] = flogsig16(v1[j]); } }
;                     u32x4 w; w.x = cvt_pk_bf16(v0[0], v0[1]); w.y = cvt_pk_bf16(v0[2], v0[3]); w.z = cvt_pk_bf16(v1[0], v1[1]); w.w = cvt_pk_bf16(v1[2], v1[3]);
;                     *(u32x4*)(rowp + bj * HALF) = w; } }
	s_add_i32 s57, s57, 2
	s_add_u32 s55, s55, 0x100
	s_addc_u32 s56, s56, 0
	s_cmp_gt_u32 s57, 41
	s_mov_b64 s[22:23], s[24:25]
	s_cbranch_scc0 .LBB0_286
	v_lshl_add_u32 v154, s53, 8, v146
	v_lshl_or_b32 v144, s54, 8, v148
	v_ashrrev_i32_e32 v155, 31, v154
	v_ashrrev_i32_e32 v145, 31, v144
	v_lshlrev_b64 v[156:157], 11, v[154:155]
	v_lshl_add_u64 v[156:157], s[10:11], 0, v[156:157]
	v_lshlrev_b64 v[158:159], 1, v[144:145]
	v_lshl_add_u64 v[144:145], v[156:157], 0, v[158:159]
	v_pk_add_f32 v[126:127], v[126:127], 0 op_sel_hi:[1,0]
	v_pk_add_f32 v[124:125], v[124:125], 0 op_sel_hi:[1,0]
	v_pk_add_f32 v[156:157], v[122:123], 0 op_sel_hi:[1,0]
	v_pk_add_f32 v[122:123], v[120:121], 0 op_sel_hi:[1,0]
	v_cvt_pk_bf16_f32 v120, v124, v125
	v_cvt_pk_bf16_f32 v121, v126, v127
	v_pk_add_f32 v[116:117], v[116:117], 0 op_sel_hi:[1,0]
	v_cvt_pk_bf16_f32 v122, v122, v123
	v_cvt_pk_bf16_f32 v123, v156, v157
	global_store_dwordx4 v[144:145], v[120:123], off
	v_pk_add_f32 v[118:119], v[118:119], 0 op_sel_hi:[1,0]
	v_pk_add_f32 v[110:111], v[110:111], 0 op_sel_hi:[1,0]
	v_pk_add_f32 v[120:121], v[114:115], 0 op_sel_hi:[1,0]
	v_pk_add_f32 v[114:115], v[112:113], 0 op_sel_hi:[1,0]
	v_cvt_pk_bf16_f32 v112, v116, v117
	v_cvt_pk_bf16_f32 v113, v118, v119
	v_pk_add_f32 v[108:109], v[108:109], 0 op_sel_hi:[1,0]
	v_cvt_pk_bf16_f32 v114, v114, v115
	v_cvt_pk_bf16_f32 v115, v120, v121
	global_store_dwordx4 v[144:145], v[112:115], off offset:256
	v_pk_add_f32 v[100:101], v[100:101], 0 op_sel_hi:[1,0]
	v_pk_add_f32 v[102:103], v[102:103], 0 op_sel_hi:[1,0]
	v_or_b32_e32 v112, 16, v154
	v_ashrrev_i32_e32 v113, 31, v112
	v_lshlrev_b64 v[112:113], 11, v[112:113]
	v_lshl_add_u64 v[112:113], s[10:11], 0, v[112:113]
	v_lshl_add_u64 v[112:113], v[112:113], 0, v[158:159]
	v_pk_add_f32 v[114:115], v[106:107], 0 op_sel_hi:[1,0]
	v_pk_add_f32 v[106:107], v[104:105], 0 op_sel_hi:[1,0]
	v_cvt_pk_bf16_f32 v104, v108, v109
	v_cvt_pk_bf16_f32 v105, v110, v111
	v_pk_add_f32 v[94:95], v[94:95], 0 op_sel_hi:[1,0]
	v_cvt_pk_bf16_f32 v106, v106, v107
	v_cvt_pk_bf16_f32 v107, v114, v115
	global_store_dwordx4 v[112:113], v[104:107], off
	v_pk_add_f32 v[92:93], v[92:93], 0 op_sel_hi:[1,0]
	v_pk_add_f32 v[84:85], v[84:85], 0 op_sel_hi:[1,0]
	v_pk_add_f32 v[104:105], v[98:99], 0 op_sel_hi:[1,0]
	v_pk_add_f32 v[98:99], v[96:97], 0 op_sel_hi:[1,0]
	v_cvt_pk_bf16_f32 v96, v100, v101
	v_cvt_pk_bf16_f32 v97, v102, v103
	v_pk_add_f32 v[86:87], v[86:87], 0 op_sel_hi:[1,0]
	v_cvt_pk_bf16_f32 v98, v98, v99
	v_cvt_pk_bf16_f32 v99, v104, v105
	global_store_dwordx4 v[112:113], v[96:99], off offset:256
	v_pk_add_f32 v[78:79], v[78:79], 0 op_sel_hi:[1,0]
	v_pk_add_f32 v[76:77], v[76:77], 0 op_sel_hi:[1,0]
	v_or_b32_e32 v96, 32, v154
	v_ashrrev_i32_e32 v97, 31, v96
	v_lshlrev_b64 v[96:97], 11, v[96:97]
	v_lshl_add_u64 v[96:97], s[10:11], 0, v[96:97]
	v_lshl_add_u64 v[96:97], v[96:97], 0, v[158:159]
	v_pk_add_f32 v[98:99], v[90:91], 0 op_sel_hi:[1,0]
	v_pk_add_f32 v[90:91], v[88:89], 0 op_sel_hi:[1,0]
	v_cvt_pk_bf16_f32 v88, v92, v93
	v_cvt_pk_bf16_f32 v89, v94, v95
	v_pk_add_f32 v[70:71], v[70:71], 0 op_sel_hi:[1,0]
	v_cvt_pk_bf16_f32 v90, v90, v91
	v_cvt_pk_bf16_f32 v91, v98, v99
	global_store_dwordx4 v[96:97], v[88:91], off
	v_pk_add_f32 v[68:69], v[68:69], 0 op_sel_hi:[1,0]
	s_mov_b64 s[22:23], 0x40000
	v_pk_add_f32 v[88:89], v[82:83], 0 op_sel_hi:[1,0]
	v_pk_add_f32 v[82:83], v[80:81], 0 op_sel_hi:[1,0]
	v_cvt_pk_bf16_f32 v80, v84, v85
	v_cvt_pk_bf16_f32 v81, v86, v87
	v_pk_add_f32 v[60:61], v[60:61], 0 op_sel_hi:[1,0]
	v_cvt_pk_bf16_f32 v82, v82, v83
	v_cvt_pk_bf16_f32 v83, v88, v89
	global_store_dwordx4 v[96:97], v[80:83], off offset:256
	v_pk_add_f32 v[62:63], v[62:63], 0 op_sel_hi:[1,0]
	v_pk_add_f32 v[54:55], v[54:55], 0 op_sel_hi:[1,0]
	v_or_b32_e32 v80, 48, v154
	v_ashrrev_i32_e32 v81, 31, v80
	v_lshlrev_b64 v[80:81], 11, v[80:81]
	v_lshl_add_u64 v[80:81], s[10:11], 0, v[80:81]
	v_lshl_add_u64 v[80:81], v[80:81], 0, v[158:159]
	v_pk_add_f32 v[82:83], v[74:75], 0 op_sel_hi:[1,0]
	v_pk_add_f32 v[74:75], v[72:73], 0 op_sel_hi:[1,0]
	v_cvt_pk_bf16_f32 v72, v76, v77
	v_cvt_pk_bf16_f32 v73, v78, v79
	v_pk_add_f32 v[52:53], v[52:53], 0 op_sel_hi:[1,0]
; __device__ __forceinline__ unsigned cvt_pk_bf16(float lo, float hi) { unsigned r; asm volatile("v_cvt_pk_bf16_f32 %0, %1, %2" : "=v"(r) : "v"(lo), "v"(hi)); return r; }
; __device__ __forceinline__ float flogsig16(float x) { return (fminf(x, 0.f) - __logf(1.0f + __expf(-fabsf(x)))) * 0.0625f; }
; #define PG8_WAIT_V(n) asm volatile("s_waitcnt vmcnt(" #n ")" ::: "memory")
; #define PG8_BAR __builtin_amdgcn_s_barrier()
;     __device__ __forceinline__ void operator()(const f32x4 (&acc)[2][2][4][2], const Unit& u, int wr, int wc, int fr, int fq) const {
;     ...
;             for (int m = 0; m < 4; ++m) { bf16_t* rowp = O + (size_t)(row0 + ai * HALF + m * 16) * ldc + col0;
; #pragma unroll
;                 for (int bj = 0; bj < 2; ++bj) { f32x4 v0 = acc[ai][bj][m][0] + bv[bj][0], v1 = acc[ai][bj][m][1] + bv[bj][1];
;                     if (act == 1) {
; #pragma unroll
;                         for (int j = 0; j < 1; ++j) { v0 = v0 * sigmoid4(v0); v1 = v1 * sigmoid4(v1); } }
;                     else if (act == 2) {
; #pragma unroll
;                         for (int j = 0; j < 1; ++j) { v0 = sigmoid4(v0); v1 = sigmoid4(v1); } }
;                     else if (act == 3) {
; #pragma unroll
;                         for (int j = 0; j < 4; ++j) { v0[j] = flogsig16(v0[j]); v1[j] = flogsig16(v1[j]); } }
;                     u32x4 w; w.x = cvt_pk_bf16(v0[0], v0[1]); w.y = cvt_pk_bf16(v0[2], v0[3]); w.z = cvt_pk_bf16(v1[0], v1[1]); w.w = cvt_pk_bf16(v1[2], v1[3]);
;                     *(u32x4*)(rowp + bj * HALF) = w; } }
; template <class Epi, class Sched>
; __device__ __forceinline__ void gemm_phase(PG8_LAS unsigned char* lds, const Gemm g, const Sched& S, const Epi& E) {
;     ...
;         if (!has_next) break;
; #pragma unroll
;         for (int a = 0; a < 2; ++a)
; #pragma unroll
;             for (int b = 0; b < 2; ++b)
; #pragma unroll
;                 for (int m = 0; m < 4; ++m)
; #pragma unroll
;                     for (int n = 0; n < 2; ++n) acc[a][b][m][n] = (f32x4){0.f, 0.f, 0.f, 0.f};
;         cur = nxt; cA = nA; cB = nB; ++ui;
;     }
;     PG8_WAIT_V(0);
;     if (wr == 0) PG8_BAR;
;     PG8_BAR;
	v_cvt_pk_bf16_f32 v74, v74, v75
	v_cvt_pk_bf16_f32 v75, v82, v83
	global_store_dwordx4 v[80:81], v[72:75], off
	v_pk_add_f32 v[48:49], v[48:49], 0 op_sel_hi:[1,0]
	v_pk_add_f32 v[38:39], v[38:39], 0 op_sel_hi:[1,0]
	v_pk_add_f32 v[72:73], v[66:67], 0 op_sel_hi:[1,0]
	v_pk_add_f32 v[66:67], v[64:65], 0 op_sel_hi:[1,0]
	v_cvt_pk_bf16_f32 v64, v68, v69
	v_cvt_pk_bf16_f32 v65, v70, v71
	v_pk_add_f32 v[36:37], v[36:37], 0 op_sel_hi:[1,0]
	v_cvt_pk_bf16_f32 v66, v66, v67
	v_cvt_pk_bf16_f32 v67, v72, v73
	global_store_dwordx4 v[80:81], v[64:67], off offset:256
	v_pk_add_f32 v[32:33], v[32:33], 0 op_sel_hi:[1,0]
	v_pk_add_f32 v[22:23], v[22:23], 0 op_sel_hi:[1,0]
	v_lshl_add_u64 v[64:65], v[144:145], 0, s[22:23]
	s_mov_b32 s22, 0x40000
	v_pk_add_f32 v[66:67], v[58:59], 0 op_sel_hi:[1,0]
	v_pk_add_f32 v[58:59], v[56:57], 0 op_sel_hi:[1,0]
	v_cvt_pk_bf16_f32 v56, v60, v61
	v_add_co_u32_e32 v60, vcc, s22, v144
	v_cvt_pk_bf16_f32 v57, v62, v63
	v_cvt_pk_bf16_f32 v58, v58, v59
	v_cvt_pk_bf16_f32 v59, v66, v67
	s_mov_b64 s[22:23], 0x48000
	s_nop 0
	v_addc_co_u32_e32 v61, vcc, 0, v145, vcc
	global_store_dwordx4 v[60:61], v[56:59], off
	v_pk_add_f32 v[20:21], v[20:21], 0 op_sel_hi:[1,0]
	v_pk_add_f32 v[16:17], v[16:17], 0 op_sel_hi:[1,0]
	v_pk_add_f32 v[56:57], v[46:47], 0 op_sel_hi:[1,0]
	v_pk_add_f32 v[46:47], v[44:45], 0 op_sel_hi:[1,0]
	v_cvt_pk_bf16_f32 v44, v52, v53
	v_cvt_pk_bf16_f32 v45, v54, v55
	s_mov_b32 s54, s51
	v_cvt_pk_bf16_f32 v46, v46, v47
	v_cvt_pk_bf16_f32 v47, v56, v57
	global_store_dwordx4 v[64:65], v[44:47], off offset:256
	s_mov_b32 s53, s52
	s_mov_b64 s[24:25], s[4:5]
	v_pk_add_f32 v[46:47], v[50:51], 0 op_sel_hi:[1,0]
	v_pk_add_f32 v[50:51], v[42:43], 0 op_sel_hi:[1,0]
	v_pk_add_f32 v[42:43], v[40:41], 0 op_sel_hi:[1,0]
	v_cvt_pk_bf16_f32 v40, v48, v49
	v_cvt_pk_bf16_f32 v41, v46, v47
	v_add_co_u32_e32 v46, vcc, s48, v144
	v_cvt_pk_bf16_f32 v42, v42, v43
	v_cvt_pk_bf16_f32 v43, v50, v51
	v_lshl_add_u64 v[44:45], v[144:145], 0, s[22:23]
	s_nop 0
	v_addc_co_u32_e32 v47, vcc, 0, v145, vcc
	global_store_dwordx4 v[46:47], v[40:43], off
	s_mov_b64 s[22:23], s[0:1]
	v_pk_add_f32 v[6:7], v[6:7], 0 op_sel_hi:[1,0]
	v_pk_add_f32 v[40:41], v[30:31], 0 op_sel_hi:[1,0]
	v_pk_add_f32 v[30:31], v[28:29], 0 op_sel_hi:[1,0]
	v_cvt_pk_bf16_f32 v28, v36, v37
	v_cvt_pk_bf16_f32 v29, v38, v39
	v_pk_add_f32 v[4:5], v[4:5], 0 op_sel_hi:[1,0]
	v_cvt_pk_bf16_f32 v30, v30, v31
	v_cvt_pk_bf16_f32 v31, v40, v41
	global_store_dwordx4 v[44:45], v[28:31], off offset:256
	s_nop 1
	v_pk_add_f32 v[30:31], v[34:35], 0 op_sel_hi:[1,0]
	v_pk_add_f32 v[34:35], v[26:27], 0 op_sel_hi:[1,0]
	v_pk_add_f32 v[26:27], v[24:25], 0 op_sel_hi:[1,0]
	v_cvt_pk_bf16_f32 v24, v32, v33
	v_cvt_pk_bf16_f32 v25, v30, v31
	v_add_co_u32_e32 v30, vcc, s49, v144
	v_cvt_pk_bf16_f32 v26, v26, v27
	v_cvt_pk_bf16_f32 v27, v34, v35
	v_lshl_add_u64 v[28:29], v[144:145], 0, s[16:17]
	s_nop 0
	v_addc_co_u32_e32 v31, vcc, 0, v145, vcc
	global_store_dwordx4 v[30:31], v[24:27], off
	s_nop 1
	v_pk_add_f32 v[24:25], v[14:15], 0 op_sel_hi:[1,0]
	v_pk_add_f32 v[14:15], v[12:13], 0 op_sel_hi:[1,0]
	v_cvt_pk_bf16_f32 v12, v20, v21
	v_cvt_pk_bf16_f32 v13, v22, v23
	s_nop 0
	v_cvt_pk_bf16_f32 v14, v14, v15
	v_cvt_pk_bf16_f32 v15, v24, v25
	global_store_dwordx4 v[28:29], v[12:15], off offset:256
	s_nop 1
	v_pk_add_f32 v[14:15], v[18:19], 0 op_sel_hi:[1,0]
	v_pk_add_f32 v[18:19], v[10:11], 0 op_sel_hi:[1,0]
	v_pk_add_f32 v[10:11], v[8:9], 0 op_sel_hi:[1,0]
	v_cvt_pk_bf16_f32 v8, v16, v17
	v_cvt_pk_bf16_f32 v9, v14, v15
	v_add_co_u32_e32 v14, vcc, s50, v144
	v_lshl_add_u64 v[12:13], v[144:145], 0, s[18:19]
	s_nop 0
	v_addc_co_u32_e32 v15, vcc, 0, v145, vcc
	v_cvt_pk_bf16_f32 v10, v10, v11
	v_cvt_pk_bf16_f32 v11, v18, v19
	global_store_dwordx4 v[14:15], v[8:11], off
	s_and_b64 vcc, exec, s[2:3]
	s_nop 0
	v_pk_add_f32 v[8:9], v[2:3], 0 op_sel_hi:[1,0]
	v_pk_add_f32 v[2:3], v[0:1], 0 op_sel_hi:[1,0]
	v_cvt_pk_bf16_f32 v0, v4, v5
	v_cvt_pk_bf16_f32 v1, v6, v7
	s_nop 0
	v_cvt_pk_bf16_f32 v2, v2, v3
	v_cvt_pk_bf16_f32 v3, v8, v9
	global_store_dwordx4 v[12:13], v[0:3], off offset:256
	s_cbranch_vccz .LBB0_275
	s_waitcnt vmcnt(0)
	s_cmpk_gt_u32 s31, 0xff
	s_cbranch_scc1 .LBB0_290
	s_barrier

; #define PG8_STAGE(bufoff, gbase, voff) do { _Pragma("unroll") for (int _i = 0; _i < 2; ++_i) \
;         __builtin_amdgcn_global_load_lds((const unsigned*)((const char*)(gbase) + (voff)[_i]), (PG8_LAS unsigned*)(lds + (bufoff) + ldsw + _i * 8192), 16, 0, 0); } while (0)
; #define PG8_LDA(dst, b, h) do { _Pragma("unroll") for (int m = 0; m < 4; ++m) _Pragma("unroll") for (int k = 0; k < 2; ++k) dst[m][k] = *(const PG8_LAS bf16x8*)(lds + PG8_SA(b, h) + aoff + m * 2048 + k * 1024); } while (0)
; #define PG8_LDB(dst, b, h) do { _Pragma("unroll") for (int n = 0; n < 2; ++n) _Pragma("unroll") for (int k = 0; k < 2; ++k) dst[n][k] = *(const PG8_LAS bf16x8*)(lds + PG8_SB(b, h) + boff + n * 2048 + k * 1024); } while (0)
; #define PG8_MMA(ai, bj, At, Bt) do { __builtin_amdgcn_s_setprio(1); _Pragma("unroll") for (int m = 0; m < 4; ++m) _Pragma("unroll") for (int n = 0; n < 2; ++n) _Pragma("unroll") for (int k = 0; k < 2; ++k) \
;         acc[ai][bj][m][n] = __builtin_amdgcn_mfma_f32_16x16x32_bf16(Bt[n][k], At[m][k], acc[ai][bj][m][n], 0, 0, 0); __builtin_amdgcn_s_setprio(0); } while (0)
; template <class Epi, class Sched>
; __device__ __forceinline__ void gemm_phase(PG8_LAS unsigned char* lds, const Gemm g, const Sched& S, const Epi& E) {
;     ...
;         const bool has_next = S.next(ui + 1, nxt);
;         const char* nA = has_next ? (const char*)g.A + (size_t)nxt.pm * tstep : cA; const char* nB = has_next ? (const char*)g.Bt + (size_t)nxt.pn * tstep : cB;
;         for (int t = 0; t < nt; t += 2) {
;             const bool last = (t == nt - 2);
;             const char* a1 = cA + (size_t)(t + 1) * kstep;
;             const char* a2 = last ? nA : cA + (size_t)(t + 2) * kstep; const char* b2 = last ? nB : cB + (size_t)(t + 2) * kstep;
;             const char* a3 = a2 + kstep; const char* b3 = b2 + kstep;
;             if (last && has_next) S.a_ready(nxt);
;             PG8_LDB(B0, 0, 0); PG8_SCHED; PG8_LDA(At, 0, 0); PG8_STAGE(PG8_SA(1, 1), a1 + hstep, voffA);
;             PG8_WAIT_L(8); PG8_BAR; PG8_WAIT_L(0); PG8_MMA(0, 0, At, B0); PG8_BAR; PG8_SCHED;
;             PG8_LDB(B1, 0, 1); PG8_STAGE(PG8_SB(0, 0), b2, voffB);
;             PG8_BAR; PG8_WAIT_L(0); PG8_MMA(0, 1, At, B1); PG8_BAR;
;             PG8_LDA(At, 0, 1); PG8_STAGE(PG8_SA(0, 0), a2, voffA);
;             PG8_BAR; PG8_WAIT_L(0); PG8_MMA(1, 0, At, B0); PG8_BAR; PG8_SCHED;
.LBB0_415:
	s_ashr_i32 s21, s20, 31
	v_cmp_lt_i64_e32 vcc, s[22:23], v[170:171]
	s_lshl_b64 s[22:23], s[20:21], 19
	s_add_u32 s22, s31, s22
	s_addc_u32 s23, s34, s23
	s_and_b64 s[24:25], vcc, exec
	s_cselect_b32 s7, s23, s1
	s_cselect_b32 s10, s22, s0
	s_ashr_i32 s19, s18, 31
	s_lshl_b64 s[24:25], s[18:19], 19
	s_add_u32 s24, s8, s24
	s_addc_u32 s25, s9, s25
	s_and_b64 s[28:29], vcc, exec
	s_cselect_b32 s19, s25, s5
	s_cselect_b32 s21, s24, s4
	s_add_u32 s0, s0, 0x40080
	s_addc_u32 s1, s1, 0
	s_add_u32 s51, s4, 0x100
	s_addc_u32 s52, s5, 0
	s_mov_b32 s53, -2
	ds_read_b128 v[24:27], v186
	ds_read_b128 v[28:31], v186 offset:1024
	ds_read_b128 v[40:43], v186 offset:2048
	ds_read_b128 v[44:47], v186 offset:3072
	s_add_u32 s4, s0, 0xfffc0080
	s_addc_u32 s5, s1, -1
	s_cmp_eq_u32 s53, 12
	s_cselect_b32 s29, s7, s5
	s_cselect_b32 s28, s10, s4
	s_cselect_b32 s5, s19, s52
	s_cselect_b32 s4, s21, s51
	s_add_i32 m0, s27, 0xc000
	ds_read_b128 v[144:147], v187
	ds_read_b128 v[148:151], v187 offset:1024
	ds_read_b128 v[182:185], v187 offset:2048
	ds_read_b128 v[192:195], v187 offset:3072
	ds_read_b128 v[196:199], v187 offset:4096
	ds_read_b128 v[200:203], v187 offset:5120
	ds_read_b128 v[204:207], v187 offset:6144
	ds_read_b128 v[208:211], v187 offset:7168
	global_load_lds_dwordx4 v166, s[0:1]
	s_nop 1
	s_add_i32 m0, s27, 0xe000
	s_nop 0
	global_load_lds_dwordx4 v168, s[0:1]
	s_waitcnt lgkmcnt(8)
	ds_read_b128 v[212:215], v189
	ds_read_b128 v[216:219], v189 offset:1024
	ds_read_b128 v[220:223], v189 offset:2048
	ds_read_b128 v[224:227], v189 offset:3072
	s_waitcnt vmcnt(8) lgkmcnt(0)
	s_barrier
	v_mfma_f32_16x16x32_bf16 v[140:143], v[24:27], v[144:147], 0
	v_mfma_f32_16x16x32_bf16 v[136:139], v[40:43], v[144:147], 0
	v_mfma_f32_16x16x32_bf16 v[124:127], v[24:27], v[182:185], 0
	v_mfma_f32_16x16x32_bf16 v[120:123], v[40:43], v[182:185], 0
	v_mfma_f32_16x16x32_bf16 v[108:111], v[24:27], v[196:199], 0
	v_mfma_f32_16x16x32_bf16 v[104:107], v[40:43], v[196:199], 0
	v_mfma_f32_16x16x32_bf16 v[92:95], v[24:27], v[204:207], 0
	v_mfma_f32_16x16x32_bf16 v[88:91], v[40:43], v[204:207], 0
	v_mfma_f32_16x16x32_bf16 v[140:143], v[28:31], v[148:151], v[140:143]
	v_mfma_f32_16x16x32_bf16 v[136:139], v[44:47], v[148:151], v[136:139]
	v_mfma_f32_16x16x32_bf16 v[124:127], v[28:31], v[192:195], v[124:127]
	v_mfma_f32_16x16x32_bf16 v[120:123], v[44:47], v[192:195], v[120:123]
	v_mfma_f32_16x16x32_bf16 v[108:111], v[28:31], v[200:203], v[108:111]
	v_mfma_f32_16x16x32_bf16 v[104:107], v[44:47], v[200:203], v[104:107]
	v_mfma_f32_16x16x32_bf16 v[92:95], v[28:31], v[208:211], v[92:95]
	v_mfma_f32_16x16x32_bf16 v[88:91], v[44:47], v[208:211], v[88:91]
	v_mfma_f32_16x16x32_bf16 v[132:135], v[212:215], v[144:147], 0
	v_mfma_f32_16x16x32_bf16 v[128:131], v[220:223], v[144:147], 0
	v_mfma_f32_16x16x32_bf16 v[116:119], v[212:215], v[182:185], 0
	v_mfma_f32_16x16x32_bf16 v[112:115], v[220:223], v[182:185], 0
	v_mfma_f32_16x16x32_bf16 v[100:103], v[212:215], v[196:199], 0
	v_mfma_f32_16x16x32_bf16 v[96:99], v[220:223], v[196:199], 0
	v_mfma_f32_16x16x32_bf16 v[84:87], v[212:215], v[204:207], 0
	v_mfma_f32_16x16x32_bf16 v[80:83], v[220:223], v[204:207], 0
	v_mfma_f32_16x16x32_bf16 v[132:135], v[216:219], v[148:151], v[132:135]
	v_mfma_f32_16x16x32_bf16 v[128:131], v[224:227], v[148:151], v[128:131]
	v_mfma_f32_16x16x32_bf16 v[116:119], v[216:219], v[192:195], v[116:119]
	v_mfma_f32_16x16x32_bf16 v[112:115], v[224:227], v[192:195], v[112:115]
	v_mfma_f32_16x16x32_bf16 v[100:103], v[216:219], v[200:203], v[100:103]
	v_mfma_f32_16x16x32_bf16 v[96:99], v[224:227], v[200:203], v[96:99]
	v_mfma_f32_16x16x32_bf16 v[84:87], v[216:219], v[208:211], v[84:87]
	v_mfma_f32_16x16x32_bf16 v[80:83], v[224:227], v[208:211], v[80:83]
	s_barrier
	ds_read_b128 v[144:147], v187 offset:16384
	ds_read_b128 v[148:151], v187 offset:17408
	ds_read_b128 v[182:185], v187 offset:18432
	ds_read_b128 v[192:195], v187 offset:19456
	ds_read_b128 v[196:199], v187 offset:20480
	ds_read_b128 v[200:203], v187 offset:21504
	ds_read_b128 v[204:207], v187 offset:22528
	ds_read_b128 v[208:211], v187 offset:23552
	s_add_i32 s54, s43, s35
	s_add_u32 s98, s4, s14
	s_addc_u32 s99, s5, s15
	s_mov_b32 m0, s54
	s_nop 0
	global_load_lds_dwordx4 v156, s[4:5]
	s_nop 1
	s_add_i32 m0, s54, 0x2000
	s_nop 0
	global_load_lds_dwordx4 v160, s[4:5]
	s_nop 1
	s_mov_b32 m0, s27
	s_add_u32 s100, s28, s14
	s_addc_u32 s101, s29, s15
	global_load_lds_dwordx4 v154, s[28:29]
	s_nop 1
	s_mov_b32 m0, s36
	s_nop 0
	global_load_lds_dwordx4 v158, s[28:29]
	s_add_u32 s54, s4, 0x40000
	s_addc_u32 s55, s5, 0
	s_add_i32 s56, s44, s35
	s_mov_b32 m0, s56
	s_nop 0
	global_load_lds_dwordx4 v156, s[54:55]
	s_nop 1
	s_add_i32 m0, s56, 0x2000
	s_nop 0
	global_load_lds_dwordx4 v160, s[54:55]
	s_waitcnt vmcnt(8) lgkmcnt(0)
	s_barrier
; #define PG8_STAGE(bufoff, gbase, voff) do { _Pragma("unroll") for (int _i = 0; _i < 2; ++_i) \
;         __builtin_amdgcn_global_load_lds((const unsigned*)((const char*)(gbase) + (voff)[_i]), (PG8_LAS unsigned*)(lds + (bufoff) + ldsw + _i * 8192), 16, 0, 0); } while (0)
; #define PG8_LDA(dst, b, h) do { _Pragma("unroll") for (int m = 0; m < 4; ++m) _Pragma("unroll") for (int k = 0; k < 2; ++k) dst[m][k] = *(const PG8_LAS bf16x8*)(lds + PG8_SA(b, h) + aoff + m * 2048 + k * 1024); } while (0)
; #define PG8_LDB(dst, b, h) do { _Pragma("unroll") for (int n = 0; n < 2; ++n) _Pragma("unroll") for (int k = 0; k < 2; ++k) dst[n][k] = *(const PG8_LAS bf16x8*)(lds + PG8_SB(b, h) + boff + n * 2048 + k * 1024); } while (0)
; #define PG8_MMA(ai, bj, At, Bt) do { __builtin_amdgcn_s_setprio(1); _Pragma("unroll") for (int m = 0; m < 4; ++m) _Pragma("unroll") for (int n = 0; n < 2; ++n) _Pragma("unroll") for (int k = 0; k < 2; ++k) \
;         acc[ai][bj][m][n] = __builtin_amdgcn_mfma_f32_16x16x32_bf16(Bt[n][k], At[m][k], acc[ai][bj][m][n], 0, 0, 0); __builtin_amdgcn_s_setprio(0); } while (0)
; #define PG8_WAIT_V(n) asm volatile("s_waitcnt vmcnt(" #n ")" ::: "memory")
; #define PG8_WAIT_L(n) asm volatile("s_waitcnt lgkmcnt(" #n ")" ::: "memory")
; #define PG8_BAR __builtin_amdgcn_s_barrier()
; #define PG8_SCHED __builtin_amdgcn_sched_barrier(0)
; template <class Epi, class Sched>
; __device__ __forceinline__ void gemm_phase(PG8_LAS unsigned char* lds, const Gemm g, const Sched& S, const Epi& E) {
;     ...
;             PG8_BAR; PG8_WAIT_L(0); PG8_MMA(1, 0, At, B0); PG8_BAR; PG8_SCHED;
;             PG8_STAGE(PG8_SB(0, 1), b2 + hstep, voffB);
;             PG8_WAIT_V(6); PG8_BAR; PG8_MMA(1, 1, At, B1); PG8_BAR;
;             PG8_LDB(B0, 1, 0); PG8_SCHED; PG8_LDA(At, 1, 0); PG8_STAGE(PG8_SA(0, 1), a2 + hstep, voffA);
;             PG8_WAIT_L(8); PG8_BAR; PG8_WAIT_L(0); PG8_MMA(0, 0, At, B0); PG8_BAR; PG8_SCHED;
;             PG8_LDB(B1, 1, 1); PG8_STAGE(PG8_SB(1, 0), b3, voffB);
;             PG8_BAR; PG8_WAIT_L(0); PG8_MMA(0, 1, At, B1); PG8_BAR;
	v_mfma_f32_16x16x32_bf16 v[76:79], v[24:27], v[144:147], 0
	v_mfma_f32_16x16x32_bf16 v[72:75], v[40:43], v[144:147], 0
	v_mfma_f32_16x16x32_bf16 v[60:63], v[24:27], v[182:185], 0
	v_mfma_f32_16x16x32_bf16 v[56:59], v[40:43], v[182:185], 0
	v_mfma_f32_16x16x32_bf16 v[36:39], v[24:27], v[196:199], 0
	v_mfma_f32_16x16x32_bf16 v[32:35], v[40:43], v[196:199], 0
	v_mfma_f32_16x16x32_bf16 v[12:15], v[24:27], v[204:207], 0
	v_mfma_f32_16x16x32_bf16 v[8:11], v[40:43], v[204:207], 0
	v_mfma_f32_16x16x32_bf16 v[76:79], v[28:31], v[148:151], v[76:79]
	v_mfma_f32_16x16x32_bf16 v[72:75], v[44:47], v[148:151], v[72:75]
	v_mfma_f32_16x16x32_bf16 v[60:63], v[28:31], v[192:195], v[60:63]
	v_mfma_f32_16x16x32_bf16 v[56:59], v[44:47], v[192:195], v[56:59]
	v_mfma_f32_16x16x32_bf16 v[36:39], v[28:31], v[200:203], v[36:39]
	v_mfma_f32_16x16x32_bf16 v[32:35], v[44:47], v[200:203], v[32:35]
	v_mfma_f32_16x16x32_bf16 v[12:15], v[28:31], v[208:211], v[12:15]
	v_mfma_f32_16x16x32_bf16 v[8:11], v[44:47], v[208:211], v[8:11]
	v_mfma_f32_16x16x32_bf16 v[20:23], v[212:215], v[196:199], 0
	v_mfma_f32_16x16x32_bf16 v[16:19], v[220:223], v[196:199], 0
	v_mfma_f32_16x16x32_bf16 v[4:7], v[212:215], v[204:207], 0
	v_mfma_f32_16x16x32_bf16 v[0:3], v[220:223], v[204:207], 0
	v_mfma_f32_16x16x32_bf16 v[24:27], v[212:215], v[144:147], 0
	v_mfma_f32_16x16x32_bf16 v[28:31], v[220:223], v[144:147], 0
	v_mfma_f32_16x16x32_bf16 v[40:43], v[212:215], v[182:185], 0
	v_mfma_f32_16x16x32_bf16 v[44:47], v[220:223], v[182:185], 0
	v_mfma_f32_16x16x32_bf16 v[20:23], v[216:219], v[200:203], v[20:23]
	v_mfma_f32_16x16x32_bf16 v[16:19], v[224:227], v[200:203], v[16:19]
	v_mfma_f32_16x16x32_bf16 v[4:7], v[216:219], v[208:211], v[4:7]
	v_mfma_f32_16x16x32_bf16 v[0:3], v[224:227], v[208:211], v[0:3]
	v_mfma_f32_16x16x32_bf16 v[24:27], v[216:219], v[148:151], v[24:27]
	v_mfma_f32_16x16x32_bf16 v[28:31], v[224:227], v[148:151], v[28:31]
	v_mfma_f32_16x16x32_bf16 v[40:43], v[216:219], v[192:195], v[40:43]
	v_mfma_f32_16x16x32_bf16 v[44:47], v[224:227], v[192:195], v[44:47]
	s_barrier
	s_add_i32 s54, 0, 0x18000
	v_add_u32_e32 v68, s54, v179
	ds_read_b128 v[48:51], v68
	ds_read_b128 v[52:55], v68 offset:1024
	ds_read_b128 v[64:67], v68 offset:2048
	ds_read_b128 v[68:71], v68 offset:3072
	s_add_u32 s28, s28, 0x40000
	s_addc_u32 s29, s29, 0
	s_mov_b32 m0, s37
	ds_read_b128 v[144:147], v187 offset:32768
	ds_read_b128 v[148:151], v187 offset:33792
	ds_read_b128 v[182:185], v187 offset:34816
	ds_read_b128 v[192:195], v187 offset:35840
	ds_read_b128 v[196:199], v187 offset:36864
	ds_read_b128 v[200:203], v187 offset:37888
	ds_read_b128 v[204:207], v187 offset:38912
	ds_read_b128 v[208:211], v187 offset:39936
	global_load_lds_dwordx4 v154, s[28:29]
	s_nop 1
	s_mov_b32 m0, s38
	s_nop 0
	global_load_lds_dwordx4 v158, s[28:29]
	s_add_i32 s28, 0, 0x1c000
	v_add_u32_e32 v162, s28, v179
	s_waitcnt lgkmcnt(8)
	ds_read_b128 v[212:215], v162
	ds_read_b128 v[216:219], v162 offset:1024
	ds_read_b128 v[220:223], v162 offset:2048
	ds_read_b128 v[224:227], v162 offset:3072
	s_waitcnt vmcnt(8) lgkmcnt(0)
	s_barrier
	v_mfma_f32_16x16x32_bf16 v[140:143], v[48:51], v[144:147], v[140:143]
	v_mfma_f32_16x16x32_bf16 v[136:139], v[64:67], v[144:147], v[136:139]
	v_mfma_f32_16x16x32_bf16 v[124:127], v[48:51], v[182:185], v[124:127]
	v_mfma_f32_16x16x32_bf16 v[120:123], v[64:67], v[182:185], v[120:123]
	v_mfma_f32_16x16x32_bf16 v[108:111], v[48:51], v[196:199], v[108:111]
	v_mfma_f32_16x16x32_bf16 v[104:107], v[64:67], v[196:199], v[104:107]
	v_mfma_f32_16x16x32_bf16 v[92:95], v[48:51], v[204:207], v[92:95]
	v_mfma_f32_16x16x32_bf16 v[88:91], v[64:67], v[204:207], v[88:91]
	v_mfma_f32_16x16x32_bf16 v[140:143], v[52:55], v[148:151], v[140:143]
	v_mfma_f32_16x16x32_bf16 v[136:139], v[68:71], v[148:151], v[136:139]
	v_mfma_f32_16x16x32_bf16 v[124:127], v[52:55], v[192:195], v[124:127]
	v_mfma_f32_16x16x32_bf16 v[120:123], v[68:71], v[192:195], v[120:123]
	v_mfma_f32_16x16x32_bf16 v[108:111], v[52:55], v[200:203], v[108:111]
	v_mfma_f32_16x16x32_bf16 v[104:107], v[68:71], v[200:203], v[104:107]
	v_mfma_f32_16x16x32_bf16 v[92:95], v[52:55], v[208:211], v[92:95]
	v_mfma_f32_16x16x32_bf16 v[88:91], v[68:71], v[208:211], v[88:91]
	v_mfma_f32_16x16x32_bf16 v[132:135], v[212:215], v[144:147], v[132:135]
	v_mfma_f32_16x16x32_bf16 v[128:131], v[220:223], v[144:147], v[128:131]
	v_mfma_f32_16x16x32_bf16 v[116:119], v[212:215], v[182:185], v[116:119]
	v_mfma_f32_16x16x32_bf16 v[112:115], v[220:223], v[182:185], v[112:115]
	v_mfma_f32_16x16x32_bf16 v[100:103], v[212:215], v[196:199], v[100:103]
	v_mfma_f32_16x16x32_bf16 v[96:99], v[220:223], v[196:199], v[96:99]
	v_mfma_f32_16x16x32_bf16 v[84:87], v[212:215], v[204:207], v[84:87]
	v_mfma_f32_16x16x32_bf16 v[80:83], v[220:223], v[204:207], v[80:83]
	v_mfma_f32_16x16x32_bf16 v[132:135], v[216:219], v[148:151], v[132:135]
	v_mfma_f32_16x16x32_bf16 v[128:131], v[224:227], v[148:151], v[128:131]
	v_mfma_f32_16x16x32_bf16 v[116:119], v[216:219], v[192:195], v[116:119]
	v_mfma_f32_16x16x32_bf16 v[112:115], v[224:227], v[192:195], v[112:115]
	v_mfma_f32_16x16x32_bf16 v[100:103], v[216:219], v[200:203], v[100:103]
	v_mfma_f32_16x16x32_bf16 v[96:99], v[224:227], v[200:203], v[96:99]
	v_mfma_f32_16x16x32_bf16 v[84:87], v[216:219], v[208:211], v[84:87]
	v_mfma_f32_16x16x32_bf16 v[80:83], v[224:227], v[208:211], v[80:83]
	s_barrier
; #define PG8_STAGE(bufoff, gbase, voff) do { _Pragma("unroll") for (int _i = 0; _i < 2; ++_i) \
;         __builtin_amdgcn_global_load_lds((const unsigned*)((const char*)(gbase) + (voff)[_i]), (PG8_LAS unsigned*)(lds + (bufoff) + ldsw + _i * 8192), 16, 0, 0); } while (0)
; #define PG8_LDA(dst, b, h) do { _Pragma("unroll") for (int m = 0; m < 4; ++m) _Pragma("unroll") for (int k = 0; k < 2; ++k) dst[m][k] = *(const PG8_LAS bf16x8*)(lds + PG8_SA(b, h) + aoff + m * 2048 + k * 1024); } while (0)
; #define PG8_LDB(dst, b, h) do { _Pragma("unroll") for (int n = 0; n < 2; ++n) _Pragma("unroll") for (int k = 0; k < 2; ++k) dst[n][k] = *(const PG8_LAS bf16x8*)(lds + PG8_SB(b, h) + boff + n * 2048 + k * 1024); } while (0)
; #define PG8_MMA(ai, bj, At, Bt) do { __builtin_amdgcn_s_setprio(1); _Pragma("unroll") for (int m = 0; m < 4; ++m) _Pragma("unroll") for (int n = 0; n < 2; ++n) _Pragma("unroll") for (int k = 0; k < 2; ++k) \
;         acc[ai][bj][m][n] = __builtin_amdgcn_mfma_f32_16x16x32_bf16(Bt[n][k], At[m][k], acc[ai][bj][m][n], 0, 0, 0); __builtin_amdgcn_s_setprio(0); } while (0)
; #define PG8_WAIT_V(n) asm volatile("s_waitcnt vmcnt(" #n ")" ::: "memory")
; template <class Epi, class Sched>
; __device__ __forceinline__ void gemm_phase(PG8_LAS unsigned char* lds, const Gemm g, const Sched& S, const Epi& E) {
;     ...
;         for (int t = 0; t < nt; t += 2) {
;             const bool last = (t == nt - 2);
;             const char* a1 = cA + (size_t)(t + 1) * kstep;
;             const char* a2 = last ? nA : cA + (size_t)(t + 2) * kstep; const char* b2 = last ? nB : cB + (size_t)(t + 2) * kstep;
;             const char* a3 = a2 + kstep; const char* b3 = b2 + kstep;
;             if (last && has_next) S.a_ready(nxt);
;             PG8_LDB(B0, 0, 0); PG8_SCHED; PG8_LDA(At, 0, 0); PG8_STAGE(PG8_SA(1, 1), a1 + hstep, voffA);
;             PG8_WAIT_L(8); PG8_BAR; PG8_WAIT_L(0); PG8_MMA(0, 0, At, B0); PG8_BAR; PG8_SCHED;
;             PG8_LDB(B1, 0, 1); PG8_STAGE(PG8_SB(0, 0), b2, voffB);
;             PG8_BAR; PG8_WAIT_L(0); PG8_MMA(0, 1, At, B1); PG8_BAR;
;     ...
;             PG8_LDA(At, 1, 1); PG8_STAGE(PG8_SA(1, 0), a3, voffA);
;             PG8_BAR; PG8_WAIT_L(0); PG8_MMA(1, 0, At, B0); PG8_BAR; PG8_SCHED;
;             PG8_STAGE(PG8_SB(1, 1), b3 + hstep, voffB);
;             PG8_WAIT_V(6); PG8_BAR; PG8_MMA(1, 1, At, B1); PG8_BAR;
	ds_read_b128 v[144:147], v187 offset:49152
	ds_read_b128 v[148:151], v187 offset:50176
	ds_read_b128 v[182:185], v187 offset:51200
	ds_read_b128 v[192:195], v187 offset:52224
	ds_read_b128 v[196:199], v187 offset:53248
	ds_read_b128 v[200:203], v187 offset:54272
	ds_read_b128 v[204:207], v187 offset:55296
	ds_read_b128 v[208:211], v187 offset:56320
	s_add_i32 s29, s54, s35
	s_mov_b32 m0, s29
	s_nop 0
	global_load_lds_dwordx4 v156, s[98:99]
	s_nop 1
	s_add_i32 m0, s29, 0x2000
	s_nop 0
	global_load_lds_dwordx4 v160, s[98:99]
	s_nop 1
	s_mov_b32 m0, s39
	s_nop 0
	global_load_lds_dwordx4 v154, s[100:101]
	s_nop 1
	s_mov_b32 m0, s40
	s_nop 0
	global_load_lds_dwordx4 v158, s[100:101]
	s_add_u32 s4, s4, 0x40080
	s_addc_u32 s5, s5, 0
	s_add_i32 s28, s28, s35
	s_mov_b32 m0, s28
	s_nop 0
	global_load_lds_dwordx4 v156, s[4:5]
	s_nop 1
	s_add_i32 m0, s28, 0x2000
	s_nop 0
	global_load_lds_dwordx4 v160, s[4:5]
	s_waitcnt vmcnt(8) lgkmcnt(0)
	s_barrier
	v_mfma_f32_16x16x32_bf16 v[76:79], v[48:51], v[144:147], v[76:79]
	v_mfma_f32_16x16x32_bf16 v[72:75], v[64:67], v[144:147], v[72:75]
	v_mfma_f32_16x16x32_bf16 v[60:63], v[48:51], v[182:185], v[60:63]
	v_mfma_f32_16x16x32_bf16 v[56:59], v[64:67], v[182:185], v[56:59]
	v_mfma_f32_16x16x32_bf16 v[36:39], v[48:51], v[196:199], v[36:39]
	v_mfma_f32_16x16x32_bf16 v[32:35], v[64:67], v[196:199], v[32:35]
	v_mfma_f32_16x16x32_bf16 v[12:15], v[48:51], v[204:207], v[12:15]
	v_mfma_f32_16x16x32_bf16 v[8:11], v[64:67], v[204:207], v[8:11]
	v_mfma_f32_16x16x32_bf16 v[76:79], v[52:55], v[148:151], v[76:79]
	v_mfma_f32_16x16x32_bf16 v[72:75], v[68:71], v[148:151], v[72:75]
	v_mfma_f32_16x16x32_bf16 v[60:63], v[52:55], v[192:195], v[60:63]
	v_mfma_f32_16x16x32_bf16 v[56:59], v[68:71], v[192:195], v[56:59]
	v_mfma_f32_16x16x32_bf16 v[36:39], v[52:55], v[200:203], v[36:39]
	v_mfma_f32_16x16x32_bf16 v[32:35], v[68:71], v[200:203], v[32:35]
	v_mfma_f32_16x16x32_bf16 v[12:15], v[52:55], v[208:211], v[12:15]
	v_mfma_f32_16x16x32_bf16 v[8:11], v[68:71], v[208:211], v[8:11]
	v_mfma_f32_16x16x32_bf16 v[24:27], v[212:215], v[144:147], v[24:27]
	v_mfma_f32_16x16x32_bf16 v[68:71], v[216:219], v[148:151], v[24:27]
	v_mfma_f32_16x16x32_bf16 v[24:27], v[220:223], v[144:147], v[28:31]
	v_mfma_f32_16x16x32_bf16 v[64:67], v[224:227], v[148:151], v[24:27]
	v_mfma_f32_16x16x32_bf16 v[24:27], v[212:215], v[182:185], v[40:43]
	v_mfma_f32_16x16x32_bf16 v[52:55], v[216:219], v[192:195], v[24:27]
	v_mfma_f32_16x16x32_bf16 v[24:27], v[220:223], v[182:185], v[44:47]
	v_mfma_f32_16x16x32_bf16 v[20:23], v[212:215], v[196:199], v[20:23]
	v_mfma_f32_16x16x32_bf16 v[16:19], v[220:223], v[196:199], v[16:19]
	v_mfma_f32_16x16x32_bf16 v[4:7], v[212:215], v[204:207], v[4:7]
	v_mfma_f32_16x16x32_bf16 v[0:3], v[220:223], v[204:207], v[0:3]
	v_mfma_f32_16x16x32_bf16 v[48:51], v[224:227], v[192:195], v[24:27]
	v_mfma_f32_16x16x32_bf16 v[20:23], v[216:219], v[200:203], v[20:23]
	v_mfma_f32_16x16x32_bf16 v[16:19], v[224:227], v[200:203], v[16:19]
	v_mfma_f32_16x16x32_bf16 v[4:7], v[216:219], v[208:211], v[4:7]
	v_mfma_f32_16x16x32_bf16 v[0:3], v[224:227], v[208:211], v[0:3]
	s_barrier
	s_add_i32 s53, s53, 2
	s_add_u32 s0, s0, 0x100
	s_addc_u32 s1, s1, 0
	s_add_u32 s51, s51, 0x100
	s_addc_u32 s52, s52, 0
	s_cmp_gt_u32 s53, 13
.LBB0_416:
	ds_read_b128 v[24:27], v186
	ds_read_b128 v[28:31], v186 offset:1024
	ds_read_b128 v[40:43], v186 offset:2048
	ds_read_b128 v[44:47], v186 offset:3072
	s_add_u32 s4, s0, 0xfffc0080
	s_addc_u32 s5, s1, -1
	s_cmp_eq_u32 s53, 12
	s_cselect_b32 s29, s7, s5
	s_cselect_b32 s28, s10, s4
	s_cselect_b32 s5, s19, s52
	s_cselect_b32 s4, s21, s51
	s_add_i32 m0, s27, 0xc000
	ds_read_b128 v[144:147], v187
	ds_read_b128 v[148:151], v187 offset:1024
	ds_read_b128 v[182:185], v187 offset:2048
	ds_read_b128 v[192:195], v187 offset:3072
	ds_read_b128 v[196:199], v187 offset:4096
	ds_read_b128 v[200:203], v187 offset:5120
	ds_read_b128 v[204:207], v187 offset:6144
	ds_read_b128 v[208:211], v187 offset:7168
	global_load_lds_dwordx4 v166, s[0:1]
	s_nop 1
	s_add_i32 m0, s27, 0xe000
	s_nop 0
	global_load_lds_dwordx4 v168, s[0:1]
	s_waitcnt lgkmcnt(8)
	ds_read_b128 v[212:215], v189
	ds_read_b128 v[216:219], v189 offset:1024
	ds_read_b128 v[220:223], v189 offset:2048
	ds_read_b128 v[224:227], v189 offset:3072
	s_waitcnt vmcnt(8) lgkmcnt(0)
	s_barrier
	v_mfma_f32_16x16x32_bf16 v[140:143], v[24:27], v[144:147], v[140:143]
	v_mfma_f32_16x16x32_bf16 v[136:139], v[40:43], v[144:147], v[136:139]
	v_mfma_f32_16x16x32_bf16 v[124:127], v[24:27], v[182:185], v[124:127]
	v_mfma_f32_16x16x32_bf16 v[120:123], v[40:43], v[182:185], v[120:123]
	v_mfma_f32_16x16x32_bf16 v[108:111], v[24:27], v[196:199], v[108:111]
	v_mfma_f32_16x16x32_bf16 v[104:107], v[40:43], v[196:199], v[104:107]
	v_mfma_f32_16x16x32_bf16 v[92:95], v[24:27], v[204:207], v[92:95]
	v_mfma_f32_16x16x32_bf16 v[88:91], v[40:43], v[204:207], v[88:91]
	v_mfma_f32_16x16x32_bf16 v[140:143], v[28:31], v[148:151], v[140:143]
	v_mfma_f32_16x16x32_bf16 v[136:139], v[44:47], v[148:151], v[136:139]
	v_mfma_f32_16x16x32_bf16 v[124:127], v[28:31], v[192:195], v[124:127]
	v_mfma_f32_16x16x32_bf16 v[120:123], v[44:47], v[192:195], v[120:123]
	v_mfma_f32_16x16x32_bf16 v[108:111], v[28:31], v[200:203], v[108:111]
	v_mfma_f32_16x16x32_bf16 v[104:107], v[44:47], v[200:203], v[104:107]
	v_mfma_f32_16x16x32_bf16 v[92:95], v[28:31], v[208:211], v[92:95]
	v_mfma_f32_16x16x32_bf16 v[88:91], v[44:47], v[208:211], v[88:91]
	v_mfma_f32_16x16x32_bf16 v[132:135], v[212:215], v[144:147], v[132:135]
	v_mfma_f32_16x16x32_bf16 v[128:131], v[220:223], v[144:147], v[128:131]
	v_mfma_f32_16x16x32_bf16 v[116:119], v[212:215], v[182:185], v[116:119]
	v_mfma_f32_16x16x32_bf16 v[112:115], v[220:223], v[182:185], v[112:115]
	v_mfma_f32_16x16x32_bf16 v[100:103], v[212:215], v[196:199], v[100:103]
	v_mfma_f32_16x16x32_bf16 v[96:99], v[220:223], v[196:199], v[96:99]
	v_mfma_f32_16x16x32_bf16 v[84:87], v[212:215], v[204:207], v[84:87]
	v_mfma_f32_16x16x32_bf16 v[80:83], v[220:223], v[204:207], v[80:83]
	v_mfma_f32_16x16x32_bf16 v[132:135], v[216:219], v[148:151], v[132:135]
	v_mfma_f32_16x16x32_bf16 v[128:131], v[224:227], v[148:151], v[128:131]
	v_mfma_f32_16x16x32_bf16 v[116:119], v[216:219], v[192:195], v[116:119]
	v_mfma_f32_16x16x32_bf16 v[112:115], v[224:227], v[192:195], v[112:115]
	v_mfma_f32_16x16x32_bf16 v[100:103], v[216:219], v[200:203], v[100:103]
	v_mfma_f32_16x16x32_bf16 v[96:99], v[224:227], v[200:203], v[96:99]
	v_mfma_f32_16x16x32_bf16 v[84:87], v[216:219], v[208:211], v[84:87]
	v_mfma_f32_16x16x32_bf16 v[80:83], v[224:227], v[208:211], v[80:83]
	s_barrier
; #define PG8_STAGE(bufoff, gbase, voff) do { _Pragma("unroll") for (int _i = 0; _i < 2; ++_i) \
;         __builtin_amdgcn_global_load_lds((const unsigned*)((const char*)(gbase) + (voff)[_i]), (PG8_LAS unsigned*)(lds + (bufoff) + ldsw + _i * 8192), 16, 0, 0); } while (0)
; #define PG8_LDA(dst, b, h) do { _Pragma("unroll") for (int m = 0; m < 4; ++m) _Pragma("unroll") for (int k = 0; k < 2; ++k) dst[m][k] = *(const PG8_LAS bf16x8*)(lds + PG8_SA(b, h) + aoff + m * 2048 + k * 1024); } while (0)
; #define PG8_LDB(dst, b, h) do { _Pragma("unroll") for (int n = 0; n < 2; ++n) _Pragma("unroll") for (int k = 0; k < 2; ++k) dst[n][k] = *(const PG8_LAS bf16x8*)(lds + PG8_SB(b, h) + boff + n * 2048 + k * 1024); } while (0)
; #define PG8_MMA(ai, bj, At, Bt) do { __builtin_amdgcn_s_setprio(1); _Pragma("unroll") for (int m = 0; m < 4; ++m) _Pragma("unroll") for (int n = 0; n < 2; ++n) _Pragma("unroll") for (int k = 0; k < 2; ++k) \
;         acc[ai][bj][m][n] = __builtin_amdgcn_mfma_f32_16x16x32_bf16(Bt[n][k], At[m][k], acc[ai][bj][m][n], 0, 0, 0); __builtin_amdgcn_s_setprio(0); } while (0)
; #define PG8_WAIT_V(n) asm volatile("s_waitcnt vmcnt(" #n ")" ::: "memory")
; #define PG8_WAIT_L(n) asm volatile("s_waitcnt lgkmcnt(" #n ")" ::: "memory")
; #define PG8_BAR __builtin_amdgcn_s_barrier()
; #define PG8_SCHED __builtin_amdgcn_sched_barrier(0)
; template <class Epi, class Sched>
; __device__ __forceinline__ void gemm_phase(PG8_LAS unsigned char* lds, const Gemm g, const Sched& S, const Epi& E) {
;     ...
;             PG8_LDA(At, 0, 1); PG8_STAGE(PG8_SA(0, 0), a2, voffA);
;             PG8_BAR; PG8_WAIT_L(0); PG8_MMA(1, 0, At, B0); PG8_BAR; PG8_SCHED;
;             PG8_STAGE(PG8_SB(0, 1), b2 + hstep, voffB);
;             PG8_WAIT_V(6); PG8_BAR; PG8_MMA(1, 1, At, B1); PG8_BAR;
;             PG8_LDB(B0, 1, 0); PG8_SCHED; PG8_LDA(At, 1, 0); PG8_STAGE(PG8_SA(0, 1), a2 + hstep, voffA);
;             PG8_WAIT_L(8); PG8_BAR; PG8_WAIT_L(0); PG8_MMA(0, 0, At, B0); PG8_BAR; PG8_SCHED;
;             PG8_LDB(B1, 1, 1); PG8_STAGE(PG8_SB(1, 0), b3, voffB);
;             PG8_BAR; PG8_WAIT_L(0); PG8_MMA(0, 1, At, B1); PG8_BAR;
	ds_read_b128 v[144:147], v187 offset:16384
	ds_read_b128 v[148:151], v187 offset:17408
	ds_read_b128 v[182:185], v187 offset:18432
	ds_read_b128 v[192:195], v187 offset:19456
	ds_read_b128 v[196:199], v187 offset:20480
	ds_read_b128 v[200:203], v187 offset:21504
	ds_read_b128 v[204:207], v187 offset:22528
	ds_read_b128 v[208:211], v187 offset:23552
	s_add_i32 s54, s43, s35
	s_add_u32 s98, s4, s14
	s_addc_u32 s99, s5, s15
	s_mov_b32 m0, s54
	s_nop 0
	global_load_lds_dwordx4 v156, s[4:5]
	s_nop 1
	s_add_i32 m0, s54, 0x2000
	s_nop 0
	global_load_lds_dwordx4 v160, s[4:5]
	s_nop 1
	s_mov_b32 m0, s27
	s_add_u32 s100, s28, s14
	s_addc_u32 s101, s29, s15
	global_load_lds_dwordx4 v154, s[28:29]
	s_nop 1
	s_mov_b32 m0, s36
	s_nop 0
	global_load_lds_dwordx4 v158, s[28:29]
	s_add_u32 s54, s4, 0x40000
	s_addc_u32 s55, s5, 0
	s_add_i32 s56, s44, s35
	s_mov_b32 m0, s56
	s_nop 0
	global_load_lds_dwordx4 v156, s[54:55]
	s_nop 1
	s_add_i32 m0, s56, 0x2000
	s_nop 0
	global_load_lds_dwordx4 v160, s[54:55]
	s_waitcnt vmcnt(8) lgkmcnt(0)
	s_barrier
	v_mfma_f32_16x16x32_bf16 v[76:79], v[24:27], v[144:147], v[76:79]
	v_mfma_f32_16x16x32_bf16 v[72:75], v[40:43], v[144:147], v[72:75]
	v_mfma_f32_16x16x32_bf16 v[60:63], v[24:27], v[182:185], v[60:63]
	v_mfma_f32_16x16x32_bf16 v[56:59], v[40:43], v[182:185], v[56:59]
	v_mfma_f32_16x16x32_bf16 v[36:39], v[24:27], v[196:199], v[36:39]
	v_mfma_f32_16x16x32_bf16 v[32:35], v[40:43], v[196:199], v[32:35]
	v_mfma_f32_16x16x32_bf16 v[12:15], v[24:27], v[204:207], v[12:15]
	v_mfma_f32_16x16x32_bf16 v[8:11], v[40:43], v[204:207], v[8:11]
	v_mfma_f32_16x16x32_bf16 v[76:79], v[28:31], v[148:151], v[76:79]
	v_mfma_f32_16x16x32_bf16 v[72:75], v[44:47], v[148:151], v[72:75]
	v_mfma_f32_16x16x32_bf16 v[60:63], v[28:31], v[192:195], v[60:63]
	v_mfma_f32_16x16x32_bf16 v[56:59], v[44:47], v[192:195], v[56:59]
	v_mfma_f32_16x16x32_bf16 v[36:39], v[28:31], v[200:203], v[36:39]
	v_mfma_f32_16x16x32_bf16 v[32:35], v[44:47], v[200:203], v[32:35]
	v_mfma_f32_16x16x32_bf16 v[12:15], v[28:31], v[208:211], v[12:15]
	v_mfma_f32_16x16x32_bf16 v[8:11], v[44:47], v[208:211], v[8:11]
	v_mfma_f32_16x16x32_bf16 v[20:23], v[212:215], v[196:199], v[20:23]
	v_mfma_f32_16x16x32_bf16 v[16:19], v[220:223], v[196:199], v[16:19]
	v_mfma_f32_16x16x32_bf16 v[4:7], v[212:215], v[204:207], v[4:7]
	v_mfma_f32_16x16x32_bf16 v[0:3], v[220:223], v[204:207], v[0:3]
	v_mfma_f32_16x16x32_bf16 v[24:27], v[212:215], v[144:147], v[68:71]
	v_mfma_f32_16x16x32_bf16 v[28:31], v[220:223], v[144:147], v[64:67]
	v_mfma_f32_16x16x32_bf16 v[40:43], v[212:215], v[182:185], v[52:55]
	v_mfma_f32_16x16x32_bf16 v[44:47], v[220:223], v[182:185], v[48:51]
	v_mfma_f32_16x16x32_bf16 v[20:23], v[216:219], v[200:203], v[20:23]
	v_mfma_f32_16x16x32_bf16 v[16:19], v[224:227], v[200:203], v[16:19]
	v_mfma_f32_16x16x32_bf16 v[4:7], v[216:219], v[208:211], v[4:7]
	v_mfma_f32_16x16x32_bf16 v[0:3], v[224:227], v[208:211], v[0:3]
	v_mfma_f32_16x16x32_bf16 v[24:27], v[216:219], v[148:151], v[24:27]
	v_mfma_f32_16x16x32_bf16 v[28:31], v[224:227], v[148:151], v[28:31]
	v_mfma_f32_16x16x32_bf16 v[40:43], v[216:219], v[192:195], v[40:43]
	v_mfma_f32_16x16x32_bf16 v[44:47], v[224:227], v[192:195], v[44:47]
	s_barrier
	s_add_i32 s54, 0, 0x18000
	v_add_u32_e32 v68, s54, v179
	ds_read_b128 v[48:51], v68
	ds_read_b128 v[52:55], v68 offset:1024
	ds_read_b128 v[64:67], v68 offset:2048
	ds_read_b128 v[68:71], v68 offset:3072
	s_add_u32 s28, s28, 0x40000
	s_addc_u32 s29, s29, 0
	s_mov_b32 m0, s37
	ds_read_b128 v[144:147], v187 offset:32768
	ds_read_b128 v[148:151], v187 offset:33792
	ds_read_b128 v[182:185], v187 offset:34816
	ds_read_b128 v[192:195], v187 offset:35840
	ds_read_b128 v[196:199], v187 offset:36864
	ds_read_b128 v[200:203], v187 offset:37888
	ds_read_b128 v[204:207], v187 offset:38912
	ds_read_b128 v[208:211], v187 offset:39936
	global_load_lds_dwordx4 v154, s[28:29]
	s_nop 1
	s_mov_b32 m0, s38
	s_nop 0
	global_load_lds_dwordx4 v158, s[28:29]
	s_add_i32 s28, 0, 0x1c000
	v_add_u32_e32 v162, s28, v179
	s_waitcnt lgkmcnt(8)
	ds_read_b128 v[212:215], v162
	ds_read_b128 v[216:219], v162 offset:1024
	ds_read_b128 v[220:223], v162 offset:2048
	ds_read_b128 v[224:227], v162 offset:3072
	s_waitcnt vmcnt(8) lgkmcnt(0)
	s_barrier
; #define PG8_STAGE(bufoff, gbase, voff) do { _Pragma("unroll") for (int _i = 0; _i < 2; ++_i) \
;         __builtin_amdgcn_global_load_lds((const unsigned*)((const char*)(gbase) + (voff)[_i]), (PG8_LAS unsigned*)(lds + (bufoff) + ldsw + _i * 8192), 16, 0, 0); } while (0)
; #define PG8_LDA(dst, b, h) do { _Pragma("unroll") for (int m = 0; m < 4; ++m) _Pragma("unroll") for (int k = 0; k < 2; ++k) dst[m][k] = *(const PG8_LAS bf16x8*)(lds + PG8_SA(b, h) + aoff + m * 2048 + k * 1024); } while (0)
; #define PG8_MMA(ai, bj, At, Bt) do { __builtin_amdgcn_s_setprio(1); _Pragma("unroll") for (int m = 0; m < 4; ++m) _Pragma("unroll") for (int n = 0; n < 2; ++n) _Pragma("unroll") for (int k = 0; k < 2; ++k) \
;         acc[ai][bj][m][n] = __builtin_amdgcn_mfma_f32_16x16x32_bf16(Bt[n][k], At[m][k], acc[ai][bj][m][n], 0, 0, 0); __builtin_amdgcn_s_setprio(0); } while (0)
; #define PG8_WAIT_V(n) asm volatile("s_waitcnt vmcnt(" #n ")" ::: "memory")
; #define PG8_WAIT_L(n) asm volatile("s_waitcnt lgkmcnt(" #n ")" ::: "memory")
; #define PG8_BAR __builtin_amdgcn_s_barrier()
; #define PG8_SCHED __builtin_amdgcn_sched_barrier(0)
;     __device__ __forceinline__ void operator()(const f32x4 (&acc)[2][2][4][2], const Unit& u, int wr, int wc, int fr, int fq) const {
;         int act = 0; const float* bias = nullptr;
;         if (mode == 1) { if (u.pn >= 8 && u.pn < 12) act = 1; else if (u.pn >= 12) { act = 3; bias = (u.pn >= 14) ? bias_b + (u.pn - 14) * 256 : bias_f + (u.pn - 12) * 256; } }
; template <class Epi, class Sched>
; __device__ __forceinline__ void gemm_phase(PG8_LAS unsigned char* lds, const Gemm g, const Sched& S, const Epi& E) {
;     ...
;             PG8_BAR; PG8_WAIT_L(0); PG8_MMA(0, 1, At, B1); PG8_BAR;
;             PG8_LDA(At, 1, 1); PG8_STAGE(PG8_SA(1, 0), a3, voffA);
;             PG8_BAR; PG8_WAIT_L(0); PG8_MMA(1, 0, At, B0); PG8_BAR; PG8_SCHED;
;             PG8_STAGE(PG8_SB(1, 1), b3 + hstep, voffB);
;             PG8_WAIT_V(6); PG8_BAR; PG8_MMA(1, 1, At, B1); PG8_BAR;
	v_mfma_f32_16x16x32_bf16 v[140:143], v[48:51], v[144:147], v[140:143]
	v_mfma_f32_16x16x32_bf16 v[136:139], v[64:67], v[144:147], v[136:139]
	v_mfma_f32_16x16x32_bf16 v[124:127], v[48:51], v[182:185], v[124:127]
	v_mfma_f32_16x16x32_bf16 v[120:123], v[64:67], v[182:185], v[120:123]
	v_mfma_f32_16x16x32_bf16 v[108:111], v[48:51], v[196:199], v[108:111]
	v_mfma_f32_16x16x32_bf16 v[104:107], v[64:67], v[196:199], v[104:107]
	v_mfma_f32_16x16x32_bf16 v[92:95], v[48:51], v[204:207], v[92:95]
	v_mfma_f32_16x16x32_bf16 v[88:91], v[64:67], v[204:207], v[88:91]
	v_mfma_f32_16x16x32_bf16 v[140:143], v[52:55], v[148:151], v[140:143]
	v_mfma_f32_16x16x32_bf16 v[136:139], v[68:71], v[148:151], v[136:139]
	v_mfma_f32_16x16x32_bf16 v[124:127], v[52:55], v[192:195], v[124:127]
	v_mfma_f32_16x16x32_bf16 v[120:123], v[68:71], v[192:195], v[120:123]
	v_mfma_f32_16x16x32_bf16 v[108:111], v[52:55], v[200:203], v[108:111]
	v_mfma_f32_16x16x32_bf16 v[104:107], v[68:71], v[200:203], v[104:107]
	v_mfma_f32_16x16x32_bf16 v[92:95], v[52:55], v[208:211], v[92:95]
	v_mfma_f32_16x16x32_bf16 v[88:91], v[68:71], v[208:211], v[88:91]
	v_mfma_f32_16x16x32_bf16 v[132:135], v[212:215], v[144:147], v[132:135]
	v_mfma_f32_16x16x32_bf16 v[128:131], v[220:223], v[144:147], v[128:131]
	v_mfma_f32_16x16x32_bf16 v[116:119], v[212:215], v[182:185], v[116:119]
	v_mfma_f32_16x16x32_bf16 v[112:115], v[220:223], v[182:185], v[112:115]
	v_mfma_f32_16x16x32_bf16 v[100:103], v[212:215], v[196:199], v[100:103]
	v_mfma_f32_16x16x32_bf16 v[96:99], v[220:223], v[196:199], v[96:99]
	v_mfma_f32_16x16x32_bf16 v[84:87], v[212:215], v[204:207], v[84:87]
	v_mfma_f32_16x16x32_bf16 v[80:83], v[220:223], v[204:207], v[80:83]
	v_mfma_f32_16x16x32_bf16 v[132:135], v[216:219], v[148:151], v[132:135]
	v_mfma_f32_16x16x32_bf16 v[128:131], v[224:227], v[148:151], v[128:131]
	v_mfma_f32_16x16x32_bf16 v[116:119], v[216:219], v[192:195], v[116:119]
	v_mfma_f32_16x16x32_bf16 v[112:115], v[224:227], v[192:195], v[112:115]
	v_mfma_f32_16x16x32_bf16 v[100:103], v[216:219], v[200:203], v[100:103]
	v_mfma_f32_16x16x32_bf16 v[96:99], v[224:227], v[200:203], v[96:99]
	v_mfma_f32_16x16x32_bf16 v[84:87], v[216:219], v[208:211], v[84:87]
	v_mfma_f32_16x16x32_bf16 v[80:83], v[224:227], v[208:211], v[80:83]
	s_barrier
	ds_read_b128 v[144:147], v187 offset:49152
	ds_read_b128 v[148:151], v187 offset:50176
	ds_read_b128 v[182:185], v187 offset:51200
	ds_read_b128 v[192:195], v187 offset:52224
	ds_read_b128 v[196:199], v187 offset:53248
	ds_read_b128 v[200:203], v187 offset:54272
	ds_read_b128 v[204:207], v187 offset:55296
	ds_read_b128 v[208:211], v187 offset:56320
	s_add_i32 s29, s54, s35
	s_mov_b32 m0, s29
	s_nop 0
	global_load_lds_dwordx4 v156, s[98:99]
	s_nop 1
	s_add_i32 m0, s29, 0x2000
	s_nop 0
	global_load_lds_dwordx4 v160, s[98:99]
	s_nop 1
	s_mov_b32 m0, s39
	s_nop 0
	global_load_lds_dwordx4 v154, s[100:101]
	s_nop 1
	s_mov_b32 m0, s40
	s_nop 0
	global_load_lds_dwordx4 v158, s[100:101]
	s_add_u32 s4, s4, 0x40080
	s_addc_u32 s5, s5, 0
	s_add_i32 s28, s28, s35
	s_mov_b32 m0, s28
	s_nop 0
	global_load_lds_dwordx4 v156, s[4:5]
	s_nop 1
	s_add_i32 m0, s28, 0x2000
	s_nop 0
	global_load_lds_dwordx4 v160, s[4:5]
	s_waitcnt vmcnt(8) lgkmcnt(0)
	s_barrier
	v_mfma_f32_16x16x32_bf16 v[76:79], v[48:51], v[144:147], v[76:79]
	v_mfma_f32_16x16x32_bf16 v[72:75], v[64:67], v[144:147], v[72:75]
	v_mfma_f32_16x16x32_bf16 v[60:63], v[48:51], v[182:185], v[60:63]
	v_mfma_f32_16x16x32_bf16 v[56:59], v[64:67], v[182:185], v[56:59]
	v_mfma_f32_16x16x32_bf16 v[36:39], v[48:51], v[196:199], v[36:39]
	v_mfma_f32_16x16x32_bf16 v[32:35], v[64:67], v[196:199], v[32:35]
	v_mfma_f32_16x16x32_bf16 v[12:15], v[48:51], v[204:207], v[12:15]
	v_mfma_f32_16x16x32_bf16 v[8:11], v[64:67], v[204:207], v[8:11]
	v_mfma_f32_16x16x32_bf16 v[76:79], v[52:55], v[148:151], v[76:79]
	v_mfma_f32_16x16x32_bf16 v[72:75], v[68:71], v[148:151], v[72:75]
	v_mfma_f32_16x16x32_bf16 v[60:63], v[52:55], v[192:195], v[60:63]
	v_mfma_f32_16x16x32_bf16 v[56:59], v[68:71], v[192:195], v[56:59]
	v_mfma_f32_16x16x32_bf16 v[36:39], v[52:55], v[200:203], v[36:39]
	v_mfma_f32_16x16x32_bf16 v[32:35], v[68:71], v[200:203], v[32:35]
	v_mfma_f32_16x16x32_bf16 v[12:15], v[52:55], v[208:211], v[12:15]
	v_mfma_f32_16x16x32_bf16 v[8:11], v[68:71], v[208:211], v[8:11]
	v_mfma_f32_16x16x32_bf16 v[24:27], v[212:215], v[144:147], v[24:27]
	v_mfma_f32_16x16x32_bf16 v[68:71], v[216:219], v[148:151], v[24:27]
	v_mfma_f32_16x16x32_bf16 v[24:27], v[220:223], v[144:147], v[28:31]
	v_mfma_f32_16x16x32_bf16 v[64:67], v[224:227], v[148:151], v[24:27]
	v_mfma_f32_16x16x32_bf16 v[24:27], v[212:215], v[182:185], v[40:43]
	v_mfma_f32_16x16x32_bf16 v[52:55], v[216:219], v[192:195], v[24:27]
	v_mfma_f32_16x16x32_bf16 v[24:27], v[220:223], v[182:185], v[44:47]
	v_mfma_f32_16x16x32_bf16 v[20:23], v[212:215], v[196:199], v[20:23]
	v_mfma_f32_16x16x32_bf16 v[16:19], v[220:223], v[196:199], v[16:19]
	v_mfma_f32_16x16x32_bf16 v[4:7], v[212:215], v[204:207], v[4:7]
	v_mfma_f32_16x16x32_bf16 v[0:3], v[220:223], v[204:207], v[0:3]
	v_mfma_f32_16x16x32_bf16 v[48:51], v[224:227], v[192:195], v[24:27]
	v_mfma_f32_16x16x32_bf16 v[20:23], v[216:219], v[200:203], v[20:23]
	v_mfma_f32_16x16x32_bf16 v[16:19], v[224:227], v[200:203], v[16:19]
	v_mfma_f32_16x16x32_bf16 v[4:7], v[216:219], v[208:211], v[4:7]
	v_mfma_f32_16x16x32_bf16 v[0:3], v[224:227], v[208:211], v[0:3]
	s_barrier
	s_add_i32 s53, s53, 2
	s_add_u32 s0, s0, 0x100
	s_addc_u32 s1, s1, 0
	s_add_u32 s51, s51, 0x100
	s_addc_u32 s52, s52, 0
	s_cmp_gt_u32 s53, 13
	s_cbranch_scc0 .LBB0_416
	s_cmp_gt_i32 s26, 11
	s_cselect_b64 s[4:5], -1, 0
	s_cmp_lt_i32 s26, 12
	s_mov_b64 s[0:1], 0
	s_cbranch_scc1 .LBB0_422
	s_lshl_b32 s10, s26, 8
	s_cmp_lt_u32 s26, 14
	s_mov_b64 s[28:29], -1
	s_cbranch_scc0 .LBB0_420
	s_lshl_b64 s[0:1], s[10:11], 2
	v_readlane_b32 s52, v245, 0
	v_readlane_b32 s53, v245, 1
	s_add_u32 s0, s52, s0
	s_addc_u32 s1, s53, s1
	s_add_u32 s0, s0, 0xffffd000
	v_readlane_b32 s54, v245, 2
	v_readlane_b32 s55, v245, 3
	v_readlane_b32 s56, v245, 4
	v_readlane_b32 s57, v245, 5
	v_readlane_b32 s58, v245, 6
	v_readlane_b32 s59, v245, 7
	v_readlane_b32 s60, v245, 8
	v_readlane_b32 s61, v245, 9
	v_readlane_b32 s62, v245, 10
	v_readlane_b32 s63, v245, 11
	v_readlane_b32 s64, v245, 12
	v_readlane_b32 s65, v245, 13
	v_readlane_b32 s66, v245, 14
	v_readlane_b32 s67, v245, 15
	s_addc_u32 s1, s1, -1
	s_mov_b64 s[28:29], 0

; #define PG8_STAGE(bufoff, gbase, voff) do { _Pragma("unroll") for (int _i = 0; _i < 2; ++_i) \
;         __builtin_amdgcn_global_load_lds((const unsigned*)((const char*)(gbase) + (voff)[_i]), (PG8_LAS unsigned*)(lds + (bufoff) + ldsw + _i * 8192), 16, 0, 0); } while (0)
; #define PG8_LDA(dst, b, h) do { _Pragma("unroll") for (int m = 0; m < 4; ++m) _Pragma("unroll") for (int k = 0; k < 2; ++k) dst[m][k] = *(const PG8_LAS bf16x8*)(lds + PG8_SA(b, h) + aoff + m * 2048 + k * 1024); } while (0)
; #define PG8_LDB(dst, b, h) do { _Pragma("unroll") for (int n = 0; n < 2; ++n) _Pragma("unroll") for (int k = 0; k < 2; ++k) dst[n][k] = *(const PG8_LAS bf16x8*)(lds + PG8_SB(b, h) + boff + n * 2048 + k * 1024); } while (0)
; #define PG8_MMA(ai, bj, At, Bt) do { __builtin_amdgcn_s_setprio(1); _Pragma("unroll") for (int m = 0; m < 4; ++m) _Pragma("unroll") for (int n = 0; n < 2; ++n) _Pragma("unroll") for (int k = 0; k < 2; ++k) \
;         acc[ai][bj][m][n] = __builtin_amdgcn_mfma_f32_16x16x32_bf16(Bt[n][k], At[m][k], acc[ai][bj][m][n], 0, 0, 0); __builtin_amdgcn_s_setprio(0); } while (0)
; template <class Epi, class Sched>
; __device__ __forceinline__ void gemm_phase(PG8_LAS unsigned char* lds, const Gemm g, const Sched& S, const Epi& E) {
;     ...
;         const bool has_next = S.next(ui + 1, nxt);
;         const char* nA = has_next ? (const char*)g.A + (size_t)nxt.pm * tstep : cA; const char* nB = has_next ? (const char*)g.Bt + (size_t)nxt.pn * tstep : cB;
;         for (int t = 0; t < nt; t += 2) {
;             const bool last = (t == nt - 2);
;             const char* a1 = cA + (size_t)(t + 1) * kstep;
;             const char* a2 = last ? nA : cA + (size_t)(t + 2) * kstep; const char* b2 = last ? nB : cB + (size_t)(t + 2) * kstep;
;             const char* a3 = a2 + kstep; const char* b3 = b2 + kstep;
;             if (last && has_next) S.a_ready(nxt);
;             PG8_LDB(B0, 0, 0); PG8_SCHED; PG8_LDA(At, 0, 0); PG8_STAGE(PG8_SA(1, 1), a1 + hstep, voffA);
;             PG8_WAIT_L(8); PG8_BAR; PG8_WAIT_L(0); PG8_MMA(0, 0, At, B0); PG8_BAR; PG8_SCHED;
;             PG8_LDB(B1, 0, 1); PG8_STAGE(PG8_SB(0, 0), b2, voffB);
;             PG8_BAR; PG8_WAIT_L(0); PG8_MMA(0, 1, At, B1); PG8_BAR;
;             PG8_LDA(At, 0, 1); PG8_STAGE(PG8_SA(0, 0), a2, voffA);
;             PG8_BAR; PG8_WAIT_L(0); PG8_MMA(1, 0, At, B0); PG8_BAR; PG8_SCHED;
.LBB0_723:
	s_ashr_i32 s11, s10, 31
	v_cmp_lt_i64_e32 vcc, s[12:13], v[140:141]
	s_lshl_b64 s[12:13], s[10:11], 19
	s_add_u32 s12, s26, s12
	s_addc_u32 s13, s27, s13
	s_and_b64 s[14:15], vcc, exec
	s_cselect_b32 s5, s13, s19
	s_cselect_b32 s11, s12, s18
	s_ashr_i32 s9, s8, 31
	s_lshl_b64 s[14:15], s[8:9], 19
	s_add_u32 s14, s28, s14
	s_addc_u32 s15, s29, s15
	s_and_b64 s[22:23], vcc, exec
	s_cselect_b32 s9, s15, s21
	s_cselect_b32 s45, s14, s20
	s_add_u32 s18, s18, 0x40080
	s_addc_u32 s19, s19, 0
	s_add_u32 s46, s20, 0x100
	s_addc_u32 s47, s21, 0
	s_mov_b32 s48, -2
	ds_read_b128 v[144:147], v151
	ds_read_b128 v[156:159], v151 offset:1024
	ds_read_b128 v[160:163], v151 offset:2048
	ds_read_b128 v[166:169], v151 offset:3072
	s_add_u32 s20, s18, 0xfffc0080
	s_addc_u32 s21, s19, -1
	s_cmp_eq_u32 s48, 12
	s_cselect_b32 s23, s5, s21
	s_cselect_b32 s22, s11, s20
	s_cselect_b32 s21, s9, s47
	s_cselect_b32 s20, s45, s46
	s_add_i32 m0, s17, 0xc000
	ds_read_b128 v[170:173], v153
	ds_read_b128 v[182:185], v153 offset:1024
	ds_read_b128 v[190:193], v153 offset:2048
	ds_read_b128 v[194:197], v153 offset:3072
	ds_read_b128 v[198:201], v153 offset:4096
	ds_read_b128 v[202:205], v153 offset:5120
	ds_read_b128 v[206:209], v153 offset:6144
	ds_read_b128 v[210:213], v153 offset:7168
	global_load_lds_dwordx4 v136, s[18:19]
	s_nop 1
	s_add_i32 m0, s17, 0xe000
	s_nop 0
	global_load_lds_dwordx4 v138, s[18:19]
	s_waitcnt lgkmcnt(8)
	ds_read_b128 v[214:217], v154
	ds_read_b128 v[218:221], v154 offset:1024
	ds_read_b128 v[222:225], v154 offset:2048
	ds_read_b128 v[226:229], v154 offset:3072
	s_waitcnt vmcnt(8) lgkmcnt(0)
	s_barrier
	v_mfma_f32_16x16x32_bf16 v[124:127], v[144:147], v[170:173], 0
	v_mfma_f32_16x16x32_bf16 v[120:123], v[160:163], v[170:173], 0
	v_mfma_f32_16x16x32_bf16 v[108:111], v[144:147], v[190:193], 0
	v_mfma_f32_16x16x32_bf16 v[104:107], v[160:163], v[190:193], 0
	v_mfma_f32_16x16x32_bf16 v[92:95], v[144:147], v[198:201], 0
	v_mfma_f32_16x16x32_bf16 v[88:91], v[160:163], v[198:201], 0
	v_mfma_f32_16x16x32_bf16 v[76:79], v[144:147], v[206:209], 0
	v_mfma_f32_16x16x32_bf16 v[72:75], v[160:163], v[206:209], 0
	v_mfma_f32_16x16x32_bf16 v[124:127], v[156:159], v[182:185], v[124:127]
	v_mfma_f32_16x16x32_bf16 v[120:123], v[166:169], v[182:185], v[120:123]
	v_mfma_f32_16x16x32_bf16 v[108:111], v[156:159], v[194:197], v[108:111]
	v_mfma_f32_16x16x32_bf16 v[104:107], v[166:169], v[194:197], v[104:107]
	v_mfma_f32_16x16x32_bf16 v[92:95], v[156:159], v[202:205], v[92:95]
	v_mfma_f32_16x16x32_bf16 v[88:91], v[166:169], v[202:205], v[88:91]
	v_mfma_f32_16x16x32_bf16 v[76:79], v[156:159], v[210:213], v[76:79]
	v_mfma_f32_16x16x32_bf16 v[72:75], v[166:169], v[210:213], v[72:75]
	v_mfma_f32_16x16x32_bf16 v[116:119], v[214:217], v[170:173], 0
	v_mfma_f32_16x16x32_bf16 v[112:115], v[222:225], v[170:173], 0
	v_mfma_f32_16x16x32_bf16 v[100:103], v[214:217], v[190:193], 0
	v_mfma_f32_16x16x32_bf16 v[96:99], v[222:225], v[190:193], 0
	v_mfma_f32_16x16x32_bf16 v[84:87], v[214:217], v[198:201], 0
	v_mfma_f32_16x16x32_bf16 v[80:83], v[222:225], v[198:201], 0
	v_mfma_f32_16x16x32_bf16 v[68:71], v[214:217], v[206:209], 0
	v_mfma_f32_16x16x32_bf16 v[64:67], v[222:225], v[206:209], 0
	v_mfma_f32_16x16x32_bf16 v[116:119], v[218:221], v[182:185], v[116:119]
	v_mfma_f32_16x16x32_bf16 v[112:115], v[226:229], v[182:185], v[112:115]
	v_mfma_f32_16x16x32_bf16 v[100:103], v[218:221], v[194:197], v[100:103]
	v_mfma_f32_16x16x32_bf16 v[96:99], v[226:229], v[194:197], v[96:99]
	v_mfma_f32_16x16x32_bf16 v[84:87], v[218:221], v[202:205], v[84:87]
	v_mfma_f32_16x16x32_bf16 v[80:83], v[226:229], v[202:205], v[80:83]
	v_mfma_f32_16x16x32_bf16 v[68:71], v[218:221], v[210:213], v[68:71]
	v_mfma_f32_16x16x32_bf16 v[64:67], v[226:229], v[210:213], v[64:67]
	s_barrier
	ds_read_b128 v[170:173], v153 offset:16384
	ds_read_b128 v[182:185], v153 offset:17408
	ds_read_b128 v[190:193], v153 offset:18432
	ds_read_b128 v[194:197], v153 offset:19456
	ds_read_b128 v[198:201], v153 offset:20480
	ds_read_b128 v[202:205], v153 offset:21504
	ds_read_b128 v[206:209], v153 offset:22528
	ds_read_b128 v[210:213], v153 offset:23552
	s_add_i32 s49, s42, s30
	s_add_u32 s98, s20, s6
	s_addc_u32 s99, s21, s7
	s_mov_b32 m0, s49
	s_nop 0
	global_load_lds_dwordx4 v130, s[20:21]
	s_nop 1
	s_add_i32 m0, s49, 0x2000
	s_nop 0
	global_load_lds_dwordx4 v134, s[20:21]
	s_nop 1
	s_mov_b32 m0, s17
	s_add_u32 s100, s22, s6
	s_addc_u32 s101, s23, s7
	global_load_lds_dwordx4 v128, s[22:23]
	s_nop 1
	s_mov_b32 m0, s31
	s_nop 0
	global_load_lds_dwordx4 v132, s[22:23]
	s_add_u32 s50, s20, 0x40000
	s_addc_u32 s51, s21, 0
	s_add_i32 s49, s43, s30
	s_mov_b32 m0, s49
	s_nop 0
	global_load_lds_dwordx4 v130, s[50:51]
	s_nop 1
	s_add_i32 m0, s49, 0x2000
	s_nop 0
	global_load_lds_dwordx4 v134, s[50:51]
	s_waitcnt vmcnt(8) lgkmcnt(0)
	s_barrier
; #define PG8_STAGE(bufoff, gbase, voff) do { _Pragma("unroll") for (int _i = 0; _i < 2; ++_i) \
;         __builtin_amdgcn_global_load_lds((const unsigned*)((const char*)(gbase) + (voff)[_i]), (PG8_LAS unsigned*)(lds + (bufoff) + ldsw + _i * 8192), 16, 0, 0); } while (0)
; #define PG8_LDA(dst, b, h) do { _Pragma("unroll") for (int m = 0; m < 4; ++m) _Pragma("unroll") for (int k = 0; k < 2; ++k) dst[m][k] = *(const PG8_LAS bf16x8*)(lds + PG8_SA(b, h) + aoff + m * 2048 + k * 1024); } while (0)
; #define PG8_LDB(dst, b, h) do { _Pragma("unroll") for (int n = 0; n < 2; ++n) _Pragma("unroll") for (int k = 0; k < 2; ++k) dst[n][k] = *(const PG8_LAS bf16x8*)(lds + PG8_SB(b, h) + boff + n * 2048 + k * 1024); } while (0)
; #define PG8_MMA(ai, bj, At, Bt) do { __builtin_amdgcn_s_setprio(1); _Pragma("unroll") for (int m = 0; m < 4; ++m) _Pragma("unroll") for (int n = 0; n < 2; ++n) _Pragma("unroll") for (int k = 0; k < 2; ++k) \
;         acc[ai][bj][m][n] = __builtin_amdgcn_mfma_f32_16x16x32_bf16(Bt[n][k], At[m][k], acc[ai][bj][m][n], 0, 0, 0); __builtin_amdgcn_s_setprio(0); } while (0)
; #define PG8_WAIT_V(n) asm volatile("s_waitcnt vmcnt(" #n ")" ::: "memory")
; #define PG8_WAIT_L(n) asm volatile("s_waitcnt lgkmcnt(" #n ")" ::: "memory")
; #define PG8_BAR __builtin_amdgcn_s_barrier()
; #define PG8_SCHED __builtin_amdgcn_sched_barrier(0)
; template <class Epi, class Sched>
; __device__ __forceinline__ void gemm_phase(PG8_LAS unsigned char* lds, const Gemm g, const Sched& S, const Epi& E) {
;     ...
;             PG8_BAR; PG8_WAIT_L(0); PG8_MMA(1, 0, At, B0); PG8_BAR; PG8_SCHED;
;             PG8_STAGE(PG8_SB(0, 1), b2 + hstep, voffB);
;             PG8_WAIT_V(6); PG8_BAR; PG8_MMA(1, 1, At, B1); PG8_BAR;
;             PG8_LDB(B0, 1, 0); PG8_SCHED; PG8_LDA(At, 1, 0); PG8_STAGE(PG8_SA(0, 1), a2 + hstep, voffA);
;             PG8_WAIT_L(8); PG8_BAR; PG8_WAIT_L(0); PG8_MMA(0, 0, At, B0); PG8_BAR; PG8_SCHED;
;             PG8_LDB(B1, 1, 1); PG8_STAGE(PG8_SB(1, 0), b3, voffB);
;             PG8_BAR; PG8_WAIT_L(0); PG8_MMA(0, 1, At, B1); PG8_BAR;
	v_mfma_f32_16x16x32_bf16 v[60:63], v[144:147], v[170:173], 0
	v_mfma_f32_16x16x32_bf16 v[56:59], v[160:163], v[170:173], 0
	v_mfma_f32_16x16x32_bf16 v[44:47], v[144:147], v[190:193], 0
	v_mfma_f32_16x16x32_bf16 v[40:43], v[160:163], v[190:193], 0
	v_mfma_f32_16x16x32_bf16 v[28:31], v[144:147], v[198:201], 0
	v_mfma_f32_16x16x32_bf16 v[24:27], v[160:163], v[198:201], 0
	v_mfma_f32_16x16x32_bf16 v[12:15], v[144:147], v[206:209], 0
	v_mfma_f32_16x16x32_bf16 v[8:11], v[160:163], v[206:209], 0
	v_mfma_f32_16x16x32_bf16 v[60:63], v[156:159], v[182:185], v[60:63]
	v_mfma_f32_16x16x32_bf16 v[56:59], v[166:169], v[182:185], v[56:59]
	v_mfma_f32_16x16x32_bf16 v[44:47], v[156:159], v[194:197], v[44:47]
	v_mfma_f32_16x16x32_bf16 v[40:43], v[166:169], v[194:197], v[40:43]
	v_mfma_f32_16x16x32_bf16 v[28:31], v[156:159], v[202:205], v[28:31]
	v_mfma_f32_16x16x32_bf16 v[24:27], v[166:169], v[202:205], v[24:27]
	v_mfma_f32_16x16x32_bf16 v[12:15], v[156:159], v[210:213], v[12:15]
	v_mfma_f32_16x16x32_bf16 v[8:11], v[166:169], v[210:213], v[8:11]
	v_mfma_f32_16x16x32_bf16 v[52:55], v[214:217], v[170:173], 0
	v_mfma_f32_16x16x32_bf16 v[48:51], v[222:225], v[170:173], 0
	v_mfma_f32_16x16x32_bf16 v[36:39], v[214:217], v[190:193], 0
	v_mfma_f32_16x16x32_bf16 v[32:35], v[222:225], v[190:193], 0
	v_mfma_f32_16x16x32_bf16 v[20:23], v[214:217], v[198:201], 0
	v_mfma_f32_16x16x32_bf16 v[16:19], v[222:225], v[198:201], 0
	v_mfma_f32_16x16x32_bf16 v[4:7], v[214:217], v[206:209], 0
	v_mfma_f32_16x16x32_bf16 v[0:3], v[222:225], v[206:209], 0
	v_mfma_f32_16x16x32_bf16 v[52:55], v[218:221], v[182:185], v[52:55]
	v_mfma_f32_16x16x32_bf16 v[48:51], v[226:229], v[182:185], v[48:51]
	v_mfma_f32_16x16x32_bf16 v[36:39], v[218:221], v[194:197], v[36:39]
	v_mfma_f32_16x16x32_bf16 v[32:35], v[226:229], v[194:197], v[32:35]
	v_mfma_f32_16x16x32_bf16 v[20:23], v[218:221], v[202:205], v[20:23]
	v_mfma_f32_16x16x32_bf16 v[16:19], v[226:229], v[202:205], v[16:19]
	v_mfma_f32_16x16x32_bf16 v[4:7], v[218:221], v[210:213], v[4:7]
	v_mfma_f32_16x16x32_bf16 v[0:3], v[226:229], v[210:213], v[0:3]
	s_barrier
	s_add_i32 s49, 0, 0x18000
	v_add_u32_e32 v155, s49, v149
	ds_read_b128 v[144:147], v155
	ds_read_b128 v[156:159], v155 offset:1024
	ds_read_b128 v[160:163], v155 offset:2048
	ds_read_b128 v[166:169], v155 offset:3072
	s_add_u32 s22, s22, 0x40000
	s_addc_u32 s23, s23, 0
	s_mov_b32 m0, s34
	ds_read_b128 v[170:173], v153 offset:32768
	ds_read_b128 v[182:185], v153 offset:33792
	ds_read_b128 v[190:193], v153 offset:34816
	ds_read_b128 v[194:197], v153 offset:35840
	ds_read_b128 v[198:201], v153 offset:36864
	ds_read_b128 v[202:205], v153 offset:37888
	ds_read_b128 v[206:209], v153 offset:38912
	ds_read_b128 v[210:213], v153 offset:39936
	global_load_lds_dwordx4 v128, s[22:23]
	s_nop 1
	s_mov_b32 m0, s35
	s_nop 0
	global_load_lds_dwordx4 v132, s[22:23]
	s_add_i32 s22, 0, 0x1c000
	v_add_u32_e32 v155, s22, v149
	s_waitcnt lgkmcnt(8)
	ds_read_b128 v[214:217], v155
	ds_read_b128 v[218:221], v155 offset:1024
	ds_read_b128 v[222:225], v155 offset:2048
	ds_read_b128 v[226:229], v155 offset:3072
	s_waitcnt vmcnt(8) lgkmcnt(0)
	s_barrier
	v_mfma_f32_16x16x32_bf16 v[124:127], v[144:147], v[170:173], v[124:127]
	v_mfma_f32_16x16x32_bf16 v[120:123], v[160:163], v[170:173], v[120:123]
	v_mfma_f32_16x16x32_bf16 v[108:111], v[144:147], v[190:193], v[108:111]
	v_mfma_f32_16x16x32_bf16 v[104:107], v[160:163], v[190:193], v[104:107]
	v_mfma_f32_16x16x32_bf16 v[92:95], v[144:147], v[198:201], v[92:95]
	v_mfma_f32_16x16x32_bf16 v[88:91], v[160:163], v[198:201], v[88:91]
	v_mfma_f32_16x16x32_bf16 v[76:79], v[144:147], v[206:209], v[76:79]
	v_mfma_f32_16x16x32_bf16 v[72:75], v[160:163], v[206:209], v[72:75]
	v_mfma_f32_16x16x32_bf16 v[124:127], v[156:159], v[182:185], v[124:127]
	v_mfma_f32_16x16x32_bf16 v[120:123], v[166:169], v[182:185], v[120:123]
	v_mfma_f32_16x16x32_bf16 v[108:111], v[156:159], v[194:197], v[108:111]
	v_mfma_f32_16x16x32_bf16 v[104:107], v[166:169], v[194:197], v[104:107]
	v_mfma_f32_16x16x32_bf16 v[92:95], v[156:159], v[202:205], v[92:95]
	v_mfma_f32_16x16x32_bf16 v[88:91], v[166:169], v[202:205], v[88:91]
	v_mfma_f32_16x16x32_bf16 v[76:79], v[156:159], v[210:213], v[76:79]
	v_mfma_f32_16x16x32_bf16 v[72:75], v[166:169], v[210:213], v[72:75]
	v_mfma_f32_16x16x32_bf16 v[116:119], v[214:217], v[170:173], v[116:119]
	v_mfma_f32_16x16x32_bf16 v[112:115], v[222:225], v[170:173], v[112:115]
	v_mfma_f32_16x16x32_bf16 v[100:103], v[214:217], v[190:193], v[100:103]
	v_mfma_f32_16x16x32_bf16 v[96:99], v[222:225], v[190:193], v[96:99]
	v_mfma_f32_16x16x32_bf16 v[84:87], v[214:217], v[198:201], v[84:87]
	v_mfma_f32_16x16x32_bf16 v[80:83], v[222:225], v[198:201], v[80:83]
	v_mfma_f32_16x16x32_bf16 v[68:71], v[214:217], v[206:209], v[68:71]
	v_mfma_f32_16x16x32_bf16 v[64:67], v[222:225], v[206:209], v[64:67]
	v_mfma_f32_16x16x32_bf16 v[116:119], v[218:221], v[182:185], v[116:119]
	v_mfma_f32_16x16x32_bf16 v[112:115], v[226:229], v[182:185], v[112:115]
	v_mfma_f32_16x16x32_bf16 v[100:103], v[218:221], v[194:197], v[100:103]
	v_mfma_f32_16x16x32_bf16 v[96:99], v[226:229], v[194:197], v[96:99]
	v_mfma_f32_16x16x32_bf16 v[84:87], v[218:221], v[202:205], v[84:87]
	v_mfma_f32_16x16x32_bf16 v[80:83], v[226:229], v[202:205], v[80:83]
	v_mfma_f32_16x16x32_bf16 v[68:71], v[218:221], v[210:213], v[68:71]
	v_mfma_f32_16x16x32_bf16 v[64:67], v[226:229], v[210:213], v[64:67]
	s_barrier
; #define PG8_STAGE(bufoff, gbase, voff) do { _Pragma("unroll") for (int _i = 0; _i < 2; ++_i) \
;         __builtin_amdgcn_global_load_lds((const unsigned*)((const char*)(gbase) + (voff)[_i]), (PG8_LAS unsigned*)(lds + (bufoff) + ldsw + _i * 8192), 16, 0, 0); } while (0)
; #define PG8_LDA(dst, b, h) do { _Pragma("unroll") for (int m = 0; m < 4; ++m) _Pragma("unroll") for (int k = 0; k < 2; ++k) dst[m][k] = *(const PG8_LAS bf16x8*)(lds + PG8_SA(b, h) + aoff + m * 2048 + k * 1024); } while (0)
; #define PG8_LDB(dst, b, h) do { _Pragma("unroll") for (int n = 0; n < 2; ++n) _Pragma("unroll") for (int k = 0; k < 2; ++k) dst[n][k] = *(const PG8_LAS bf16x8*)(lds + PG8_SB(b, h) + boff + n * 2048 + k * 1024); } while (0)
; #define PG8_MMA(ai, bj, At, Bt) do { __builtin_amdgcn_s_setprio(1); _Pragma("unroll") for (int m = 0; m < 4; ++m) _Pragma("unroll") for (int n = 0; n < 2; ++n) _Pragma("unroll") for (int k = 0; k < 2; ++k) \
;         acc[ai][bj][m][n] = __builtin_amdgcn_mfma_f32_16x16x32_bf16(Bt[n][k], At[m][k], acc[ai][bj][m][n], 0, 0, 0); __builtin_amdgcn_s_setprio(0); } while (0)
; #define PG8_WAIT_V(n) asm volatile("s_waitcnt vmcnt(" #n ")" ::: "memory")
; template <class Epi, class Sched>
; __device__ __forceinline__ void gemm_phase(PG8_LAS unsigned char* lds, const Gemm g, const Sched& S, const Epi& E) {
;     ...
;         for (int t = 0; t < nt; t += 2) {
;             const bool last = (t == nt - 2);
;             const char* a1 = cA + (size_t)(t + 1) * kstep;
;             const char* a2 = last ? nA : cA + (size_t)(t + 2) * kstep; const char* b2 = last ? nB : cB + (size_t)(t + 2) * kstep;
;             const char* a3 = a2 + kstep; const char* b3 = b2 + kstep;
;             if (last && has_next) S.a_ready(nxt);
;             PG8_LDB(B0, 0, 0); PG8_SCHED; PG8_LDA(At, 0, 0); PG8_STAGE(PG8_SA(1, 1), a1 + hstep, voffA);
;             PG8_WAIT_L(8); PG8_BAR; PG8_WAIT_L(0); PG8_MMA(0, 0, At, B0); PG8_BAR; PG8_SCHED;
;             PG8_LDB(B1, 0, 1); PG8_STAGE(PG8_SB(0, 0), b2, voffB);
;             PG8_BAR; PG8_WAIT_L(0); PG8_MMA(0, 1, At, B1); PG8_BAR;
;     ...
;             PG8_LDA(At, 1, 1); PG8_STAGE(PG8_SA(1, 0), a3, voffA);
;             PG8_BAR; PG8_WAIT_L(0); PG8_MMA(1, 0, At, B0); PG8_BAR; PG8_SCHED;
;             PG8_STAGE(PG8_SB(1, 1), b3 + hstep, voffB);
;             PG8_WAIT_V(6); PG8_BAR; PG8_MMA(1, 1, At, B1); PG8_BAR;
	ds_read_b128 v[170:173], v153 offset:49152
	ds_read_b128 v[182:185], v153 offset:50176
	ds_read_b128 v[190:193], v153 offset:51200
	ds_read_b128 v[194:197], v153 offset:52224
	ds_read_b128 v[198:201], v153 offset:53248
	ds_read_b128 v[202:205], v153 offset:54272
	ds_read_b128 v[206:209], v153 offset:55296
	ds_read_b128 v[210:213], v153 offset:56320
	s_add_i32 s23, s49, s30
	s_mov_b32 m0, s23
	s_nop 0
	global_load_lds_dwordx4 v130, s[98:99]
	s_nop 1
	s_add_i32 m0, s23, 0x2000
	s_nop 0
	global_load_lds_dwordx4 v134, s[98:99]
	s_nop 1
	s_mov_b32 m0, s37
	s_nop 0
	global_load_lds_dwordx4 v128, s[100:101]
	s_nop 1
	s_mov_b32 m0, s38
	s_nop 0
	global_load_lds_dwordx4 v132, s[100:101]
	s_add_u32 s20, s20, 0x40080
	s_addc_u32 s21, s21, 0
	s_add_i32 s22, s22, s30
	s_mov_b32 m0, s22
	s_nop 0
	global_load_lds_dwordx4 v130, s[20:21]
	s_nop 1
	s_add_i32 m0, s22, 0x2000
	s_nop 0
	global_load_lds_dwordx4 v134, s[20:21]
	s_waitcnt vmcnt(8) lgkmcnt(0)
	s_barrier
	v_mfma_f32_16x16x32_bf16 v[60:63], v[144:147], v[170:173], v[60:63]
	v_mfma_f32_16x16x32_bf16 v[56:59], v[160:163], v[170:173], v[56:59]
	v_mfma_f32_16x16x32_bf16 v[44:47], v[144:147], v[190:193], v[44:47]
	v_mfma_f32_16x16x32_bf16 v[40:43], v[160:163], v[190:193], v[40:43]
	v_mfma_f32_16x16x32_bf16 v[28:31], v[144:147], v[198:201], v[28:31]
	v_mfma_f32_16x16x32_bf16 v[24:27], v[160:163], v[198:201], v[24:27]
	v_mfma_f32_16x16x32_bf16 v[12:15], v[144:147], v[206:209], v[12:15]
	v_mfma_f32_16x16x32_bf16 v[8:11], v[160:163], v[206:209], v[8:11]
	v_mfma_f32_16x16x32_bf16 v[60:63], v[156:159], v[182:185], v[60:63]
	v_mfma_f32_16x16x32_bf16 v[56:59], v[166:169], v[182:185], v[56:59]
	v_mfma_f32_16x16x32_bf16 v[44:47], v[156:159], v[194:197], v[44:47]
	v_mfma_f32_16x16x32_bf16 v[40:43], v[166:169], v[194:197], v[40:43]
	v_mfma_f32_16x16x32_bf16 v[28:31], v[156:159], v[202:205], v[28:31]
	v_mfma_f32_16x16x32_bf16 v[24:27], v[166:169], v[202:205], v[24:27]
	v_mfma_f32_16x16x32_bf16 v[12:15], v[156:159], v[210:213], v[12:15]
	v_mfma_f32_16x16x32_bf16 v[8:11], v[166:169], v[210:213], v[8:11]
	v_mfma_f32_16x16x32_bf16 v[52:55], v[214:217], v[170:173], v[52:55]
	v_mfma_f32_16x16x32_bf16 v[48:51], v[222:225], v[170:173], v[48:51]
	v_mfma_f32_16x16x32_bf16 v[36:39], v[214:217], v[190:193], v[36:39]
	v_mfma_f32_16x16x32_bf16 v[32:35], v[222:225], v[190:193], v[32:35]
	v_mfma_f32_16x16x32_bf16 v[20:23], v[214:217], v[198:201], v[20:23]
	v_mfma_f32_16x16x32_bf16 v[16:19], v[222:225], v[198:201], v[16:19]
	v_mfma_f32_16x16x32_bf16 v[4:7], v[214:217], v[206:209], v[4:7]
	v_mfma_f32_16x16x32_bf16 v[0:3], v[222:225], v[206:209], v[0:3]
	v_mfma_f32_16x16x32_bf16 v[52:55], v[218:221], v[182:185], v[52:55]
	v_mfma_f32_16x16x32_bf16 v[48:51], v[226:229], v[182:185], v[48:51]
	v_mfma_f32_16x16x32_bf16 v[36:39], v[218:221], v[194:197], v[36:39]
	v_mfma_f32_16x16x32_bf16 v[32:35], v[226:229], v[194:197], v[32:35]
	v_mfma_f32_16x16x32_bf16 v[20:23], v[218:221], v[202:205], v[20:23]
	v_mfma_f32_16x16x32_bf16 v[16:19], v[226:229], v[202:205], v[16:19]
	v_mfma_f32_16x16x32_bf16 v[4:7], v[218:221], v[210:213], v[4:7]
	v_mfma_f32_16x16x32_bf16 v[0:3], v[226:229], v[210:213], v[0:3]
	s_barrier
	s_add_i32 s48, s48, 2
	s_add_u32 s18, s18, 0x100
	s_addc_u32 s19, s19, 0
	s_add_u32 s46, s46, 0x100
	s_addc_u32 s47, s47, 0
	s_cmp_gt_u32 s48, 13
.LBB0_724:
	ds_read_b128 v[144:147], v151
	ds_read_b128 v[156:159], v151 offset:1024
	ds_read_b128 v[160:163], v151 offset:2048
	ds_read_b128 v[166:169], v151 offset:3072
	s_add_u32 s20, s18, 0xfffc0080
	s_addc_u32 s21, s19, -1
	s_cmp_eq_u32 s48, 12
	s_cselect_b32 s23, s5, s21
	s_cselect_b32 s22, s11, s20
	s_cselect_b32 s21, s9, s47
	s_cselect_b32 s20, s45, s46
	s_add_i32 m0, s17, 0xc000
	ds_read_b128 v[170:173], v153
	ds_read_b128 v[182:185], v153 offset:1024
	ds_read_b128 v[190:193], v153 offset:2048
	ds_read_b128 v[194:197], v153 offset:3072
	ds_read_b128 v[198:201], v153 offset:4096
	ds_read_b128 v[202:205], v153 offset:5120
	ds_read_b128 v[206:209], v153 offset:6144
	ds_read_b128 v[210:213], v153 offset:7168
	global_load_lds_dwordx4 v136, s[18:19]
	s_nop 1
	s_add_i32 m0, s17, 0xe000
	s_nop 0
	global_load_lds_dwordx4 v138, s[18:19]
	s_waitcnt lgkmcnt(8)
	ds_read_b128 v[214:217], v154
	ds_read_b128 v[218:221], v154 offset:1024
	ds_read_b128 v[222:225], v154 offset:2048
	ds_read_b128 v[226:229], v154 offset:3072
	s_waitcnt vmcnt(8) lgkmcnt(0)
	s_barrier
	v_mfma_f32_16x16x32_bf16 v[124:127], v[144:147], v[170:173], v[124:127]
	v_mfma_f32_16x16x32_bf16 v[120:123], v[160:163], v[170:173], v[120:123]
	v_mfma_f32_16x16x32_bf16 v[108:111], v[144:147], v[190:193], v[108:111]
	v_mfma_f32_16x16x32_bf16 v[104:107], v[160:163], v[190:193], v[104:107]
	v_mfma_f32_16x16x32_bf16 v[92:95], v[144:147], v[198:201], v[92:95]
	v_mfma_f32_16x16x32_bf16 v[88:91], v[160:163], v[198:201], v[88:91]
	v_mfma_f32_16x16x32_bf16 v[76:79], v[144:147], v[206:209], v[76:79]
	v_mfma_f32_16x16x32_bf16 v[72:75], v[160:163], v[206:209], v[72:75]
	v_mfma_f32_16x16x32_bf16 v[124:127], v[156:159], v[182:185], v[124:127]
	v_mfma_f32_16x16x32_bf16 v[120:123], v[166:169], v[182:185], v[120:123]
	v_mfma_f32_16x16x32_bf16 v[108:111], v[156:159], v[194:197], v[108:111]
	v_mfma_f32_16x16x32_bf16 v[104:107], v[166:169], v[194:197], v[104:107]
	v_mfma_f32_16x16x32_bf16 v[92:95], v[156:159], v[202:205], v[92:95]
	v_mfma_f32_16x16x32_bf16 v[88:91], v[166:169], v[202:205], v[88:91]
	v_mfma_f32_16x16x32_bf16 v[76:79], v[156:159], v[210:213], v[76:79]
	v_mfma_f32_16x16x32_bf16 v[72:75], v[166:169], v[210:213], v[72:75]
	v_mfma_f32_16x16x32_bf16 v[116:119], v[214:217], v[170:173], v[116:119]
	v_mfma_f32_16x16x32_bf16 v[112:115], v[222:225], v[170:173], v[112:115]
	v_mfma_f32_16x16x32_bf16 v[100:103], v[214:217], v[190:193], v[100:103]
	v_mfma_f32_16x16x32_bf16 v[96:99], v[222:225], v[190:193], v[96:99]
	v_mfma_f32_16x16x32_bf16 v[84:87], v[214:217], v[198:201], v[84:87]
	v_mfma_f32_16x16x32_bf16 v[80:83], v[222:225], v[198:201], v[80:83]
	v_mfma_f32_16x16x32_bf16 v[68:71], v[214:217], v[206:209], v[68:71]
	v_mfma_f32_16x16x32_bf16 v[64:67], v[222:225], v[206:209], v[64:67]
	v_mfma_f32_16x16x32_bf16 v[116:119], v[218:221], v[182:185], v[116:119]
	v_mfma_f32_16x16x32_bf16 v[112:115], v[226:229], v[182:185], v[112:115]
	v_mfma_f32_16x16x32_bf16 v[100:103], v[218:221], v[194:197], v[100:103]
	v_mfma_f32_16x16x32_bf16 v[96:99], v[226:229], v[194:197], v[96:99]
	v_mfma_f32_16x16x32_bf16 v[84:87], v[218:221], v[202:205], v[84:87]
	v_mfma_f32_16x16x32_bf16 v[80:83], v[226:229], v[202:205], v[80:83]
	v_mfma_f32_16x16x32_bf16 v[68:71], v[218:221], v[210:213], v[68:71]
	v_mfma_f32_16x16x32_bf16 v[64:67], v[226:229], v[210:213], v[64:67]
	s_barrier
; #define PG8_STAGE(bufoff, gbase, voff) do { _Pragma("unroll") for (int _i = 0; _i < 2; ++_i) \
;         __builtin_amdgcn_global_load_lds((const unsigned*)((const char*)(gbase) + (voff)[_i]), (PG8_LAS unsigned*)(lds + (bufoff) + ldsw + _i * 8192), 16, 0, 0); } while (0)
; #define PG8_LDA(dst, b, h) do { _Pragma("unroll") for (int m = 0; m < 4; ++m) _Pragma("unroll") for (int k = 0; k < 2; ++k) dst[m][k] = *(const PG8_LAS bf16x8*)(lds + PG8_SA(b, h) + aoff + m * 2048 + k * 1024); } while (0)
; #define PG8_LDB(dst, b, h) do { _Pragma("unroll") for (int n = 0; n < 2; ++n) _Pragma("unroll") for (int k = 0; k < 2; ++k) dst[n][k] = *(const PG8_LAS bf16x8*)(lds + PG8_SB(b, h) + boff + n * 2048 + k * 1024); } while (0)
; #define PG8_MMA(ai, bj, At, Bt) do { __builtin_amdgcn_s_setprio(1); _Pragma("unroll") for (int m = 0; m < 4; ++m) _Pragma("unroll") for (int n = 0; n < 2; ++n) _Pragma("unroll") for (int k = 0; k < 2; ++k) \
;         acc[ai][bj][m][n] = __builtin_amdgcn_mfma_f32_16x16x32_bf16(Bt[n][k], At[m][k], acc[ai][bj][m][n], 0, 0, 0); __builtin_amdgcn_s_setprio(0); } while (0)
; #define PG8_WAIT_V(n) asm volatile("s_waitcnt vmcnt(" #n ")" ::: "memory")
; #define PG8_WAIT_L(n) asm volatile("s_waitcnt lgkmcnt(" #n ")" ::: "memory")
; #define PG8_BAR __builtin_amdgcn_s_barrier()
; #define PG8_SCHED __builtin_amdgcn_sched_barrier(0)
; template <class Epi, class Sched>
; __device__ __forceinline__ void gemm_phase(PG8_LAS unsigned char* lds, const Gemm g, const Sched& S, const Epi& E) {
;     ...
;             PG8_LDA(At, 0, 1); PG8_STAGE(PG8_SA(0, 0), a2, voffA);
;             PG8_BAR; PG8_WAIT_L(0); PG8_MMA(1, 0, At, B0); PG8_BAR; PG8_SCHED;
;             PG8_STAGE(PG8_SB(0, 1), b2 + hstep, voffB);
;             PG8_WAIT_V(6); PG8_BAR; PG8_MMA(1, 1, At, B1); PG8_BAR;
;             PG8_LDB(B0, 1, 0); PG8_SCHED; PG8_LDA(At, 1, 0); PG8_STAGE(PG8_SA(0, 1), a2 + hstep, voffA);
;             PG8_WAIT_L(8); PG8_BAR; PG8_WAIT_L(0); PG8_MMA(0, 0, At, B0); PG8_BAR; PG8_SCHED;
;             PG8_LDB(B1, 1, 1); PG8_STAGE(PG8_SB(1, 0), b3, voffB);
;             PG8_BAR; PG8_WAIT_L(0); PG8_MMA(0, 1, At, B1); PG8_BAR;
	ds_read_b128 v[170:173], v153 offset:16384
	ds_read_b128 v[182:185], v153 offset:17408
	ds_read_b128 v[190:193], v153 offset:18432
	ds_read_b128 v[194:197], v153 offset:19456
	ds_read_b128 v[198:201], v153 offset:20480
	ds_read_b128 v[202:205], v153 offset:21504
	ds_read_b128 v[206:209], v153 offset:22528
	ds_read_b128 v[210:213], v153 offset:23552
	s_add_i32 s49, s42, s30
	s_add_u32 s98, s20, s6
	s_addc_u32 s99, s21, s7
	s_mov_b32 m0, s49
	s_nop 0
	global_load_lds_dwordx4 v130, s[20:21]
	s_nop 1
	s_add_i32 m0, s49, 0x2000
	s_nop 0
	global_load_lds_dwordx4 v134, s[20:21]
	s_nop 1
	s_mov_b32 m0, s17
	s_add_u32 s100, s22, s6
	s_addc_u32 s101, s23, s7
	global_load_lds_dwordx4 v128, s[22:23]
	s_nop 1
	s_mov_b32 m0, s31
	s_nop 0
	global_load_lds_dwordx4 v132, s[22:23]
	s_add_u32 s50, s20, 0x40000
	s_addc_u32 s51, s21, 0
	s_add_i32 s49, s43, s30
	s_mov_b32 m0, s49
	s_nop 0
	global_load_lds_dwordx4 v130, s[50:51]
	s_nop 1
	s_add_i32 m0, s49, 0x2000
	s_nop 0
	global_load_lds_dwordx4 v134, s[50:51]
	s_waitcnt vmcnt(8) lgkmcnt(0)
	s_barrier
	v_mfma_f32_16x16x32_bf16 v[60:63], v[144:147], v[170:173], v[60:63]
	v_mfma_f32_16x16x32_bf16 v[56:59], v[160:163], v[170:173], v[56:59]
	v_mfma_f32_16x16x32_bf16 v[44:47], v[144:147], v[190:193], v[44:47]
	v_mfma_f32_16x16x32_bf16 v[40:43], v[160:163], v[190:193], v[40:43]
	v_mfma_f32_16x16x32_bf16 v[28:31], v[144:147], v[198:201], v[28:31]
	v_mfma_f32_16x16x32_bf16 v[24:27], v[160:163], v[198:201], v[24:27]
	v_mfma_f32_16x16x32_bf16 v[12:15], v[144:147], v[206:209], v[12:15]
	v_mfma_f32_16x16x32_bf16 v[8:11], v[160:163], v[206:209], v[8:11]
	v_mfma_f32_16x16x32_bf16 v[60:63], v[156:159], v[182:185], v[60:63]
	v_mfma_f32_16x16x32_bf16 v[56:59], v[166:169], v[182:185], v[56:59]
	v_mfma_f32_16x16x32_bf16 v[44:47], v[156:159], v[194:197], v[44:47]
	v_mfma_f32_16x16x32_bf16 v[40:43], v[166:169], v[194:197], v[40:43]
	v_mfma_f32_16x16x32_bf16 v[28:31], v[156:159], v[202:205], v[28:31]
	v_mfma_f32_16x16x32_bf16 v[24:27], v[166:169], v[202:205], v[24:27]
	v_mfma_f32_16x16x32_bf16 v[12:15], v[156:159], v[210:213], v[12:15]
	v_mfma_f32_16x16x32_bf16 v[8:11], v[166:169], v[210:213], v[8:11]
	v_mfma_f32_16x16x32_bf16 v[52:55], v[214:217], v[170:173], v[52:55]
	v_mfma_f32_16x16x32_bf16 v[48:51], v[222:225], v[170:173], v[48:51]
	v_mfma_f32_16x16x32_bf16 v[36:39], v[214:217], v[190:193], v[36:39]
	v_mfma_f32_16x16x32_bf16 v[32:35], v[222:225], v[190:193], v[32:35]
	v_mfma_f32_16x16x32_bf16 v[20:23], v[214:217], v[198:201], v[20:23]
	v_mfma_f32_16x16x32_bf16 v[16:19], v[222:225], v[198:201], v[16:19]
	v_mfma_f32_16x16x32_bf16 v[4:7], v[214:217], v[206:209], v[4:7]
	v_mfma_f32_16x16x32_bf16 v[0:3], v[222:225], v[206:209], v[0:3]
	v_mfma_f32_16x16x32_bf16 v[52:55], v[218:221], v[182:185], v[52:55]
	v_mfma_f32_16x16x32_bf16 v[48:51], v[226:229], v[182:185], v[48:51]
	v_mfma_f32_16x16x32_bf16 v[36:39], v[218:221], v[194:197], v[36:39]
	v_mfma_f32_16x16x32_bf16 v[32:35], v[226:229], v[194:197], v[32:35]
	v_mfma_f32_16x16x32_bf16 v[20:23], v[218:221], v[202:205], v[20:23]
	v_mfma_f32_16x16x32_bf16 v[16:19], v[226:229], v[202:205], v[16:19]
	v_mfma_f32_16x16x32_bf16 v[4:7], v[218:221], v[210:213], v[4:7]
	v_mfma_f32_16x16x32_bf16 v[0:3], v[226:229], v[210:213], v[0:3]
	s_barrier
	s_add_i32 s49, 0, 0x18000
	v_add_u32_e32 v155, s49, v149
	ds_read_b128 v[144:147], v155
	ds_read_b128 v[156:159], v155 offset:1024
	ds_read_b128 v[160:163], v155 offset:2048
	ds_read_b128 v[166:169], v155 offset:3072
	s_add_u32 s22, s22, 0x40000
	s_addc_u32 s23, s23, 0
	s_mov_b32 m0, s34
	ds_read_b128 v[170:173], v153 offset:32768
	ds_read_b128 v[182:185], v153 offset:33792
	ds_read_b128 v[190:193], v153 offset:34816
	ds_read_b128 v[194:197], v153 offset:35840
	ds_read_b128 v[198:201], v153 offset:36864
	ds_read_b128 v[202:205], v153 offset:37888
	ds_read_b128 v[206:209], v153 offset:38912
	ds_read_b128 v[210:213], v153 offset:39936
	global_load_lds_dwordx4 v128, s[22:23]
	s_nop 1
	s_mov_b32 m0, s35
	s_nop 0
	global_load_lds_dwordx4 v132, s[22:23]
	s_add_i32 s22, 0, 0x1c000
	v_add_u32_e32 v155, s22, v149
	s_waitcnt lgkmcnt(8)
	ds_read_b128 v[214:217], v155
	ds_read_b128 v[218:221], v155 offset:1024
	ds_read_b128 v[222:225], v155 offset:2048
	ds_read_b128 v[226:229], v155 offset:3072
	s_waitcnt vmcnt(8) lgkmcnt(0)
	s_barrier
	v_mfma_f32_16x16x32_bf16 v[124:127], v[144:147], v[170:173], v[124:127]
	v_mfma_f32_16x16x32_bf16 v[120:123], v[160:163], v[170:173], v[120:123]
	v_mfma_f32_16x16x32_bf16 v[108:111], v[144:147], v[190:193], v[108:111]
	v_mfma_f32_16x16x32_bf16 v[104:107], v[160:163], v[190:193], v[104:107]
	v_mfma_f32_16x16x32_bf16 v[92:95], v[144:147], v[198:201], v[92:95]
	v_mfma_f32_16x16x32_bf16 v[88:91], v[160:163], v[198:201], v[88:91]
	v_mfma_f32_16x16x32_bf16 v[76:79], v[144:147], v[206:209], v[76:79]
	v_mfma_f32_16x16x32_bf16 v[72:75], v[160:163], v[206:209], v[72:75]
	v_mfma_f32_16x16x32_bf16 v[124:127], v[156:159], v[182:185], v[124:127]
	v_mfma_f32_16x16x32_bf16 v[120:123], v[166:169], v[182:185], v[120:123]
	v_mfma_f32_16x16x32_bf16 v[108:111], v[156:159], v[194:197], v[108:111]
	v_mfma_f32_16x16x32_bf16 v[104:107], v[166:169], v[194:197], v[104:107]
	v_mfma_f32_16x16x32_bf16 v[92:95], v[156:159], v[202:205], v[92:95]
	v_mfma_f32_16x16x32_bf16 v[88:91], v[166:169], v[202:205], v[88:91]
	v_mfma_f32_16x16x32_bf16 v[76:79], v[156:159], v[210:213], v[76:79]
	v_mfma_f32_16x16x32_bf16 v[72:75], v[166:169], v[210:213], v[72:75]
	v_mfma_f32_16x16x32_bf16 v[116:119], v[214:217], v[170:173], v[116:119]
	v_mfma_f32_16x16x32_bf16 v[112:115], v[222:225], v[170:173], v[112:115]
	v_mfma_f32_16x16x32_bf16 v[100:103], v[214:217], v[190:193], v[100:103]
	v_mfma_f32_16x16x32_bf16 v[96:99], v[222:225], v[190:193], v[96:99]
	v_mfma_f32_16x16x32_bf16 v[84:87], v[214:217], v[198:201], v[84:87]
	v_mfma_f32_16x16x32_bf16 v[80:83], v[222:225], v[198:201], v[80:83]
	v_mfma_f32_16x16x32_bf16 v[68:71], v[214:217], v[206:209], v[68:71]
	v_mfma_f32_16x16x32_bf16 v[64:67], v[222:225], v[206:209], v[64:67]
	v_mfma_f32_16x16x32_bf16 v[116:119], v[218:221], v[182:185], v[116:119]
	v_mfma_f32_16x16x32_bf16 v[112:115], v[226:229], v[182:185], v[112:115]
	v_mfma_f32_16x16x32_bf16 v[100:103], v[218:221], v[194:197], v[100:103]
	v_mfma_f32_16x16x32_bf16 v[96:99], v[226:229], v[194:197], v[96:99]
	v_mfma_f32_16x16x32_bf16 v[84:87], v[218:221], v[202:205], v[84:87]
	v_mfma_f32_16x16x32_bf16 v[80:83], v[226:229], v[202:205], v[80:83]
	v_mfma_f32_16x16x32_bf16 v[68:71], v[218:221], v[210:213], v[68:71]
	v_mfma_f32_16x16x32_bf16 v[64:67], v[226:229], v[210:213], v[64:67]
	s_barrier
; #define PG8_STAGE(bufoff, gbase, voff) do { _Pragma("unroll") for (int _i = 0; _i < 2; ++_i) \
;         __builtin_amdgcn_global_load_lds((const unsigned*)((const char*)(gbase) + (voff)[_i]), (PG8_LAS unsigned*)(lds + (bufoff) + ldsw + _i * 8192), 16, 0, 0); } while (0)
; #define PG8_LDA(dst, b, h) do { _Pragma("unroll") for (int m = 0; m < 4; ++m) _Pragma("unroll") for (int k = 0; k < 2; ++k) dst[m][k] = *(const PG8_LAS bf16x8*)(lds + PG8_SA(b, h) + aoff + m * 2048 + k * 1024); } while (0)
; #define PG8_MMA(ai, bj, At, Bt) do { __builtin_amdgcn_s_setprio(1); _Pragma("unroll") for (int m = 0; m < 4; ++m) _Pragma("unroll") for (int n = 0; n < 2; ++n) _Pragma("unroll") for (int k = 0; k < 2; ++k) \
;         acc[ai][bj][m][n] = __builtin_amdgcn_mfma_f32_16x16x32_bf16(Bt[n][k], At[m][k], acc[ai][bj][m][n], 0, 0, 0); __builtin_amdgcn_s_setprio(0); } while (0)
; #define PG8_WAIT_V(n) asm volatile("s_waitcnt vmcnt(" #n ")" ::: "memory")
; #define PG8_WAIT_L(n) asm volatile("s_waitcnt lgkmcnt(" #n ")" ::: "memory")
; #define PG8_BAR __builtin_amdgcn_s_barrier()
; #define PG8_SCHED __builtin_amdgcn_sched_barrier(0)
; __device__ __forceinline__ f32x4 sigmoid4(f32x4 x) {
;     f32x4 d;
; #pragma unroll
;     for (int j = 0; j < 4; ++j) d[j] = 1.0f + __expf(-fmaxf(x[j], -20.0f));
;     const float p01 = d[0] * d[1], p23 = d[2] * d[3], r = __builtin_amdgcn_rcpf(p01 * p23), r01 = r * p23, r23 = r * p01;
;     return (f32x4){r01 * d[1], r01 * d[0], r23 * d[3], r23 * d[2]};
; }
; template <class Epi, class Sched>
; __device__ __forceinline__ void gemm_phase(PG8_LAS unsigned char* lds, const Gemm g, const Sched& S, const Epi& E) {
;     ...
;             PG8_BAR; PG8_WAIT_L(0); PG8_MMA(0, 1, At, B1); PG8_BAR;
;             PG8_LDA(At, 1, 1); PG8_STAGE(PG8_SA(1, 0), a3, voffA);
;             PG8_BAR; PG8_WAIT_L(0); PG8_MMA(1, 0, At, B0); PG8_BAR; PG8_SCHED;
;             PG8_STAGE(PG8_SB(1, 1), b3 + hstep, voffB);
;             PG8_WAIT_V(6); PG8_BAR; PG8_MMA(1, 1, At, B1); PG8_BAR;
	ds_read_b128 v[170:173], v153 offset:49152
	ds_read_b128 v[182:185], v153 offset:50176
	ds_read_b128 v[190:193], v153 offset:51200
	ds_read_b128 v[194:197], v153 offset:52224
	ds_read_b128 v[198:201], v153 offset:53248
	ds_read_b128 v[202:205], v153 offset:54272
	ds_read_b128 v[206:209], v153 offset:55296
	ds_read_b128 v[210:213], v153 offset:56320
	s_add_i32 s23, s49, s30
	s_mov_b32 m0, s23
	s_nop 0
	global_load_lds_dwordx4 v130, s[98:99]
	s_nop 1
	s_add_i32 m0, s23, 0x2000
	s_nop 0
	global_load_lds_dwordx4 v134, s[98:99]
	s_nop 1
	s_mov_b32 m0, s37
	s_nop 0
	global_load_lds_dwordx4 v128, s[100:101]
	s_nop 1
	s_mov_b32 m0, s38
	s_nop 0
	global_load_lds_dwordx4 v132, s[100:101]
	s_add_u32 s20, s20, 0x40080
	s_addc_u32 s21, s21, 0
	s_add_i32 s22, s22, s30
	s_mov_b32 m0, s22
	s_nop 0
	global_load_lds_dwordx4 v130, s[20:21]
	s_nop 1
	s_add_i32 m0, s22, 0x2000
	s_nop 0
	global_load_lds_dwordx4 v134, s[20:21]
	s_waitcnt vmcnt(8) lgkmcnt(0)
	s_barrier
	v_mfma_f32_16x16x32_bf16 v[60:63], v[144:147], v[170:173], v[60:63]
	v_mfma_f32_16x16x32_bf16 v[56:59], v[160:163], v[170:173], v[56:59]
	v_mfma_f32_16x16x32_bf16 v[44:47], v[144:147], v[190:193], v[44:47]
	v_mfma_f32_16x16x32_bf16 v[40:43], v[160:163], v[190:193], v[40:43]
	v_mfma_f32_16x16x32_bf16 v[28:31], v[144:147], v[198:201], v[28:31]
	v_mfma_f32_16x16x32_bf16 v[24:27], v[160:163], v[198:201], v[24:27]
	v_mfma_f32_16x16x32_bf16 v[12:15], v[144:147], v[206:209], v[12:15]
	v_mfma_f32_16x16x32_bf16 v[8:11], v[160:163], v[206:209], v[8:11]
	v_mfma_f32_16x16x32_bf16 v[60:63], v[156:159], v[182:185], v[60:63]
	v_mfma_f32_16x16x32_bf16 v[56:59], v[166:169], v[182:185], v[56:59]
	v_mfma_f32_16x16x32_bf16 v[44:47], v[156:159], v[194:197], v[44:47]
	v_mfma_f32_16x16x32_bf16 v[40:43], v[166:169], v[194:197], v[40:43]
	v_mfma_f32_16x16x32_bf16 v[28:31], v[156:159], v[202:205], v[28:31]
	v_mfma_f32_16x16x32_bf16 v[24:27], v[166:169], v[202:205], v[24:27]
	v_mfma_f32_16x16x32_bf16 v[12:15], v[156:159], v[210:213], v[12:15]
	v_mfma_f32_16x16x32_bf16 v[8:11], v[166:169], v[210:213], v[8:11]
	v_mfma_f32_16x16x32_bf16 v[52:55], v[214:217], v[170:173], v[52:55]
	v_mfma_f32_16x16x32_bf16 v[48:51], v[222:225], v[170:173], v[48:51]
	v_mfma_f32_16x16x32_bf16 v[36:39], v[214:217], v[190:193], v[36:39]
	v_mfma_f32_16x16x32_bf16 v[32:35], v[222:225], v[190:193], v[32:35]
	v_mfma_f32_16x16x32_bf16 v[20:23], v[214:217], v[198:201], v[20:23]
	v_mfma_f32_16x16x32_bf16 v[16:19], v[222:225], v[198:201], v[16:19]
	v_mfma_f32_16x16x32_bf16 v[4:7], v[214:217], v[206:209], v[4:7]
	v_mfma_f32_16x16x32_bf16 v[0:3], v[222:225], v[206:209], v[0:3]
	v_mfma_f32_16x16x32_bf16 v[52:55], v[218:221], v[182:185], v[52:55]
	v_mfma_f32_16x16x32_bf16 v[48:51], v[226:229], v[182:185], v[48:51]
	v_mfma_f32_16x16x32_bf16 v[36:39], v[218:221], v[194:197], v[36:39]
	v_mfma_f32_16x16x32_bf16 v[32:35], v[226:229], v[194:197], v[32:35]
	v_mfma_f32_16x16x32_bf16 v[20:23], v[218:221], v[202:205], v[20:23]
	v_mfma_f32_16x16x32_bf16 v[16:19], v[226:229], v[202:205], v[16:19]
	v_mfma_f32_16x16x32_bf16 v[4:7], v[218:221], v[210:213], v[4:7]
	v_mfma_f32_16x16x32_bf16 v[0:3], v[226:229], v[210:213], v[0:3]
	s_barrier
	s_add_i32 s48, s48, 2
	s_add_u32 s18, s18, 0x100
	s_addc_u32 s19, s19, 0
	s_add_u32 s46, s46, 0x100
	s_addc_u32 s47, s47, 0
	s_cmp_gt_u32 s48, 13
	s_cbranch_scc0 .LBB0_724
	s_cmp_gt_i32 s4, 5
	s_cselect_b64 s[18:19], -1, 0
	s_cmp_lt_i32 s4, 6
	v_pk_add_f32 v[144:145], v[126:127], 0 op_sel_hi:[1,0]
	v_pk_add_f32 v[146:147], v[124:125], 0 op_sel_hi:[1,0]
	v_pk_add_f32 v[124:125], v[122:123], 0 op_sel_hi:[1,0]
	v_pk_add_f32 v[126:127], v[120:121], 0 op_sel_hi:[1,0]
	s_cbranch_scc1 .LBB0_727
	v_max_f32_e32 v122, 0xc1a00000, v144
	v_mul_f32_e32 v122, 0xbfb8aa3b, v122
	v_exp_f32_e32 v123, v122
	v_max_f32_e32 v120, 0xc1a00000, v146
	v_max_f32_e32 v121, 0xc1a00000, v147
	v_max_f32_e32 v122, 0xc1a00000, v145
	v_mul_f32_e32 v120, 0xbfb8aa3b, v120
	v_mul_f32_e32 v121, 0xbfb8aa3b, v121
	v_mul_f32_e32 v122, 0xbfb8aa3b, v122
	v_exp_f32_e32 v120, v120
	v_exp_f32_e32 v121, v121
	v_exp_f32_e32 v122, v122
	v_max_f32_e32 v124, 0xc1a00000, v124
	v_pk_add_f32 v[120:121], v[120:121], 1.0 op_sel_hi:[1,0]
	v_pk_add_f32 v[122:123], v[122:123], 1.0 op_sel_hi:[1,0]
	v_mov_b32_e32 v144, v120
	v_mov_b32_e32 v145, v123
	v_pk_mov_b32 v[146:147], v[120:121], v[122:123] op_sel:[1,0]
	v_mul_f32_e32 v124, 0xbfb8aa3b, v124
	v_pk_mul_f32 v[144:145], v[144:145], v[146:147]
	v_exp_f32_e32 v147, v124
	v_max_f32_e32 v126, 0xc1a00000, v126
	v_max_f32_e32 v127, 0xc1a00000, v127
	v_max_f32_e32 v124, 0xc1a00000, v125
	v_mul_f32_e32 v146, v144, v145
	v_mul_f32_e32 v126, 0xbfb8aa3b, v126
	v_mul_f32_e32 v127, 0xbfb8aa3b, v127
	v_mul_f32_e32 v124, 0xbfb8aa3b, v124
	v_rcp_f32_e32 v155, v146
	v_exp_f32_e32 v126, v126
	v_exp_f32_e32 v127, v127
	v_exp_f32_e32 v146, v124
	v_mul_f32_e32 v124, v145, v155
	v_mul_f32_e32 v144, v144, v155
	v_pk_add_f32 v[126:127], v[126:127], 1.0 op_sel_hi:[1,0]
	v_pk_add_f32 v[156:157], v[146:147], 1.0 op_sel_hi:[1,0]
	v_mov_b32_e32 v146, v126
	v_mov_b32_e32 v147, v157
	v_pk_mov_b32 v[158:159], v[126:127], v[156:157] op_sel:[1,0]
	v_pk_mul_f32 v[144:145], v[122:123], v[144:145] op_sel_hi:[1,0]
	v_pk_mul_f32 v[158:159], v[146:147], v[158:159]
	s_nop 0
	v_mul_f32_e32 v125, v158, v159
	v_rcp_f32_e32 v125, v125
	s_nop 0
	v_pk_mul_f32 v[146:147], v[120:121], v[124:125] op_sel:[1,0] op_sel_hi:[0,0]
	v_mul_f32_e32 v120, v159, v125
	v_mul_f32_e32 v122, v158, v125
	v_pk_mul_f32 v[124:125], v[156:157], v[122:123] op_sel_hi:[1,0]
	v_pk_mul_f32 v[126:127], v[126:127], v[120:121] op_sel:[1,0] op_sel_hi:[0,0]

; #define PG8_STAGE(bufoff, gbase, voff) do { _Pragma("unroll") for (int _i = 0; _i < 2; ++_i) \
;         __builtin_amdgcn_global_load_lds((const unsigned*)((const char*)(gbase) + (voff)[_i]), (PG8_LAS unsigned*)(lds + (bufoff) + ldsw + _i * 8192), 16, 0, 0); } while (0)
; #define PG8_LDA(dst, b, h) do { _Pragma("unroll") for (int m = 0; m < 4; ++m) _Pragma("unroll") for (int k = 0; k < 2; ++k) dst[m][k] = *(const PG8_LAS bf16x8*)(lds + PG8_SA(b, h) + aoff + m * 2048 + k * 1024); } while (0)
; #define PG8_LDB(dst, b, h) do { _Pragma("unroll") for (int n = 0; n < 2; ++n) _Pragma("unroll") for (int k = 0; k < 2; ++k) dst[n][k] = *(const PG8_LAS bf16x8*)(lds + PG8_SB(b, h) + boff + n * 2048 + k * 1024); } while (0)
; #define PG8_MMA(ai, bj, At, Bt) do { __builtin_amdgcn_s_setprio(1); _Pragma("unroll") for (int m = 0; m < 4; ++m) _Pragma("unroll") for (int n = 0; n < 2; ++n) _Pragma("unroll") for (int k = 0; k < 2; ++k) \
;         acc[ai][bj][m][n] = __builtin_amdgcn_mfma_f32_16x16x32_bf16(Bt[n][k], At[m][k], acc[ai][bj][m][n], 0, 0, 0); __builtin_amdgcn_s_setprio(0); } while (0)
; template <class Epi, class Sched>
; __device__ __forceinline__ void gemm_phase(PG8_LAS unsigned char* lds, const Gemm g, const Sched& S, const Epi& E) {
;     ...
;         const bool has_next = S.next(ui + 1, nxt);
;         const char* nA = has_next ? (const char*)g.A + (size_t)nxt.pm * tstep : cA; const char* nB = has_next ? (const char*)g.Bt + (size_t)nxt.pn * tstep : cB;
;         for (int t = 0; t < nt; t += 2) {
;             const bool last = (t == nt - 2);
;             const char* a1 = cA + (size_t)(t + 1) * kstep;
;             const char* a2 = last ? nA : cA + (size_t)(t + 2) * kstep; const char* b2 = last ? nB : cB + (size_t)(t + 2) * kstep;
;             const char* a3 = a2 + kstep; const char* b3 = b2 + kstep;
;             if (last && has_next) S.a_ready(nxt);
;             PG8_LDB(B0, 0, 0); PG8_SCHED; PG8_LDA(At, 0, 0); PG8_STAGE(PG8_SA(1, 1), a1 + hstep, voffA);
;             PG8_WAIT_L(8); PG8_BAR; PG8_WAIT_L(0); PG8_MMA(0, 0, At, B0); PG8_BAR; PG8_SCHED;
;             PG8_LDB(B1, 0, 1); PG8_STAGE(PG8_SB(0, 0), b2, voffB);
;             PG8_BAR; PG8_WAIT_L(0); PG8_MMA(0, 1, At, B1); PG8_BAR;
;             PG8_LDA(At, 0, 1); PG8_STAGE(PG8_SA(0, 0), a2, voffA);
;             PG8_BAR; PG8_WAIT_L(0); PG8_MMA(1, 0, At, B0); PG8_BAR; PG8_SCHED;
.LBB0_990:
	s_ashr_i32 s11, s10, 31
	v_cmp_lt_i64_e32 vcc, s[12:13], v[140:141]
	s_lshl_b64 s[12:13], s[10:11], 19
	s_add_u32 s12, s27, s12
	s_addc_u32 s13, s28, s13
	s_and_b64 s[14:15], vcc, exec
	s_cselect_b32 s11, s13, s19
	s_cselect_b32 s43, s12, s18
	s_ashr_i32 s9, s8, 31
	s_lshl_b64 s[14:15], s[8:9], 19
	s_add_u32 s14, s96, s14
	s_addc_u32 s15, s97, s15
	s_and_b64 s[22:23], vcc, exec
	s_cselect_b32 s9, s15, s21
	s_cselect_b32 s44, s14, s20
	s_add_u32 s18, s18, 0x40080
	s_addc_u32 s19, s19, 0
	s_add_u32 s45, s20, 0x100
	s_addc_u32 s46, s21, 0
	s_mov_b32 s47, -2
	ds_read_b128 v[144:147], v153
	ds_read_b128 v[156:159], v153 offset:1024
	ds_read_b128 v[160:163], v153 offset:2048
	ds_read_b128 v[164:167], v153 offset:3072
	s_add_u32 s20, s18, 0xfffc0080
	s_addc_u32 s21, s19, -1
	s_cmp_eq_u32 s47, 12
	s_cselect_b32 s23, s11, s21
	s_cselect_b32 s22, s43, s20
	s_cselect_b32 s21, s9, s46
	s_cselect_b32 s20, s44, s45
	s_add_i32 m0, s17, 0xc000
	ds_read_b128 v[168:171], v154
	ds_read_b128 v[172:175], v154 offset:1024
	ds_read_b128 v[182:185], v154 offset:2048
	ds_read_b128 v[190:193], v154 offset:3072
	ds_read_b128 v[194:197], v154 offset:4096
	ds_read_b128 v[198:201], v154 offset:5120
	ds_read_b128 v[202:205], v154 offset:6144
	ds_read_b128 v[206:209], v154 offset:7168
	global_load_lds_dwordx4 v136, s[18:19]
	s_nop 1
	s_add_i32 m0, s17, 0xe000
	s_nop 0
	global_load_lds_dwordx4 v138, s[18:19]
	s_waitcnt lgkmcnt(8)
	ds_read_b128 v[210:213], v155
	ds_read_b128 v[214:217], v155 offset:1024
	ds_read_b128 v[218:221], v155 offset:2048
	ds_read_b128 v[222:225], v155 offset:3072
	s_waitcnt vmcnt(8) lgkmcnt(0)
	s_barrier
	v_mfma_f32_16x16x32_bf16 v[124:127], v[144:147], v[168:171], 0
	v_mfma_f32_16x16x32_bf16 v[120:123], v[160:163], v[168:171], 0
	v_mfma_f32_16x16x32_bf16 v[112:115], v[144:147], v[182:185], 0
	v_mfma_f32_16x16x32_bf16 v[104:107], v[160:163], v[182:185], 0
	v_mfma_f32_16x16x32_bf16 v[96:99], v[144:147], v[194:197], 0
	v_mfma_f32_16x16x32_bf16 v[88:91], v[160:163], v[194:197], 0
	v_mfma_f32_16x16x32_bf16 v[80:83], v[144:147], v[202:205], 0
	v_mfma_f32_16x16x32_bf16 v[72:75], v[160:163], v[202:205], 0
	v_mfma_f32_16x16x32_bf16 v[124:127], v[156:159], v[172:175], v[124:127]
	v_mfma_f32_16x16x32_bf16 v[120:123], v[164:167], v[172:175], v[120:123]
	v_mfma_f32_16x16x32_bf16 v[112:115], v[156:159], v[190:193], v[112:115]
	v_mfma_f32_16x16x32_bf16 v[104:107], v[164:167], v[190:193], v[104:107]
	v_mfma_f32_16x16x32_bf16 v[96:99], v[156:159], v[198:201], v[96:99]
	v_mfma_f32_16x16x32_bf16 v[88:91], v[164:167], v[198:201], v[88:91]
	v_mfma_f32_16x16x32_bf16 v[80:83], v[156:159], v[206:209], v[80:83]
	v_mfma_f32_16x16x32_bf16 v[72:75], v[164:167], v[206:209], v[72:75]
	v_mfma_f32_16x16x32_bf16 v[116:119], v[210:213], v[168:171], 0
	v_mfma_f32_16x16x32_bf16 v[108:111], v[218:221], v[168:171], 0
	v_mfma_f32_16x16x32_bf16 v[100:103], v[210:213], v[182:185], 0
	v_mfma_f32_16x16x32_bf16 v[92:95], v[218:221], v[182:185], 0
	v_mfma_f32_16x16x32_bf16 v[84:87], v[210:213], v[194:197], 0
	v_mfma_f32_16x16x32_bf16 v[76:79], v[218:221], v[194:197], 0
	v_mfma_f32_16x16x32_bf16 v[68:71], v[210:213], v[202:205], 0
	v_mfma_f32_16x16x32_bf16 v[64:67], v[218:221], v[202:205], 0
	v_mfma_f32_16x16x32_bf16 v[116:119], v[214:217], v[172:175], v[116:119]
	v_mfma_f32_16x16x32_bf16 v[108:111], v[222:225], v[172:175], v[108:111]
	v_mfma_f32_16x16x32_bf16 v[100:103], v[214:217], v[190:193], v[100:103]
	v_mfma_f32_16x16x32_bf16 v[92:95], v[222:225], v[190:193], v[92:95]
	v_mfma_f32_16x16x32_bf16 v[84:87], v[214:217], v[198:201], v[84:87]
	v_mfma_f32_16x16x32_bf16 v[76:79], v[222:225], v[198:201], v[76:79]
	v_mfma_f32_16x16x32_bf16 v[68:71], v[214:217], v[206:209], v[68:71]
	v_mfma_f32_16x16x32_bf16 v[64:67], v[222:225], v[206:209], v[64:67]
	s_barrier
	ds_read_b128 v[168:171], v154 offset:16384
	ds_read_b128 v[172:175], v154 offset:17408
	ds_read_b128 v[182:185], v154 offset:18432
	ds_read_b128 v[190:193], v154 offset:19456
	ds_read_b128 v[194:197], v154 offset:20480
	ds_read_b128 v[198:201], v154 offset:21504
	ds_read_b128 v[202:205], v154 offset:22528
	ds_read_b128 v[206:209], v154 offset:23552
	s_add_i32 s48, s39, s29
	s_add_u32 s98, s20, s6
	s_addc_u32 s99, s21, s7
	s_mov_b32 m0, s48
	s_nop 0
	global_load_lds_dwordx4 v130, s[20:21]
	s_nop 1
	s_add_i32 m0, s48, 0x2000
	s_nop 0
	global_load_lds_dwordx4 v134, s[20:21]
	s_nop 1
	s_mov_b32 m0, s17
	s_add_u32 s100, s22, s6
	s_addc_u32 s101, s23, s7
	global_load_lds_dwordx4 v128, s[22:23]
	s_nop 1
	s_mov_b32 m0, s30
	s_nop 0
	global_load_lds_dwordx4 v132, s[22:23]
	s_add_u32 s48, s20, 0x40000
	s_addc_u32 s49, s21, 0
	s_add_i32 s50, s40, s29
	s_mov_b32 m0, s50
	s_nop 0
	global_load_lds_dwordx4 v130, s[48:49]
	s_nop 1
	s_add_i32 m0, s50, 0x2000
	s_nop 0
	global_load_lds_dwordx4 v134, s[48:49]
	s_waitcnt vmcnt(8) lgkmcnt(0)
	s_barrier
; #define PG8_STAGE(bufoff, gbase, voff) do { _Pragma("unroll") for (int _i = 0; _i < 2; ++_i) \
;         __builtin_amdgcn_global_load_lds((const unsigned*)((const char*)(gbase) + (voff)[_i]), (PG8_LAS unsigned*)(lds + (bufoff) + ldsw + _i * 8192), 16, 0, 0); } while (0)
; #define PG8_LDA(dst, b, h) do { _Pragma("unroll") for (int m = 0; m < 4; ++m) _Pragma("unroll") for (int k = 0; k < 2; ++k) dst[m][k] = *(const PG8_LAS bf16x8*)(lds + PG8_SA(b, h) + aoff + m * 2048 + k * 1024); } while (0)
; #define PG8_LDB(dst, b, h) do { _Pragma("unroll") for (int n = 0; n < 2; ++n) _Pragma("unroll") for (int k = 0; k < 2; ++k) dst[n][k] = *(const PG8_LAS bf16x8*)(lds + PG8_SB(b, h) + boff + n * 2048 + k * 1024); } while (0)
; #define PG8_MMA(ai, bj, At, Bt) do { __builtin_amdgcn_s_setprio(1); _Pragma("unroll") for (int m = 0; m < 4; ++m) _Pragma("unroll") for (int n = 0; n < 2; ++n) _Pragma("unroll") for (int k = 0; k < 2; ++k) \
;         acc[ai][bj][m][n] = __builtin_amdgcn_mfma_f32_16x16x32_bf16(Bt[n][k], At[m][k], acc[ai][bj][m][n], 0, 0, 0); __builtin_amdgcn_s_setprio(0); } while (0)
; #define PG8_WAIT_V(n) asm volatile("s_waitcnt vmcnt(" #n ")" ::: "memory")
; #define PG8_WAIT_L(n) asm volatile("s_waitcnt lgkmcnt(" #n ")" ::: "memory")
; #define PG8_BAR __builtin_amdgcn_s_barrier()
; #define PG8_SCHED __builtin_amdgcn_sched_barrier(0)
; template <class Epi, class Sched>
; __device__ __forceinline__ void gemm_phase(PG8_LAS unsigned char* lds, const Gemm g, const Sched& S, const Epi& E) {
;     ...
;             PG8_BAR; PG8_WAIT_L(0); PG8_MMA(1, 0, At, B0); PG8_BAR; PG8_SCHED;
;             PG8_STAGE(PG8_SB(0, 1), b2 + hstep, voffB);
;             PG8_WAIT_V(6); PG8_BAR; PG8_MMA(1, 1, At, B1); PG8_BAR;
;             PG8_LDB(B0, 1, 0); PG8_SCHED; PG8_LDA(At, 1, 0); PG8_STAGE(PG8_SA(0, 1), a2 + hstep, voffA);
;             PG8_WAIT_L(8); PG8_BAR; PG8_WAIT_L(0); PG8_MMA(0, 0, At, B0); PG8_BAR; PG8_SCHED;
;             PG8_LDB(B1, 1, 1); PG8_STAGE(PG8_SB(1, 0), b3, voffB);
;             PG8_BAR; PG8_WAIT_L(0); PG8_MMA(0, 1, At, B1); PG8_BAR;
	v_mfma_f32_16x16x32_bf16 v[60:63], v[144:147], v[168:171], 0
	v_mfma_f32_16x16x32_bf16 v[56:59], v[160:163], v[168:171], 0
	v_mfma_f32_16x16x32_bf16 v[48:51], v[144:147], v[182:185], 0
	v_mfma_f32_16x16x32_bf16 v[40:43], v[160:163], v[182:185], 0
	v_mfma_f32_16x16x32_bf16 v[32:35], v[144:147], v[194:197], 0
	v_mfma_f32_16x16x32_bf16 v[24:27], v[160:163], v[194:197], 0
	v_mfma_f32_16x16x32_bf16 v[16:19], v[144:147], v[202:205], 0
	v_mfma_f32_16x16x32_bf16 v[8:11], v[160:163], v[202:205], 0
	v_mfma_f32_16x16x32_bf16 v[60:63], v[156:159], v[172:175], v[60:63]
	v_mfma_f32_16x16x32_bf16 v[56:59], v[164:167], v[172:175], v[56:59]
	v_mfma_f32_16x16x32_bf16 v[48:51], v[156:159], v[190:193], v[48:51]
	v_mfma_f32_16x16x32_bf16 v[40:43], v[164:167], v[190:193], v[40:43]
	v_mfma_f32_16x16x32_bf16 v[32:35], v[156:159], v[198:201], v[32:35]
	v_mfma_f32_16x16x32_bf16 v[24:27], v[164:167], v[198:201], v[24:27]
	v_mfma_f32_16x16x32_bf16 v[16:19], v[156:159], v[206:209], v[16:19]
	v_mfma_f32_16x16x32_bf16 v[8:11], v[164:167], v[206:209], v[8:11]
	v_mfma_f32_16x16x32_bf16 v[52:55], v[210:213], v[168:171], 0
	v_mfma_f32_16x16x32_bf16 v[44:47], v[218:221], v[168:171], 0
	v_mfma_f32_16x16x32_bf16 v[36:39], v[210:213], v[182:185], 0
	v_mfma_f32_16x16x32_bf16 v[28:31], v[218:221], v[182:185], 0
	v_mfma_f32_16x16x32_bf16 v[20:23], v[210:213], v[194:197], 0
	v_mfma_f32_16x16x32_bf16 v[12:15], v[218:221], v[194:197], 0
	v_mfma_f32_16x16x32_bf16 v[4:7], v[210:213], v[202:205], 0
	v_mfma_f32_16x16x32_bf16 v[0:3], v[218:221], v[202:205], 0
	v_mfma_f32_16x16x32_bf16 v[52:55], v[214:217], v[172:175], v[52:55]
	v_mfma_f32_16x16x32_bf16 v[44:47], v[222:225], v[172:175], v[44:47]
	v_mfma_f32_16x16x32_bf16 v[36:39], v[214:217], v[190:193], v[36:39]
	v_mfma_f32_16x16x32_bf16 v[28:31], v[222:225], v[190:193], v[28:31]
	v_mfma_f32_16x16x32_bf16 v[20:23], v[214:217], v[198:201], v[20:23]
	v_mfma_f32_16x16x32_bf16 v[12:15], v[222:225], v[198:201], v[12:15]
	v_mfma_f32_16x16x32_bf16 v[4:7], v[214:217], v[206:209], v[4:7]
	v_mfma_f32_16x16x32_bf16 v[0:3], v[222:225], v[206:209], v[0:3]
	s_barrier
	s_add_i32 s48, 0, 0x18000
	v_add_u32_e32 v164, s48, v151
	ds_read_b128 v[144:147], v164
	ds_read_b128 v[156:159], v164 offset:1024
	ds_read_b128 v[160:163], v164 offset:2048
	ds_read_b128 v[164:167], v164 offset:3072
	s_add_u32 s22, s22, 0x40000
	s_addc_u32 s23, s23, 0
	s_mov_b32 m0, s31
	ds_read_b128 v[168:171], v154 offset:32768
	ds_read_b128 v[172:175], v154 offset:33792
	ds_read_b128 v[182:185], v154 offset:34816
	ds_read_b128 v[190:193], v154 offset:35840
	ds_read_b128 v[194:197], v154 offset:36864
	ds_read_b128 v[198:201], v154 offset:37888
	ds_read_b128 v[202:205], v154 offset:38912
	ds_read_b128 v[206:209], v154 offset:39936
	global_load_lds_dwordx4 v128, s[22:23]
	s_nop 1
	s_mov_b32 m0, s34
	s_nop 0
	global_load_lds_dwordx4 v132, s[22:23]
	s_add_i32 s22, 0, 0x1c000
	v_add_u32_e32 v179, s22, v151
	s_waitcnt lgkmcnt(8)
	ds_read_b128 v[210:213], v179
	ds_read_b128 v[214:217], v179 offset:1024
	ds_read_b128 v[218:221], v179 offset:2048
	ds_read_b128 v[222:225], v179 offset:3072
	s_waitcnt vmcnt(8) lgkmcnt(0)
	s_barrier
	v_mfma_f32_16x16x32_bf16 v[124:127], v[144:147], v[168:171], v[124:127]
	v_mfma_f32_16x16x32_bf16 v[120:123], v[160:163], v[168:171], v[120:123]
	v_mfma_f32_16x16x32_bf16 v[112:115], v[144:147], v[182:185], v[112:115]
	v_mfma_f32_16x16x32_bf16 v[104:107], v[160:163], v[182:185], v[104:107]
	v_mfma_f32_16x16x32_bf16 v[96:99], v[144:147], v[194:197], v[96:99]
	v_mfma_f32_16x16x32_bf16 v[88:91], v[160:163], v[194:197], v[88:91]
	v_mfma_f32_16x16x32_bf16 v[80:83], v[144:147], v[202:205], v[80:83]
	v_mfma_f32_16x16x32_bf16 v[72:75], v[160:163], v[202:205], v[72:75]
	v_mfma_f32_16x16x32_bf16 v[124:127], v[156:159], v[172:175], v[124:127]
	v_mfma_f32_16x16x32_bf16 v[120:123], v[164:167], v[172:175], v[120:123]
	v_mfma_f32_16x16x32_bf16 v[112:115], v[156:159], v[190:193], v[112:115]
	v_mfma_f32_16x16x32_bf16 v[104:107], v[164:167], v[190:193], v[104:107]
	v_mfma_f32_16x16x32_bf16 v[96:99], v[156:159], v[198:201], v[96:99]
	v_mfma_f32_16x16x32_bf16 v[88:91], v[164:167], v[198:201], v[88:91]
	v_mfma_f32_16x16x32_bf16 v[80:83], v[156:159], v[206:209], v[80:83]
	v_mfma_f32_16x16x32_bf16 v[72:75], v[164:167], v[206:209], v[72:75]
	v_mfma_f32_16x16x32_bf16 v[116:119], v[210:213], v[168:171], v[116:119]
	v_mfma_f32_16x16x32_bf16 v[108:111], v[218:221], v[168:171], v[108:111]
	v_mfma_f32_16x16x32_bf16 v[100:103], v[210:213], v[182:185], v[100:103]
	v_mfma_f32_16x16x32_bf16 v[92:95], v[218:221], v[182:185], v[92:95]
	v_mfma_f32_16x16x32_bf16 v[84:87], v[210:213], v[194:197], v[84:87]
	v_mfma_f32_16x16x32_bf16 v[76:79], v[218:221], v[194:197], v[76:79]
	v_mfma_f32_16x16x32_bf16 v[68:71], v[210:213], v[202:205], v[68:71]
	v_mfma_f32_16x16x32_bf16 v[64:67], v[218:221], v[202:205], v[64:67]
	v_mfma_f32_16x16x32_bf16 v[116:119], v[214:217], v[172:175], v[116:119]
	v_mfma_f32_16x16x32_bf16 v[108:111], v[222:225], v[172:175], v[108:111]
	v_mfma_f32_16x16x32_bf16 v[100:103], v[214:217], v[190:193], v[100:103]
	v_mfma_f32_16x16x32_bf16 v[92:95], v[222:225], v[190:193], v[92:95]
	v_mfma_f32_16x16x32_bf16 v[84:87], v[214:217], v[198:201], v[84:87]
	v_mfma_f32_16x16x32_bf16 v[76:79], v[222:225], v[198:201], v[76:79]
	v_mfma_f32_16x16x32_bf16 v[68:71], v[214:217], v[206:209], v[68:71]
	v_mfma_f32_16x16x32_bf16 v[64:67], v[222:225], v[206:209], v[64:67]
	s_barrier
; #define PG8_STAGE(bufoff, gbase, voff) do { _Pragma("unroll") for (int _i = 0; _i < 2; ++_i) \
;         __builtin_amdgcn_global_load_lds((const unsigned*)((const char*)(gbase) + (voff)[_i]), (PG8_LAS unsigned*)(lds + (bufoff) + ldsw + _i * 8192), 16, 0, 0); } while (0)
; #define PG8_LDA(dst, b, h) do { _Pragma("unroll") for (int m = 0; m < 4; ++m) _Pragma("unroll") for (int k = 0; k < 2; ++k) dst[m][k] = *(const PG8_LAS bf16x8*)(lds + PG8_SA(b, h) + aoff + m * 2048 + k * 1024); } while (0)
; #define PG8_LDB(dst, b, h) do { _Pragma("unroll") for (int n = 0; n < 2; ++n) _Pragma("unroll") for (int k = 0; k < 2; ++k) dst[n][k] = *(const PG8_LAS bf16x8*)(lds + PG8_SB(b, h) + boff + n * 2048 + k * 1024); } while (0)
; #define PG8_MMA(ai, bj, At, Bt) do { __builtin_amdgcn_s_setprio(1); _Pragma("unroll") for (int m = 0; m < 4; ++m) _Pragma("unroll") for (int n = 0; n < 2; ++n) _Pragma("unroll") for (int k = 0; k < 2; ++k) \
;         acc[ai][bj][m][n] = __builtin_amdgcn_mfma_f32_16x16x32_bf16(Bt[n][k], At[m][k], acc[ai][bj][m][n], 0, 0, 0); __builtin_amdgcn_s_setprio(0); } while (0)
; #define PG8_WAIT_V(n) asm volatile("s_waitcnt vmcnt(" #n ")" ::: "memory")
; template <class Epi, class Sched>
; __device__ __forceinline__ void gemm_phase(PG8_LAS unsigned char* lds, const Gemm g, const Sched& S, const Epi& E) {
;     ...
;         for (int t = 0; t < nt; t += 2) {
;             const bool last = (t == nt - 2);
;             const char* a1 = cA + (size_t)(t + 1) * kstep;
;             const char* a2 = last ? nA : cA + (size_t)(t + 2) * kstep; const char* b2 = last ? nB : cB + (size_t)(t + 2) * kstep;
;             const char* a3 = a2 + kstep; const char* b3 = b2 + kstep;
;             if (last && has_next) S.a_ready(nxt);
;             PG8_LDB(B0, 0, 0); PG8_SCHED; PG8_LDA(At, 0, 0); PG8_STAGE(PG8_SA(1, 1), a1 + hstep, voffA);
;             PG8_WAIT_L(8); PG8_BAR; PG8_WAIT_L(0); PG8_MMA(0, 0, At, B0); PG8_BAR; PG8_SCHED;
;             PG8_LDB(B1, 0, 1); PG8_STAGE(PG8_SB(0, 0), b2, voffB);
;             PG8_BAR; PG8_WAIT_L(0); PG8_MMA(0, 1, At, B1); PG8_BAR;
;     ...
;             PG8_LDA(At, 1, 1); PG8_STAGE(PG8_SA(1, 0), a3, voffA);
;             PG8_BAR; PG8_WAIT_L(0); PG8_MMA(1, 0, At, B0); PG8_BAR; PG8_SCHED;
;             PG8_STAGE(PG8_SB(1, 1), b3 + hstep, voffB);
;             PG8_WAIT_V(6); PG8_BAR; PG8_MMA(1, 1, At, B1); PG8_BAR;
	ds_read_b128 v[168:171], v154 offset:49152
	ds_read_b128 v[172:175], v154 offset:50176
	ds_read_b128 v[182:185], v154 offset:51200
	ds_read_b128 v[190:193], v154 offset:52224
	ds_read_b128 v[194:197], v154 offset:53248
	ds_read_b128 v[198:201], v154 offset:54272
	ds_read_b128 v[202:205], v154 offset:55296
	ds_read_b128 v[206:209], v154 offset:56320
	s_add_i32 s23, s48, s29
	s_mov_b32 m0, s23
	s_nop 0
	global_load_lds_dwordx4 v130, s[98:99]
	s_nop 1
	s_add_i32 m0, s23, 0x2000
	s_nop 0
	global_load_lds_dwordx4 v134, s[98:99]
	s_nop 1
	s_mov_b32 m0, s36
	s_nop 0
	global_load_lds_dwordx4 v128, s[100:101]
	s_nop 1
	s_mov_b32 m0, s37
	s_nop 0
	global_load_lds_dwordx4 v132, s[100:101]
	s_add_u32 s20, s20, 0x40080
	s_addc_u32 s21, s21, 0
	s_add_i32 s22, s22, s29
	s_mov_b32 m0, s22
	s_nop 0
	global_load_lds_dwordx4 v130, s[20:21]
	s_nop 1
	s_add_i32 m0, s22, 0x2000
	s_nop 0
	global_load_lds_dwordx4 v134, s[20:21]
	s_waitcnt vmcnt(8) lgkmcnt(0)
	s_barrier
	v_mfma_f32_16x16x32_bf16 v[60:63], v[144:147], v[168:171], v[60:63]
	v_mfma_f32_16x16x32_bf16 v[56:59], v[160:163], v[168:171], v[56:59]
	v_mfma_f32_16x16x32_bf16 v[48:51], v[144:147], v[182:185], v[48:51]
	v_mfma_f32_16x16x32_bf16 v[40:43], v[160:163], v[182:185], v[40:43]
	v_mfma_f32_16x16x32_bf16 v[32:35], v[144:147], v[194:197], v[32:35]
	v_mfma_f32_16x16x32_bf16 v[24:27], v[160:163], v[194:197], v[24:27]
	v_mfma_f32_16x16x32_bf16 v[16:19], v[144:147], v[202:205], v[16:19]
	v_mfma_f32_16x16x32_bf16 v[8:11], v[160:163], v[202:205], v[8:11]
	v_mfma_f32_16x16x32_bf16 v[60:63], v[156:159], v[172:175], v[60:63]
	v_mfma_f32_16x16x32_bf16 v[56:59], v[164:167], v[172:175], v[56:59]
	v_mfma_f32_16x16x32_bf16 v[48:51], v[156:159], v[190:193], v[48:51]
	v_mfma_f32_16x16x32_bf16 v[40:43], v[164:167], v[190:193], v[40:43]
	v_mfma_f32_16x16x32_bf16 v[32:35], v[156:159], v[198:201], v[32:35]
	v_mfma_f32_16x16x32_bf16 v[24:27], v[164:167], v[198:201], v[24:27]
	v_mfma_f32_16x16x32_bf16 v[16:19], v[156:159], v[206:209], v[16:19]
	v_mfma_f32_16x16x32_bf16 v[8:11], v[164:167], v[206:209], v[8:11]
	v_mfma_f32_16x16x32_bf16 v[52:55], v[210:213], v[168:171], v[52:55]
	v_mfma_f32_16x16x32_bf16 v[44:47], v[218:221], v[168:171], v[44:47]
	v_mfma_f32_16x16x32_bf16 v[36:39], v[210:213], v[182:185], v[36:39]
	v_mfma_f32_16x16x32_bf16 v[28:31], v[218:221], v[182:185], v[28:31]
	v_mfma_f32_16x16x32_bf16 v[20:23], v[210:213], v[194:197], v[20:23]
	v_mfma_f32_16x16x32_bf16 v[12:15], v[218:221], v[194:197], v[12:15]
	v_mfma_f32_16x16x32_bf16 v[4:7], v[210:213], v[202:205], v[4:7]
	v_mfma_f32_16x16x32_bf16 v[0:3], v[218:221], v[202:205], v[0:3]
	v_mfma_f32_16x16x32_bf16 v[52:55], v[214:217], v[172:175], v[52:55]
	v_mfma_f32_16x16x32_bf16 v[44:47], v[222:225], v[172:175], v[44:47]
	v_mfma_f32_16x16x32_bf16 v[36:39], v[214:217], v[190:193], v[36:39]
	v_mfma_f32_16x16x32_bf16 v[28:31], v[222:225], v[190:193], v[28:31]
	v_mfma_f32_16x16x32_bf16 v[20:23], v[214:217], v[198:201], v[20:23]
	v_mfma_f32_16x16x32_bf16 v[12:15], v[222:225], v[198:201], v[12:15]
	v_mfma_f32_16x16x32_bf16 v[4:7], v[214:217], v[206:209], v[4:7]
	v_mfma_f32_16x16x32_bf16 v[0:3], v[222:225], v[206:209], v[0:3]
	s_barrier
	s_add_i32 s47, s47, 2
	s_add_u32 s18, s18, 0x100
	s_addc_u32 s19, s19, 0
	s_add_u32 s45, s45, 0x100
	s_addc_u32 s46, s46, 0
	s_cmp_gt_u32 s47, 13
.LBB0_991:
	ds_read_b128 v[144:147], v153
	ds_read_b128 v[156:159], v153 offset:1024
	ds_read_b128 v[160:163], v153 offset:2048
	ds_read_b128 v[164:167], v153 offset:3072
	s_add_u32 s20, s18, 0xfffc0080
	s_addc_u32 s21, s19, -1
	s_cmp_eq_u32 s47, 12
	s_cselect_b32 s23, s11, s21
	s_cselect_b32 s22, s43, s20
	s_cselect_b32 s21, s9, s46
	s_cselect_b32 s20, s44, s45
	s_add_i32 m0, s17, 0xc000
	ds_read_b128 v[168:171], v154
	ds_read_b128 v[172:175], v154 offset:1024
	ds_read_b128 v[182:185], v154 offset:2048
	ds_read_b128 v[190:193], v154 offset:3072
	ds_read_b128 v[194:197], v154 offset:4096
	ds_read_b128 v[198:201], v154 offset:5120
	ds_read_b128 v[202:205], v154 offset:6144
	ds_read_b128 v[206:209], v154 offset:7168
	global_load_lds_dwordx4 v136, s[18:19]
	s_nop 1
	s_add_i32 m0, s17, 0xe000
	s_nop 0
	global_load_lds_dwordx4 v138, s[18:19]
	s_waitcnt lgkmcnt(8)
	ds_read_b128 v[210:213], v155
	ds_read_b128 v[214:217], v155 offset:1024
	ds_read_b128 v[218:221], v155 offset:2048
	ds_read_b128 v[222:225], v155 offset:3072
	s_waitcnt vmcnt(8) lgkmcnt(0)
	s_barrier
	v_mfma_f32_16x16x32_bf16 v[124:127], v[144:147], v[168:171], v[124:127]
	v_mfma_f32_16x16x32_bf16 v[120:123], v[160:163], v[168:171], v[120:123]
	v_mfma_f32_16x16x32_bf16 v[112:115], v[144:147], v[182:185], v[112:115]
	v_mfma_f32_16x16x32_bf16 v[104:107], v[160:163], v[182:185], v[104:107]
	v_mfma_f32_16x16x32_bf16 v[96:99], v[144:147], v[194:197], v[96:99]
	v_mfma_f32_16x16x32_bf16 v[88:91], v[160:163], v[194:197], v[88:91]
	v_mfma_f32_16x16x32_bf16 v[80:83], v[144:147], v[202:205], v[80:83]
	v_mfma_f32_16x16x32_bf16 v[72:75], v[160:163], v[202:205], v[72:75]
	v_mfma_f32_16x16x32_bf16 v[124:127], v[156:159], v[172:175], v[124:127]
	v_mfma_f32_16x16x32_bf16 v[120:123], v[164:167], v[172:175], v[120:123]
	v_mfma_f32_16x16x32_bf16 v[112:115], v[156:159], v[190:193], v[112:115]
	v_mfma_f32_16x16x32_bf16 v[104:107], v[164:167], v[190:193], v[104:107]
	v_mfma_f32_16x16x32_bf16 v[96:99], v[156:159], v[198:201], v[96:99]
	v_mfma_f32_16x16x32_bf16 v[88:91], v[164:167], v[198:201], v[88:91]
	v_mfma_f32_16x16x32_bf16 v[80:83], v[156:159], v[206:209], v[80:83]
	v_mfma_f32_16x16x32_bf16 v[72:75], v[164:167], v[206:209], v[72:75]
	v_mfma_f32_16x16x32_bf16 v[116:119], v[210:213], v[168:171], v[116:119]
	v_mfma_f32_16x16x32_bf16 v[108:111], v[218:221], v[168:171], v[108:111]
	v_mfma_f32_16x16x32_bf16 v[100:103], v[210:213], v[182:185], v[100:103]
	v_mfma_f32_16x16x32_bf16 v[92:95], v[218:221], v[182:185], v[92:95]
	v_mfma_f32_16x16x32_bf16 v[84:87], v[210:213], v[194:197], v[84:87]
	v_mfma_f32_16x16x32_bf16 v[76:79], v[218:221], v[194:197], v[76:79]
	v_mfma_f32_16x16x32_bf16 v[68:71], v[210:213], v[202:205], v[68:71]
	v_mfma_f32_16x16x32_bf16 v[64:67], v[218:221], v[202:205], v[64:67]
	v_mfma_f32_16x16x32_bf16 v[116:119], v[214:217], v[172:175], v[116:119]
	v_mfma_f32_16x16x32_bf16 v[108:111], v[222:225], v[172:175], v[108:111]
	v_mfma_f32_16x16x32_bf16 v[100:103], v[214:217], v[190:193], v[100:103]
	v_mfma_f32_16x16x32_bf16 v[92:95], v[222:225], v[190:193], v[92:95]
	v_mfma_f32_16x16x32_bf16 v[84:87], v[214:217], v[198:201], v[84:87]
	v_mfma_f32_16x16x32_bf16 v[76:79], v[222:225], v[198:201], v[76:79]
	v_mfma_f32_16x16x32_bf16 v[68:71], v[214:217], v[206:209], v[68:71]
	v_mfma_f32_16x16x32_bf16 v[64:67], v[222:225], v[206:209], v[64:67]
	s_barrier
; #define PG8_STAGE(bufoff, gbase, voff) do { _Pragma("unroll") for (int _i = 0; _i < 2; ++_i) \
;         __builtin_amdgcn_global_load_lds((const unsigned*)((const char*)(gbase) + (voff)[_i]), (PG8_LAS unsigned*)(lds + (bufoff) + ldsw + _i * 8192), 16, 0, 0); } while (0)
; #define PG8_LDA(dst, b, h) do { _Pragma("unroll") for (int m = 0; m < 4; ++m) _Pragma("unroll") for (int k = 0; k < 2; ++k) dst[m][k] = *(const PG8_LAS bf16x8*)(lds + PG8_SA(b, h) + aoff + m * 2048 + k * 1024); } while (0)
; #define PG8_LDB(dst, b, h) do { _Pragma("unroll") for (int n = 0; n < 2; ++n) _Pragma("unroll") for (int k = 0; k < 2; ++k) dst[n][k] = *(const PG8_LAS bf16x8*)(lds + PG8_SB(b, h) + boff + n * 2048 + k * 1024); } while (0)
; #define PG8_MMA(ai, bj, At, Bt) do { __builtin_amdgcn_s_setprio(1); _Pragma("unroll") for (int m = 0; m < 4; ++m) _Pragma("unroll") for (int n = 0; n < 2; ++n) _Pragma("unroll") for (int k = 0; k < 2; ++k) \
;         acc[ai][bj][m][n] = __builtin_amdgcn_mfma_f32_16x16x32_bf16(Bt[n][k], At[m][k], acc[ai][bj][m][n], 0, 0, 0); __builtin_amdgcn_s_setprio(0); } while (0)
; #define PG8_WAIT_V(n) asm volatile("s_waitcnt vmcnt(" #n ")" ::: "memory")
; #define PG8_WAIT_L(n) asm volatile("s_waitcnt lgkmcnt(" #n ")" ::: "memory")
; #define PG8_BAR __builtin_amdgcn_s_barrier()
; #define PG8_SCHED __builtin_amdgcn_sched_barrier(0)
; template <class Epi, class Sched>
; __device__ __forceinline__ void gemm_phase(PG8_LAS unsigned char* lds, const Gemm g, const Sched& S, const Epi& E) {
;     ...
;             PG8_LDA(At, 0, 1); PG8_STAGE(PG8_SA(0, 0), a2, voffA);
;             PG8_BAR; PG8_WAIT_L(0); PG8_MMA(1, 0, At, B0); PG8_BAR; PG8_SCHED;
;             PG8_STAGE(PG8_SB(0, 1), b2 + hstep, voffB);
;             PG8_WAIT_V(6); PG8_BAR; PG8_MMA(1, 1, At, B1); PG8_BAR;
;             PG8_LDB(B0, 1, 0); PG8_SCHED; PG8_LDA(At, 1, 0); PG8_STAGE(PG8_SA(0, 1), a2 + hstep, voffA);
;             PG8_WAIT_L(8); PG8_BAR; PG8_WAIT_L(0); PG8_MMA(0, 0, At, B0); PG8_BAR; PG8_SCHED;
;             PG8_LDB(B1, 1, 1); PG8_STAGE(PG8_SB(1, 0), b3, voffB);
;             PG8_BAR; PG8_WAIT_L(0); PG8_MMA(0, 1, At, B1); PG8_BAR;
	ds_read_b128 v[168:171], v154 offset:16384
	ds_read_b128 v[172:175], v154 offset:17408
	ds_read_b128 v[182:185], v154 offset:18432
	ds_read_b128 v[190:193], v154 offset:19456
	ds_read_b128 v[194:197], v154 offset:20480
	ds_read_b128 v[198:201], v154 offset:21504
	ds_read_b128 v[202:205], v154 offset:22528
	ds_read_b128 v[206:209], v154 offset:23552
	s_add_i32 s48, s39, s29
	s_add_u32 s98, s20, s6
	s_addc_u32 s99, s21, s7
	s_mov_b32 m0, s48
	s_nop 0
	global_load_lds_dwordx4 v130, s[20:21]
	s_nop 1
	s_add_i32 m0, s48, 0x2000
	s_nop 0
	global_load_lds_dwordx4 v134, s[20:21]
	s_nop 1
	s_mov_b32 m0, s17
	s_add_u32 s100, s22, s6
	s_addc_u32 s101, s23, s7
	global_load_lds_dwordx4 v128, s[22:23]
	s_nop 1
	s_mov_b32 m0, s30
	s_nop 0
	global_load_lds_dwordx4 v132, s[22:23]
	s_add_u32 s48, s20, 0x40000
	s_addc_u32 s49, s21, 0
	s_add_i32 s50, s40, s29
	s_mov_b32 m0, s50
	s_nop 0
	global_load_lds_dwordx4 v130, s[48:49]
	s_nop 1
	s_add_i32 m0, s50, 0x2000
	s_nop 0
	global_load_lds_dwordx4 v134, s[48:49]
	s_waitcnt vmcnt(8) lgkmcnt(0)
	s_barrier
	v_mfma_f32_16x16x32_bf16 v[60:63], v[144:147], v[168:171], v[60:63]
	v_mfma_f32_16x16x32_bf16 v[56:59], v[160:163], v[168:171], v[56:59]
	v_mfma_f32_16x16x32_bf16 v[48:51], v[144:147], v[182:185], v[48:51]
	v_mfma_f32_16x16x32_bf16 v[40:43], v[160:163], v[182:185], v[40:43]
	v_mfma_f32_16x16x32_bf16 v[32:35], v[144:147], v[194:197], v[32:35]
	v_mfma_f32_16x16x32_bf16 v[24:27], v[160:163], v[194:197], v[24:27]
	v_mfma_f32_16x16x32_bf16 v[16:19], v[144:147], v[202:205], v[16:19]
	v_mfma_f32_16x16x32_bf16 v[8:11], v[160:163], v[202:205], v[8:11]
	v_mfma_f32_16x16x32_bf16 v[60:63], v[156:159], v[172:175], v[60:63]
	v_mfma_f32_16x16x32_bf16 v[56:59], v[164:167], v[172:175], v[56:59]
	v_mfma_f32_16x16x32_bf16 v[48:51], v[156:159], v[190:193], v[48:51]
	v_mfma_f32_16x16x32_bf16 v[40:43], v[164:167], v[190:193], v[40:43]
	v_mfma_f32_16x16x32_bf16 v[32:35], v[156:159], v[198:201], v[32:35]
	v_mfma_f32_16x16x32_bf16 v[24:27], v[164:167], v[198:201], v[24:27]
	v_mfma_f32_16x16x32_bf16 v[16:19], v[156:159], v[206:209], v[16:19]
	v_mfma_f32_16x16x32_bf16 v[8:11], v[164:167], v[206:209], v[8:11]
	v_mfma_f32_16x16x32_bf16 v[52:55], v[210:213], v[168:171], v[52:55]
	v_mfma_f32_16x16x32_bf16 v[44:47], v[218:221], v[168:171], v[44:47]
	v_mfma_f32_16x16x32_bf16 v[36:39], v[210:213], v[182:185], v[36:39]
	v_mfma_f32_16x16x32_bf16 v[28:31], v[218:221], v[182:185], v[28:31]
	v_mfma_f32_16x16x32_bf16 v[20:23], v[210:213], v[194:197], v[20:23]
	v_mfma_f32_16x16x32_bf16 v[12:15], v[218:221], v[194:197], v[12:15]
	v_mfma_f32_16x16x32_bf16 v[4:7], v[210:213], v[202:205], v[4:7]
	v_mfma_f32_16x16x32_bf16 v[0:3], v[218:221], v[202:205], v[0:3]
	v_mfma_f32_16x16x32_bf16 v[52:55], v[214:217], v[172:175], v[52:55]
	v_mfma_f32_16x16x32_bf16 v[44:47], v[222:225], v[172:175], v[44:47]
	v_mfma_f32_16x16x32_bf16 v[36:39], v[214:217], v[190:193], v[36:39]
	v_mfma_f32_16x16x32_bf16 v[28:31], v[222:225], v[190:193], v[28:31]
	v_mfma_f32_16x16x32_bf16 v[20:23], v[214:217], v[198:201], v[20:23]
	v_mfma_f32_16x16x32_bf16 v[12:15], v[222:225], v[198:201], v[12:15]
	v_mfma_f32_16x16x32_bf16 v[4:7], v[214:217], v[206:209], v[4:7]
	v_mfma_f32_16x16x32_bf16 v[0:3], v[222:225], v[206:209], v[0:3]
	s_barrier
	s_add_i32 s48, 0, 0x18000
	v_add_u32_e32 v164, s48, v151
	ds_read_b128 v[144:147], v164
	ds_read_b128 v[156:159], v164 offset:1024
	ds_read_b128 v[160:163], v164 offset:2048
	ds_read_b128 v[164:167], v164 offset:3072
	s_add_u32 s22, s22, 0x40000
	s_addc_u32 s23, s23, 0
	s_mov_b32 m0, s31
	ds_read_b128 v[168:171], v154 offset:32768
	ds_read_b128 v[172:175], v154 offset:33792
	ds_read_b128 v[182:185], v154 offset:34816
	ds_read_b128 v[190:193], v154 offset:35840
	ds_read_b128 v[194:197], v154 offset:36864
	ds_read_b128 v[198:201], v154 offset:37888
	ds_read_b128 v[202:205], v154 offset:38912
	ds_read_b128 v[206:209], v154 offset:39936
	global_load_lds_dwordx4 v128, s[22:23]
	s_nop 1
	s_mov_b32 m0, s34
	s_nop 0
	global_load_lds_dwordx4 v132, s[22:23]
	s_add_i32 s22, 0, 0x1c000
	v_add_u32_e32 v179, s22, v151
	s_waitcnt lgkmcnt(8)
	ds_read_b128 v[210:213], v179
	ds_read_b128 v[214:217], v179 offset:1024
	ds_read_b128 v[218:221], v179 offset:2048
	ds_read_b128 v[222:225], v179 offset:3072
	s_waitcnt vmcnt(8) lgkmcnt(0)
	s_barrier
	v_mfma_f32_16x16x32_bf16 v[124:127], v[144:147], v[168:171], v[124:127]
	v_mfma_f32_16x16x32_bf16 v[120:123], v[160:163], v[168:171], v[120:123]
	v_mfma_f32_16x16x32_bf16 v[112:115], v[144:147], v[182:185], v[112:115]
	v_mfma_f32_16x16x32_bf16 v[104:107], v[160:163], v[182:185], v[104:107]
	v_mfma_f32_16x16x32_bf16 v[96:99], v[144:147], v[194:197], v[96:99]
	v_mfma_f32_16x16x32_bf16 v[88:91], v[160:163], v[194:197], v[88:91]
	v_mfma_f32_16x16x32_bf16 v[80:83], v[144:147], v[202:205], v[80:83]
	v_mfma_f32_16x16x32_bf16 v[72:75], v[160:163], v[202:205], v[72:75]
	v_mfma_f32_16x16x32_bf16 v[124:127], v[156:159], v[172:175], v[124:127]
	v_mfma_f32_16x16x32_bf16 v[120:123], v[164:167], v[172:175], v[120:123]
	v_mfma_f32_16x16x32_bf16 v[112:115], v[156:159], v[190:193], v[112:115]
	v_mfma_f32_16x16x32_bf16 v[104:107], v[164:167], v[190:193], v[104:107]
	v_mfma_f32_16x16x32_bf16 v[96:99], v[156:159], v[198:201], v[96:99]
	v_mfma_f32_16x16x32_bf16 v[88:91], v[164:167], v[198:201], v[88:91]
	v_mfma_f32_16x16x32_bf16 v[80:83], v[156:159], v[206:209], v[80:83]
	v_mfma_f32_16x16x32_bf16 v[72:75], v[164:167], v[206:209], v[72:75]
	v_mfma_f32_16x16x32_bf16 v[116:119], v[210:213], v[168:171], v[116:119]
	v_mfma_f32_16x16x32_bf16 v[108:111], v[218:221], v[168:171], v[108:111]
	v_mfma_f32_16x16x32_bf16 v[100:103], v[210:213], v[182:185], v[100:103]
	v_mfma_f32_16x16x32_bf16 v[92:95], v[218:221], v[182:185], v[92:95]
	v_mfma_f32_16x16x32_bf16 v[84:87], v[210:213], v[194:197], v[84:87]
	v_mfma_f32_16x16x32_bf16 v[76:79], v[218:221], v[194:197], v[76:79]
	v_mfma_f32_16x16x32_bf16 v[68:71], v[210:213], v[202:205], v[68:71]
	v_mfma_f32_16x16x32_bf16 v[64:67], v[218:221], v[202:205], v[64:67]
	v_mfma_f32_16x16x32_bf16 v[116:119], v[214:217], v[172:175], v[116:119]
	v_mfma_f32_16x16x32_bf16 v[108:111], v[222:225], v[172:175], v[108:111]
	v_mfma_f32_16x16x32_bf16 v[100:103], v[214:217], v[190:193], v[100:103]
	v_mfma_f32_16x16x32_bf16 v[92:95], v[222:225], v[190:193], v[92:95]
	v_mfma_f32_16x16x32_bf16 v[84:87], v[214:217], v[198:201], v[84:87]
	v_mfma_f32_16x16x32_bf16 v[76:79], v[222:225], v[198:201], v[76:79]
	v_mfma_f32_16x16x32_bf16 v[68:71], v[214:217], v[206:209], v[68:71]
	v_mfma_f32_16x16x32_bf16 v[64:67], v[222:225], v[206:209], v[64:67]
	s_barrier
; __device__ __forceinline__ unsigned cvt_pk_bf16(float lo, float hi) { unsigned r; asm volatile("v_cvt_pk_bf16_f32 %0, %1, %2" : "=v"(r) : "v"(lo), "v"(hi)); return r; }
; __device__ __forceinline__ float bf_lo(unsigned u) { return __uint_as_float(u << 16); }
; __device__ __forceinline__ float bf_hi(unsigned u) { return __uint_as_float(u & 0xffff0000u); }
; #define PG8_STAGE(bufoff, gbase, voff) do { _Pragma("unroll") for (int _i = 0; _i < 2; ++_i) \
;         __builtin_amdgcn_global_load_lds((const unsigned*)((const char*)(gbase) + (voff)[_i]), (PG8_LAS unsigned*)(lds + (bufoff) + ldsw + _i * 8192), 16, 0, 0); } while (0)
;     __device__ __forceinline__ void operator()(const f32x4 (&acc)[2][2][4][2], const Unit& u, int wr, int wc, int fr, int fq) const {
;     ...
;             for (int m = 0; m < 4; ++m) { const size_t r = (size_t)(row0 + ai * HALF + m * 16); bf16_t* rowp = O + r * ldc + col0; const bf16_t* gp = G + r * ldg + col0;
; #pragma unroll
;                 for (int bj = 0; bj < 2; ++bj) { const u32x4 gw = *(const u32x4*)(gp + bj * HALF);
;                     f32x4 v0 = acc[ai][bj][m][0], v1 = acc[ai][bj][m][1];
;                     v0[0] *= bf_lo(gw.x); v0[1] *= bf_hi(gw.x); v0[2] *= bf_lo(gw.y); v0[3] *= bf_hi(gw.y);
;                     v1[0] *= bf_lo(gw.z); v1[1] *= bf_hi(gw.z); v1[2] *= bf_lo(gw.w); v1[3] *= bf_hi(gw.w);
;                     if (ACCUM) { const u32x4 pw = *(const u32x4*)(rowp + bj * HALF);
;                         v0[0] += bf_lo(pw.x); v0[1] += bf_hi(pw.x); v0[2] += bf_lo(pw.y); v0[3] += bf_hi(pw.y);
;                         v1[0] += bf_lo(pw.z); v1[1] += bf_hi(pw.z); v1[2] += bf_lo(pw.w); v1[3] += bf_hi(pw.w); }
;                     u32x4 w; w.x = cvt_pk_bf16(v0[0], v0[1]); w.y = cvt_pk_bf16(v0[2], v0[3]); w.z = cvt_pk_bf16(v1[0], v1[1]); w.w = cvt_pk_bf16(v1[2], v1[3]);
;                     *(u32x4*)(rowp + bj * HALF) = w; } }
; template <class Epi, class Sched>
; __device__ __forceinline__ void gemm_phase(PG8_LAS unsigned char* lds, const Gemm g, const Sched& S, const Epi& E) {
;     ...
;             PG8_BAR; PG8_WAIT_L(0); PG8_MMA(0, 1, At, B1); PG8_BAR;
;             PG8_LDA(At, 1, 1); PG8_STAGE(PG8_SA(1, 0), a3, voffA);
;             PG8_BAR; PG8_WAIT_L(0); PG8_MMA(1, 0, At, B0); PG8_BAR; PG8_SCHED;
;             PG8_STAGE(PG8_SB(1, 1), b3 + hstep, voffB);
;             PG8_WAIT_V(6); PG8_BAR; PG8_MMA(1, 1, At, B1); PG8_BAR;
	ds_read_b128 v[168:171], v154 offset:49152
	ds_read_b128 v[172:175], v154 offset:50176
	ds_read_b128 v[182:185], v154 offset:51200
	ds_read_b128 v[190:193], v154 offset:52224
	ds_read_b128 v[194:197], v154 offset:53248
	ds_read_b128 v[198:201], v154 offset:54272
	ds_read_b128 v[202:205], v154 offset:55296
	ds_read_b128 v[206:209], v154 offset:56320
	s_add_i32 s23, s48, s29
	s_mov_b32 m0, s23
	s_nop 0
	global_load_lds_dwordx4 v130, s[98:99]
	s_nop 1
	s_add_i32 m0, s23, 0x2000
	s_nop 0
	global_load_lds_dwordx4 v134, s[98:99]
	s_nop 1
	s_mov_b32 m0, s36
	s_nop 0
	global_load_lds_dwordx4 v128, s[100:101]
	s_nop 1
	s_mov_b32 m0, s37
	s_nop 0
	global_load_lds_dwordx4 v132, s[100:101]
	s_add_u32 s20, s20, 0x40080
	s_addc_u32 s21, s21, 0
	s_add_i32 s22, s22, s29
	s_mov_b32 m0, s22
	s_nop 0
	global_load_lds_dwordx4 v130, s[20:21]
	s_nop 1
	s_add_i32 m0, s22, 0x2000
	s_nop 0
	global_load_lds_dwordx4 v134, s[20:21]
	s_waitcnt vmcnt(8) lgkmcnt(0)
	s_barrier
	v_mfma_f32_16x16x32_bf16 v[60:63], v[144:147], v[168:171], v[60:63]
	v_mfma_f32_16x16x32_bf16 v[56:59], v[160:163], v[168:171], v[56:59]
	v_mfma_f32_16x16x32_bf16 v[48:51], v[144:147], v[182:185], v[48:51]
	v_mfma_f32_16x16x32_bf16 v[40:43], v[160:163], v[182:185], v[40:43]
	v_mfma_f32_16x16x32_bf16 v[32:35], v[144:147], v[194:197], v[32:35]
	v_mfma_f32_16x16x32_bf16 v[24:27], v[160:163], v[194:197], v[24:27]
	v_mfma_f32_16x16x32_bf16 v[16:19], v[144:147], v[202:205], v[16:19]
	v_mfma_f32_16x16x32_bf16 v[8:11], v[160:163], v[202:205], v[8:11]
	v_mfma_f32_16x16x32_bf16 v[60:63], v[156:159], v[172:175], v[60:63]
	v_mfma_f32_16x16x32_bf16 v[56:59], v[164:167], v[172:175], v[56:59]
	v_mfma_f32_16x16x32_bf16 v[48:51], v[156:159], v[190:193], v[48:51]
	v_mfma_f32_16x16x32_bf16 v[40:43], v[164:167], v[190:193], v[40:43]
	v_mfma_f32_16x16x32_bf16 v[32:35], v[156:159], v[198:201], v[32:35]
	v_mfma_f32_16x16x32_bf16 v[24:27], v[164:167], v[198:201], v[24:27]
	v_mfma_f32_16x16x32_bf16 v[16:19], v[156:159], v[206:209], v[16:19]
	v_mfma_f32_16x16x32_bf16 v[8:11], v[164:167], v[206:209], v[8:11]
	v_mfma_f32_16x16x32_bf16 v[52:55], v[210:213], v[168:171], v[52:55]
	v_mfma_f32_16x16x32_bf16 v[44:47], v[218:221], v[168:171], v[44:47]
	v_mfma_f32_16x16x32_bf16 v[36:39], v[210:213], v[182:185], v[36:39]
	v_mfma_f32_16x16x32_bf16 v[28:31], v[218:221], v[182:185], v[28:31]
	v_mfma_f32_16x16x32_bf16 v[20:23], v[210:213], v[194:197], v[20:23]
	v_mfma_f32_16x16x32_bf16 v[12:15], v[218:221], v[194:197], v[12:15]
	v_mfma_f32_16x16x32_bf16 v[4:7], v[210:213], v[202:205], v[4:7]
	v_mfma_f32_16x16x32_bf16 v[0:3], v[218:221], v[202:205], v[0:3]
	v_mfma_f32_16x16x32_bf16 v[52:55], v[214:217], v[172:175], v[52:55]
	v_mfma_f32_16x16x32_bf16 v[44:47], v[222:225], v[172:175], v[44:47]
	v_mfma_f32_16x16x32_bf16 v[36:39], v[214:217], v[190:193], v[36:39]
	v_mfma_f32_16x16x32_bf16 v[28:31], v[222:225], v[190:193], v[28:31]
	v_mfma_f32_16x16x32_bf16 v[20:23], v[214:217], v[198:201], v[20:23]
	v_mfma_f32_16x16x32_bf16 v[12:15], v[222:225], v[198:201], v[12:15]
	v_mfma_f32_16x16x32_bf16 v[4:7], v[214:217], v[206:209], v[4:7]
	v_mfma_f32_16x16x32_bf16 v[0:3], v[222:225], v[206:209], v[0:3]
	s_barrier
	s_add_i32 s47, s47, 2
	s_add_u32 s18, s18, 0x100
	s_addc_u32 s19, s19, 0
	s_add_u32 s45, s45, 0x100
	s_addc_u32 s46, s46, 0
	s_cmp_gt_u32 s47, 13
	s_cbranch_scc0 .LBB0_991
	v_lshl_or_b32 v144, s42, 8, v152
	v_lshl_add_u32 v146, s16, 8, v150
	v_ashrrev_i32_e32 v145, 31, v144
	v_mov_b64_e32 v[148:149], s[4:5]
	v_lshlrev_b64 v[144:145], 1, v[144:145]
	v_mad_i64_i32 v[156:157], s[18:19], v146, s41, v[148:149]
	v_lshl_add_u64 v[160:161], v[156:157], 0, v[144:145]
	global_load_dwordx4 v[156:159], v[160:161], off offset:3072
	s_and_b64 vcc, exec, s[2:3]
	s_mov_b32 s42, s8
	s_mov_b32 s16, s10
	s_mov_b64 s[20:21], s[14:15]
	s_waitcnt vmcnt(0)
	v_lshlrev_b32_e32 v147, 16, v156
	v_and_b32_e32 v156, 0xffff0000, v156
	v_lshlrev_b32_e32 v162, 16, v157
	v_and_b32_e32 v157, 0xffff0000, v157
	v_lshlrev_b32_e32 v164, 16, v159
	v_and_b32_e32 v159, 0xffff0000, v159
	v_lshlrev_b32_e32 v163, 16, v158
	v_and_b32_e32 v158, 0xffff0000, v158
	v_mul_f32_e32 v124, v124, v147
	v_mul_f32_e32 v125, v125, v156
	v_mul_f32_e32 v126, v126, v162
	v_mul_f32_e32 v127, v127, v157
	v_mul_f32_e32 v123, v123, v159
	v_mul_f32_e32 v147, v120, v163
	v_mul_f32_e32 v156, v121, v158
	v_mul_f32_e32 v157, v122, v164
	v_cvt_pk_bf16_f32 v120, v124, v125
	v_cvt_pk_bf16_f32 v121, v126, v127
	v_cvt_pk_bf16_f32 v122, v147, v156
	v_cvt_pk_bf16_f32 v123, v157, v123
	global_load_dwordx4 v[124:127], v[160:161], off offset:3328
	v_ashrrev_i32_e32 v147, 31, v146
	v_lshlrev_b64 v[158:159], 11, v[146:147]
	v_lshl_add_u64 v[158:159], s[0:1], 0, v[158:159]
	v_or_b32_e32 v156, 16, v146
	v_lshl_add_u64 v[158:159], v[158:159], 0, v[144:145]
	v_mad_i64_i32 v[160:161], s[18:19], v156, s41, v[148:149]
	global_store_dwordx4 v[158:159], v[120:123], off
	v_lshl_add_u64 v[160:161], v[160:161], 0, v[144:145]
	v_ashrrev_i32_e32 v157, 31, v156
	s_waitcnt vmcnt(0)
	v_lshlrev_b32_e32 v120, 16, v124
	v_and_b32_e32 v121, 0xffff0000, v124
	v_lshlrev_b32_e32 v122, 16, v125
	v_and_b32_e32 v123, 0xffff0000, v125
	v_lshlrev_b32_e32 v124, 16, v126
	v_and_b32_e32 v125, 0xffff0000, v126
	v_lshlrev_b32_e32 v126, 16, v127
	v_and_b32_e32 v127, 0xffff0000, v127
	v_mul_f32_e32 v116, v116, v120
	v_mul_f32_e32 v117, v117, v121
	v_mul_f32_e32 v118, v118, v122
	v_mul_f32_e32 v119, v119, v123
	v_mul_f32_e32 v111, v111, v127
	v_mul_f32_e32 v120, v108, v124
	v_mul_f32_e32 v121, v109, v125
	v_mul_f32_e32 v122, v110, v126
	v_cvt_pk_bf16_f32 v108, v116, v117
	v_cvt_pk_bf16_f32 v109, v118, v119
	v_cvt_pk_bf16_f32 v110, v120, v121
	v_cvt_pk_bf16_f32 v111, v122, v111
	global_load_dwordx4 v[116:119], v[160:161], off offset:3072
	s_nop 0
	global_store_dwordx4 v[158:159], v[108:111], off offset:256
	s_waitcnt vmcnt(0)
; __device__ __forceinline__ unsigned cvt_pk_bf16(float lo, float hi) { unsigned r; asm volatile("v_cvt_pk_bf16_f32 %0, %1, %2" : "=v"(r) : "v"(lo), "v"(hi)); return r; }
; __device__ __forceinline__ float bf_lo(unsigned u) { return __uint_as_float(u << 16); }
; __device__ __forceinline__ float bf_hi(unsigned u) { return __uint_as_float(u & 0xffff0000u); }
;     __device__ __forceinline__ void operator()(const f32x4 (&acc)[2][2][4][2], const Unit& u, int wr, int wc, int fr, int fq) const {
;     ...
;             for (int m = 0; m < 4; ++m) { const size_t r = (size_t)(row0 + ai * HALF + m * 16); bf16_t* rowp = O + r * ldc + col0; const bf16_t* gp = G + r * ldg + col0;
; #pragma unroll
;                 for (int bj = 0; bj < 2; ++bj) { const u32x4 gw = *(const u32x4*)(gp + bj * HALF);
;                     f32x4 v0 = acc[ai][bj][m][0], v1 = acc[ai][bj][m][1];
;                     v0[0] *= bf_lo(gw.x); v0[1] *= bf_hi(gw.x); v0[2] *= bf_lo(gw.y); v0[3] *= bf_hi(gw.y);
;                     v1[0] *= bf_lo(gw.z); v1[1] *= bf_hi(gw.z); v1[2] *= bf_lo(gw.w); v1[3] *= bf_hi(gw.w);
;                     if (ACCUM) { const u32x4 pw = *(const u32x4*)(rowp + bj * HALF);
;                         v0[0] += bf_lo(pw.x); v0[1] += bf_hi(pw.x); v0[2] += bf_lo(pw.y); v0[3] += bf_hi(pw.y);
;                         v1[0] += bf_lo(pw.z); v1[1] += bf_hi(pw.z); v1[2] += bf_lo(pw.w); v1[3] += bf_hi(pw.w); }
;                     u32x4 w; w.x = cvt_pk_bf16(v0[0], v0[1]); w.y = cvt_pk_bf16(v0[2], v0[3]); w.z = cvt_pk_bf16(v1[0], v1[1]); w.w = cvt_pk_bf16(v1[2], v1[3]);
;                     *(u32x4*)(rowp + bj * HALF) = w; } }
	s_nop 0
	v_lshlrev_b32_e32 v108, 16, v116
	v_and_b32_e32 v109, 0xffff0000, v116
	v_lshlrev_b32_e32 v110, 16, v117
	v_and_b32_e32 v111, 0xffff0000, v117
	v_lshlrev_b32_e32 v116, 16, v118
	v_and_b32_e32 v117, 0xffff0000, v118
	v_lshlrev_b32_e32 v118, 16, v119
	v_and_b32_e32 v119, 0xffff0000, v119
	v_mul_f32_e32 v108, v112, v108
	v_mul_f32_e32 v109, v113, v109
	v_mul_f32_e32 v110, v114, v110
	v_mul_f32_e32 v111, v115, v111
	v_mul_f32_e32 v107, v107, v119
	v_mul_f32_e32 v112, v104, v116
	v_mul_f32_e32 v113, v105, v117
	v_mul_f32_e32 v114, v106, v118
	v_cvt_pk_bf16_f32 v104, v108, v109
	v_cvt_pk_bf16_f32 v105, v110, v111
	v_cvt_pk_bf16_f32 v106, v112, v113
	v_cvt_pk_bf16_f32 v107, v114, v107
	global_load_dwordx4 v[108:111], v[160:161], off offset:3328
	v_lshlrev_b64 v[116:117], 11, v[156:157]
	v_lshl_add_u64 v[116:117], s[0:1], 0, v[116:117]
	v_or_b32_e32 v112, 32, v146
	v_lshl_add_u64 v[116:117], v[116:117], 0, v[144:145]
	v_mad_i64_i32 v[114:115], s[18:19], v112, s41, v[148:149]
	global_store_dwordx4 v[116:117], v[104:107], off
	v_lshl_add_u64 v[114:115], v[114:115], 0, v[144:145]
	v_ashrrev_i32_e32 v113, 31, v112
	s_waitcnt vmcnt(0)
	v_lshlrev_b32_e32 v104, 16, v108
	v_and_b32_e32 v105, 0xffff0000, v108
	v_lshlrev_b32_e32 v106, 16, v109
	v_and_b32_e32 v107, 0xffff0000, v109
	v_lshlrev_b32_e32 v108, 16, v110
	v_and_b32_e32 v109, 0xffff0000, v110
	v_lshlrev_b32_e32 v110, 16, v111
	v_and_b32_e32 v111, 0xffff0000, v111
	v_mul_f32_e32 v100, v100, v104
	v_mul_f32_e32 v101, v101, v105
	v_mul_f32_e32 v102, v102, v106
	v_mul_f32_e32 v103, v103, v107
	v_mul_f32_e32 v95, v95, v111
	v_mul_f32_e32 v104, v92, v108
	v_mul_f32_e32 v105, v93, v109
	v_mul_f32_e32 v106, v94, v110
	v_cvt_pk_bf16_f32 v92, v100, v101
	v_cvt_pk_bf16_f32 v93, v102, v103
	v_cvt_pk_bf16_f32 v94, v104, v105
	v_cvt_pk_bf16_f32 v95, v106, v95
	global_load_dwordx4 v[100:103], v[114:115], off offset:3072
	s_nop 0
	global_store_dwordx4 v[116:117], v[92:95], off offset:256
	s_waitcnt vmcnt(0)
	s_nop 0
	v_lshlrev_b32_e32 v92, 16, v100
	v_and_b32_e32 v93, 0xffff0000, v100
	v_lshlrev_b32_e32 v94, 16, v101
	v_and_b32_e32 v95, 0xffff0000, v101
	v_lshlrev_b32_e32 v100, 16, v102
	v_and_b32_e32 v101, 0xffff0000, v102
	v_lshlrev_b32_e32 v102, 16, v103
	v_and_b32_e32 v103, 0xffff0000, v103
	v_mul_f32_e32 v92, v96, v92
	v_mul_f32_e32 v93, v97, v93
	v_mul_f32_e32 v94, v98, v94
	v_mul_f32_e32 v95, v99, v95
	v_mul_f32_e32 v91, v91, v103
	v_mul_f32_e32 v96, v88, v100
	v_mul_f32_e32 v97, v89, v101
	v_mul_f32_e32 v98, v90, v102
	v_cvt_pk_bf16_f32 v88, v92, v93
	v_cvt_pk_bf16_f32 v89, v94, v95
	v_cvt_pk_bf16_f32 v90, v96, v97
	v_cvt_pk_bf16_f32 v91, v98, v91
	global_load_dwordx4 v[92:95], v[114:115], off offset:3328
	v_lshlrev_b64 v[100:101], 11, v[112:113]
	v_lshl_add_u64 v[100:101], s[0:1], 0, v[100:101]
	v_or_b32_e32 v96, 48, v146
	v_lshl_add_u64 v[100:101], v[100:101], 0, v[144:145]
	v_mad_i64_i32 v[98:99], s[18:19], v96, s41, v[148:149]
	global_store_dwordx4 v[100:101], v[88:91], off
	v_lshl_add_u64 v[98:99], v[98:99], 0, v[144:145]
	v_ashrrev_i32_e32 v97, 31, v96
	s_waitcnt vmcnt(0)
	v_lshlrev_b32_e32 v88, 16, v92
	v_and_b32_e32 v89, 0xffff0000, v92
	v_lshlrev_b32_e32 v90, 16, v93
	v_and_b32_e32 v91, 0xffff0000, v93
	v_lshlrev_b32_e32 v92, 16, v94
	v_and_b32_e32 v93, 0xffff0000, v94
	v_lshlrev_b32_e32 v94, 16, v95
	v_and_b32_e32 v95, 0xffff0000, v95
	v_mul_f32_e32 v84, v84, v88
	v_mul_f32_e32 v85, v85, v89
	v_mul_f32_e32 v86, v86, v90
	v_mul_f32_e32 v87, v87, v91
	v_mul_f32_e32 v79, v79, v95
	v_mul_f32_e32 v88, v76, v92
	v_mul_f32_e32 v89, v77, v93
	v_mul_f32_e32 v90, v78, v94
	v_cvt_pk_bf16_f32 v76, v84, v85
	v_cvt_pk_bf16_f32 v77, v86, v87
	v_cvt_pk_bf16_f32 v78, v88, v89
	v_cvt_pk_bf16_f32 v79, v90, v79
	global_load_dwordx4 v[84:87], v[98:99], off offset:3072
	s_nop 0
	global_store_dwordx4 v[100:101], v[76:79], off offset:256
	s_waitcnt vmcnt(0)
	s_nop 0
	v_lshlrev_b32_e32 v76, 16, v84
	v_and_b32_e32 v77, 0xffff0000, v84
	v_lshlrev_b32_e32 v78, 16, v85
	v_and_b32_e32 v79, 0xffff0000, v85
	v_lshlrev_b32_e32 v84, 16, v86
	v_and_b32_e32 v85, 0xffff0000, v86
	v_lshlrev_b32_e32 v86, 16, v87
	v_and_b32_e32 v87, 0xffff0000, v87
	v_mul_f32_e32 v76, v80, v76
	v_mul_f32_e32 v77, v81, v77
	v_mul_f32_e32 v78, v82, v78
	v_mul_f32_e32 v79, v83, v79
	v_mul_f32_e32 v75, v75, v87
	v_mul_f32_e32 v80, v72, v84
	v_mul_f32_e32 v81, v73, v85
	v_mul_f32_e32 v82, v74, v86
	v_cvt_pk_bf16_f32 v72, v76, v77
	v_cvt_pk_bf16_f32 v73, v78, v79
	v_cvt_pk_bf16_f32 v74, v80, v81
	v_cvt_pk_bf16_f32 v75, v82, v75
	global_load_dwordx4 v[76:79], v[98:99], off offset:3328
	v_lshlrev_b64 v[84:85], 11, v[96:97]
	v_lshl_add_u64 v[84:85], s[0:1], 0, v[84:85]
	v_add_u32_e32 v80, 0x80, v146
	v_lshl_add_u64 v[84:85], v[84:85], 0, v[144:145]
	v_mad_i64_i32 v[82:83], s[18:19], v80, s41, v[148:149]
	global_store_dwordx4 v[84:85], v[72:75], off
	v_lshl_add_u64 v[82:83], v[82:83], 0, v[144:145]
	v_ashrrev_i32_e32 v81, 31, v80
	s_waitcnt vmcnt(0)
	v_lshlrev_b32_e32 v72, 16, v76
	v_and_b32_e32 v73, 0xffff0000, v76
	v_lshlrev_b32_e32 v74, 16, v77
	v_and_b32_e32 v75, 0xffff0000, v77
	v_lshlrev_b32_e32 v76, 16, v78
	v_and_b32_e32 v77, 0xffff0000, v78
	v_lshlrev_b32_e32 v78, 16, v79
	v_and_b32_e32 v79, 0xffff0000, v79
	v_mul_f32_e32 v68, v68, v72
	v_mul_f32_e32 v69, v69, v73
	v_mul_f32_e32 v70, v70, v74
	v_mul_f32_e32 v71, v71, v75
	v_mul_f32_e32 v67, v67, v79
	v_mul_f32_e32 v72, v64, v76
	v_mul_f32_e32 v73, v65, v77
	v_mul_f32_e32 v74, v66, v78
	v_cvt_pk_bf16_f32 v64, v68, v69
	v_cvt_pk_bf16_f32 v65, v70, v71
	v_cvt_pk_bf16_f32 v66, v72, v73
	v_cvt_pk_bf16_f32 v67, v74, v67
	global_load_dwordx4 v[68:71], v[82:83], off offset:3072
	s_nop 0
	global_store_dwordx4 v[84:85], v[64:67], off offset:256
	s_waitcnt vmcnt(0)
; __device__ __forceinline__ unsigned cvt_pk_bf16(float lo, float hi) { unsigned r; asm volatile("v_cvt_pk_bf16_f32 %0, %1, %2" : "=v"(r) : "v"(lo), "v"(hi)); return r; }
; __device__ __forceinline__ float bf_lo(unsigned u) { return __uint_as_float(u << 16); }
; __device__ __forceinline__ float bf_hi(unsigned u) { return __uint_as_float(u & 0xffff0000u); }
;     __device__ __forceinline__ void operator()(const f32x4 (&acc)[2][2][4][2], const Unit& u, int wr, int wc, int fr, int fq) const {
;     ...
;             for (int m = 0; m < 4; ++m) { const size_t r = (size_t)(row0 + ai * HALF + m * 16); bf16_t* rowp = O + r * ldc + col0; const bf16_t* gp = G + r * ldg + col0;
; #pragma unroll
;                 for (int bj = 0; bj < 2; ++bj) { const u32x4 gw = *(const u32x4*)(gp + bj * HALF);
;                     f32x4 v0 = acc[ai][bj][m][0], v1 = acc[ai][bj][m][1];
;                     v0[0] *= bf_lo(gw.x); v0[1] *= bf_hi(gw.x); v0[2] *= bf_lo(gw.y); v0[3] *= bf_hi(gw.y);
;                     v1[0] *= bf_lo(gw.z); v1[1] *= bf_hi(gw.z); v1[2] *= bf_lo(gw.w); v1[3] *= bf_hi(gw.w);
;                     if (ACCUM) { const u32x4 pw = *(const u32x4*)(rowp + bj * HALF);
;                         v0[0] += bf_lo(pw.x); v0[1] += bf_hi(pw.x); v0[2] += bf_lo(pw.y); v0[3] += bf_hi(pw.y);
;                         v1[0] += bf_lo(pw.z); v1[1] += bf_hi(pw.z); v1[2] += bf_lo(pw.w); v1[3] += bf_hi(pw.w); }
;                     u32x4 w; w.x = cvt_pk_bf16(v0[0], v0[1]); w.y = cvt_pk_bf16(v0[2], v0[3]); w.z = cvt_pk_bf16(v1[0], v1[1]); w.w = cvt_pk_bf16(v1[2], v1[3]);
;                     *(u32x4*)(rowp + bj * HALF) = w; } }
	s_nop 0
	v_lshlrev_b32_e32 v64, 16, v68
	v_and_b32_e32 v65, 0xffff0000, v68
	v_lshlrev_b32_e32 v66, 16, v69
	v_and_b32_e32 v67, 0xffff0000, v69
	v_lshlrev_b32_e32 v68, 16, v70
	v_and_b32_e32 v69, 0xffff0000, v70
	v_lshlrev_b32_e32 v70, 16, v71
	v_and_b32_e32 v71, 0xffff0000, v71
	v_mul_f32_e32 v60, v60, v64
	v_mul_f32_e32 v61, v61, v65
	v_mul_f32_e32 v62, v62, v66
	v_mul_f32_e32 v63, v63, v67
	v_mul_f32_e32 v59, v59, v71
	v_mul_f32_e32 v64, v56, v68
	v_mul_f32_e32 v65, v57, v69
	v_mul_f32_e32 v66, v58, v70
	v_cvt_pk_bf16_f32 v56, v60, v61
	v_cvt_pk_bf16_f32 v57, v62, v63
	v_cvt_pk_bf16_f32 v58, v64, v65
	v_cvt_pk_bf16_f32 v59, v66, v59
	global_load_dwordx4 v[60:63], v[82:83], off offset:3328
	v_lshlrev_b64 v[68:69], 11, v[80:81]
	v_lshl_add_u64 v[68:69], s[0:1], 0, v[68:69]
	v_add_u32_e32 v64, 0x90, v146
	v_lshl_add_u64 v[68:69], v[68:69], 0, v[144:145]
	v_mad_i64_i32 v[66:67], s[18:19], v64, s41, v[148:149]
	global_store_dwordx4 v[68:69], v[56:59], off
	v_lshl_add_u64 v[66:67], v[66:67], 0, v[144:145]
	v_ashrrev_i32_e32 v65, 31, v64
	s_waitcnt vmcnt(0)
	v_lshlrev_b32_e32 v56, 16, v60
	v_and_b32_e32 v57, 0xffff0000, v60
	v_lshlrev_b32_e32 v58, 16, v61
	v_and_b32_e32 v59, 0xffff0000, v61
	v_lshlrev_b32_e32 v60, 16, v62
	v_and_b32_e32 v61, 0xffff0000, v62
	v_lshlrev_b32_e32 v62, 16, v63
	v_and_b32_e32 v63, 0xffff0000, v63
	v_mul_f32_e32 v52, v52, v56
	v_mul_f32_e32 v53, v53, v57
	v_mul_f32_e32 v54, v54, v58
	v_mul_f32_e32 v55, v55, v59
	v_mul_f32_e32 v47, v47, v63
	v_mul_f32_e32 v56, v44, v60
	v_mul_f32_e32 v57, v45, v61
	v_mul_f32_e32 v58, v46, v62
	v_cvt_pk_bf16_f32 v44, v52, v53
	v_cvt_pk_bf16_f32 v45, v54, v55
	v_cvt_pk_bf16_f32 v46, v56, v57
	v_cvt_pk_bf16_f32 v47, v58, v47
	global_load_dwordx4 v[52:55], v[66:67], off offset:3072
	s_nop 0
	global_store_dwordx4 v[68:69], v[44:47], off offset:256
	s_waitcnt vmcnt(0)
	s_nop 0
	v_lshlrev_b32_e32 v44, 16, v52
	v_and_b32_e32 v45, 0xffff0000, v52
	v_lshlrev_b32_e32 v46, 16, v53
	v_and_b32_e32 v47, 0xffff0000, v53
	v_lshlrev_b32_e32 v52, 16, v54
	v_and_b32_e32 v53, 0xffff0000, v54
	v_lshlrev_b32_e32 v54, 16, v55
	v_and_b32_e32 v55, 0xffff0000, v55
	v_mul_f32_e32 v44, v48, v44
	v_mul_f32_e32 v45, v49, v45
	v_mul_f32_e32 v46, v50, v46
	v_mul_f32_e32 v47, v51, v47
	v_mul_f32_e32 v43, v43, v55
	v_mul_f32_e32 v48, v40, v52
	v_mul_f32_e32 v49, v41, v53
	v_mul_f32_e32 v50, v42, v54
	v_cvt_pk_bf16_f32 v40, v44, v45
	v_cvt_pk_bf16_f32 v41, v46, v47
	v_cvt_pk_bf16_f32 v42, v48, v49
	v_cvt_pk_bf16_f32 v43, v50, v43
	global_load_dwordx4 v[44:47], v[66:67], off offset:3328
	v_lshlrev_b64 v[52:53], 11, v[64:65]
	v_lshl_add_u64 v[52:53], s[0:1], 0, v[52:53]
	v_add_u32_e32 v48, 0xa0, v146
	v_lshl_add_u64 v[52:53], v[52:53], 0, v[144:145]
	v_mad_i64_i32 v[50:51], s[18:19], v48, s41, v[148:149]
	global_store_dwordx4 v[52:53], v[40:43], off
	v_lshl_add_u64 v[50:51], v[50:51], 0, v[144:145]
	v_ashrrev_i32_e32 v49, 31, v48
	s_waitcnt vmcnt(0)
	v_lshlrev_b32_e32 v40, 16, v44
	v_and_b32_e32 v41, 0xffff0000, v44
	v_lshlrev_b32_e32 v42, 16, v45
	v_and_b32_e32 v43, 0xffff0000, v45
	v_lshlrev_b32_e32 v44, 16, v46
	v_and_b32_e32 v45, 0xffff0000, v46
	v_lshlrev_b32_e32 v46, 16, v47
	v_and_b32_e32 v47, 0xffff0000, v47
	v_mul_f32_e32 v36, v36, v40
	v_mul_f32_e32 v37, v37, v41
	v_mul_f32_e32 v38, v38, v42
	v_mul_f32_e32 v39, v39, v43
	v_mul_f32_e32 v31, v31, v47
	v_mul_f32_e32 v40, v28, v44
	v_mul_f32_e32 v41, v29, v45
	v_mul_f32_e32 v42, v30, v46
	v_cvt_pk_bf16_f32 v28, v36, v37
	v_cvt_pk_bf16_f32 v29, v38, v39
	v_cvt_pk_bf16_f32 v30, v40, v41
	v_cvt_pk_bf16_f32 v31, v42, v31
	global_load_dwordx4 v[36:39], v[50:51], off offset:3072
	s_nop 0
	global_store_dwordx4 v[52:53], v[28:31], off offset:256
	s_waitcnt vmcnt(0)
; __device__ __forceinline__ unsigned cvt_pk_bf16(float lo, float hi) { unsigned r; asm volatile("v_cvt_pk_bf16_f32 %0, %1, %2" : "=v"(r) : "v"(lo), "v"(hi)); return r; }
; __device__ __forceinline__ float bf_lo(unsigned u) { return __uint_as_float(u << 16); }
; __device__ __forceinline__ float bf_hi(unsigned u) { return __uint_as_float(u & 0xffff0000u); }
; #define PG8_WAIT_V(n) asm volatile("s_waitcnt vmcnt(" #n ")" ::: "memory")
; #define PG8_BAR __builtin_amdgcn_s_barrier()
;     __device__ __forceinline__ void operator()(const f32x4 (&acc)[2][2][4][2], const Unit& u, int wr, int wc, int fr, int fq) const {
;     ...
;             for (int m = 0; m < 4; ++m) { const size_t r = (size_t)(row0 + ai * HALF + m * 16); bf16_t* rowp = O + r * ldc + col0; const bf16_t* gp = G + r * ldg + col0;
; #pragma unroll
;                 for (int bj = 0; bj < 2; ++bj) { const u32x4 gw = *(const u32x4*)(gp + bj * HALF);
;                     f32x4 v0 = acc[ai][bj][m][0], v1 = acc[ai][bj][m][1];
;                     v0[0] *= bf_lo(gw.x); v0[1] *= bf_hi(gw.x); v0[2] *= bf_lo(gw.y); v0[3] *= bf_hi(gw.y);
;                     v1[0] *= bf_lo(gw.z); v1[1] *= bf_hi(gw.z); v1[2] *= bf_lo(gw.w); v1[3] *= bf_hi(gw.w);
;                     if (ACCUM) { const u32x4 pw = *(const u32x4*)(rowp + bj * HALF);
;                         v0[0] += bf_lo(pw.x); v0[1] += bf_hi(pw.x); v0[2] += bf_lo(pw.y); v0[3] += bf_hi(pw.y);
;                         v1[0] += bf_lo(pw.z); v1[1] += bf_hi(pw.z); v1[2] += bf_lo(pw.w); v1[3] += bf_hi(pw.w); }
;                     u32x4 w; w.x = cvt_pk_bf16(v0[0], v0[1]); w.y = cvt_pk_bf16(v0[2], v0[3]); w.z = cvt_pk_bf16(v1[0], v1[1]); w.w = cvt_pk_bf16(v1[2], v1[3]);
;                     *(u32x4*)(rowp + bj * HALF) = w; } }
; template <class Epi, class Sched>
; __device__ __forceinline__ void gemm_phase(PG8_LAS unsigned char* lds, const Gemm g, const Sched& S, const Epi& E) {
;     ...
;         if (!has_next) break;
; #pragma unroll
;         for (int a = 0; a < 2; ++a)
; #pragma unroll
;             for (int b = 0; b < 2; ++b)
; #pragma unroll
;                 for (int m = 0; m < 4; ++m)
; #pragma unroll
;                     for (int n = 0; n < 2; ++n) acc[a][b][m][n] = (f32x4){0.f, 0.f, 0.f, 0.f};
;         cur = nxt; cA = nA; cB = nB; ++ui;
;     }
;     PG8_WAIT_V(0);
;     if (wr == 0) PG8_BAR;
;     PG8_BAR;
	s_nop 0
	v_lshlrev_b32_e32 v28, 16, v36
	v_and_b32_e32 v29, 0xffff0000, v36
	v_lshlrev_b32_e32 v30, 16, v37
	v_and_b32_e32 v31, 0xffff0000, v37
	v_lshlrev_b32_e32 v36, 16, v38
	v_and_b32_e32 v37, 0xffff0000, v38
	v_lshlrev_b32_e32 v38, 16, v39
	v_and_b32_e32 v39, 0xffff0000, v39
	v_mul_f32_e32 v28, v32, v28
	v_mul_f32_e32 v29, v33, v29
	v_mul_f32_e32 v30, v34, v30
	v_mul_f32_e32 v31, v35, v31
	v_mul_f32_e32 v27, v27, v39
	v_mul_f32_e32 v32, v24, v36
	v_mul_f32_e32 v33, v25, v37
	v_mul_f32_e32 v34, v26, v38
	v_cvt_pk_bf16_f32 v24, v28, v29
	v_cvt_pk_bf16_f32 v25, v30, v31
	v_cvt_pk_bf16_f32 v26, v32, v33
	v_cvt_pk_bf16_f32 v27, v34, v27
	global_load_dwordx4 v[28:31], v[50:51], off offset:3328
	v_lshlrev_b64 v[36:37], 11, v[48:49]
	v_lshl_add_u64 v[36:37], s[0:1], 0, v[36:37]
	v_add_u32_e32 v32, 0xb0, v146
	v_lshl_add_u64 v[36:37], v[36:37], 0, v[144:145]
	v_mad_i64_i32 v[34:35], s[18:19], v32, s41, v[148:149]
	global_store_dwordx4 v[36:37], v[24:27], off
	v_lshl_add_u64 v[34:35], v[34:35], 0, v[144:145]
	v_ashrrev_i32_e32 v33, 31, v32
	s_mov_b64 s[18:19], s[12:13]
	s_waitcnt vmcnt(0)
	v_lshlrev_b32_e32 v24, 16, v28
	v_and_b32_e32 v25, 0xffff0000, v28
	v_lshlrev_b32_e32 v26, 16, v29
	v_and_b32_e32 v27, 0xffff0000, v29
	v_lshlrev_b32_e32 v28, 16, v30
	v_and_b32_e32 v29, 0xffff0000, v30
	v_lshlrev_b32_e32 v30, 16, v31
	v_and_b32_e32 v31, 0xffff0000, v31
	v_mul_f32_e32 v20, v20, v24
	v_mul_f32_e32 v21, v21, v25
	v_mul_f32_e32 v22, v22, v26
	v_mul_f32_e32 v23, v23, v27
	v_mul_f32_e32 v15, v15, v31
	v_mul_f32_e32 v24, v12, v28
	v_mul_f32_e32 v25, v13, v29
	v_mul_f32_e32 v26, v14, v30
	v_cvt_pk_bf16_f32 v12, v20, v21
	v_cvt_pk_bf16_f32 v13, v22, v23
	v_cvt_pk_bf16_f32 v14, v24, v25
	v_cvt_pk_bf16_f32 v15, v26, v15
	global_load_dwordx4 v[20:23], v[34:35], off offset:3072
	s_nop 0
	global_store_dwordx4 v[36:37], v[12:15], off offset:256
	s_waitcnt vmcnt(0)
	s_nop 0
	v_lshlrev_b32_e32 v12, 16, v20
	v_and_b32_e32 v13, 0xffff0000, v20
	v_lshlrev_b32_e32 v14, 16, v21
	v_and_b32_e32 v15, 0xffff0000, v21
	v_lshlrev_b32_e32 v20, 16, v22
	v_and_b32_e32 v21, 0xffff0000, v22
	v_lshlrev_b32_e32 v22, 16, v23
	v_and_b32_e32 v23, 0xffff0000, v23
	v_mul_f32_e32 v12, v16, v12
	v_mul_f32_e32 v13, v17, v13
	v_mul_f32_e32 v14, v18, v14
	v_mul_f32_e32 v15, v19, v15
	v_mul_f32_e32 v11, v11, v23
	v_mul_f32_e32 v16, v8, v20
	v_mul_f32_e32 v17, v9, v21
	v_mul_f32_e32 v18, v10, v22
	v_cvt_pk_bf16_f32 v8, v12, v13
	v_cvt_pk_bf16_f32 v9, v14, v15
	v_cvt_pk_bf16_f32 v10, v16, v17
	v_cvt_pk_bf16_f32 v11, v18, v11
	global_load_dwordx4 v[12:15], v[34:35], off offset:3328
	v_lshlrev_b64 v[16:17], 11, v[32:33]
	v_lshl_add_u64 v[16:17], s[0:1], 0, v[16:17]
	v_lshl_add_u64 v[16:17], v[16:17], 0, v[144:145]
	global_store_dwordx4 v[16:17], v[8:11], off
	s_waitcnt vmcnt(0)
	s_nop 0
	v_lshlrev_b32_e32 v8, 16, v12
	v_and_b32_e32 v9, 0xffff0000, v12
	v_lshlrev_b32_e32 v10, 16, v13
	v_and_b32_e32 v11, 0xffff0000, v13
	v_lshlrev_b32_e32 v12, 16, v14
	v_and_b32_e32 v13, 0xffff0000, v14
	v_lshlrev_b32_e32 v14, 16, v15
	v_and_b32_e32 v15, 0xffff0000, v15
	v_mul_f32_e32 v3, v3, v15
	v_mul_f32_e32 v4, v4, v8
	v_mul_f32_e32 v5, v5, v9
	v_mul_f32_e32 v6, v6, v10
	v_mul_f32_e32 v7, v7, v11
	v_mul_f32_e32 v8, v0, v12
	v_mul_f32_e32 v9, v1, v13
	v_mul_f32_e32 v10, v2, v14
	v_cvt_pk_bf16_f32 v0, v4, v5
	v_cvt_pk_bf16_f32 v1, v6, v7
	v_cvt_pk_bf16_f32 v2, v8, v9
	v_cvt_pk_bf16_f32 v3, v10, v3
	global_store_dwordx4 v[16:17], v[0:3], off offset:256
	s_cbranch_vccz .LBB0_984
	s_waitcnt vmcnt(0)
	s_cmpk_gt_u32 s25, 0xff
	s_cbranch_scc1 .LBB0_995
	s_barrier

; #define PG8_STAGE(bufoff, gbase, voff) do { _Pragma("unroll") for (int _i = 0; _i < 2; ++_i) \
;         __builtin_amdgcn_global_load_lds((const unsigned*)((const char*)(gbase) + (voff)[_i]), (PG8_LAS unsigned*)(lds + (bufoff) + ldsw + _i * 8192), 16, 0, 0); } while (0)
; #define PG8_LDA(dst, b, h) do { _Pragma("unroll") for (int m = 0; m < 4; ++m) _Pragma("unroll") for (int k = 0; k < 2; ++k) dst[m][k] = *(const PG8_LAS bf16x8*)(lds + PG8_SA(b, h) + aoff + m * 2048 + k * 1024); } while (0)
; #define PG8_LDB(dst, b, h) do { _Pragma("unroll") for (int n = 0; n < 2; ++n) _Pragma("unroll") for (int k = 0; k < 2; ++k) dst[n][k] = *(const PG8_LAS bf16x8*)(lds + PG8_SB(b, h) + boff + n * 2048 + k * 1024); } while (0)
; #define PG8_WAIT_V(n) asm volatile("s_waitcnt vmcnt(" #n ")" ::: "memory")
; #define PG8_WAIT_L(n) asm volatile("s_waitcnt lgkmcnt(" #n ")" ::: "memory")
; #define PG8_BAR __builtin_amdgcn_s_barrier()
; #define PG8_SCHED __builtin_amdgcn_sched_barrier(0)
; template <class Epi, class Sched>
; __device__ __forceinline__ void gemm_phase(PG8_LAS unsigned char* lds, const Gemm g, const Sched& S, const Epi& E) {
;     ...
;         const bool has_next = S.next(ui + 1, nxt);
;         const char* nA = has_next ? (const char*)g.A + (size_t)nxt.pm * tstep : cA; const char* nB = has_next ? (const char*)g.Bt + (size_t)nxt.pn * tstep : cB;
;         for (int t = 0; t < nt; t += 2) {
;             const bool last = (t == nt - 2);
;             const char* a1 = cA + (size_t)(t + 1) * kstep;
;             const char* a2 = last ? nA : cA + (size_t)(t + 2) * kstep; const char* b2 = last ? nB : cB + (size_t)(t + 2) * kstep;
;             const char* a3 = a2 + kstep; const char* b3 = b2 + kstep;
;             if (last && has_next) S.a_ready(nxt);
;             PG8_LDB(B0, 0, 0); PG8_SCHED; PG8_LDA(At, 0, 0); PG8_STAGE(PG8_SA(1, 1), a1 + hstep, voffA);
;             PG8_WAIT_L(8); PG8_BAR; PG8_WAIT_L(0); PG8_MMA(0, 0, At, B0); PG8_BAR; PG8_SCHED;
;             PG8_LDB(B1, 0, 1); PG8_STAGE(PG8_SB(0, 0), b2, voffB);
;             PG8_BAR; PG8_WAIT_L(0); PG8_MMA(0, 1, At, B1); PG8_BAR;
;             PG8_LDA(At, 0, 1); PG8_STAGE(PG8_SA(0, 0), a2, voffA);
;             PG8_BAR; PG8_WAIT_L(0); PG8_MMA(1, 0, At, B0); PG8_BAR; PG8_SCHED;
;             PG8_STAGE(PG8_SB(0, 1), b2 + hstep, voffB);
;             PG8_WAIT_V(6); PG8_BAR; PG8_MMA(1, 1, At, B1); PG8_BAR;
.LBB0_1010:
	s_ashr_i32 s11, s10, 31
	v_cmp_lt_i64_e32 vcc, s[12:13], v[140:141]
	s_lshl_b64 s[12:13], s[10:11], 19
	s_add_u32 s12, s27, s12
	s_addc_u32 s13, s28, s13
	s_and_b64 s[14:15], vcc, exec
	s_cselect_b32 s11, s13, s19
	s_cselect_b32 s43, s12, s18
	s_ashr_i32 s9, s8, 31
	s_lshl_b64 s[14:15], s[8:9], 19
	s_add_u32 s14, s94, s14
	s_addc_u32 s15, s95, s15
	s_and_b64 s[22:23], vcc, exec
	s_cselect_b32 s9, s15, s21
	s_cselect_b32 s44, s14, s20
	s_add_u32 s18, s18, 0x40080
	s_addc_u32 s19, s19, 0
	s_add_u32 s45, s20, 0x100
	s_addc_u32 s46, s21, 0
	s_mov_b32 s47, -2
	ds_read_b128 v[144:147], v153
	ds_read_b128 v[156:159], v153 offset:1024
	ds_read_b128 v[160:163], v153 offset:2048
	ds_read_b128 v[164:167], v153 offset:3072
	s_add_u32 s20, s18, 0xfffc0080
	s_addc_u32 s21, s19, -1
	s_cmp_eq_u32 s47, 12
	s_cselect_b32 s23, s11, s21
	s_cselect_b32 s22, s43, s20
	s_cselect_b32 s21, s9, s46
	s_cselect_b32 s20, s44, s45
	s_add_i32 m0, s17, 0xc000
	ds_read_b128 v[168:171], v154
	ds_read_b128 v[172:175], v154 offset:1024
	ds_read_b128 v[182:185], v154 offset:2048
	ds_read_b128 v[190:193], v154 offset:3072
	ds_read_b128 v[194:197], v154 offset:4096
	ds_read_b128 v[198:201], v154 offset:5120
	ds_read_b128 v[202:205], v154 offset:6144
	ds_read_b128 v[206:209], v154 offset:7168
	global_load_lds_dwordx4 v136, s[18:19]
	s_nop 1
	s_add_i32 m0, s17, 0xe000
	s_nop 0
	global_load_lds_dwordx4 v138, s[18:19]
	s_waitcnt lgkmcnt(8)
	ds_read_b128 v[210:213], v155
	ds_read_b128 v[214:217], v155 offset:1024
	ds_read_b128 v[218:221], v155 offset:2048
	ds_read_b128 v[222:225], v155 offset:3072
	s_waitcnt vmcnt(8) lgkmcnt(0)
	s_barrier
	v_mfma_f32_16x16x32_bf16 v[124:127], v[144:147], v[168:171], 0
	v_mfma_f32_16x16x32_bf16 v[120:123], v[160:163], v[168:171], 0
	v_mfma_f32_16x16x32_bf16 v[108:111], v[144:147], v[182:185], 0
	v_mfma_f32_16x16x32_bf16 v[104:107], v[160:163], v[182:185], 0
	v_mfma_f32_16x16x32_bf16 v[92:95], v[144:147], v[194:197], 0
	v_mfma_f32_16x16x32_bf16 v[88:91], v[160:163], v[194:197], 0
	v_mfma_f32_16x16x32_bf16 v[76:79], v[144:147], v[202:205], 0
	v_mfma_f32_16x16x32_bf16 v[72:75], v[160:163], v[202:205], 0
	v_mfma_f32_16x16x32_bf16 v[124:127], v[156:159], v[172:175], v[124:127]
	v_mfma_f32_16x16x32_bf16 v[120:123], v[164:167], v[172:175], v[120:123]
	v_mfma_f32_16x16x32_bf16 v[108:111], v[156:159], v[190:193], v[108:111]
	v_mfma_f32_16x16x32_bf16 v[104:107], v[164:167], v[190:193], v[104:107]
	v_mfma_f32_16x16x32_bf16 v[92:95], v[156:159], v[198:201], v[92:95]
	v_mfma_f32_16x16x32_bf16 v[88:91], v[164:167], v[198:201], v[88:91]
	v_mfma_f32_16x16x32_bf16 v[76:79], v[156:159], v[206:209], v[76:79]
	v_mfma_f32_16x16x32_bf16 v[72:75], v[164:167], v[206:209], v[72:75]
	v_mfma_f32_16x16x32_bf16 v[116:119], v[210:213], v[168:171], 0
	v_mfma_f32_16x16x32_bf16 v[112:115], v[218:221], v[168:171], 0
	v_mfma_f32_16x16x32_bf16 v[100:103], v[210:213], v[182:185], 0
	v_mfma_f32_16x16x32_bf16 v[96:99], v[218:221], v[182:185], 0
	v_mfma_f32_16x16x32_bf16 v[84:87], v[210:213], v[194:197], 0
	v_mfma_f32_16x16x32_bf16 v[80:83], v[218:221], v[194:197], 0
	v_mfma_f32_16x16x32_bf16 v[68:71], v[210:213], v[202:205], 0
	v_mfma_f32_16x16x32_bf16 v[64:67], v[218:221], v[202:205], 0
	v_mfma_f32_16x16x32_bf16 v[116:119], v[214:217], v[172:175], v[116:119]
	v_mfma_f32_16x16x32_bf16 v[112:115], v[222:225], v[172:175], v[112:115]
	v_mfma_f32_16x16x32_bf16 v[100:103], v[214:217], v[190:193], v[100:103]
	v_mfma_f32_16x16x32_bf16 v[96:99], v[222:225], v[190:193], v[96:99]
	v_mfma_f32_16x16x32_bf16 v[84:87], v[214:217], v[198:201], v[84:87]
	v_mfma_f32_16x16x32_bf16 v[80:83], v[222:225], v[198:201], v[80:83]
	v_mfma_f32_16x16x32_bf16 v[68:71], v[214:217], v[206:209], v[68:71]
	v_mfma_f32_16x16x32_bf16 v[64:67], v[222:225], v[206:209], v[64:67]
	s_barrier
	ds_read_b128 v[168:171], v154 offset:16384
	ds_read_b128 v[172:175], v154 offset:17408
	ds_read_b128 v[182:185], v154 offset:18432
	ds_read_b128 v[190:193], v154 offset:19456
	ds_read_b128 v[194:197], v154 offset:20480
	ds_read_b128 v[198:201], v154 offset:21504
	ds_read_b128 v[202:205], v154 offset:22528
	ds_read_b128 v[206:209], v154 offset:23552
	s_add_i32 s48, s39, s29
	s_add_u32 s98, s20, s6
	s_addc_u32 s99, s21, s7
	s_mov_b32 m0, s48
	s_nop 0
	global_load_lds_dwordx4 v130, s[20:21]
	s_nop 1
	s_add_i32 m0, s48, 0x2000
	s_nop 0
	global_load_lds_dwordx4 v134, s[20:21]
	s_nop 1
	s_mov_b32 m0, s17
	s_add_u32 s100, s22, s6
	s_addc_u32 s101, s23, s7
	global_load_lds_dwordx4 v128, s[22:23]
	s_nop 1
	s_mov_b32 m0, s30
	s_nop 0
	global_load_lds_dwordx4 v132, s[22:23]
	s_add_u32 s48, s20, 0x40000
	s_addc_u32 s49, s21, 0
	s_add_i32 s50, s40, s29
	s_mov_b32 m0, s50
	s_nop 0
	global_load_lds_dwordx4 v130, s[48:49]
	s_nop 1
	s_add_i32 m0, s50, 0x2000
	s_nop 0
	global_load_lds_dwordx4 v134, s[48:49]
	s_waitcnt vmcnt(8) lgkmcnt(0)
	s_barrier
; #define PG8_STAGE(bufoff, gbase, voff) do { _Pragma("unroll") for (int _i = 0; _i < 2; ++_i) \
;         __builtin_amdgcn_global_load_lds((const unsigned*)((const char*)(gbase) + (voff)[_i]), (PG8_LAS unsigned*)(lds + (bufoff) + ldsw + _i * 8192), 16, 0, 0); } while (0)
; #define PG8_LDA(dst, b, h) do { _Pragma("unroll") for (int m = 0; m < 4; ++m) _Pragma("unroll") for (int k = 0; k < 2; ++k) dst[m][k] = *(const PG8_LAS bf16x8*)(lds + PG8_SA(b, h) + aoff + m * 2048 + k * 1024); } while (0)
; #define PG8_LDB(dst, b, h) do { _Pragma("unroll") for (int n = 0; n < 2; ++n) _Pragma("unroll") for (int k = 0; k < 2; ++k) dst[n][k] = *(const PG8_LAS bf16x8*)(lds + PG8_SB(b, h) + boff + n * 2048 + k * 1024); } while (0)
; template <class Epi, class Sched>
; __device__ __forceinline__ void gemm_phase(PG8_LAS unsigned char* lds, const Gemm g, const Sched& S, const Epi& E) {
;     ...
;         for (int t = 0; t < nt; t += 2) {
;             const bool last = (t == nt - 2);
;             const char* a1 = cA + (size_t)(t + 1) * kstep;
;             const char* a2 = last ? nA : cA + (size_t)(t + 2) * kstep; const char* b2 = last ? nB : cB + (size_t)(t + 2) * kstep;
;             const char* a3 = a2 + kstep; const char* b3 = b2 + kstep;
;             if (last && has_next) S.a_ready(nxt);
;             PG8_LDB(B0, 0, 0); PG8_SCHED; PG8_LDA(At, 0, 0); PG8_STAGE(PG8_SA(1, 1), a1 + hstep, voffA);
;             PG8_WAIT_L(8); PG8_BAR; PG8_WAIT_L(0); PG8_MMA(0, 0, At, B0); PG8_BAR; PG8_SCHED;
;             PG8_LDB(B1, 0, 1); PG8_STAGE(PG8_SB(0, 0), b2, voffB);
;             PG8_BAR; PG8_WAIT_L(0); PG8_MMA(0, 1, At, B1); PG8_BAR;
;             PG8_LDA(At, 0, 1); PG8_STAGE(PG8_SA(0, 0), a2, voffA);
;             PG8_BAR; PG8_WAIT_L(0); PG8_MMA(1, 0, At, B0); PG8_BAR; PG8_SCHED;
;             PG8_STAGE(PG8_SB(0, 1), b2 + hstep, voffB);
;             PG8_WAIT_V(6); PG8_BAR; PG8_MMA(1, 1, At, B1); PG8_BAR;
;             PG8_LDB(B0, 1, 0); PG8_SCHED; PG8_LDA(At, 1, 0); PG8_STAGE(PG8_SA(0, 1), a2 + hstep, voffA);
;             PG8_WAIT_L(8); PG8_BAR; PG8_WAIT_L(0); PG8_MMA(0, 0, At, B0); PG8_BAR; PG8_SCHED;
;             PG8_LDB(B1, 1, 1); PG8_STAGE(PG8_SB(1, 0), b3, voffB);
;             PG8_BAR; PG8_WAIT_L(0); PG8_MMA(0, 1, At, B1); PG8_BAR;
;             PG8_LDA(At, 1, 1); PG8_STAGE(PG8_SA(1, 0), a3, voffA);
;             PG8_BAR; PG8_WAIT_L(0); PG8_MMA(1, 0, At, B0); PG8_BAR; PG8_SCHED;
	v_mfma_f32_16x16x32_bf16 v[60:63], v[144:147], v[168:171], 0
	v_mfma_f32_16x16x32_bf16 v[56:59], v[160:163], v[168:171], 0
	v_mfma_f32_16x16x32_bf16 v[44:47], v[144:147], v[182:185], 0
	v_mfma_f32_16x16x32_bf16 v[40:43], v[160:163], v[182:185], 0
	v_mfma_f32_16x16x32_bf16 v[28:31], v[144:147], v[194:197], 0
	v_mfma_f32_16x16x32_bf16 v[24:27], v[160:163], v[194:197], 0
	v_mfma_f32_16x16x32_bf16 v[12:15], v[144:147], v[202:205], 0
	v_mfma_f32_16x16x32_bf16 v[8:11], v[160:163], v[202:205], 0
	v_mfma_f32_16x16x32_bf16 v[60:63], v[156:159], v[172:175], v[60:63]
	v_mfma_f32_16x16x32_bf16 v[56:59], v[164:167], v[172:175], v[56:59]
	v_mfma_f32_16x16x32_bf16 v[44:47], v[156:159], v[190:193], v[44:47]
	v_mfma_f32_16x16x32_bf16 v[40:43], v[164:167], v[190:193], v[40:43]
	v_mfma_f32_16x16x32_bf16 v[28:31], v[156:159], v[198:201], v[28:31]
	v_mfma_f32_16x16x32_bf16 v[24:27], v[164:167], v[198:201], v[24:27]
	v_mfma_f32_16x16x32_bf16 v[12:15], v[156:159], v[206:209], v[12:15]
	v_mfma_f32_16x16x32_bf16 v[8:11], v[164:167], v[206:209], v[8:11]
	v_mfma_f32_16x16x32_bf16 v[52:55], v[210:213], v[168:171], 0
	v_mfma_f32_16x16x32_bf16 v[48:51], v[218:221], v[168:171], 0
	v_mfma_f32_16x16x32_bf16 v[36:39], v[210:213], v[182:185], 0
	v_mfma_f32_16x16x32_bf16 v[32:35], v[218:221], v[182:185], 0
	v_mfma_f32_16x16x32_bf16 v[20:23], v[210:213], v[194:197], 0
	v_mfma_f32_16x16x32_bf16 v[16:19], v[218:221], v[194:197], 0
	v_mfma_f32_16x16x32_bf16 v[4:7], v[210:213], v[202:205], 0
	v_mfma_f32_16x16x32_bf16 v[0:3], v[218:221], v[202:205], 0
	v_mfma_f32_16x16x32_bf16 v[52:55], v[214:217], v[172:175], v[52:55]
	v_mfma_f32_16x16x32_bf16 v[48:51], v[222:225], v[172:175], v[48:51]
	v_mfma_f32_16x16x32_bf16 v[36:39], v[214:217], v[190:193], v[36:39]
	v_mfma_f32_16x16x32_bf16 v[32:35], v[222:225], v[190:193], v[32:35]
	v_mfma_f32_16x16x32_bf16 v[20:23], v[214:217], v[198:201], v[20:23]
	v_mfma_f32_16x16x32_bf16 v[16:19], v[222:225], v[198:201], v[16:19]
	v_mfma_f32_16x16x32_bf16 v[4:7], v[214:217], v[206:209], v[4:7]
	v_mfma_f32_16x16x32_bf16 v[0:3], v[222:225], v[206:209], v[0:3]
	s_barrier
	s_add_i32 s48, 0, 0x18000
	v_add_u32_e32 v164, s48, v151
	ds_read_b128 v[144:147], v164
	ds_read_b128 v[156:159], v164 offset:1024
	ds_read_b128 v[160:163], v164 offset:2048
	ds_read_b128 v[164:167], v164 offset:3072
	s_add_u32 s22, s22, 0x40000
	s_addc_u32 s23, s23, 0
	s_mov_b32 m0, s31
	ds_read_b128 v[168:171], v154 offset:32768
	ds_read_b128 v[172:175], v154 offset:33792
	ds_read_b128 v[182:185], v154 offset:34816
	ds_read_b128 v[190:193], v154 offset:35840
	ds_read_b128 v[194:197], v154 offset:36864
	ds_read_b128 v[198:201], v154 offset:37888
	ds_read_b128 v[202:205], v154 offset:38912
	ds_read_b128 v[206:209], v154 offset:39936
	global_load_lds_dwordx4 v128, s[22:23]
	s_nop 1
	s_mov_b32 m0, s34
	s_nop 0
	global_load_lds_dwordx4 v132, s[22:23]
	s_add_i32 s22, 0, 0x1c000
	v_add_u32_e32 v179, s22, v151
	s_waitcnt lgkmcnt(8)
	ds_read_b128 v[210:213], v179
	ds_read_b128 v[214:217], v179 offset:1024
	ds_read_b128 v[218:221], v179 offset:2048
	ds_read_b128 v[222:225], v179 offset:3072
	s_waitcnt vmcnt(8) lgkmcnt(0)
	s_barrier
	v_mfma_f32_16x16x32_bf16 v[124:127], v[144:147], v[168:171], v[124:127]
	v_mfma_f32_16x16x32_bf16 v[120:123], v[160:163], v[168:171], v[120:123]
	v_mfma_f32_16x16x32_bf16 v[108:111], v[144:147], v[182:185], v[108:111]
	v_mfma_f32_16x16x32_bf16 v[104:107], v[160:163], v[182:185], v[104:107]
	v_mfma_f32_16x16x32_bf16 v[92:95], v[144:147], v[194:197], v[92:95]
	v_mfma_f32_16x16x32_bf16 v[88:91], v[160:163], v[194:197], v[88:91]
	v_mfma_f32_16x16x32_bf16 v[76:79], v[144:147], v[202:205], v[76:79]
	v_mfma_f32_16x16x32_bf16 v[72:75], v[160:163], v[202:205], v[72:75]
	v_mfma_f32_16x16x32_bf16 v[124:127], v[156:159], v[172:175], v[124:127]
	v_mfma_f32_16x16x32_bf16 v[120:123], v[164:167], v[172:175], v[120:123]
	v_mfma_f32_16x16x32_bf16 v[108:111], v[156:159], v[190:193], v[108:111]
	v_mfma_f32_16x16x32_bf16 v[104:107], v[164:167], v[190:193], v[104:107]
	v_mfma_f32_16x16x32_bf16 v[92:95], v[156:159], v[198:201], v[92:95]
	v_mfma_f32_16x16x32_bf16 v[88:91], v[164:167], v[198:201], v[88:91]
	v_mfma_f32_16x16x32_bf16 v[76:79], v[156:159], v[206:209], v[76:79]
	v_mfma_f32_16x16x32_bf16 v[72:75], v[164:167], v[206:209], v[72:75]
	v_mfma_f32_16x16x32_bf16 v[116:119], v[210:213], v[168:171], v[116:119]
	v_mfma_f32_16x16x32_bf16 v[112:115], v[218:221], v[168:171], v[112:115]
	v_mfma_f32_16x16x32_bf16 v[100:103], v[210:213], v[182:185], v[100:103]
	v_mfma_f32_16x16x32_bf16 v[96:99], v[218:221], v[182:185], v[96:99]
	v_mfma_f32_16x16x32_bf16 v[84:87], v[210:213], v[194:197], v[84:87]
	v_mfma_f32_16x16x32_bf16 v[80:83], v[218:221], v[194:197], v[80:83]
	v_mfma_f32_16x16x32_bf16 v[68:71], v[210:213], v[202:205], v[68:71]
	v_mfma_f32_16x16x32_bf16 v[64:67], v[218:221], v[202:205], v[64:67]
	v_mfma_f32_16x16x32_bf16 v[116:119], v[214:217], v[172:175], v[116:119]
	v_mfma_f32_16x16x32_bf16 v[112:115], v[222:225], v[172:175], v[112:115]
	v_mfma_f32_16x16x32_bf16 v[100:103], v[214:217], v[190:193], v[100:103]
	v_mfma_f32_16x16x32_bf16 v[96:99], v[222:225], v[190:193], v[96:99]
	v_mfma_f32_16x16x32_bf16 v[84:87], v[214:217], v[198:201], v[84:87]
	v_mfma_f32_16x16x32_bf16 v[80:83], v[222:225], v[198:201], v[80:83]
	v_mfma_f32_16x16x32_bf16 v[68:71], v[214:217], v[206:209], v[68:71]
	v_mfma_f32_16x16x32_bf16 v[64:67], v[222:225], v[206:209], v[64:67]
	s_barrier
; #define PG8_STAGE(bufoff, gbase, voff) do { _Pragma("unroll") for (int _i = 0; _i < 2; ++_i) \
;         __builtin_amdgcn_global_load_lds((const unsigned*)((const char*)(gbase) + (voff)[_i]), (PG8_LAS unsigned*)(lds + (bufoff) + ldsw + _i * 8192), 16, 0, 0); } while (0)
; #define PG8_LDA(dst, b, h) do { _Pragma("unroll") for (int m = 0; m < 4; ++m) _Pragma("unroll") for (int k = 0; k < 2; ++k) dst[m][k] = *(const PG8_LAS bf16x8*)(lds + PG8_SA(b, h) + aoff + m * 2048 + k * 1024); } while (0)
; #define PG8_WAIT_V(n) asm volatile("s_waitcnt vmcnt(" #n ")" ::: "memory")
; template <class Epi, class Sched>
; __device__ __forceinline__ void gemm_phase(PG8_LAS unsigned char* lds, const Gemm g, const Sched& S, const Epi& E) {
;     ...
;         for (int t = 0; t < nt; t += 2) {
;             const bool last = (t == nt - 2);
;             const char* a1 = cA + (size_t)(t + 1) * kstep;
;             const char* a2 = last ? nA : cA + (size_t)(t + 2) * kstep; const char* b2 = last ? nB : cB + (size_t)(t + 2) * kstep;
;             const char* a3 = a2 + kstep; const char* b3 = b2 + kstep;
;             if (last && has_next) S.a_ready(nxt);
;             PG8_LDB(B0, 0, 0); PG8_SCHED; PG8_LDA(At, 0, 0); PG8_STAGE(PG8_SA(1, 1), a1 + hstep, voffA);
;             PG8_WAIT_L(8); PG8_BAR; PG8_WAIT_L(0); PG8_MMA(0, 0, At, B0); PG8_BAR; PG8_SCHED;
;             PG8_LDB(B1, 0, 1); PG8_STAGE(PG8_SB(0, 0), b2, voffB);
;             PG8_BAR; PG8_WAIT_L(0); PG8_MMA(0, 1, At, B1); PG8_BAR;
;             PG8_LDA(At, 0, 1); PG8_STAGE(PG8_SA(0, 0), a2, voffA);
;             PG8_BAR; PG8_WAIT_L(0); PG8_MMA(1, 0, At, B0); PG8_BAR; PG8_SCHED;
;             PG8_STAGE(PG8_SB(0, 1), b2 + hstep, voffB);
;             PG8_WAIT_V(6); PG8_BAR; PG8_MMA(1, 1, At, B1); PG8_BAR;
;             PG8_LDB(B0, 1, 0); PG8_SCHED; PG8_LDA(At, 1, 0); PG8_STAGE(PG8_SA(0, 1), a2 + hstep, voffA);
;             PG8_WAIT_L(8); PG8_BAR; PG8_WAIT_L(0); PG8_MMA(0, 0, At, B0); PG8_BAR; PG8_SCHED;
;             PG8_LDB(B1, 1, 1); PG8_STAGE(PG8_SB(1, 0), b3, voffB);
;             PG8_BAR; PG8_WAIT_L(0); PG8_MMA(0, 1, At, B1); PG8_BAR;
;             PG8_LDA(At, 1, 1); PG8_STAGE(PG8_SA(1, 0), a3, voffA);
;             PG8_BAR; PG8_WAIT_L(0); PG8_MMA(1, 0, At, B0); PG8_BAR; PG8_SCHED;
;             PG8_STAGE(PG8_SB(1, 1), b3 + hstep, voffB);
;             PG8_WAIT_V(6); PG8_BAR; PG8_MMA(1, 1, At, B1); PG8_BAR;
	ds_read_b128 v[168:171], v154 offset:49152
	ds_read_b128 v[172:175], v154 offset:50176
	ds_read_b128 v[182:185], v154 offset:51200
	ds_read_b128 v[190:193], v154 offset:52224
	ds_read_b128 v[194:197], v154 offset:53248
	ds_read_b128 v[198:201], v154 offset:54272
	ds_read_b128 v[202:205], v154 offset:55296
	ds_read_b128 v[206:209], v154 offset:56320
	s_add_i32 s23, s48, s29
	s_mov_b32 m0, s23
	s_nop 0
	global_load_lds_dwordx4 v130, s[98:99]
	s_nop 1
	s_add_i32 m0, s23, 0x2000
	s_nop 0
	global_load_lds_dwordx4 v134, s[98:99]
	s_nop 1
	s_mov_b32 m0, s36
	s_nop 0
	global_load_lds_dwordx4 v128, s[100:101]
	s_nop 1
	s_mov_b32 m0, s37
	s_nop 0
	global_load_lds_dwordx4 v132, s[100:101]
	s_add_u32 s20, s20, 0x40080
	s_addc_u32 s21, s21, 0
	s_add_i32 s22, s22, s29
	s_mov_b32 m0, s22
	s_nop 0
	global_load_lds_dwordx4 v130, s[20:21]
	s_nop 1
	s_add_i32 m0, s22, 0x2000
	s_nop 0
	global_load_lds_dwordx4 v134, s[20:21]
	s_waitcnt vmcnt(8) lgkmcnt(0)
	s_barrier
	v_mfma_f32_16x16x32_bf16 v[60:63], v[144:147], v[168:171], v[60:63]
	v_mfma_f32_16x16x32_bf16 v[56:59], v[160:163], v[168:171], v[56:59]
	v_mfma_f32_16x16x32_bf16 v[44:47], v[144:147], v[182:185], v[44:47]
	v_mfma_f32_16x16x32_bf16 v[40:43], v[160:163], v[182:185], v[40:43]
	v_mfma_f32_16x16x32_bf16 v[28:31], v[144:147], v[194:197], v[28:31]
	v_mfma_f32_16x16x32_bf16 v[24:27], v[160:163], v[194:197], v[24:27]
	v_mfma_f32_16x16x32_bf16 v[12:15], v[144:147], v[202:205], v[12:15]
	v_mfma_f32_16x16x32_bf16 v[8:11], v[160:163], v[202:205], v[8:11]
	v_mfma_f32_16x16x32_bf16 v[60:63], v[156:159], v[172:175], v[60:63]
	v_mfma_f32_16x16x32_bf16 v[56:59], v[164:167], v[172:175], v[56:59]
	v_mfma_f32_16x16x32_bf16 v[44:47], v[156:159], v[190:193], v[44:47]
	v_mfma_f32_16x16x32_bf16 v[40:43], v[164:167], v[190:193], v[40:43]
	v_mfma_f32_16x16x32_bf16 v[28:31], v[156:159], v[198:201], v[28:31]
	v_mfma_f32_16x16x32_bf16 v[24:27], v[164:167], v[198:201], v[24:27]
	v_mfma_f32_16x16x32_bf16 v[12:15], v[156:159], v[206:209], v[12:15]
	v_mfma_f32_16x16x32_bf16 v[8:11], v[164:167], v[206:209], v[8:11]
	v_mfma_f32_16x16x32_bf16 v[52:55], v[210:213], v[168:171], v[52:55]
	v_mfma_f32_16x16x32_bf16 v[48:51], v[218:221], v[168:171], v[48:51]
	v_mfma_f32_16x16x32_bf16 v[36:39], v[210:213], v[182:185], v[36:39]
	v_mfma_f32_16x16x32_bf16 v[32:35], v[218:221], v[182:185], v[32:35]
	v_mfma_f32_16x16x32_bf16 v[20:23], v[210:213], v[194:197], v[20:23]
	v_mfma_f32_16x16x32_bf16 v[16:19], v[218:221], v[194:197], v[16:19]
	v_mfma_f32_16x16x32_bf16 v[4:7], v[210:213], v[202:205], v[4:7]
	v_mfma_f32_16x16x32_bf16 v[0:3], v[218:221], v[202:205], v[0:3]
	v_mfma_f32_16x16x32_bf16 v[52:55], v[214:217], v[172:175], v[52:55]
	v_mfma_f32_16x16x32_bf16 v[48:51], v[222:225], v[172:175], v[48:51]
	v_mfma_f32_16x16x32_bf16 v[36:39], v[214:217], v[190:193], v[36:39]
	v_mfma_f32_16x16x32_bf16 v[32:35], v[222:225], v[190:193], v[32:35]
	v_mfma_f32_16x16x32_bf16 v[20:23], v[214:217], v[198:201], v[20:23]
	v_mfma_f32_16x16x32_bf16 v[16:19], v[222:225], v[198:201], v[16:19]
	v_mfma_f32_16x16x32_bf16 v[4:7], v[214:217], v[206:209], v[4:7]
	v_mfma_f32_16x16x32_bf16 v[0:3], v[222:225], v[206:209], v[0:3]
	s_barrier
	s_add_i32 s47, s47, 2
	s_add_u32 s18, s18, 0x100
	s_addc_u32 s19, s19, 0
	s_add_u32 s45, s45, 0x100
	s_addc_u32 s46, s46, 0
	s_cmp_gt_u32 s47, 13
.LBB0_1011:
	ds_read_b128 v[144:147], v153
	ds_read_b128 v[156:159], v153 offset:1024
	ds_read_b128 v[160:163], v153 offset:2048
	ds_read_b128 v[164:167], v153 offset:3072
	s_add_u32 s20, s18, 0xfffc0080
	s_addc_u32 s21, s19, -1
	s_cmp_eq_u32 s47, 12
	s_cselect_b32 s23, s11, s21
	s_cselect_b32 s22, s43, s20
	s_cselect_b32 s21, s9, s46
	s_cselect_b32 s20, s44, s45
	s_add_i32 m0, s17, 0xc000
	ds_read_b128 v[168:171], v154
	ds_read_b128 v[172:175], v154 offset:1024
	ds_read_b128 v[182:185], v154 offset:2048
	ds_read_b128 v[190:193], v154 offset:3072
	ds_read_b128 v[194:197], v154 offset:4096
	ds_read_b128 v[198:201], v154 offset:5120
	ds_read_b128 v[202:205], v154 offset:6144
	ds_read_b128 v[206:209], v154 offset:7168
	global_load_lds_dwordx4 v136, s[18:19]
	s_nop 1
	s_add_i32 m0, s17, 0xe000
	s_nop 0
	global_load_lds_dwordx4 v138, s[18:19]
	s_waitcnt lgkmcnt(8)
	ds_read_b128 v[210:213], v155
	ds_read_b128 v[214:217], v155 offset:1024
	ds_read_b128 v[218:221], v155 offset:2048
	ds_read_b128 v[222:225], v155 offset:3072
	s_waitcnt vmcnt(8) lgkmcnt(0)
	s_barrier
	v_mfma_f32_16x16x32_bf16 v[124:127], v[144:147], v[168:171], v[124:127]
	v_mfma_f32_16x16x32_bf16 v[120:123], v[160:163], v[168:171], v[120:123]
	v_mfma_f32_16x16x32_bf16 v[108:111], v[144:147], v[182:185], v[108:111]
	v_mfma_f32_16x16x32_bf16 v[104:107], v[160:163], v[182:185], v[104:107]
	v_mfma_f32_16x16x32_bf16 v[92:95], v[144:147], v[194:197], v[92:95]
	v_mfma_f32_16x16x32_bf16 v[88:91], v[160:163], v[194:197], v[88:91]
	v_mfma_f32_16x16x32_bf16 v[76:79], v[144:147], v[202:205], v[76:79]
	v_mfma_f32_16x16x32_bf16 v[72:75], v[160:163], v[202:205], v[72:75]
	v_mfma_f32_16x16x32_bf16 v[124:127], v[156:159], v[172:175], v[124:127]
	v_mfma_f32_16x16x32_bf16 v[120:123], v[164:167], v[172:175], v[120:123]
	v_mfma_f32_16x16x32_bf16 v[108:111], v[156:159], v[190:193], v[108:111]
	v_mfma_f32_16x16x32_bf16 v[104:107], v[164:167], v[190:193], v[104:107]
	v_mfma_f32_16x16x32_bf16 v[92:95], v[156:159], v[198:201], v[92:95]
	v_mfma_f32_16x16x32_bf16 v[88:91], v[164:167], v[198:201], v[88:91]
	v_mfma_f32_16x16x32_bf16 v[76:79], v[156:159], v[206:209], v[76:79]
	v_mfma_f32_16x16x32_bf16 v[72:75], v[164:167], v[206:209], v[72:75]
	v_mfma_f32_16x16x32_bf16 v[116:119], v[210:213], v[168:171], v[116:119]
	v_mfma_f32_16x16x32_bf16 v[112:115], v[218:221], v[168:171], v[112:115]
	v_mfma_f32_16x16x32_bf16 v[100:103], v[210:213], v[182:185], v[100:103]
	v_mfma_f32_16x16x32_bf16 v[96:99], v[218:221], v[182:185], v[96:99]
	v_mfma_f32_16x16x32_bf16 v[84:87], v[210:213], v[194:197], v[84:87]
	v_mfma_f32_16x16x32_bf16 v[80:83], v[218:221], v[194:197], v[80:83]
	v_mfma_f32_16x16x32_bf16 v[68:71], v[210:213], v[202:205], v[68:71]
	v_mfma_f32_16x16x32_bf16 v[64:67], v[218:221], v[202:205], v[64:67]
	v_mfma_f32_16x16x32_bf16 v[116:119], v[214:217], v[172:175], v[116:119]
	v_mfma_f32_16x16x32_bf16 v[112:115], v[222:225], v[172:175], v[112:115]
	v_mfma_f32_16x16x32_bf16 v[100:103], v[214:217], v[190:193], v[100:103]
	v_mfma_f32_16x16x32_bf16 v[96:99], v[222:225], v[190:193], v[96:99]
	v_mfma_f32_16x16x32_bf16 v[84:87], v[214:217], v[198:201], v[84:87]
	v_mfma_f32_16x16x32_bf16 v[80:83], v[222:225], v[198:201], v[80:83]
	v_mfma_f32_16x16x32_bf16 v[68:71], v[214:217], v[206:209], v[68:71]
	v_mfma_f32_16x16x32_bf16 v[64:67], v[222:225], v[206:209], v[64:67]
	s_barrier
; #define PG8_STAGE(bufoff, gbase, voff) do { _Pragma("unroll") for (int _i = 0; _i < 2; ++_i) \
;         __builtin_amdgcn_global_load_lds((const unsigned*)((const char*)(gbase) + (voff)[_i]), (PG8_LAS unsigned*)(lds + (bufoff) + ldsw + _i * 8192), 16, 0, 0); } while (0)
; #define PG8_LDA(dst, b, h) do { _Pragma("unroll") for (int m = 0; m < 4; ++m) _Pragma("unroll") for (int k = 0; k < 2; ++k) dst[m][k] = *(const PG8_LAS bf16x8*)(lds + PG8_SA(b, h) + aoff + m * 2048 + k * 1024); } while (0)
; #define PG8_WAIT_V(n) asm volatile("s_waitcnt vmcnt(" #n ")" ::: "memory")
; template <class Epi, class Sched>
; __device__ __forceinline__ void gemm_phase(PG8_LAS unsigned char* lds, const Gemm g, const Sched& S, const Epi& E) {
;     ...
;         for (int t = 0; t < nt; t += 2) {
;             const bool last = (t == nt - 2);
;             const char* a1 = cA + (size_t)(t + 1) * kstep;
;             const char* a2 = last ? nA : cA + (size_t)(t + 2) * kstep; const char* b2 = last ? nB : cB + (size_t)(t + 2) * kstep;
;             const char* a3 = a2 + kstep; const char* b3 = b2 + kstep;
;             if (last && has_next) S.a_ready(nxt);
;             PG8_LDB(B0, 0, 0); PG8_SCHED; PG8_LDA(At, 0, 0); PG8_STAGE(PG8_SA(1, 1), a1 + hstep, voffA);
;             PG8_WAIT_L(8); PG8_BAR; PG8_WAIT_L(0); PG8_MMA(0, 0, At, B0); PG8_BAR; PG8_SCHED;
;             PG8_LDB(B1, 0, 1); PG8_STAGE(PG8_SB(0, 0), b2, voffB);
;             PG8_BAR; PG8_WAIT_L(0); PG8_MMA(0, 1, At, B1); PG8_BAR;
;             PG8_LDA(At, 0, 1); PG8_STAGE(PG8_SA(0, 0), a2, voffA);
;             PG8_BAR; PG8_WAIT_L(0); PG8_MMA(1, 0, At, B0); PG8_BAR; PG8_SCHED;
;             PG8_STAGE(PG8_SB(0, 1), b2 + hstep, voffB);
;             PG8_WAIT_V(6); PG8_BAR; PG8_MMA(1, 1, At, B1); PG8_BAR;
;             PG8_LDB(B0, 1, 0); PG8_SCHED; PG8_LDA(At, 1, 0); PG8_STAGE(PG8_SA(0, 1), a2 + hstep, voffA);
;             PG8_WAIT_L(8); PG8_BAR; PG8_WAIT_L(0); PG8_MMA(0, 0, At, B0); PG8_BAR; PG8_SCHED;
;             PG8_LDB(B1, 1, 1); PG8_STAGE(PG8_SB(1, 0), b3, voffB);
;             PG8_BAR; PG8_WAIT_L(0); PG8_MMA(0, 1, At, B1); PG8_BAR;
;             PG8_LDA(At, 1, 1); PG8_STAGE(PG8_SA(1, 0), a3, voffA);
;             PG8_BAR; PG8_WAIT_L(0); PG8_MMA(1, 0, At, B0); PG8_BAR; PG8_SCHED;
;             PG8_STAGE(PG8_SB(1, 1), b3 + hstep, voffB);
;             PG8_WAIT_V(6); PG8_BAR; PG8_MMA(1, 1, At, B1); PG8_BAR;
	ds_read_b128 v[168:171], v154 offset:16384
	ds_read_b128 v[172:175], v154 offset:17408
	ds_read_b128 v[182:185], v154 offset:18432
	ds_read_b128 v[190:193], v154 offset:19456
	ds_read_b128 v[194:197], v154 offset:20480
	ds_read_b128 v[198:201], v154 offset:21504
	ds_read_b128 v[202:205], v154 offset:22528
	ds_read_b128 v[206:209], v154 offset:23552
	s_add_i32 s48, s39, s29
	s_add_u32 s98, s20, s6
	s_addc_u32 s99, s21, s7
	s_mov_b32 m0, s48
	s_nop 0
	global_load_lds_dwordx4 v130, s[20:21]
	s_nop 1
	s_add_i32 m0, s48, 0x2000
	s_nop 0
	global_load_lds_dwordx4 v134, s[20:21]
	s_nop 1
	s_mov_b32 m0, s17
	s_add_u32 s100, s22, s6
	s_addc_u32 s101, s23, s7
	global_load_lds_dwordx4 v128, s[22:23]
	s_nop 1
	s_mov_b32 m0, s30
	s_nop 0
	global_load_lds_dwordx4 v132, s[22:23]
	s_add_u32 s48, s20, 0x40000
	s_addc_u32 s49, s21, 0
	s_add_i32 s50, s40, s29
	s_mov_b32 m0, s50
	s_nop 0
	global_load_lds_dwordx4 v130, s[48:49]
	s_nop 1
	s_add_i32 m0, s50, 0x2000
	s_nop 0
	global_load_lds_dwordx4 v134, s[48:49]
	s_waitcnt vmcnt(8) lgkmcnt(0)
	s_barrier
	v_mfma_f32_16x16x32_bf16 v[60:63], v[144:147], v[168:171], v[60:63]
	v_mfma_f32_16x16x32_bf16 v[56:59], v[160:163], v[168:171], v[56:59]
	v_mfma_f32_16x16x32_bf16 v[44:47], v[144:147], v[182:185], v[44:47]
	v_mfma_f32_16x16x32_bf16 v[40:43], v[160:163], v[182:185], v[40:43]
	v_mfma_f32_16x16x32_bf16 v[28:31], v[144:147], v[194:197], v[28:31]
	v_mfma_f32_16x16x32_bf16 v[24:27], v[160:163], v[194:197], v[24:27]
	v_mfma_f32_16x16x32_bf16 v[12:15], v[144:147], v[202:205], v[12:15]
	v_mfma_f32_16x16x32_bf16 v[8:11], v[160:163], v[202:205], v[8:11]
	v_mfma_f32_16x16x32_bf16 v[60:63], v[156:159], v[172:175], v[60:63]
	v_mfma_f32_16x16x32_bf16 v[56:59], v[164:167], v[172:175], v[56:59]
	v_mfma_f32_16x16x32_bf16 v[44:47], v[156:159], v[190:193], v[44:47]
	v_mfma_f32_16x16x32_bf16 v[40:43], v[164:167], v[190:193], v[40:43]
	v_mfma_f32_16x16x32_bf16 v[28:31], v[156:159], v[198:201], v[28:31]
	v_mfma_f32_16x16x32_bf16 v[24:27], v[164:167], v[198:201], v[24:27]
	v_mfma_f32_16x16x32_bf16 v[12:15], v[156:159], v[206:209], v[12:15]
	v_mfma_f32_16x16x32_bf16 v[8:11], v[164:167], v[206:209], v[8:11]
	v_mfma_f32_16x16x32_bf16 v[52:55], v[210:213], v[168:171], v[52:55]
	v_mfma_f32_16x16x32_bf16 v[48:51], v[218:221], v[168:171], v[48:51]
	v_mfma_f32_16x16x32_bf16 v[36:39], v[210:213], v[182:185], v[36:39]
	v_mfma_f32_16x16x32_bf16 v[32:35], v[218:221], v[182:185], v[32:35]
	v_mfma_f32_16x16x32_bf16 v[20:23], v[210:213], v[194:197], v[20:23]
	v_mfma_f32_16x16x32_bf16 v[16:19], v[218:221], v[194:197], v[16:19]
	v_mfma_f32_16x16x32_bf16 v[4:7], v[210:213], v[202:205], v[4:7]
	v_mfma_f32_16x16x32_bf16 v[0:3], v[218:221], v[202:205], v[0:3]
	v_mfma_f32_16x16x32_bf16 v[52:55], v[214:217], v[172:175], v[52:55]
	v_mfma_f32_16x16x32_bf16 v[48:51], v[222:225], v[172:175], v[48:51]
	v_mfma_f32_16x16x32_bf16 v[36:39], v[214:217], v[190:193], v[36:39]
	v_mfma_f32_16x16x32_bf16 v[32:35], v[222:225], v[190:193], v[32:35]
	v_mfma_f32_16x16x32_bf16 v[20:23], v[214:217], v[198:201], v[20:23]
	v_mfma_f32_16x16x32_bf16 v[16:19], v[222:225], v[198:201], v[16:19]
	v_mfma_f32_16x16x32_bf16 v[4:7], v[214:217], v[206:209], v[4:7]
	v_mfma_f32_16x16x32_bf16 v[0:3], v[222:225], v[206:209], v[0:3]
	s_barrier
	s_add_i32 s48, 0, 0x18000
	v_add_u32_e32 v164, s48, v151
	ds_read_b128 v[144:147], v164
	ds_read_b128 v[156:159], v164 offset:1024
	ds_read_b128 v[160:163], v164 offset:2048
	ds_read_b128 v[164:167], v164 offset:3072
	s_add_u32 s22, s22, 0x40000
	s_addc_u32 s23, s23, 0
	s_mov_b32 m0, s31
	ds_read_b128 v[168:171], v154 offset:32768
	ds_read_b128 v[172:175], v154 offset:33792
	ds_read_b128 v[182:185], v154 offset:34816
	ds_read_b128 v[190:193], v154 offset:35840
	ds_read_b128 v[194:197], v154 offset:36864
	ds_read_b128 v[198:201], v154 offset:37888
	ds_read_b128 v[202:205], v154 offset:38912
	ds_read_b128 v[206:209], v154 offset:39936
	global_load_lds_dwordx4 v128, s[22:23]
	s_nop 1
	s_mov_b32 m0, s34
	s_nop 0
	global_load_lds_dwordx4 v132, s[22:23]
	s_add_i32 s22, 0, 0x1c000
	v_add_u32_e32 v179, s22, v151
	s_waitcnt lgkmcnt(8)
	ds_read_b128 v[210:213], v179
	ds_read_b128 v[214:217], v179 offset:1024
	ds_read_b128 v[218:221], v179 offset:2048
	ds_read_b128 v[222:225], v179 offset:3072
	s_waitcnt vmcnt(8) lgkmcnt(0)
	s_barrier
	v_mfma_f32_16x16x32_bf16 v[124:127], v[144:147], v[168:171], v[124:127]
	v_mfma_f32_16x16x32_bf16 v[120:123], v[160:163], v[168:171], v[120:123]
	v_mfma_f32_16x16x32_bf16 v[108:111], v[144:147], v[182:185], v[108:111]
	v_mfma_f32_16x16x32_bf16 v[104:107], v[160:163], v[182:185], v[104:107]
	v_mfma_f32_16x16x32_bf16 v[92:95], v[144:147], v[194:197], v[92:95]
	v_mfma_f32_16x16x32_bf16 v[88:91], v[160:163], v[194:197], v[88:91]
	v_mfma_f32_16x16x32_bf16 v[76:79], v[144:147], v[202:205], v[76:79]
	v_mfma_f32_16x16x32_bf16 v[72:75], v[160:163], v[202:205], v[72:75]
	v_mfma_f32_16x16x32_bf16 v[124:127], v[156:159], v[172:175], v[124:127]
	v_mfma_f32_16x16x32_bf16 v[120:123], v[164:167], v[172:175], v[120:123]
	v_mfma_f32_16x16x32_bf16 v[108:111], v[156:159], v[190:193], v[108:111]
	v_mfma_f32_16x16x32_bf16 v[104:107], v[164:167], v[190:193], v[104:107]
	v_mfma_f32_16x16x32_bf16 v[92:95], v[156:159], v[198:201], v[92:95]
	v_mfma_f32_16x16x32_bf16 v[88:91], v[164:167], v[198:201], v[88:91]
	v_mfma_f32_16x16x32_bf16 v[76:79], v[156:159], v[206:209], v[76:79]
	v_mfma_f32_16x16x32_bf16 v[72:75], v[164:167], v[206:209], v[72:75]
	v_mfma_f32_16x16x32_bf16 v[116:119], v[210:213], v[168:171], v[116:119]
	v_mfma_f32_16x16x32_bf16 v[112:115], v[218:221], v[168:171], v[112:115]
	v_mfma_f32_16x16x32_bf16 v[100:103], v[210:213], v[182:185], v[100:103]
	v_mfma_f32_16x16x32_bf16 v[96:99], v[218:221], v[182:185], v[96:99]
	v_mfma_f32_16x16x32_bf16 v[84:87], v[210:213], v[194:197], v[84:87]
	v_mfma_f32_16x16x32_bf16 v[80:83], v[218:221], v[194:197], v[80:83]
	v_mfma_f32_16x16x32_bf16 v[68:71], v[210:213], v[202:205], v[68:71]
	v_mfma_f32_16x16x32_bf16 v[64:67], v[218:221], v[202:205], v[64:67]
	v_mfma_f32_16x16x32_bf16 v[116:119], v[214:217], v[172:175], v[116:119]
	v_mfma_f32_16x16x32_bf16 v[112:115], v[222:225], v[172:175], v[112:115]
	v_mfma_f32_16x16x32_bf16 v[100:103], v[214:217], v[190:193], v[100:103]
	v_mfma_f32_16x16x32_bf16 v[96:99], v[222:225], v[190:193], v[96:99]
	v_mfma_f32_16x16x32_bf16 v[84:87], v[214:217], v[198:201], v[84:87]
	v_mfma_f32_16x16x32_bf16 v[80:83], v[222:225], v[198:201], v[80:83]
	v_mfma_f32_16x16x32_bf16 v[68:71], v[214:217], v[206:209], v[68:71]
	v_mfma_f32_16x16x32_bf16 v[64:67], v[222:225], v[206:209], v[64:67]
	s_barrier
; #define PG8_WAIT_V(n) asm volatile("s_waitcnt vmcnt(" #n ")" ::: "memory")
;     __device__ __forceinline__ void operator()(const f32x4 (&acc)[2][2][4][2], const Unit& u, int wr, int wc, int fr, int fq) const {
;     ...
;             for (int m = 0; m < 4; ++m) { const size_t r = (size_t)(row0 + ai * HALF + m * 16); bf16_t* rowp = O + r * ldc + col0; const bf16_t* gp = G + r * ldg + col0;
; #pragma unroll
;                 for (int bj = 0; bj < 2; ++bj) { const u32x4 gw = *(const u32x4*)(gp + bj * HALF);
;                     f32x4 v0 = acc[ai][bj][m][0], v1 = acc[ai][bj][m][1];
; template <class Epi, class Sched>
; __device__ __forceinline__ void gemm_phase(PG8_LAS unsigned char* lds, const Gemm g, const Sched& S, const Epi& E) {
;     ...
;         for (int t = 0; t < nt; t += 2) {
;             const bool last = (t == nt - 2);
;             const char* a1 = cA + (size_t)(t + 1) * kstep;
;             const char* a2 = last ? nA : cA + (size_t)(t + 2) * kstep; const char* b2 = last ? nB : cB + (size_t)(t + 2) * kstep;
;             const char* a3 = a2 + kstep; const char* b3 = b2 + kstep;
;             if (last && has_next) S.a_ready(nxt);
;             PG8_LDB(B0, 0, 0); PG8_SCHED; PG8_LDA(At, 0, 0); PG8_STAGE(PG8_SA(1, 1), a1 + hstep, voffA);
;             PG8_WAIT_L(8); PG8_BAR; PG8_WAIT_L(0); PG8_MMA(0, 0, At, B0); PG8_BAR; PG8_SCHED;
;             PG8_LDB(B1, 0, 1); PG8_STAGE(PG8_SB(0, 0), b2, voffB);
;             PG8_BAR; PG8_WAIT_L(0); PG8_MMA(0, 1, At, B1); PG8_BAR;
;             PG8_LDA(At, 0, 1); PG8_STAGE(PG8_SA(0, 0), a2, voffA);
;             PG8_BAR; PG8_WAIT_L(0); PG8_MMA(1, 0, At, B0); PG8_BAR; PG8_SCHED;
;             PG8_STAGE(PG8_SB(0, 1), b2 + hstep, voffB);
;             PG8_WAIT_V(6); PG8_BAR; PG8_MMA(1, 1, At, B1); PG8_BAR;
;             PG8_LDB(B0, 1, 0); PG8_SCHED; PG8_LDA(At, 1, 0); PG8_STAGE(PG8_SA(0, 1), a2 + hstep, voffA);
;             PG8_WAIT_L(8); PG8_BAR; PG8_WAIT_L(0); PG8_MMA(0, 0, At, B0); PG8_BAR; PG8_SCHED;
;             PG8_LDB(B1, 1, 1); PG8_STAGE(PG8_SB(1, 0), b3, voffB);
;             PG8_BAR; PG8_WAIT_L(0); PG8_MMA(0, 1, At, B1); PG8_BAR;
;             PG8_LDA(At, 1, 1); PG8_STAGE(PG8_SA(1, 0), a3, voffA);
;             PG8_BAR; PG8_WAIT_L(0); PG8_MMA(1, 0, At, B0); PG8_BAR; PG8_SCHED;
;             PG8_STAGE(PG8_SB(1, 1), b3 + hstep, voffB);
;             PG8_WAIT_V(6); PG8_BAR; PG8_MMA(1, 1, At, B1); PG8_BAR;
	ds_read_b128 v[168:171], v154 offset:49152
	ds_read_b128 v[172:175], v154 offset:50176
	ds_read_b128 v[182:185], v154 offset:51200
	ds_read_b128 v[190:193], v154 offset:52224
	ds_read_b128 v[194:197], v154 offset:53248
	ds_read_b128 v[198:201], v154 offset:54272
	ds_read_b128 v[202:205], v154 offset:55296
	ds_read_b128 v[206:209], v154 offset:56320
	s_add_i32 s23, s48, s29
	s_mov_b32 m0, s23
	s_nop 0
	global_load_lds_dwordx4 v130, s[98:99]
	s_nop 1
	s_add_i32 m0, s23, 0x2000
	s_nop 0
	global_load_lds_dwordx4 v134, s[98:99]
	s_nop 1
	s_mov_b32 m0, s36
	s_nop 0
	global_load_lds_dwordx4 v128, s[100:101]
	s_nop 1
	s_mov_b32 m0, s37
	s_nop 0
	global_load_lds_dwordx4 v132, s[100:101]
	s_add_u32 s20, s20, 0x40080
	s_addc_u32 s21, s21, 0
	s_add_i32 s22, s22, s29
	s_mov_b32 m0, s22
	s_nop 0
	global_load_lds_dwordx4 v130, s[20:21]
	s_nop 1
	s_add_i32 m0, s22, 0x2000
	s_nop 0
	global_load_lds_dwordx4 v134, s[20:21]
	s_waitcnt vmcnt(8) lgkmcnt(0)
	s_barrier
	v_mfma_f32_16x16x32_bf16 v[60:63], v[144:147], v[168:171], v[60:63]
	v_mfma_f32_16x16x32_bf16 v[56:59], v[160:163], v[168:171], v[56:59]
	v_mfma_f32_16x16x32_bf16 v[44:47], v[144:147], v[182:185], v[44:47]
	v_mfma_f32_16x16x32_bf16 v[40:43], v[160:163], v[182:185], v[40:43]
	v_mfma_f32_16x16x32_bf16 v[28:31], v[144:147], v[194:197], v[28:31]
	v_mfma_f32_16x16x32_bf16 v[24:27], v[160:163], v[194:197], v[24:27]
	v_mfma_f32_16x16x32_bf16 v[12:15], v[144:147], v[202:205], v[12:15]
	v_mfma_f32_16x16x32_bf16 v[8:11], v[160:163], v[202:205], v[8:11]
	v_mfma_f32_16x16x32_bf16 v[60:63], v[156:159], v[172:175], v[60:63]
	v_mfma_f32_16x16x32_bf16 v[56:59], v[164:167], v[172:175], v[56:59]
	v_mfma_f32_16x16x32_bf16 v[44:47], v[156:159], v[190:193], v[44:47]
	v_mfma_f32_16x16x32_bf16 v[40:43], v[164:167], v[190:193], v[40:43]
	v_mfma_f32_16x16x32_bf16 v[28:31], v[156:159], v[198:201], v[28:31]
	v_mfma_f32_16x16x32_bf16 v[24:27], v[164:167], v[198:201], v[24:27]
	v_mfma_f32_16x16x32_bf16 v[12:15], v[156:159], v[206:209], v[12:15]
	v_mfma_f32_16x16x32_bf16 v[8:11], v[164:167], v[206:209], v[8:11]
	v_mfma_f32_16x16x32_bf16 v[52:55], v[210:213], v[168:171], v[52:55]
	v_mfma_f32_16x16x32_bf16 v[48:51], v[218:221], v[168:171], v[48:51]
	v_mfma_f32_16x16x32_bf16 v[36:39], v[210:213], v[182:185], v[36:39]
	v_mfma_f32_16x16x32_bf16 v[32:35], v[218:221], v[182:185], v[32:35]
	v_mfma_f32_16x16x32_bf16 v[20:23], v[210:213], v[194:197], v[20:23]
	v_mfma_f32_16x16x32_bf16 v[16:19], v[218:221], v[194:197], v[16:19]
	v_mfma_f32_16x16x32_bf16 v[4:7], v[210:213], v[202:205], v[4:7]
	v_mfma_f32_16x16x32_bf16 v[0:3], v[218:221], v[202:205], v[0:3]
	v_mfma_f32_16x16x32_bf16 v[52:55], v[214:217], v[172:175], v[52:55]
	v_mfma_f32_16x16x32_bf16 v[48:51], v[222:225], v[172:175], v[48:51]
	v_mfma_f32_16x16x32_bf16 v[36:39], v[214:217], v[190:193], v[36:39]
	v_mfma_f32_16x16x32_bf16 v[32:35], v[222:225], v[190:193], v[32:35]
	v_mfma_f32_16x16x32_bf16 v[20:23], v[214:217], v[198:201], v[20:23]
	v_mfma_f32_16x16x32_bf16 v[16:19], v[222:225], v[198:201], v[16:19]
	v_mfma_f32_16x16x32_bf16 v[4:7], v[214:217], v[206:209], v[4:7]
	v_mfma_f32_16x16x32_bf16 v[0:3], v[222:225], v[206:209], v[0:3]
	s_barrier
	s_add_i32 s47, s47, 2
	s_add_u32 s18, s18, 0x100
	s_addc_u32 s19, s19, 0
	s_add_u32 s45, s45, 0x100
	s_addc_u32 s46, s46, 0
	s_cmp_gt_u32 s47, 13
	s_cbranch_scc0 .LBB0_1011
	v_lshl_add_u32 v146, s16, 8, v150
	v_lshl_or_b32 v144, s42, 8, v152
	v_ashrrev_i32_e32 v147, 31, v146
	v_ashrrev_i32_e32 v145, 31, v144
	v_mov_b64_e32 v[148:149], s[4:5]
	v_lshlrev_b64 v[160:161], 11, v[146:147]
	v_lshlrev_b64 v[144:145], 1, v[144:145]
	v_mad_i64_i32 v[156:157], s[18:19], v146, s41, v[148:149]
	v_lshl_add_u64 v[160:161], s[0:1], 0, v[160:161]
	v_lshl_add_u64 v[164:165], v[156:157], 0, v[144:145]
	v_lshl_add_u64 v[166:167], v[160:161], 0, v[144:145]
	global_load_dwordx4 v[156:159], v[164:165], off
	global_load_dwordx4 v[160:163], v[166:167], off
	s_and_b64 vcc, exec, s[2:3]
	s_mov_b32 s42, s8
	s_mov_b32 s16, s10
	s_mov_b64 s[20:21], s[14:15]
	s_waitcnt vmcnt(0)
	v_lshlrev_b32_e32 v147, 16, v156
	v_and_b32_e32 v156, 0xffff0000, v156
	v_lshlrev_b32_e32 v168, 16, v157
	v_and_b32_e32 v157, 0xffff0000, v157
	v_lshlrev_b32_e32 v169, 16, v158
	v_and_b32_e32 v158, 0xffff0000, v158
	v_lshlrev_b32_e32 v170, 16, v159
	v_and_b32_e32 v159, 0xffff0000, v159
	v_lshlrev_b32_e32 v171, 16, v160
	v_and_b32_e32 v160, 0xffff0000, v160
	v_lshlrev_b32_e32 v172, 16, v161
	v_and_b32_e32 v161, 0xffff0000, v161
	v_lshlrev_b32_e32 v173, 16, v162
	v_and_b32_e32 v162, 0xffff0000, v162
	v_lshlrev_b32_e32 v174, 16, v163
	v_and_b32_e32 v163, 0xffff0000, v163
	v_fmac_f32_e32 v171, v124, v147
	v_fmac_f32_e32 v160, v125, v156
	v_fmac_f32_e32 v172, v126, v168
	v_fmac_f32_e32 v161, v127, v157
	v_fmac_f32_e32 v173, v120, v169
	v_fmac_f32_e32 v162, v121, v158
	v_fmac_f32_e32 v174, v122, v170
	v_fmac_f32_e32 v163, v123, v159
	v_cvt_pk_bf16_f32 v120, v171, v160
	v_cvt_pk_bf16_f32 v121, v172, v161
	v_cvt_pk_bf16_f32 v122, v173, v162
	v_cvt_pk_bf16_f32 v123, v174, v163
	global_load_dwordx4 v[124:127], v[164:165], off offset:256
	global_load_dwordx4 v[156:159], v[166:167], off offset:256
	v_or_b32_e32 v160, 16, v146
	global_store_dwordx4 v[166:167], v[120:123], off
	v_mad_i64_i32 v[162:163], s[18:19], v160, s41, v[148:149]
	v_lshl_add_u64 v[162:163], v[162:163], 0, v[144:145]
	s_waitcnt vmcnt(0)
; __device__ __forceinline__ unsigned cvt_pk_bf16(float lo, float hi) { unsigned r; asm volatile("v_cvt_pk_bf16_f32 %0, %1, %2" : "=v"(r) : "v"(lo), "v"(hi)); return r; }
; __device__ __forceinline__ float bf_lo(unsigned u) { return __uint_as_float(u << 16); }
; __device__ __forceinline__ float bf_hi(unsigned u) { return __uint_as_float(u & 0xffff0000u); }
;     __device__ __forceinline__ void operator()(const f32x4 (&acc)[2][2][4][2], const Unit& u, int wr, int wc, int fr, int fq) const {
;     ...
;             for (int m = 0; m < 4; ++m) { const size_t r = (size_t)(row0 + ai * HALF + m * 16); bf16_t* rowp = O + r * ldc + col0; const bf16_t* gp = G + r * ldg + col0;
; #pragma unroll
;                 for (int bj = 0; bj < 2; ++bj) { const u32x4 gw = *(const u32x4*)(gp + bj * HALF);
;                     f32x4 v0 = acc[ai][bj][m][0], v1 = acc[ai][bj][m][1];
;                     v0[0] *= bf_lo(gw.x); v0[1] *= bf_hi(gw.x); v0[2] *= bf_lo(gw.y); v0[3] *= bf_hi(gw.y);
;                     v1[0] *= bf_lo(gw.z); v1[1] *= bf_hi(gw.z); v1[2] *= bf_lo(gw.w); v1[3] *= bf_hi(gw.w);
;                     if (ACCUM) { const u32x4 pw = *(const u32x4*)(rowp + bj * HALF);
;                         v0[0] += bf_lo(pw.x); v0[1] += bf_hi(pw.x); v0[2] += bf_lo(pw.y); v0[3] += bf_hi(pw.y);
;                         v1[0] += bf_lo(pw.z); v1[1] += bf_hi(pw.z); v1[2] += bf_lo(pw.w); v1[3] += bf_hi(pw.w); }
;                     u32x4 w; w.x = cvt_pk_bf16(v0[0], v0[1]); w.y = cvt_pk_bf16(v0[2], v0[3]); w.z = cvt_pk_bf16(v1[0], v1[1]); w.w = cvt_pk_bf16(v1[2], v1[3]);
;                     *(u32x4*)(rowp + bj * HALF) = w; } }
	v_lshlrev_b32_e32 v122, 16, v125
	v_lshlrev_b32_e32 v161, 16, v157
	v_lshlrev_b32_e32 v120, 16, v124
	v_and_b32_e32 v121, 0xffff0000, v124
	v_and_b32_e32 v123, 0xffff0000, v125
	v_lshlrev_b32_e32 v124, 16, v126
	v_and_b32_e32 v125, 0xffff0000, v126
	v_lshlrev_b32_e32 v147, 16, v156
	v_and_b32_e32 v156, 0xffff0000, v156
	v_and_b32_e32 v157, 0xffff0000, v157
	v_lshlrev_b32_e32 v164, 16, v158
	v_and_b32_e32 v158, 0xffff0000, v158
	v_fmac_f32_e32 v161, v118, v122
	v_fmac_f32_e32 v147, v116, v120
	v_fmac_f32_e32 v156, v117, v121
	v_fmac_f32_e32 v157, v119, v123
	v_fmac_f32_e32 v164, v112, v124
	v_fmac_f32_e32 v158, v113, v125
	v_cvt_pk_bf16_f32 v112, v147, v156
	v_cvt_pk_bf16_f32 v113, v161, v157
	v_ashrrev_i32_e32 v161, 31, v160
	v_lshlrev_b64 v[120:121], 11, v[160:161]
	v_lshl_add_u64 v[120:121], s[0:1], 0, v[120:121]
	v_lshlrev_b32_e32 v126, 16, v127
	v_and_b32_e32 v127, 0xffff0000, v127
	v_lshlrev_b32_e32 v165, 16, v159
	v_and_b32_e32 v159, 0xffff0000, v159
	v_lshl_add_u64 v[124:125], v[120:121], 0, v[144:145]
	v_fmac_f32_e32 v165, v114, v126
	v_fmac_f32_e32 v159, v115, v127
	v_cvt_pk_bf16_f32 v114, v164, v158
	v_cvt_pk_bf16_f32 v115, v165, v159
	global_load_dwordx4 v[116:119], v[162:163], off
	global_load_dwordx4 v[120:123], v[124:125], off
	s_waitcnt vmcnt(0)
	v_lshlrev_b32_e32 v126, 16, v120
	global_store_dwordx4 v[166:167], v[112:115], off offset:256
	v_and_b32_e32 v120, 0xffff0000, v120
	v_lshlrev_b32_e32 v127, 16, v121
	v_lshlrev_b32_e32 v112, 16, v116
	v_and_b32_e32 v113, 0xffff0000, v116
	v_lshlrev_b32_e32 v114, 16, v117
	v_and_b32_e32 v115, 0xffff0000, v117
	v_lshlrev_b32_e32 v116, 16, v118
	v_and_b32_e32 v117, 0xffff0000, v118
	v_lshlrev_b32_e32 v118, 16, v119
	v_and_b32_e32 v119, 0xffff0000, v119
	v_and_b32_e32 v121, 0xffff0000, v121
	v_lshlrev_b32_e32 v147, 16, v122
	v_and_b32_e32 v122, 0xffff0000, v122
	v_lshlrev_b32_e32 v156, 16, v123
	v_and_b32_e32 v123, 0xffff0000, v123
	v_fmac_f32_e32 v126, v108, v112
	v_fmac_f32_e32 v120, v109, v113
	v_fmac_f32_e32 v127, v110, v114
	v_fmac_f32_e32 v121, v111, v115
	v_fmac_f32_e32 v147, v104, v116
	v_fmac_f32_e32 v122, v105, v117
	v_fmac_f32_e32 v156, v106, v118
	v_fmac_f32_e32 v123, v107, v119
	v_cvt_pk_bf16_f32 v104, v126, v120
	v_cvt_pk_bf16_f32 v105, v127, v121
	v_cvt_pk_bf16_f32 v106, v147, v122
	v_cvt_pk_bf16_f32 v107, v156, v123
	global_load_dwordx4 v[108:111], v[162:163], off offset:256
	global_load_dwordx4 v[112:115], v[124:125], off offset:256
	v_or_b32_e32 v116, 32, v146
	global_store_dwordx4 v[124:125], v[104:107], off
	v_mad_i64_i32 v[118:119], s[18:19], v116, s41, v[148:149]
	v_lshl_add_u64 v[118:119], v[118:119], 0, v[144:145]
	s_waitcnt vmcnt(0)
	v_lshlrev_b32_e32 v104, 16, v108
	v_lshlrev_b32_e32 v117, 16, v112
	v_and_b32_e32 v105, 0xffff0000, v108
	v_lshlrev_b32_e32 v108, 16, v110
	v_and_b32_e32 v112, 0xffff0000, v112
	v_lshlrev_b32_e32 v121, 16, v114
	v_fmac_f32_e32 v117, v100, v104
	v_fmac_f32_e32 v112, v101, v105
	v_fmac_f32_e32 v121, v96, v108
	v_cvt_pk_bf16_f32 v96, v117, v112
	v_ashrrev_i32_e32 v117, 31, v116
	v_lshlrev_b64 v[104:105], 11, v[116:117]
	v_lshlrev_b32_e32 v106, 16, v109
	v_and_b32_e32 v107, 0xffff0000, v109
	v_and_b32_e32 v109, 0xffff0000, v110
	v_and_b32_e32 v114, 0xffff0000, v114
	v_lshl_add_u64 v[104:105], s[0:1], 0, v[104:105]
	v_lshlrev_b32_e32 v110, 16, v111
	v_and_b32_e32 v111, 0xffff0000, v111
	v_lshlrev_b32_e32 v120, 16, v113
	v_and_b32_e32 v113, 0xffff0000, v113
	v_lshlrev_b32_e32 v122, 16, v115
	v_and_b32_e32 v115, 0xffff0000, v115
	v_fmac_f32_e32 v114, v97, v109
	v_lshl_add_u64 v[108:109], v[104:105], 0, v[144:145]
	v_fmac_f32_e32 v120, v102, v106
	v_fmac_f32_e32 v113, v103, v107
	v_fmac_f32_e32 v122, v98, v110
	v_fmac_f32_e32 v115, v99, v111
	v_cvt_pk_bf16_f32 v97, v120, v113
	v_cvt_pk_bf16_f32 v98, v121, v114
	v_cvt_pk_bf16_f32 v99, v122, v115
	global_load_dwordx4 v[100:103], v[118:119], off
	global_load_dwordx4 v[104:107], v[108:109], off
	s_waitcnt vmcnt(0)
	v_lshlrev_b32_e32 v110, 16, v104
	global_store_dwordx4 v[124:125], v[96:99], off offset:256
	v_and_b32_e32 v104, 0xffff0000, v104
	v_lshlrev_b32_e32 v111, 16, v105
	v_lshlrev_b32_e32 v96, 16, v100
	v_and_b32_e32 v97, 0xffff0000, v100
	v_lshlrev_b32_e32 v98, 16, v101
	v_and_b32_e32 v99, 0xffff0000, v101
	v_lshlrev_b32_e32 v100, 16, v102
	v_and_b32_e32 v101, 0xffff0000, v102
	v_lshlrev_b32_e32 v102, 16, v103
	v_and_b32_e32 v103, 0xffff0000, v103
	v_and_b32_e32 v105, 0xffff0000, v105
	v_lshlrev_b32_e32 v112, 16, v106
	v_and_b32_e32 v106, 0xffff0000, v106
	v_lshlrev_b32_e32 v113, 16, v107
	v_and_b32_e32 v107, 0xffff0000, v107
	v_fmac_f32_e32 v110, v92, v96
	v_fmac_f32_e32 v104, v93, v97
	v_fmac_f32_e32 v111, v94, v98
	v_fmac_f32_e32 v105, v95, v99
	v_fmac_f32_e32 v112, v88, v100
	v_fmac_f32_e32 v106, v89, v101
	v_fmac_f32_e32 v113, v90, v102
	v_fmac_f32_e32 v107, v91, v103
	v_cvt_pk_bf16_f32 v88, v110, v104
	v_cvt_pk_bf16_f32 v89, v111, v105
	v_cvt_pk_bf16_f32 v90, v112, v106
	v_cvt_pk_bf16_f32 v91, v113, v107
	global_load_dwordx4 v[92:95], v[118:119], off offset:256
	global_load_dwordx4 v[96:99], v[108:109], off offset:256
	v_or_b32_e32 v100, 48, v146
	global_store_dwordx4 v[108:109], v[88:91], off
	v_mad_i64_i32 v[102:103], s[18:19], v100, s41, v[148:149]
	v_lshl_add_u64 v[102:103], v[102:103], 0, v[144:145]
	s_waitcnt vmcnt(0)
; __device__ __forceinline__ unsigned cvt_pk_bf16(float lo, float hi) { unsigned r; asm volatile("v_cvt_pk_bf16_f32 %0, %1, %2" : "=v"(r) : "v"(lo), "v"(hi)); return r; }
; __device__ __forceinline__ float bf_lo(unsigned u) { return __uint_as_float(u << 16); }
; __device__ __forceinline__ float bf_hi(unsigned u) { return __uint_as_float(u & 0xffff0000u); }
;     __device__ __forceinline__ void operator()(const f32x4 (&acc)[2][2][4][2], const Unit& u, int wr, int wc, int fr, int fq) const {
;     ...
;             for (int m = 0; m < 4; ++m) { const size_t r = (size_t)(row0 + ai * HALF + m * 16); bf16_t* rowp = O + r * ldc + col0; const bf16_t* gp = G + r * ldg + col0;
; #pragma unroll
;                 for (int bj = 0; bj < 2; ++bj) { const u32x4 gw = *(const u32x4*)(gp + bj * HALF);
;                     f32x4 v0 = acc[ai][bj][m][0], v1 = acc[ai][bj][m][1];
;                     v0[0] *= bf_lo(gw.x); v0[1] *= bf_hi(gw.x); v0[2] *= bf_lo(gw.y); v0[3] *= bf_hi(gw.y);
;                     v1[0] *= bf_lo(gw.z); v1[1] *= bf_hi(gw.z); v1[2] *= bf_lo(gw.w); v1[3] *= bf_hi(gw.w);
;                     if (ACCUM) { const u32x4 pw = *(const u32x4*)(rowp + bj * HALF);
;                         v0[0] += bf_lo(pw.x); v0[1] += bf_hi(pw.x); v0[2] += bf_lo(pw.y); v0[3] += bf_hi(pw.y);
;                         v1[0] += bf_lo(pw.z); v1[1] += bf_hi(pw.z); v1[2] += bf_lo(pw.w); v1[3] += bf_hi(pw.w); }
;                     u32x4 w; w.x = cvt_pk_bf16(v0[0], v0[1]); w.y = cvt_pk_bf16(v0[2], v0[3]); w.z = cvt_pk_bf16(v1[0], v1[1]); w.w = cvt_pk_bf16(v1[2], v1[3]);
;                     *(u32x4*)(rowp + bj * HALF) = w; } }
	v_lshlrev_b32_e32 v88, 16, v92
	v_lshlrev_b32_e32 v101, 16, v96
	v_and_b32_e32 v89, 0xffff0000, v92
	v_lshlrev_b32_e32 v92, 16, v94
	v_and_b32_e32 v96, 0xffff0000, v96
	v_lshlrev_b32_e32 v105, 16, v98
	v_fmac_f32_e32 v101, v84, v88
	v_fmac_f32_e32 v96, v85, v89
	v_fmac_f32_e32 v105, v80, v92
	v_cvt_pk_bf16_f32 v80, v101, v96
	v_ashrrev_i32_e32 v101, 31, v100
	v_lshlrev_b64 v[88:89], 11, v[100:101]
	v_lshlrev_b32_e32 v90, 16, v93
	v_and_b32_e32 v91, 0xffff0000, v93
	v_and_b32_e32 v93, 0xffff0000, v94
	v_and_b32_e32 v98, 0xffff0000, v98
	v_lshl_add_u64 v[88:89], s[0:1], 0, v[88:89]
	v_lshlrev_b32_e32 v94, 16, v95
	v_and_b32_e32 v95, 0xffff0000, v95
	v_lshlrev_b32_e32 v104, 16, v97
	v_and_b32_e32 v97, 0xffff0000, v97
	v_lshlrev_b32_e32 v106, 16, v99
	v_and_b32_e32 v99, 0xffff0000, v99
	v_fmac_f32_e32 v98, v81, v93
	v_lshl_add_u64 v[92:93], v[88:89], 0, v[144:145]
	v_fmac_f32_e32 v104, v86, v90
	v_fmac_f32_e32 v97, v87, v91
	v_fmac_f32_e32 v106, v82, v94
	v_fmac_f32_e32 v99, v83, v95
	v_cvt_pk_bf16_f32 v81, v104, v97
	v_cvt_pk_bf16_f32 v82, v105, v98
	v_cvt_pk_bf16_f32 v83, v106, v99
	global_load_dwordx4 v[84:87], v[102:103], off
	global_load_dwordx4 v[88:91], v[92:93], off
	s_waitcnt vmcnt(0)
	v_lshlrev_b32_e32 v94, 16, v88
	global_store_dwordx4 v[108:109], v[80:83], off offset:256
	v_and_b32_e32 v88, 0xffff0000, v88
	v_lshlrev_b32_e32 v95, 16, v89
	v_lshlrev_b32_e32 v80, 16, v84
	v_and_b32_e32 v81, 0xffff0000, v84
	v_lshlrev_b32_e32 v82, 16, v85
	v_and_b32_e32 v83, 0xffff0000, v85
	v_lshlrev_b32_e32 v84, 16, v86
	v_and_b32_e32 v85, 0xffff0000, v86
	v_lshlrev_b32_e32 v86, 16, v87
	v_and_b32_e32 v87, 0xffff0000, v87
	v_and_b32_e32 v89, 0xffff0000, v89
	v_lshlrev_b32_e32 v96, 16, v90
	v_and_b32_e32 v90, 0xffff0000, v90
	v_lshlrev_b32_e32 v97, 16, v91
	v_and_b32_e32 v91, 0xffff0000, v91
	v_fmac_f32_e32 v94, v76, v80
	v_fmac_f32_e32 v88, v77, v81
	v_fmac_f32_e32 v95, v78, v82
	v_fmac_f32_e32 v89, v79, v83
	v_fmac_f32_e32 v96, v72, v84
	v_fmac_f32_e32 v90, v73, v85
	v_fmac_f32_e32 v97, v74, v86
	v_fmac_f32_e32 v91, v75, v87
	v_cvt_pk_bf16_f32 v72, v94, v88
	v_cvt_pk_bf16_f32 v73, v95, v89
	v_cvt_pk_bf16_f32 v74, v96, v90
	v_cvt_pk_bf16_f32 v75, v97, v91
	global_load_dwordx4 v[76:79], v[102:103], off offset:256
	global_load_dwordx4 v[80:83], v[92:93], off offset:256
	v_add_u32_e32 v84, 0x80, v146
	global_store_dwordx4 v[92:93], v[72:75], off
	v_mad_i64_i32 v[86:87], s[18:19], v84, s41, v[148:149]
	v_lshl_add_u64 v[86:87], v[86:87], 0, v[144:145]
	s_waitcnt vmcnt(0)
	v_lshlrev_b32_e32 v72, 16, v76
	v_lshlrev_b32_e32 v85, 16, v80
	v_and_b32_e32 v73, 0xffff0000, v76
	v_lshlrev_b32_e32 v76, 16, v78
	v_and_b32_e32 v80, 0xffff0000, v80
	v_lshlrev_b32_e32 v89, 16, v82
	v_fmac_f32_e32 v85, v68, v72
	v_fmac_f32_e32 v80, v69, v73
	v_fmac_f32_e32 v89, v64, v76
	v_cvt_pk_bf16_f32 v64, v85, v80
	v_ashrrev_i32_e32 v85, 31, v84
	v_lshlrev_b64 v[72:73], 11, v[84:85]
	v_lshlrev_b32_e32 v74, 16, v77
	v_and_b32_e32 v75, 0xffff0000, v77
	v_and_b32_e32 v77, 0xffff0000, v78
	v_and_b32_e32 v82, 0xffff0000, v82
	v_lshl_add_u64 v[72:73], s[0:1], 0, v[72:73]
	v_lshlrev_b32_e32 v78, 16, v79
	v_and_b32_e32 v79, 0xffff0000, v79
	v_lshlrev_b32_e32 v88, 16, v81
	v_and_b32_e32 v81, 0xffff0000, v81
	v_lshlrev_b32_e32 v90, 16, v83
	v_and_b32_e32 v83, 0xffff0000, v83
	v_fmac_f32_e32 v82, v65, v77
	v_lshl_add_u64 v[76:77], v[72:73], 0, v[144:145]
	v_fmac_f32_e32 v88, v70, v74
	v_fmac_f32_e32 v81, v71, v75
	v_fmac_f32_e32 v90, v66, v78
	v_fmac_f32_e32 v83, v67, v79
	v_cvt_pk_bf16_f32 v65, v88, v81
	v_cvt_pk_bf16_f32 v66, v89, v82
	v_cvt_pk_bf16_f32 v67, v90, v83
	global_load_dwordx4 v[68:71], v[86:87], off
	global_load_dwordx4 v[72:75], v[76:77], off
	s_waitcnt vmcnt(0)
	v_lshlrev_b32_e32 v78, 16, v72
	global_store_dwordx4 v[92:93], v[64:67], off offset:256
	v_and_b32_e32 v72, 0xffff0000, v72
	v_lshlrev_b32_e32 v79, 16, v73
	v_lshlrev_b32_e32 v64, 16, v68
	v_and_b32_e32 v65, 0xffff0000, v68
	v_lshlrev_b32_e32 v66, 16, v69
	v_and_b32_e32 v67, 0xffff0000, v69
	v_lshlrev_b32_e32 v68, 16, v70
	v_and_b32_e32 v69, 0xffff0000, v70
	v_lshlrev_b32_e32 v70, 16, v71
	v_and_b32_e32 v71, 0xffff0000, v71
	v_and_b32_e32 v73, 0xffff0000, v73
	v_lshlrev_b32_e32 v80, 16, v74
	v_and_b32_e32 v74, 0xffff0000, v74
	v_lshlrev_b32_e32 v81, 16, v75
	v_and_b32_e32 v75, 0xffff0000, v75
	v_fmac_f32_e32 v78, v60, v64
	v_fmac_f32_e32 v72, v61, v65
	v_fmac_f32_e32 v79, v62, v66
	v_fmac_f32_e32 v73, v63, v67
	v_fmac_f32_e32 v80, v56, v68
	v_fmac_f32_e32 v74, v57, v69
	v_fmac_f32_e32 v81, v58, v70
	v_fmac_f32_e32 v75, v59, v71
	v_cvt_pk_bf16_f32 v56, v78, v72
	v_cvt_pk_bf16_f32 v57, v79, v73
	v_cvt_pk_bf16_f32 v58, v80, v74
	v_cvt_pk_bf16_f32 v59, v81, v75
	global_load_dwordx4 v[60:63], v[86:87], off offset:256
	global_load_dwordx4 v[64:67], v[76:77], off offset:256
	v_add_u32_e32 v68, 0x90, v146
	global_store_dwordx4 v[76:77], v[56:59], off
	v_mad_i64_i32 v[70:71], s[18:19], v68, s41, v[148:149]
	v_lshl_add_u64 v[70:71], v[70:71], 0, v[144:145]
	s_waitcnt vmcnt(0)
	v_lshlrev_b32_e32 v56, 16, v60
	v_lshlrev_b32_e32 v69, 16, v64
	v_and_b32_e32 v57, 0xffff0000, v60
	v_lshlrev_b32_e32 v60, 16, v62
	v_and_b32_e32 v64, 0xffff0000, v64
	v_lshlrev_b32_e32 v73, 16, v66
	v_fmac_f32_e32 v69, v52, v56
	v_fmac_f32_e32 v64, v53, v57
	v_fmac_f32_e32 v73, v48, v60
	v_cvt_pk_bf16_f32 v48, v69, v64
	v_ashrrev_i32_e32 v69, 31, v68
	v_lshlrev_b64 v[56:57], 11, v[68:69]
	v_lshlrev_b32_e32 v58, 16, v61
	v_and_b32_e32 v59, 0xffff0000, v61
	v_and_b32_e32 v61, 0xffff0000, v62
	v_and_b32_e32 v66, 0xffff0000, v66
	v_lshl_add_u64 v[56:57], s[0:1], 0, v[56:57]
	v_lshlrev_b32_e32 v62, 16, v63
	v_and_b32_e32 v63, 0xffff0000, v63
	v_lshlrev_b32_e32 v72, 16, v65
	v_and_b32_e32 v65, 0xffff0000, v65
	v_lshlrev_b32_e32 v74, 16, v67
	v_and_b32_e32 v67, 0xffff0000, v67
	v_fmac_f32_e32 v66, v49, v61
	v_lshl_add_u64 v[60:61], v[56:57], 0, v[144:145]
	v_fmac_f32_e32 v72, v54, v58
	v_fmac_f32_e32 v65, v55, v59
	v_fmac_f32_e32 v74, v50, v62
	v_fmac_f32_e32 v67, v51, v63
	v_cvt_pk_bf16_f32 v49, v72, v65
	v_cvt_pk_bf16_f32 v50, v73, v66
	v_cvt_pk_bf16_f32 v51, v74, v67
	global_load_dwordx4 v[52:55], v[70:71], off
	global_load_dwordx4 v[56:59], v[60:61], off
	s_waitcnt vmcnt(0)
; __device__ __forceinline__ unsigned cvt_pk_bf16(float lo, float hi) { unsigned r; asm volatile("v_cvt_pk_bf16_f32 %0, %1, %2" : "=v"(r) : "v"(lo), "v"(hi)); return r; }
; __device__ __forceinline__ float bf_lo(unsigned u) { return __uint_as_float(u << 16); }
; __device__ __forceinline__ float bf_hi(unsigned u) { return __uint_as_float(u & 0xffff0000u); }
;     __device__ __forceinline__ void operator()(const f32x4 (&acc)[2][2][4][2], const Unit& u, int wr, int wc, int fr, int fq) const {
;     ...
;             for (int m = 0; m < 4; ++m) { const size_t r = (size_t)(row0 + ai * HALF + m * 16); bf16_t* rowp = O + r * ldc + col0; const bf16_t* gp = G + r * ldg + col0;
; #pragma unroll
;                 for (int bj = 0; bj < 2; ++bj) { const u32x4 gw = *(const u32x4*)(gp + bj * HALF);
;                     f32x4 v0 = acc[ai][bj][m][0], v1 = acc[ai][bj][m][1];
;                     v0[0] *= bf_lo(gw.x); v0[1] *= bf_hi(gw.x); v0[2] *= bf_lo(gw.y); v0[3] *= bf_hi(gw.y);
;                     v1[0] *= bf_lo(gw.z); v1[1] *= bf_hi(gw.z); v1[2] *= bf_lo(gw.w); v1[3] *= bf_hi(gw.w);
;                     if (ACCUM) { const u32x4 pw = *(const u32x4*)(rowp + bj * HALF);
;                         v0[0] += bf_lo(pw.x); v0[1] += bf_hi(pw.x); v0[2] += bf_lo(pw.y); v0[3] += bf_hi(pw.y);
;                         v1[0] += bf_lo(pw.z); v1[1] += bf_hi(pw.z); v1[2] += bf_lo(pw.w); v1[3] += bf_hi(pw.w); }
;                     u32x4 w; w.x = cvt_pk_bf16(v0[0], v0[1]); w.y = cvt_pk_bf16(v0[2], v0[3]); w.z = cvt_pk_bf16(v1[0], v1[1]); w.w = cvt_pk_bf16(v1[2], v1[3]);
;                     *(u32x4*)(rowp + bj * HALF) = w; } }
	v_lshlrev_b32_e32 v62, 16, v56
	global_store_dwordx4 v[76:77], v[48:51], off offset:256
	v_and_b32_e32 v56, 0xffff0000, v56
	v_lshlrev_b32_e32 v63, 16, v57
	v_lshlrev_b32_e32 v48, 16, v52
	v_and_b32_e32 v49, 0xffff0000, v52
	v_lshlrev_b32_e32 v50, 16, v53
	v_and_b32_e32 v51, 0xffff0000, v53
	v_lshlrev_b32_e32 v52, 16, v54
	v_and_b32_e32 v53, 0xffff0000, v54
	v_lshlrev_b32_e32 v54, 16, v55
	v_and_b32_e32 v55, 0xffff0000, v55
	v_and_b32_e32 v57, 0xffff0000, v57
	v_lshlrev_b32_e32 v64, 16, v58
	v_and_b32_e32 v58, 0xffff0000, v58
	v_lshlrev_b32_e32 v65, 16, v59
	v_and_b32_e32 v59, 0xffff0000, v59
	v_fmac_f32_e32 v62, v44, v48
	v_fmac_f32_e32 v56, v45, v49
	v_fmac_f32_e32 v63, v46, v50
	v_fmac_f32_e32 v57, v47, v51
	v_fmac_f32_e32 v64, v40, v52
	v_fmac_f32_e32 v58, v41, v53
	v_fmac_f32_e32 v65, v42, v54
	v_fmac_f32_e32 v59, v43, v55
	v_cvt_pk_bf16_f32 v40, v62, v56
	v_cvt_pk_bf16_f32 v41, v63, v57
	v_cvt_pk_bf16_f32 v42, v64, v58
	v_cvt_pk_bf16_f32 v43, v65, v59
	global_load_dwordx4 v[44:47], v[70:71], off offset:256
	global_load_dwordx4 v[48:51], v[60:61], off offset:256
	v_add_u32_e32 v52, 0xa0, v146
	global_store_dwordx4 v[60:61], v[40:43], off
	v_mad_i64_i32 v[54:55], s[18:19], v52, s41, v[148:149]
	v_lshl_add_u64 v[54:55], v[54:55], 0, v[144:145]
	s_waitcnt vmcnt(0)
	v_lshlrev_b32_e32 v40, 16, v44
	v_lshlrev_b32_e32 v53, 16, v48
	v_and_b32_e32 v41, 0xffff0000, v44
	v_lshlrev_b32_e32 v44, 16, v46
	v_and_b32_e32 v48, 0xffff0000, v48
	v_lshlrev_b32_e32 v57, 16, v50
	v_fmac_f32_e32 v53, v36, v40
	v_fmac_f32_e32 v48, v37, v41
	v_fmac_f32_e32 v57, v32, v44
	v_cvt_pk_bf16_f32 v32, v53, v48
	v_ashrrev_i32_e32 v53, 31, v52
	v_lshlrev_b64 v[40:41], 11, v[52:53]
	v_lshlrev_b32_e32 v42, 16, v45
	v_and_b32_e32 v43, 0xffff0000, v45
	v_and_b32_e32 v45, 0xffff0000, v46
	v_and_b32_e32 v50, 0xffff0000, v50
	v_lshl_add_u64 v[40:41], s[0:1], 0, v[40:41]
	v_lshlrev_b32_e32 v46, 16, v47
	v_and_b32_e32 v47, 0xffff0000, v47
	v_lshlrev_b32_e32 v56, 16, v49
	v_and_b32_e32 v49, 0xffff0000, v49
	v_lshlrev_b32_e32 v58, 16, v51
	v_and_b32_e32 v51, 0xffff0000, v51
	v_fmac_f32_e32 v50, v33, v45
	v_lshl_add_u64 v[44:45], v[40:41], 0, v[144:145]
	v_fmac_f32_e32 v56, v38, v42
	v_fmac_f32_e32 v49, v39, v43
	v_fmac_f32_e32 v58, v34, v46
	v_fmac_f32_e32 v51, v35, v47
	v_cvt_pk_bf16_f32 v33, v56, v49
	v_cvt_pk_bf16_f32 v34, v57, v50
	v_cvt_pk_bf16_f32 v35, v58, v51
	global_load_dwordx4 v[36:39], v[54:55], off
	global_load_dwordx4 v[40:43], v[44:45], off
	s_waitcnt vmcnt(0)
	v_lshlrev_b32_e32 v46, 16, v40
	global_store_dwordx4 v[60:61], v[32:35], off offset:256
	v_and_b32_e32 v40, 0xffff0000, v40
	v_lshlrev_b32_e32 v47, 16, v41
	v_lshlrev_b32_e32 v32, 16, v36
	v_and_b32_e32 v33, 0xffff0000, v36
	v_lshlrev_b32_e32 v34, 16, v37
	v_and_b32_e32 v35, 0xffff0000, v37
	v_lshlrev_b32_e32 v36, 16, v38
	v_and_b32_e32 v37, 0xffff0000, v38
	v_lshlrev_b32_e32 v38, 16, v39
	v_and_b32_e32 v39, 0xffff0000, v39
	v_and_b32_e32 v41, 0xffff0000, v41
	v_lshlrev_b32_e32 v48, 16, v42
	v_and_b32_e32 v42, 0xffff0000, v42
	v_lshlrev_b32_e32 v49, 16, v43
	v_and_b32_e32 v43, 0xffff0000, v43
	v_fmac_f32_e32 v46, v28, v32
	v_fmac_f32_e32 v40, v29, v33
	v_fmac_f32_e32 v47, v30, v34
	v_fmac_f32_e32 v41, v31, v35
	v_fmac_f32_e32 v48, v24, v36
	v_fmac_f32_e32 v42, v25, v37
	v_fmac_f32_e32 v49, v26, v38
	v_fmac_f32_e32 v43, v27, v39
	v_cvt_pk_bf16_f32 v24, v46, v40
	v_cvt_pk_bf16_f32 v25, v47, v41
	v_cvt_pk_bf16_f32 v26, v48, v42
	v_cvt_pk_bf16_f32 v27, v49, v43
	global_load_dwordx4 v[28:31], v[54:55], off offset:256
	global_load_dwordx4 v[32:35], v[44:45], off offset:256
	v_add_u32_e32 v36, 0xb0, v146
	global_store_dwordx4 v[44:45], v[24:27], off
	v_mad_i64_i32 v[38:39], s[18:19], v36, s41, v[148:149]
	v_lshl_add_u64 v[38:39], v[38:39], 0, v[144:145]
	s_mov_b64 s[18:19], s[12:13]
	s_waitcnt vmcnt(0)
; __device__ __forceinline__ unsigned cvt_pk_bf16(float lo, float hi) { unsigned r; asm volatile("v_cvt_pk_bf16_f32 %0, %1, %2" : "=v"(r) : "v"(lo), "v"(hi)); return r; }
; __device__ __forceinline__ float bf_lo(unsigned u) { return __uint_as_float(u << 16); }
; __device__ __forceinline__ float bf_hi(unsigned u) { return __uint_as_float(u & 0xffff0000u); }
; #define PG8_WAIT_V(n) asm volatile("s_waitcnt vmcnt(" #n ")" ::: "memory")
;     __device__ __forceinline__ void operator()(const f32x4 (&acc)[2][2][4][2], const Unit& u, int wr, int wc, int fr, int fq) const {
;     ...
;             for (int m = 0; m < 4; ++m) { const size_t r = (size_t)(row0 + ai * HALF + m * 16); bf16_t* rowp = O + r * ldc + col0; const bf16_t* gp = G + r * ldg + col0;
; #pragma unroll
;                 for (int bj = 0; bj < 2; ++bj) { const u32x4 gw = *(const u32x4*)(gp + bj * HALF);
;                     f32x4 v0 = acc[ai][bj][m][0], v1 = acc[ai][bj][m][1];
;                     v0[0] *= bf_lo(gw.x); v0[1] *= bf_hi(gw.x); v0[2] *= bf_lo(gw.y); v0[3] *= bf_hi(gw.y);
;                     v1[0] *= bf_lo(gw.z); v1[1] *= bf_hi(gw.z); v1[2] *= bf_lo(gw.w); v1[3] *= bf_hi(gw.w);
;                     if (ACCUM) { const u32x4 pw = *(const u32x4*)(rowp + bj * HALF);
;                         v0[0] += bf_lo(pw.x); v0[1] += bf_hi(pw.x); v0[2] += bf_lo(pw.y); v0[3] += bf_hi(pw.y);
;                         v1[0] += bf_lo(pw.z); v1[1] += bf_hi(pw.z); v1[2] += bf_lo(pw.w); v1[3] += bf_hi(pw.w); }
;                     u32x4 w; w.x = cvt_pk_bf16(v0[0], v0[1]); w.y = cvt_pk_bf16(v0[2], v0[3]); w.z = cvt_pk_bf16(v1[0], v1[1]); w.w = cvt_pk_bf16(v1[2], v1[3]);
;                     *(u32x4*)(rowp + bj * HALF) = w; } }
; template <class Epi, class Sched>
; __device__ __forceinline__ void gemm_phase(PG8_LAS unsigned char* lds, const Gemm g, const Sched& S, const Epi& E) {
;     ...
;         if constexpr (!Epi::AFTER_DRAIN) { E(acc, cur, wr, wc, fr, fq); S.done(cur); }
;         if (!has_next) break;
; #pragma unroll
;         for (int a = 0; a < 2; ++a)
; #pragma unroll
;             for (int b = 0; b < 2; ++b)
; #pragma unroll
;                 for (int m = 0; m < 4; ++m)
; #pragma unroll
;                     for (int n = 0; n < 2; ++n) acc[a][b][m][n] = (f32x4){0.f, 0.f, 0.f, 0.f};
;         cur = nxt; cA = nA; cB = nB; ++ui;
;     }
;     PG8_WAIT_V(0);
;     if (wr == 0) PG8_BAR;
;     PG8_BAR;
	v_lshlrev_b32_e32 v24, 16, v28
	v_lshlrev_b32_e32 v37, 16, v32
	v_and_b32_e32 v25, 0xffff0000, v28
	v_lshlrev_b32_e32 v28, 16, v30
	v_and_b32_e32 v32, 0xffff0000, v32
	v_lshlrev_b32_e32 v41, 16, v34
	v_fmac_f32_e32 v37, v20, v24
	v_fmac_f32_e32 v32, v21, v25
	v_fmac_f32_e32 v41, v16, v28
	v_cvt_pk_bf16_f32 v16, v37, v32
	v_ashrrev_i32_e32 v37, 31, v36
	v_lshlrev_b64 v[24:25], 11, v[36:37]
	v_lshlrev_b32_e32 v26, 16, v29
	v_and_b32_e32 v27, 0xffff0000, v29
	v_and_b32_e32 v29, 0xffff0000, v30
	v_and_b32_e32 v34, 0xffff0000, v34
	v_lshl_add_u64 v[24:25], s[0:1], 0, v[24:25]
	v_lshlrev_b32_e32 v30, 16, v31
	v_and_b32_e32 v31, 0xffff0000, v31
	v_lshlrev_b32_e32 v40, 16, v33
	v_and_b32_e32 v33, 0xffff0000, v33
	v_lshlrev_b32_e32 v42, 16, v35
	v_and_b32_e32 v35, 0xffff0000, v35
	v_fmac_f32_e32 v34, v17, v29
	v_lshl_add_u64 v[28:29], v[24:25], 0, v[144:145]
	v_fmac_f32_e32 v40, v22, v26
	v_fmac_f32_e32 v33, v23, v27
	v_fmac_f32_e32 v42, v18, v30
	v_fmac_f32_e32 v35, v19, v31
	v_cvt_pk_bf16_f32 v17, v40, v33
	v_cvt_pk_bf16_f32 v18, v41, v34
	v_cvt_pk_bf16_f32 v19, v42, v35
	global_load_dwordx4 v[20:23], v[38:39], off
	global_load_dwordx4 v[24:27], v[28:29], off
	s_waitcnt vmcnt(0)
	v_lshlrev_b32_e32 v30, 16, v24
	global_store_dwordx4 v[44:45], v[16:19], off offset:256
	v_and_b32_e32 v24, 0xffff0000, v24
	v_lshlrev_b32_e32 v31, 16, v25
	v_lshlrev_b32_e32 v16, 16, v20
	v_and_b32_e32 v17, 0xffff0000, v20
	v_lshlrev_b32_e32 v18, 16, v21
	v_and_b32_e32 v19, 0xffff0000, v21
	v_lshlrev_b32_e32 v20, 16, v22
	v_and_b32_e32 v21, 0xffff0000, v22
	v_lshlrev_b32_e32 v22, 16, v23
	v_and_b32_e32 v23, 0xffff0000, v23
	v_and_b32_e32 v25, 0xffff0000, v25
	v_lshlrev_b32_e32 v32, 16, v26
	v_and_b32_e32 v26, 0xffff0000, v26
	v_lshlrev_b32_e32 v33, 16, v27
	v_and_b32_e32 v27, 0xffff0000, v27
	v_fmac_f32_e32 v30, v12, v16
	v_fmac_f32_e32 v24, v13, v17
	v_fmac_f32_e32 v31, v14, v18
	v_fmac_f32_e32 v25, v15, v19
	v_fmac_f32_e32 v32, v8, v20
	v_fmac_f32_e32 v26, v9, v21
	v_fmac_f32_e32 v33, v10, v22
	v_fmac_f32_e32 v27, v11, v23
	v_cvt_pk_bf16_f32 v8, v30, v24
	v_cvt_pk_bf16_f32 v9, v31, v25
	v_cvt_pk_bf16_f32 v10, v32, v26
	v_cvt_pk_bf16_f32 v11, v33, v27
	global_load_dwordx4 v[12:15], v[38:39], off offset:256
	global_load_dwordx4 v[16:19], v[28:29], off offset:256
	s_waitcnt vmcnt(0)
	v_lshlrev_b32_e32 v20, 16, v16
	global_store_dwordx4 v[28:29], v[8:11], off
	v_and_b32_e32 v16, 0xffff0000, v16
	v_lshlrev_b32_e32 v21, 16, v17
	v_lshlrev_b32_e32 v8, 16, v12
	v_and_b32_e32 v9, 0xffff0000, v12
	v_lshlrev_b32_e32 v10, 16, v13
	v_and_b32_e32 v11, 0xffff0000, v13
	v_lshlrev_b32_e32 v12, 16, v14
	v_and_b32_e32 v13, 0xffff0000, v14
	v_lshlrev_b32_e32 v14, 16, v15
	v_and_b32_e32 v15, 0xffff0000, v15
	v_and_b32_e32 v17, 0xffff0000, v17
	v_lshlrev_b32_e32 v22, 16, v18
	v_and_b32_e32 v18, 0xffff0000, v18
	v_lshlrev_b32_e32 v23, 16, v19
	v_and_b32_e32 v19, 0xffff0000, v19
	v_fmac_f32_e32 v20, v4, v8
	v_fmac_f32_e32 v16, v5, v9
	v_fmac_f32_e32 v21, v6, v10
	v_fmac_f32_e32 v17, v7, v11
	v_fmac_f32_e32 v22, v0, v12
	v_fmac_f32_e32 v18, v1, v13
	v_fmac_f32_e32 v23, v2, v14
	v_fmac_f32_e32 v19, v3, v15
	v_cvt_pk_bf16_f32 v0, v20, v16
	v_cvt_pk_bf16_f32 v1, v21, v17
	v_cvt_pk_bf16_f32 v2, v22, v18
	v_cvt_pk_bf16_f32 v3, v23, v19
	global_store_dwordx4 v[28:29], v[0:3], off offset:256
	s_cbranch_vccz .LBB0_1004
	s_waitcnt vmcnt(0)
	s_cmpk_gt_u32 s25, 0xff
	s_cbranch_scc1 .LBB0_1015
	s_barrier

; #define PG8_STAGE(bufoff, gbase, voff) do { _Pragma("unroll") for (int _i = 0; _i < 2; ++_i) \
;         __builtin_amdgcn_global_load_lds((const unsigned*)((const char*)(gbase) + (voff)[_i]), (PG8_LAS unsigned*)(lds + (bufoff) + ldsw + _i * 8192), 16, 0, 0); } while (0)
; #define PG8_LDA(dst, b, h) do { _Pragma("unroll") for (int m = 0; m < 4; ++m) _Pragma("unroll") for (int k = 0; k < 2; ++k) dst[m][k] = *(const PG8_LAS bf16x8*)(lds + PG8_SA(b, h) + aoff + m * 2048 + k * 1024); } while (0)
; #define PG8_LDB(dst, b, h) do { _Pragma("unroll") for (int n = 0; n < 2; ++n) _Pragma("unroll") for (int k = 0; k < 2; ++k) dst[n][k] = *(const PG8_LAS bf16x8*)(lds + PG8_SB(b, h) + boff + n * 2048 + k * 1024); } while (0)
; #define PG8_WAIT_V(n) asm volatile("s_waitcnt vmcnt(" #n ")" ::: "memory")
; #define PG8_WAIT_L(n) asm volatile("s_waitcnt lgkmcnt(" #n ")" ::: "memory")
; #define PG8_BAR __builtin_amdgcn_s_barrier()
; #define PG8_SCHED __builtin_amdgcn_sched_barrier(0)
; template <class Epi, class Sched>
; __device__ __forceinline__ void gemm_phase(PG8_LAS unsigned char* lds, const Gemm g, const Sched& S, const Epi& E) {
;     ...
;         const bool has_next = S.next(ui + 1, nxt);
;         const char* nA = has_next ? (const char*)g.A + (size_t)nxt.pm * tstep : cA; const char* nB = has_next ? (const char*)g.Bt + (size_t)nxt.pn * tstep : cB;
;         for (int t = 0; t < nt; t += 2) {
;             const bool last = (t == nt - 2);
;             const char* a1 = cA + (size_t)(t + 1) * kstep;
;             const char* a2 = last ? nA : cA + (size_t)(t + 2) * kstep; const char* b2 = last ? nB : cB + (size_t)(t + 2) * kstep;
;             const char* a3 = a2 + kstep; const char* b3 = b2 + kstep;
;             if (last && has_next) S.a_ready(nxt);
;             PG8_LDB(B0, 0, 0); PG8_SCHED; PG8_LDA(At, 0, 0); PG8_STAGE(PG8_SA(1, 1), a1 + hstep, voffA);
;             PG8_WAIT_L(8); PG8_BAR; PG8_WAIT_L(0); PG8_MMA(0, 0, At, B0); PG8_BAR; PG8_SCHED;
;             PG8_LDB(B1, 0, 1); PG8_STAGE(PG8_SB(0, 0), b2, voffB);
;             PG8_BAR; PG8_WAIT_L(0); PG8_MMA(0, 1, At, B1); PG8_BAR;
;             PG8_LDA(At, 0, 1); PG8_STAGE(PG8_SA(0, 0), a2, voffA);
;             PG8_BAR; PG8_WAIT_L(0); PG8_MMA(1, 0, At, B0); PG8_BAR; PG8_SCHED;
;             PG8_STAGE(PG8_SB(0, 1), b2 + hstep, voffB);
;             PG8_WAIT_V(6); PG8_BAR; PG8_MMA(1, 1, At, B1); PG8_BAR;
.LBB0_1082:
	s_ashr_i32 s17, s16, 31
	v_cmp_lt_i64_e32 vcc, s[18:19], v[140:141]
	s_lshl_b64 s[18:19], s[16:17], 19
	s_add_u32 s18, s35, s18
	s_addc_u32 s19, s36, s19
	s_and_b64 s[20:21], vcc, exec
	s_cselect_b32 s17, s19, s25
	s_cselect_b32 s52, s18, s24
	s_ashr_i32 s15, s14, 31
	s_lshl_b64 s[20:21], s[14:15], 19
	s_add_u32 s20, s72, s20
	s_addc_u32 s21, s73, s21
	s_and_b64 s[28:29], vcc, exec
	s_cselect_b32 s15, s21, s27
	s_cselect_b32 s53, s20, s26
	s_add_u32 s24, s24, 0x40080
	s_addc_u32 s25, s25, 0
	s_add_u32 s54, s26, 0x100
	s_addc_u32 s55, s27, 0
	s_mov_b32 s56, -2
	ds_read_b128 v[152:155], v149
	ds_read_b128 v[156:159], v149 offset:1024
	ds_read_b128 v[160:163], v149 offset:2048
	ds_read_b128 v[164:167], v149 offset:3072
	s_add_u32 s26, s24, 0xfffc0080
	s_addc_u32 s27, s25, -1
	s_cmp_eq_u32 s56, 12
	s_cselect_b32 s29, s17, s27
	s_cselect_b32 s28, s52, s26
	s_cselect_b32 s27, s15, s55
	s_cselect_b32 s26, s53, s54
	s_add_i32 m0, s23, 0xc000
	ds_read_b128 v[168:171], v150
	ds_read_b128 v[172:175], v150 offset:1024
	ds_read_b128 v[182:185], v150 offset:2048
	ds_read_b128 v[190:193], v150 offset:3072
	ds_read_b128 v[194:197], v150 offset:4096
	ds_read_b128 v[198:201], v150 offset:5120
	ds_read_b128 v[202:205], v150 offset:6144
	ds_read_b128 v[206:209], v150 offset:7168
	global_load_lds_dwordx4 v136, s[24:25]
	s_nop 1
	s_add_i32 m0, s23, 0xe000
	s_nop 0
	global_load_lds_dwordx4 v138, s[24:25]
	s_waitcnt lgkmcnt(8)
	ds_read_b128 v[210:213], v151
	ds_read_b128 v[214:217], v151 offset:1024
	ds_read_b128 v[218:221], v151 offset:2048
	ds_read_b128 v[222:225], v151 offset:3072
	s_waitcnt vmcnt(8) lgkmcnt(0)
	s_barrier
	v_mfma_f32_16x16x32_bf16 v[124:127], v[152:155], v[168:171], 0
	v_mfma_f32_16x16x32_bf16 v[120:123], v[160:163], v[168:171], 0
	v_mfma_f32_16x16x32_bf16 v[108:111], v[152:155], v[182:185], 0
	v_mfma_f32_16x16x32_bf16 v[104:107], v[160:163], v[182:185], 0
	v_mfma_f32_16x16x32_bf16 v[92:95], v[152:155], v[194:197], 0
	v_mfma_f32_16x16x32_bf16 v[88:91], v[160:163], v[194:197], 0
	v_mfma_f32_16x16x32_bf16 v[76:79], v[152:155], v[202:205], 0
	v_mfma_f32_16x16x32_bf16 v[72:75], v[160:163], v[202:205], 0
	v_mfma_f32_16x16x32_bf16 v[124:127], v[156:159], v[172:175], v[124:127]
	v_mfma_f32_16x16x32_bf16 v[120:123], v[164:167], v[172:175], v[120:123]
	v_mfma_f32_16x16x32_bf16 v[108:111], v[156:159], v[190:193], v[108:111]
	v_mfma_f32_16x16x32_bf16 v[104:107], v[164:167], v[190:193], v[104:107]
	v_mfma_f32_16x16x32_bf16 v[92:95], v[156:159], v[198:201], v[92:95]
	v_mfma_f32_16x16x32_bf16 v[88:91], v[164:167], v[198:201], v[88:91]
	v_mfma_f32_16x16x32_bf16 v[76:79], v[156:159], v[206:209], v[76:79]
	v_mfma_f32_16x16x32_bf16 v[72:75], v[164:167], v[206:209], v[72:75]
	v_mfma_f32_16x16x32_bf16 v[116:119], v[210:213], v[168:171], 0
	v_mfma_f32_16x16x32_bf16 v[112:115], v[218:221], v[168:171], 0
	v_mfma_f32_16x16x32_bf16 v[100:103], v[210:213], v[182:185], 0
	v_mfma_f32_16x16x32_bf16 v[96:99], v[218:221], v[182:185], 0
	v_mfma_f32_16x16x32_bf16 v[84:87], v[210:213], v[194:197], 0
	v_mfma_f32_16x16x32_bf16 v[80:83], v[218:221], v[194:197], 0
	v_mfma_f32_16x16x32_bf16 v[68:71], v[210:213], v[202:205], 0
	v_mfma_f32_16x16x32_bf16 v[64:67], v[218:221], v[202:205], 0
	v_mfma_f32_16x16x32_bf16 v[116:119], v[214:217], v[172:175], v[116:119]
	v_mfma_f32_16x16x32_bf16 v[112:115], v[222:225], v[172:175], v[112:115]
	v_mfma_f32_16x16x32_bf16 v[100:103], v[214:217], v[190:193], v[100:103]
	v_mfma_f32_16x16x32_bf16 v[96:99], v[222:225], v[190:193], v[96:99]
	v_mfma_f32_16x16x32_bf16 v[84:87], v[214:217], v[198:201], v[84:87]
	v_mfma_f32_16x16x32_bf16 v[80:83], v[222:225], v[198:201], v[80:83]
	v_mfma_f32_16x16x32_bf16 v[68:71], v[214:217], v[206:209], v[68:71]
	v_mfma_f32_16x16x32_bf16 v[64:67], v[222:225], v[206:209], v[64:67]
	s_barrier
	ds_read_b128 v[168:171], v150 offset:16384
	ds_read_b128 v[172:175], v150 offset:17408
	ds_read_b128 v[182:185], v150 offset:18432
	ds_read_b128 v[190:193], v150 offset:19456
	ds_read_b128 v[194:197], v150 offset:20480
	ds_read_b128 v[198:201], v150 offset:21504
	ds_read_b128 v[202:205], v150 offset:22528
	ds_read_b128 v[206:209], v150 offset:23552
	s_add_i32 s57, s45, s37
	s_add_u32 s98, s26, s6
	s_addc_u32 s99, s27, s7
	s_mov_b32 m0, s57
	s_nop 0
	global_load_lds_dwordx4 v130, s[26:27]
	s_nop 1
	s_add_i32 m0, s57, 0x2000
	s_nop 0
	global_load_lds_dwordx4 v134, s[26:27]
	s_nop 1
	s_mov_b32 m0, s23
	s_add_u32 s100, s28, s6
	s_addc_u32 s101, s29, s7
	global_load_lds_dwordx4 v128, s[28:29]
	s_nop 1
	s_mov_b32 m0, s38
	s_nop 0
	global_load_lds_dwordx4 v132, s[28:29]
	s_add_u32 s58, s26, 0x40000
	s_addc_u32 s59, s27, 0
	s_add_i32 s57, s46, s37
	s_mov_b32 m0, s57
	s_nop 0
	global_load_lds_dwordx4 v130, s[58:59]
	s_nop 1
	s_add_i32 m0, s57, 0x2000
	s_nop 0
	global_load_lds_dwordx4 v134, s[58:59]
	s_waitcnt vmcnt(8) lgkmcnt(0)
	s_barrier
; #define PG8_STAGE(bufoff, gbase, voff) do { _Pragma("unroll") for (int _i = 0; _i < 2; ++_i) \
;         __builtin_amdgcn_global_load_lds((const unsigned*)((const char*)(gbase) + (voff)[_i]), (PG8_LAS unsigned*)(lds + (bufoff) + ldsw + _i * 8192), 16, 0, 0); } while (0)
; #define PG8_LDA(dst, b, h) do { _Pragma("unroll") for (int m = 0; m < 4; ++m) _Pragma("unroll") for (int k = 0; k < 2; ++k) dst[m][k] = *(const PG8_LAS bf16x8*)(lds + PG8_SA(b, h) + aoff + m * 2048 + k * 1024); } while (0)
; #define PG8_LDB(dst, b, h) do { _Pragma("unroll") for (int n = 0; n < 2; ++n) _Pragma("unroll") for (int k = 0; k < 2; ++k) dst[n][k] = *(const PG8_LAS bf16x8*)(lds + PG8_SB(b, h) + boff + n * 2048 + k * 1024); } while (0)
; template <class Epi, class Sched>
; __device__ __forceinline__ void gemm_phase(PG8_LAS unsigned char* lds, const Gemm g, const Sched& S, const Epi& E) {
;     ...
;         for (int t = 0; t < nt; t += 2) {
;             const bool last = (t == nt - 2);
;             const char* a1 = cA + (size_t)(t + 1) * kstep;
;             const char* a2 = last ? nA : cA + (size_t)(t + 2) * kstep; const char* b2 = last ? nB : cB + (size_t)(t + 2) * kstep;
;             const char* a3 = a2 + kstep; const char* b3 = b2 + kstep;
;             if (last && has_next) S.a_ready(nxt);
;             PG8_LDB(B0, 0, 0); PG8_SCHED; PG8_LDA(At, 0, 0); PG8_STAGE(PG8_SA(1, 1), a1 + hstep, voffA);
;             PG8_WAIT_L(8); PG8_BAR; PG8_WAIT_L(0); PG8_MMA(0, 0, At, B0); PG8_BAR; PG8_SCHED;
;             PG8_LDB(B1, 0, 1); PG8_STAGE(PG8_SB(0, 0), b2, voffB);
;             PG8_BAR; PG8_WAIT_L(0); PG8_MMA(0, 1, At, B1); PG8_BAR;
;             PG8_LDA(At, 0, 1); PG8_STAGE(PG8_SA(0, 0), a2, voffA);
;             PG8_BAR; PG8_WAIT_L(0); PG8_MMA(1, 0, At, B0); PG8_BAR; PG8_SCHED;
;             PG8_STAGE(PG8_SB(0, 1), b2 + hstep, voffB);
;             PG8_WAIT_V(6); PG8_BAR; PG8_MMA(1, 1, At, B1); PG8_BAR;
;             PG8_LDB(B0, 1, 0); PG8_SCHED; PG8_LDA(At, 1, 0); PG8_STAGE(PG8_SA(0, 1), a2 + hstep, voffA);
;             PG8_WAIT_L(8); PG8_BAR; PG8_WAIT_L(0); PG8_MMA(0, 0, At, B0); PG8_BAR; PG8_SCHED;
;             PG8_LDB(B1, 1, 1); PG8_STAGE(PG8_SB(1, 0), b3, voffB);
;             PG8_BAR; PG8_WAIT_L(0); PG8_MMA(0, 1, At, B1); PG8_BAR;
;             PG8_LDA(At, 1, 1); PG8_STAGE(PG8_SA(1, 0), a3, voffA);
;             PG8_BAR; PG8_WAIT_L(0); PG8_MMA(1, 0, At, B0); PG8_BAR; PG8_SCHED;
	v_mfma_f32_16x16x32_bf16 v[60:63], v[152:155], v[168:171], 0
	v_mfma_f32_16x16x32_bf16 v[56:59], v[160:163], v[168:171], 0
	v_mfma_f32_16x16x32_bf16 v[48:51], v[152:155], v[182:185], 0
	v_mfma_f32_16x16x32_bf16 v[40:43], v[160:163], v[182:185], 0
	v_mfma_f32_16x16x32_bf16 v[32:35], v[152:155], v[194:197], 0
	v_mfma_f32_16x16x32_bf16 v[24:27], v[160:163], v[194:197], 0
	v_mfma_f32_16x16x32_bf16 v[16:19], v[152:155], v[202:205], 0
	v_mfma_f32_16x16x32_bf16 v[8:11], v[160:163], v[202:205], 0
	v_mfma_f32_16x16x32_bf16 v[60:63], v[156:159], v[172:175], v[60:63]
	v_mfma_f32_16x16x32_bf16 v[56:59], v[164:167], v[172:175], v[56:59]
	v_mfma_f32_16x16x32_bf16 v[48:51], v[156:159], v[190:193], v[48:51]
	v_mfma_f32_16x16x32_bf16 v[40:43], v[164:167], v[190:193], v[40:43]
	v_mfma_f32_16x16x32_bf16 v[32:35], v[156:159], v[198:201], v[32:35]
	v_mfma_f32_16x16x32_bf16 v[24:27], v[164:167], v[198:201], v[24:27]
	v_mfma_f32_16x16x32_bf16 v[16:19], v[156:159], v[206:209], v[16:19]
	v_mfma_f32_16x16x32_bf16 v[8:11], v[164:167], v[206:209], v[8:11]
	v_mfma_f32_16x16x32_bf16 v[52:55], v[210:213], v[168:171], 0
	v_mfma_f32_16x16x32_bf16 v[44:47], v[218:221], v[168:171], 0
	v_mfma_f32_16x16x32_bf16 v[36:39], v[210:213], v[182:185], 0
	v_mfma_f32_16x16x32_bf16 v[28:31], v[218:221], v[182:185], 0
	v_mfma_f32_16x16x32_bf16 v[20:23], v[210:213], v[194:197], 0
	v_mfma_f32_16x16x32_bf16 v[12:15], v[218:221], v[194:197], 0
	v_mfma_f32_16x16x32_bf16 v[4:7], v[210:213], v[202:205], 0
	v_mfma_f32_16x16x32_bf16 v[0:3], v[218:221], v[202:205], 0
	v_mfma_f32_16x16x32_bf16 v[52:55], v[214:217], v[172:175], v[52:55]
	v_mfma_f32_16x16x32_bf16 v[44:47], v[222:225], v[172:175], v[44:47]
	v_mfma_f32_16x16x32_bf16 v[36:39], v[214:217], v[190:193], v[36:39]
	v_mfma_f32_16x16x32_bf16 v[28:31], v[222:225], v[190:193], v[28:31]
	v_mfma_f32_16x16x32_bf16 v[20:23], v[214:217], v[198:201], v[20:23]
	v_mfma_f32_16x16x32_bf16 v[12:15], v[222:225], v[198:201], v[12:15]
	v_mfma_f32_16x16x32_bf16 v[4:7], v[214:217], v[206:209], v[4:7]
	v_mfma_f32_16x16x32_bf16 v[0:3], v[222:225], v[206:209], v[0:3]
	s_barrier
	s_add_i32 s57, 0, 0x18000
	v_add_u32_e32 v164, s57, v147
	ds_read_b128 v[152:155], v164
	ds_read_b128 v[156:159], v164 offset:1024
	ds_read_b128 v[160:163], v164 offset:2048
	ds_read_b128 v[164:167], v164 offset:3072
	s_add_u32 s28, s28, 0x40000
	s_addc_u32 s29, s29, 0
	s_mov_b32 m0, s39
	ds_read_b128 v[168:171], v150 offset:32768
	ds_read_b128 v[172:175], v150 offset:33792
	ds_read_b128 v[182:185], v150 offset:34816
	ds_read_b128 v[190:193], v150 offset:35840
	ds_read_b128 v[194:197], v150 offset:36864
	ds_read_b128 v[198:201], v150 offset:37888
	ds_read_b128 v[202:205], v150 offset:38912
	ds_read_b128 v[206:209], v150 offset:39936
	global_load_lds_dwordx4 v128, s[28:29]
	s_nop 1
	s_mov_b32 m0, s40
	s_nop 0
	global_load_lds_dwordx4 v132, s[28:29]
	s_add_i32 s28, 0, 0x1c000
	v_add_u32_e32 v179, s28, v147
	s_waitcnt lgkmcnt(8)
	ds_read_b128 v[210:213], v179
	ds_read_b128 v[214:217], v179 offset:1024
	ds_read_b128 v[218:221], v179 offset:2048
	ds_read_b128 v[222:225], v179 offset:3072
	s_waitcnt vmcnt(8) lgkmcnt(0)
	s_barrier
	v_mfma_f32_16x16x32_bf16 v[124:127], v[152:155], v[168:171], v[124:127]
	v_mfma_f32_16x16x32_bf16 v[120:123], v[160:163], v[168:171], v[120:123]
	v_mfma_f32_16x16x32_bf16 v[108:111], v[152:155], v[182:185], v[108:111]
	v_mfma_f32_16x16x32_bf16 v[104:107], v[160:163], v[182:185], v[104:107]
	v_mfma_f32_16x16x32_bf16 v[92:95], v[152:155], v[194:197], v[92:95]
	v_mfma_f32_16x16x32_bf16 v[88:91], v[160:163], v[194:197], v[88:91]
	v_mfma_f32_16x16x32_bf16 v[76:79], v[152:155], v[202:205], v[76:79]
	v_mfma_f32_16x16x32_bf16 v[72:75], v[160:163], v[202:205], v[72:75]
	v_mfma_f32_16x16x32_bf16 v[124:127], v[156:159], v[172:175], v[124:127]
	v_mfma_f32_16x16x32_bf16 v[120:123], v[164:167], v[172:175], v[120:123]
	v_mfma_f32_16x16x32_bf16 v[108:111], v[156:159], v[190:193], v[108:111]
	v_mfma_f32_16x16x32_bf16 v[104:107], v[164:167], v[190:193], v[104:107]
	v_mfma_f32_16x16x32_bf16 v[92:95], v[156:159], v[198:201], v[92:95]
	v_mfma_f32_16x16x32_bf16 v[88:91], v[164:167], v[198:201], v[88:91]
	v_mfma_f32_16x16x32_bf16 v[76:79], v[156:159], v[206:209], v[76:79]
	v_mfma_f32_16x16x32_bf16 v[72:75], v[164:167], v[206:209], v[72:75]
	v_mfma_f32_16x16x32_bf16 v[116:119], v[210:213], v[168:171], v[116:119]
	v_mfma_f32_16x16x32_bf16 v[112:115], v[218:221], v[168:171], v[112:115]
	v_mfma_f32_16x16x32_bf16 v[100:103], v[210:213], v[182:185], v[100:103]
	v_mfma_f32_16x16x32_bf16 v[96:99], v[218:221], v[182:185], v[96:99]
	v_mfma_f32_16x16x32_bf16 v[84:87], v[210:213], v[194:197], v[84:87]
	v_mfma_f32_16x16x32_bf16 v[80:83], v[218:221], v[194:197], v[80:83]
	v_mfma_f32_16x16x32_bf16 v[68:71], v[210:213], v[202:205], v[68:71]
	v_mfma_f32_16x16x32_bf16 v[64:67], v[218:221], v[202:205], v[64:67]
	v_mfma_f32_16x16x32_bf16 v[116:119], v[214:217], v[172:175], v[116:119]
	v_mfma_f32_16x16x32_bf16 v[112:115], v[222:225], v[172:175], v[112:115]
	v_mfma_f32_16x16x32_bf16 v[100:103], v[214:217], v[190:193], v[100:103]
	v_mfma_f32_16x16x32_bf16 v[96:99], v[222:225], v[190:193], v[96:99]
	v_mfma_f32_16x16x32_bf16 v[84:87], v[214:217], v[198:201], v[84:87]
	v_mfma_f32_16x16x32_bf16 v[80:83], v[222:225], v[198:201], v[80:83]
	v_mfma_f32_16x16x32_bf16 v[68:71], v[214:217], v[206:209], v[68:71]
	v_mfma_f32_16x16x32_bf16 v[64:67], v[222:225], v[206:209], v[64:67]
	s_barrier
; #define PG8_STAGE(bufoff, gbase, voff) do { _Pragma("unroll") for (int _i = 0; _i < 2; ++_i) \
;         __builtin_amdgcn_global_load_lds((const unsigned*)((const char*)(gbase) + (voff)[_i]), (PG8_LAS unsigned*)(lds + (bufoff) + ldsw + _i * 8192), 16, 0, 0); } while (0)
; #define PG8_LDA(dst, b, h) do { _Pragma("unroll") for (int m = 0; m < 4; ++m) _Pragma("unroll") for (int k = 0; k < 2; ++k) dst[m][k] = *(const PG8_LAS bf16x8*)(lds + PG8_SA(b, h) + aoff + m * 2048 + k * 1024); } while (0)
; #define PG8_WAIT_V(n) asm volatile("s_waitcnt vmcnt(" #n ")" ::: "memory")
; template <class Epi, class Sched>
; __device__ __forceinline__ void gemm_phase(PG8_LAS unsigned char* lds, const Gemm g, const Sched& S, const Epi& E) {
;     ...
;         for (int t = 0; t < nt; t += 2) {
;             const bool last = (t == nt - 2);
;             const char* a1 = cA + (size_t)(t + 1) * kstep;
;             const char* a2 = last ? nA : cA + (size_t)(t + 2) * kstep; const char* b2 = last ? nB : cB + (size_t)(t + 2) * kstep;
;             const char* a3 = a2 + kstep; const char* b3 = b2 + kstep;
;             if (last && has_next) S.a_ready(nxt);
;             PG8_LDB(B0, 0, 0); PG8_SCHED; PG8_LDA(At, 0, 0); PG8_STAGE(PG8_SA(1, 1), a1 + hstep, voffA);
;             PG8_WAIT_L(8); PG8_BAR; PG8_WAIT_L(0); PG8_MMA(0, 0, At, B0); PG8_BAR; PG8_SCHED;
;             PG8_LDB(B1, 0, 1); PG8_STAGE(PG8_SB(0, 0), b2, voffB);
;             PG8_BAR; PG8_WAIT_L(0); PG8_MMA(0, 1, At, B1); PG8_BAR;
;             PG8_LDA(At, 0, 1); PG8_STAGE(PG8_SA(0, 0), a2, voffA);
;             PG8_BAR; PG8_WAIT_L(0); PG8_MMA(1, 0, At, B0); PG8_BAR; PG8_SCHED;
;             PG8_STAGE(PG8_SB(0, 1), b2 + hstep, voffB);
;             PG8_WAIT_V(6); PG8_BAR; PG8_MMA(1, 1, At, B1); PG8_BAR;
;             PG8_LDB(B0, 1, 0); PG8_SCHED; PG8_LDA(At, 1, 0); PG8_STAGE(PG8_SA(0, 1), a2 + hstep, voffA);
;             PG8_WAIT_L(8); PG8_BAR; PG8_WAIT_L(0); PG8_MMA(0, 0, At, B0); PG8_BAR; PG8_SCHED;
;             PG8_LDB(B1, 1, 1); PG8_STAGE(PG8_SB(1, 0), b3, voffB);
;             PG8_BAR; PG8_WAIT_L(0); PG8_MMA(0, 1, At, B1); PG8_BAR;
;             PG8_LDA(At, 1, 1); PG8_STAGE(PG8_SA(1, 0), a3, voffA);
;             PG8_BAR; PG8_WAIT_L(0); PG8_MMA(1, 0, At, B0); PG8_BAR; PG8_SCHED;
;             PG8_STAGE(PG8_SB(1, 1), b3 + hstep, voffB);
;             PG8_WAIT_V(6); PG8_BAR; PG8_MMA(1, 1, At, B1); PG8_BAR;
	ds_read_b128 v[168:171], v150 offset:49152
	ds_read_b128 v[172:175], v150 offset:50176
	ds_read_b128 v[182:185], v150 offset:51200
	ds_read_b128 v[190:193], v150 offset:52224
	ds_read_b128 v[194:197], v150 offset:53248
	ds_read_b128 v[198:201], v150 offset:54272
	ds_read_b128 v[202:205], v150 offset:55296
	ds_read_b128 v[206:209], v150 offset:56320
	s_add_i32 s29, s57, s37
	s_mov_b32 m0, s29
	s_nop 0
	global_load_lds_dwordx4 v130, s[98:99]
	s_nop 1
	s_add_i32 m0, s29, 0x2000
	s_nop 0
	global_load_lds_dwordx4 v134, s[98:99]
	s_nop 1
	s_mov_b32 m0, s42
	s_nop 0
	global_load_lds_dwordx4 v128, s[100:101]
	s_nop 1
	s_mov_b32 m0, s43
	s_nop 0
	global_load_lds_dwordx4 v132, s[100:101]
	s_add_u32 s26, s26, 0x40080
	s_addc_u32 s27, s27, 0
	s_add_i32 s28, s28, s37
	s_mov_b32 m0, s28
	s_nop 0
	global_load_lds_dwordx4 v130, s[26:27]
	s_nop 1
	s_add_i32 m0, s28, 0x2000
	s_nop 0
	global_load_lds_dwordx4 v134, s[26:27]
	s_waitcnt vmcnt(8) lgkmcnt(0)
	s_barrier
	v_mfma_f32_16x16x32_bf16 v[60:63], v[152:155], v[168:171], v[60:63]
	v_mfma_f32_16x16x32_bf16 v[56:59], v[160:163], v[168:171], v[56:59]
	v_mfma_f32_16x16x32_bf16 v[48:51], v[152:155], v[182:185], v[48:51]
	v_mfma_f32_16x16x32_bf16 v[40:43], v[160:163], v[182:185], v[40:43]
	v_mfma_f32_16x16x32_bf16 v[32:35], v[152:155], v[194:197], v[32:35]
	v_mfma_f32_16x16x32_bf16 v[24:27], v[160:163], v[194:197], v[24:27]
	v_mfma_f32_16x16x32_bf16 v[16:19], v[152:155], v[202:205], v[16:19]
	v_mfma_f32_16x16x32_bf16 v[8:11], v[160:163], v[202:205], v[8:11]
	v_mfma_f32_16x16x32_bf16 v[60:63], v[156:159], v[172:175], v[60:63]
	v_mfma_f32_16x16x32_bf16 v[56:59], v[164:167], v[172:175], v[56:59]
	v_mfma_f32_16x16x32_bf16 v[48:51], v[156:159], v[190:193], v[48:51]
	v_mfma_f32_16x16x32_bf16 v[40:43], v[164:167], v[190:193], v[40:43]
	v_mfma_f32_16x16x32_bf16 v[32:35], v[156:159], v[198:201], v[32:35]
	v_mfma_f32_16x16x32_bf16 v[24:27], v[164:167], v[198:201], v[24:27]
	v_mfma_f32_16x16x32_bf16 v[16:19], v[156:159], v[206:209], v[16:19]
	v_mfma_f32_16x16x32_bf16 v[8:11], v[164:167], v[206:209], v[8:11]
	v_mfma_f32_16x16x32_bf16 v[52:55], v[210:213], v[168:171], v[52:55]
	v_mfma_f32_16x16x32_bf16 v[44:47], v[218:221], v[168:171], v[44:47]
	v_mfma_f32_16x16x32_bf16 v[36:39], v[210:213], v[182:185], v[36:39]
	v_mfma_f32_16x16x32_bf16 v[28:31], v[218:221], v[182:185], v[28:31]
	v_mfma_f32_16x16x32_bf16 v[20:23], v[210:213], v[194:197], v[20:23]
	v_mfma_f32_16x16x32_bf16 v[12:15], v[218:221], v[194:197], v[12:15]
	v_mfma_f32_16x16x32_bf16 v[4:7], v[210:213], v[202:205], v[4:7]
	v_mfma_f32_16x16x32_bf16 v[0:3], v[218:221], v[202:205], v[0:3]
	v_mfma_f32_16x16x32_bf16 v[52:55], v[214:217], v[172:175], v[52:55]
	v_mfma_f32_16x16x32_bf16 v[44:47], v[222:225], v[172:175], v[44:47]
	v_mfma_f32_16x16x32_bf16 v[36:39], v[214:217], v[190:193], v[36:39]
	v_mfma_f32_16x16x32_bf16 v[28:31], v[222:225], v[190:193], v[28:31]
	v_mfma_f32_16x16x32_bf16 v[20:23], v[214:217], v[198:201], v[20:23]
	v_mfma_f32_16x16x32_bf16 v[12:15], v[222:225], v[198:201], v[12:15]
	v_mfma_f32_16x16x32_bf16 v[4:7], v[214:217], v[206:209], v[4:7]
	v_mfma_f32_16x16x32_bf16 v[0:3], v[222:225], v[206:209], v[0:3]
	s_barrier
	s_add_i32 s56, s56, 2
	s_add_u32 s24, s24, 0x100
	s_addc_u32 s25, s25, 0
	s_add_u32 s54, s54, 0x100
	s_addc_u32 s55, s55, 0
	s_cmp_gt_u32 s56, 13
.LBB0_1083:
	ds_read_b128 v[152:155], v149
	ds_read_b128 v[156:159], v149 offset:1024
	ds_read_b128 v[160:163], v149 offset:2048
	ds_read_b128 v[164:167], v149 offset:3072
	s_add_u32 s26, s24, 0xfffc0080
	s_addc_u32 s27, s25, -1
	s_cmp_eq_u32 s56, 12
	s_cselect_b32 s29, s17, s27
	s_cselect_b32 s28, s52, s26
	s_cselect_b32 s27, s15, s55
	s_cselect_b32 s26, s53, s54
	s_add_i32 m0, s23, 0xc000
	ds_read_b128 v[168:171], v150
	ds_read_b128 v[172:175], v150 offset:1024
	ds_read_b128 v[182:185], v150 offset:2048
	ds_read_b128 v[190:193], v150 offset:3072
	ds_read_b128 v[194:197], v150 offset:4096
	ds_read_b128 v[198:201], v150 offset:5120
	ds_read_b128 v[202:205], v150 offset:6144
	ds_read_b128 v[206:209], v150 offset:7168
	global_load_lds_dwordx4 v136, s[24:25]
	s_nop 1
	s_add_i32 m0, s23, 0xe000
	s_nop 0
	global_load_lds_dwordx4 v138, s[24:25]
	s_waitcnt lgkmcnt(8)
	ds_read_b128 v[210:213], v151
	ds_read_b128 v[214:217], v151 offset:1024
	ds_read_b128 v[218:221], v151 offset:2048
	ds_read_b128 v[222:225], v151 offset:3072
	s_waitcnt vmcnt(8) lgkmcnt(0)
	s_barrier
	v_mfma_f32_16x16x32_bf16 v[124:127], v[152:155], v[168:171], v[124:127]
	v_mfma_f32_16x16x32_bf16 v[120:123], v[160:163], v[168:171], v[120:123]
	v_mfma_f32_16x16x32_bf16 v[108:111], v[152:155], v[182:185], v[108:111]
	v_mfma_f32_16x16x32_bf16 v[104:107], v[160:163], v[182:185], v[104:107]
	v_mfma_f32_16x16x32_bf16 v[92:95], v[152:155], v[194:197], v[92:95]
	v_mfma_f32_16x16x32_bf16 v[88:91], v[160:163], v[194:197], v[88:91]
	v_mfma_f32_16x16x32_bf16 v[76:79], v[152:155], v[202:205], v[76:79]
	v_mfma_f32_16x16x32_bf16 v[72:75], v[160:163], v[202:205], v[72:75]
	v_mfma_f32_16x16x32_bf16 v[124:127], v[156:159], v[172:175], v[124:127]
	v_mfma_f32_16x16x32_bf16 v[120:123], v[164:167], v[172:175], v[120:123]
	v_mfma_f32_16x16x32_bf16 v[108:111], v[156:159], v[190:193], v[108:111]
	v_mfma_f32_16x16x32_bf16 v[104:107], v[164:167], v[190:193], v[104:107]
	v_mfma_f32_16x16x32_bf16 v[92:95], v[156:159], v[198:201], v[92:95]
	v_mfma_f32_16x16x32_bf16 v[88:91], v[164:167], v[198:201], v[88:91]
	v_mfma_f32_16x16x32_bf16 v[76:79], v[156:159], v[206:209], v[76:79]
	v_mfma_f32_16x16x32_bf16 v[72:75], v[164:167], v[206:209], v[72:75]
	v_mfma_f32_16x16x32_bf16 v[116:119], v[210:213], v[168:171], v[116:119]
	v_mfma_f32_16x16x32_bf16 v[112:115], v[218:221], v[168:171], v[112:115]
	v_mfma_f32_16x16x32_bf16 v[100:103], v[210:213], v[182:185], v[100:103]
	v_mfma_f32_16x16x32_bf16 v[96:99], v[218:221], v[182:185], v[96:99]
	v_mfma_f32_16x16x32_bf16 v[84:87], v[210:213], v[194:197], v[84:87]
	v_mfma_f32_16x16x32_bf16 v[80:83], v[218:221], v[194:197], v[80:83]
	v_mfma_f32_16x16x32_bf16 v[68:71], v[210:213], v[202:205], v[68:71]
	v_mfma_f32_16x16x32_bf16 v[64:67], v[218:221], v[202:205], v[64:67]
	v_mfma_f32_16x16x32_bf16 v[116:119], v[214:217], v[172:175], v[116:119]
	v_mfma_f32_16x16x32_bf16 v[112:115], v[222:225], v[172:175], v[112:115]
	v_mfma_f32_16x16x32_bf16 v[100:103], v[214:217], v[190:193], v[100:103]
	v_mfma_f32_16x16x32_bf16 v[96:99], v[222:225], v[190:193], v[96:99]
	v_mfma_f32_16x16x32_bf16 v[84:87], v[214:217], v[198:201], v[84:87]
	v_mfma_f32_16x16x32_bf16 v[80:83], v[222:225], v[198:201], v[80:83]
	v_mfma_f32_16x16x32_bf16 v[68:71], v[214:217], v[206:209], v[68:71]
	v_mfma_f32_16x16x32_bf16 v[64:67], v[222:225], v[206:209], v[64:67]
	s_barrier
; #define PG8_STAGE(bufoff, gbase, voff) do { _Pragma("unroll") for (int _i = 0; _i < 2; ++_i) \
;         __builtin_amdgcn_global_load_lds((const unsigned*)((const char*)(gbase) + (voff)[_i]), (PG8_LAS unsigned*)(lds + (bufoff) + ldsw + _i * 8192), 16, 0, 0); } while (0)
; #define PG8_LDA(dst, b, h) do { _Pragma("unroll") for (int m = 0; m < 4; ++m) _Pragma("unroll") for (int k = 0; k < 2; ++k) dst[m][k] = *(const PG8_LAS bf16x8*)(lds + PG8_SA(b, h) + aoff + m * 2048 + k * 1024); } while (0)
; #define PG8_WAIT_V(n) asm volatile("s_waitcnt vmcnt(" #n ")" ::: "memory")
; template <class Epi, class Sched>
; __device__ __forceinline__ void gemm_phase(PG8_LAS unsigned char* lds, const Gemm g, const Sched& S, const Epi& E) {
;     ...
;         for (int t = 0; t < nt; t += 2) {
;             const bool last = (t == nt - 2);
;             const char* a1 = cA + (size_t)(t + 1) * kstep;
;             const char* a2 = last ? nA : cA + (size_t)(t + 2) * kstep; const char* b2 = last ? nB : cB + (size_t)(t + 2) * kstep;
;             const char* a3 = a2 + kstep; const char* b3 = b2 + kstep;
;             if (last && has_next) S.a_ready(nxt);
;             PG8_LDB(B0, 0, 0); PG8_SCHED; PG8_LDA(At, 0, 0); PG8_STAGE(PG8_SA(1, 1), a1 + hstep, voffA);
;             PG8_WAIT_L(8); PG8_BAR; PG8_WAIT_L(0); PG8_MMA(0, 0, At, B0); PG8_BAR; PG8_SCHED;
;             PG8_LDB(B1, 0, 1); PG8_STAGE(PG8_SB(0, 0), b2, voffB);
;             PG8_BAR; PG8_WAIT_L(0); PG8_MMA(0, 1, At, B1); PG8_BAR;
;             PG8_LDA(At, 0, 1); PG8_STAGE(PG8_SA(0, 0), a2, voffA);
;             PG8_BAR; PG8_WAIT_L(0); PG8_MMA(1, 0, At, B0); PG8_BAR; PG8_SCHED;
;             PG8_STAGE(PG8_SB(0, 1), b2 + hstep, voffB);
;             PG8_WAIT_V(6); PG8_BAR; PG8_MMA(1, 1, At, B1); PG8_BAR;
;             PG8_LDB(B0, 1, 0); PG8_SCHED; PG8_LDA(At, 1, 0); PG8_STAGE(PG8_SA(0, 1), a2 + hstep, voffA);
;             PG8_WAIT_L(8); PG8_BAR; PG8_WAIT_L(0); PG8_MMA(0, 0, At, B0); PG8_BAR; PG8_SCHED;
;             PG8_LDB(B1, 1, 1); PG8_STAGE(PG8_SB(1, 0), b3, voffB);
;             PG8_BAR; PG8_WAIT_L(0); PG8_MMA(0, 1, At, B1); PG8_BAR;
;             PG8_LDA(At, 1, 1); PG8_STAGE(PG8_SA(1, 0), a3, voffA);
;             PG8_BAR; PG8_WAIT_L(0); PG8_MMA(1, 0, At, B0); PG8_BAR; PG8_SCHED;
;             PG8_STAGE(PG8_SB(1, 1), b3 + hstep, voffB);
;             PG8_WAIT_V(6); PG8_BAR; PG8_MMA(1, 1, At, B1); PG8_BAR;
	ds_read_b128 v[168:171], v150 offset:16384
	ds_read_b128 v[172:175], v150 offset:17408
	ds_read_b128 v[182:185], v150 offset:18432
	ds_read_b128 v[190:193], v150 offset:19456
	ds_read_b128 v[194:197], v150 offset:20480
	ds_read_b128 v[198:201], v150 offset:21504
	ds_read_b128 v[202:205], v150 offset:22528
	ds_read_b128 v[206:209], v150 offset:23552
	s_add_i32 s57, s45, s37
	s_add_u32 s98, s26, s6
	s_addc_u32 s99, s27, s7
	s_mov_b32 m0, s57
	s_nop 0
	global_load_lds_dwordx4 v130, s[26:27]
	s_nop 1
	s_add_i32 m0, s57, 0x2000
	s_nop 0
	global_load_lds_dwordx4 v134, s[26:27]
	s_nop 1
	s_mov_b32 m0, s23
	s_add_u32 s100, s28, s6
	s_addc_u32 s101, s29, s7
	global_load_lds_dwordx4 v128, s[28:29]
	s_nop 1
	s_mov_b32 m0, s38
	s_nop 0
	global_load_lds_dwordx4 v132, s[28:29]
	s_add_u32 s58, s26, 0x40000
	s_addc_u32 s59, s27, 0
	s_add_i32 s57, s46, s37
	s_mov_b32 m0, s57
	s_nop 0
	global_load_lds_dwordx4 v130, s[58:59]
	s_nop 1
	s_add_i32 m0, s57, 0x2000
	s_nop 0
	global_load_lds_dwordx4 v134, s[58:59]
	s_waitcnt vmcnt(8) lgkmcnt(0)
	s_barrier
	v_mfma_f32_16x16x32_bf16 v[60:63], v[152:155], v[168:171], v[60:63]
	v_mfma_f32_16x16x32_bf16 v[56:59], v[160:163], v[168:171], v[56:59]
	v_mfma_f32_16x16x32_bf16 v[48:51], v[152:155], v[182:185], v[48:51]
	v_mfma_f32_16x16x32_bf16 v[40:43], v[160:163], v[182:185], v[40:43]
	v_mfma_f32_16x16x32_bf16 v[32:35], v[152:155], v[194:197], v[32:35]
	v_mfma_f32_16x16x32_bf16 v[24:27], v[160:163], v[194:197], v[24:27]
	v_mfma_f32_16x16x32_bf16 v[16:19], v[152:155], v[202:205], v[16:19]
	v_mfma_f32_16x16x32_bf16 v[8:11], v[160:163], v[202:205], v[8:11]
	v_mfma_f32_16x16x32_bf16 v[60:63], v[156:159], v[172:175], v[60:63]
	v_mfma_f32_16x16x32_bf16 v[56:59], v[164:167], v[172:175], v[56:59]
	v_mfma_f32_16x16x32_bf16 v[48:51], v[156:159], v[190:193], v[48:51]
	v_mfma_f32_16x16x32_bf16 v[40:43], v[164:167], v[190:193], v[40:43]
	v_mfma_f32_16x16x32_bf16 v[32:35], v[156:159], v[198:201], v[32:35]
	v_mfma_f32_16x16x32_bf16 v[24:27], v[164:167], v[198:201], v[24:27]
	v_mfma_f32_16x16x32_bf16 v[16:19], v[156:159], v[206:209], v[16:19]
	v_mfma_f32_16x16x32_bf16 v[8:11], v[164:167], v[206:209], v[8:11]
	v_mfma_f32_16x16x32_bf16 v[52:55], v[210:213], v[168:171], v[52:55]
	v_mfma_f32_16x16x32_bf16 v[44:47], v[218:221], v[168:171], v[44:47]
	v_mfma_f32_16x16x32_bf16 v[36:39], v[210:213], v[182:185], v[36:39]
	v_mfma_f32_16x16x32_bf16 v[28:31], v[218:221], v[182:185], v[28:31]
	v_mfma_f32_16x16x32_bf16 v[20:23], v[210:213], v[194:197], v[20:23]
	v_mfma_f32_16x16x32_bf16 v[12:15], v[218:221], v[194:197], v[12:15]
	v_mfma_f32_16x16x32_bf16 v[4:7], v[210:213], v[202:205], v[4:7]
	v_mfma_f32_16x16x32_bf16 v[0:3], v[218:221], v[202:205], v[0:3]
	v_mfma_f32_16x16x32_bf16 v[52:55], v[214:217], v[172:175], v[52:55]
	v_mfma_f32_16x16x32_bf16 v[44:47], v[222:225], v[172:175], v[44:47]
	v_mfma_f32_16x16x32_bf16 v[36:39], v[214:217], v[190:193], v[36:39]
	v_mfma_f32_16x16x32_bf16 v[28:31], v[222:225], v[190:193], v[28:31]
	v_mfma_f32_16x16x32_bf16 v[20:23], v[214:217], v[198:201], v[20:23]
	v_mfma_f32_16x16x32_bf16 v[12:15], v[222:225], v[198:201], v[12:15]
	v_mfma_f32_16x16x32_bf16 v[4:7], v[214:217], v[206:209], v[4:7]
	v_mfma_f32_16x16x32_bf16 v[0:3], v[222:225], v[206:209], v[0:3]
	s_barrier
	s_add_i32 s57, 0, 0x18000
	v_add_u32_e32 v164, s57, v147
	ds_read_b128 v[152:155], v164
	ds_read_b128 v[156:159], v164 offset:1024
	ds_read_b128 v[160:163], v164 offset:2048
	ds_read_b128 v[164:167], v164 offset:3072
	s_add_u32 s28, s28, 0x40000
	s_addc_u32 s29, s29, 0
	s_mov_b32 m0, s39
	ds_read_b128 v[168:171], v150 offset:32768
	ds_read_b128 v[172:175], v150 offset:33792
	ds_read_b128 v[182:185], v150 offset:34816
	ds_read_b128 v[190:193], v150 offset:35840
	ds_read_b128 v[194:197], v150 offset:36864
	ds_read_b128 v[198:201], v150 offset:37888
	ds_read_b128 v[202:205], v150 offset:38912
	ds_read_b128 v[206:209], v150 offset:39936
	global_load_lds_dwordx4 v128, s[28:29]
	s_nop 1
	s_mov_b32 m0, s40
	s_nop 0
	global_load_lds_dwordx4 v132, s[28:29]
	s_add_i32 s28, 0, 0x1c000
	v_add_u32_e32 v179, s28, v147
	s_waitcnt lgkmcnt(8)
	ds_read_b128 v[210:213], v179
	ds_read_b128 v[214:217], v179 offset:1024
	ds_read_b128 v[218:221], v179 offset:2048
	ds_read_b128 v[222:225], v179 offset:3072
	s_waitcnt vmcnt(8) lgkmcnt(0)
	s_barrier
	v_mfma_f32_16x16x32_bf16 v[124:127], v[152:155], v[168:171], v[124:127]
	v_mfma_f32_16x16x32_bf16 v[120:123], v[160:163], v[168:171], v[120:123]
	v_mfma_f32_16x16x32_bf16 v[108:111], v[152:155], v[182:185], v[108:111]
	v_mfma_f32_16x16x32_bf16 v[104:107], v[160:163], v[182:185], v[104:107]
	v_mfma_f32_16x16x32_bf16 v[92:95], v[152:155], v[194:197], v[92:95]
	v_mfma_f32_16x16x32_bf16 v[88:91], v[160:163], v[194:197], v[88:91]
	v_mfma_f32_16x16x32_bf16 v[76:79], v[152:155], v[202:205], v[76:79]
	v_mfma_f32_16x16x32_bf16 v[72:75], v[160:163], v[202:205], v[72:75]
	v_mfma_f32_16x16x32_bf16 v[124:127], v[156:159], v[172:175], v[124:127]
	v_mfma_f32_16x16x32_bf16 v[120:123], v[164:167], v[172:175], v[120:123]
	v_mfma_f32_16x16x32_bf16 v[108:111], v[156:159], v[190:193], v[108:111]
	v_mfma_f32_16x16x32_bf16 v[104:107], v[164:167], v[190:193], v[104:107]
	v_mfma_f32_16x16x32_bf16 v[92:95], v[156:159], v[198:201], v[92:95]
	v_mfma_f32_16x16x32_bf16 v[88:91], v[164:167], v[198:201], v[88:91]
	v_mfma_f32_16x16x32_bf16 v[76:79], v[156:159], v[206:209], v[76:79]
	v_mfma_f32_16x16x32_bf16 v[72:75], v[164:167], v[206:209], v[72:75]
	v_mfma_f32_16x16x32_bf16 v[116:119], v[210:213], v[168:171], v[116:119]
	v_mfma_f32_16x16x32_bf16 v[112:115], v[218:221], v[168:171], v[112:115]
	v_mfma_f32_16x16x32_bf16 v[100:103], v[210:213], v[182:185], v[100:103]
	v_mfma_f32_16x16x32_bf16 v[96:99], v[218:221], v[182:185], v[96:99]
	v_mfma_f32_16x16x32_bf16 v[84:87], v[210:213], v[194:197], v[84:87]
	v_mfma_f32_16x16x32_bf16 v[80:83], v[218:221], v[194:197], v[80:83]
	v_mfma_f32_16x16x32_bf16 v[68:71], v[210:213], v[202:205], v[68:71]
	v_mfma_f32_16x16x32_bf16 v[64:67], v[218:221], v[202:205], v[64:67]
	v_mfma_f32_16x16x32_bf16 v[116:119], v[214:217], v[172:175], v[116:119]
	v_mfma_f32_16x16x32_bf16 v[112:115], v[222:225], v[172:175], v[112:115]
	v_mfma_f32_16x16x32_bf16 v[100:103], v[214:217], v[190:193], v[100:103]
	v_mfma_f32_16x16x32_bf16 v[96:99], v[222:225], v[190:193], v[96:99]
	v_mfma_f32_16x16x32_bf16 v[84:87], v[214:217], v[198:201], v[84:87]
	v_mfma_f32_16x16x32_bf16 v[80:83], v[222:225], v[198:201], v[80:83]
	v_mfma_f32_16x16x32_bf16 v[68:71], v[214:217], v[206:209], v[68:71]
	v_mfma_f32_16x16x32_bf16 v[64:67], v[222:225], v[206:209], v[64:67]
	s_barrier
;     __device__ __forceinline__ void operator()(const f32x4 (&acc)[2][2][4][2], const Unit& u, int wr, int wc, int fr, int fq) const {
;     ...
;             for (int m = 0; m < 4; ++m) { bf16_t* rowp = O + (size_t)(row0 + ai * HALF + m * 16) * ldc + col0;
; #pragma unroll
;                 for (int bj = 0; bj < 2; ++bj) { f32x4 v0 = acc[ai][bj][m][0] + bv[bj][0], v1 = acc[ai][bj][m][1] + bv[bj][1];
;                     if (act == 1) {
; #pragma unroll
;                         for (int j = 0; j < 1; ++j) { v0 = v0 * sigmoid4(v0); v1 = v1 * sigmoid4(v1); } }
; template <class Epi, class Sched>
; __device__ __forceinline__ void gemm_phase(PG8_LAS unsigned char* lds, const Gemm g, const Sched& S, const Epi& E) {
;     ...
;         for (int t = 0; t < nt; t += 2) {
;             const bool last = (t == nt - 2);
;             const char* a1 = cA + (size_t)(t + 1) * kstep;
;             const char* a2 = last ? nA : cA + (size_t)(t + 2) * kstep; const char* b2 = last ? nB : cB + (size_t)(t + 2) * kstep;
;             const char* a3 = a2 + kstep; const char* b3 = b2 + kstep;
;             if (last && has_next) S.a_ready(nxt);
;             PG8_LDB(B0, 0, 0); PG8_SCHED; PG8_LDA(At, 0, 0); PG8_STAGE(PG8_SA(1, 1), a1 + hstep, voffA);
;             PG8_WAIT_L(8); PG8_BAR; PG8_WAIT_L(0); PG8_MMA(0, 0, At, B0); PG8_BAR; PG8_SCHED;
;             PG8_LDB(B1, 0, 1); PG8_STAGE(PG8_SB(0, 0), b2, voffB);
;             PG8_BAR; PG8_WAIT_L(0); PG8_MMA(0, 1, At, B1); PG8_BAR;
;             PG8_LDA(At, 0, 1); PG8_STAGE(PG8_SA(0, 0), a2, voffA);
;             PG8_BAR; PG8_WAIT_L(0); PG8_MMA(1, 0, At, B0); PG8_BAR; PG8_SCHED;
;             PG8_STAGE(PG8_SB(0, 1), b2 + hstep, voffB);
;             PG8_WAIT_V(6); PG8_BAR; PG8_MMA(1, 1, At, B1); PG8_BAR;
;             PG8_LDB(B0, 1, 0); PG8_SCHED; PG8_LDA(At, 1, 0); PG8_STAGE(PG8_SA(0, 1), a2 + hstep, voffA);
;             PG8_WAIT_L(8); PG8_BAR; PG8_WAIT_L(0); PG8_MMA(0, 0, At, B0); PG8_BAR; PG8_SCHED;
;             PG8_LDB(B1, 1, 1); PG8_STAGE(PG8_SB(1, 0), b3, voffB);
;             PG8_BAR; PG8_WAIT_L(0); PG8_MMA(0, 1, At, B1); PG8_BAR;
;             PG8_LDA(At, 1, 1); PG8_STAGE(PG8_SA(1, 0), a3, voffA);
;             PG8_BAR; PG8_WAIT_L(0); PG8_MMA(1, 0, At, B0); PG8_BAR; PG8_SCHED;
;             PG8_STAGE(PG8_SB(1, 1), b3 + hstep, voffB);
;             PG8_WAIT_V(6); PG8_BAR; PG8_MMA(1, 1, At, B1); PG8_BAR;
	ds_read_b128 v[168:171], v150 offset:49152
	ds_read_b128 v[172:175], v150 offset:50176
	ds_read_b128 v[182:185], v150 offset:51200
	ds_read_b128 v[190:193], v150 offset:52224
	ds_read_b128 v[194:197], v150 offset:53248
	ds_read_b128 v[198:201], v150 offset:54272
	ds_read_b128 v[202:205], v150 offset:55296
	ds_read_b128 v[206:209], v150 offset:56320
	s_add_i32 s29, s57, s37
	s_mov_b32 m0, s29
	s_nop 0
	global_load_lds_dwordx4 v130, s[98:99]
	s_nop 1
	s_add_i32 m0, s29, 0x2000
	s_nop 0
	global_load_lds_dwordx4 v134, s[98:99]
	s_nop 1
	s_mov_b32 m0, s42
	s_nop 0
	global_load_lds_dwordx4 v128, s[100:101]
	s_nop 1
	s_mov_b32 m0, s43
	s_nop 0
	global_load_lds_dwordx4 v132, s[100:101]
	s_add_u32 s26, s26, 0x40080
	s_addc_u32 s27, s27, 0
	s_add_i32 s28, s28, s37
	s_mov_b32 m0, s28
	s_nop 0
	global_load_lds_dwordx4 v130, s[26:27]
	s_nop 1
	s_add_i32 m0, s28, 0x2000
	s_nop 0
	global_load_lds_dwordx4 v134, s[26:27]
	s_waitcnt vmcnt(8) lgkmcnt(0)
	s_barrier
	v_mfma_f32_16x16x32_bf16 v[60:63], v[152:155], v[168:171], v[60:63]
	v_mfma_f32_16x16x32_bf16 v[56:59], v[160:163], v[168:171], v[56:59]
	v_mfma_f32_16x16x32_bf16 v[48:51], v[152:155], v[182:185], v[48:51]
	v_mfma_f32_16x16x32_bf16 v[40:43], v[160:163], v[182:185], v[40:43]
	v_mfma_f32_16x16x32_bf16 v[32:35], v[152:155], v[194:197], v[32:35]
	v_mfma_f32_16x16x32_bf16 v[24:27], v[160:163], v[194:197], v[24:27]
	v_mfma_f32_16x16x32_bf16 v[16:19], v[152:155], v[202:205], v[16:19]
	v_mfma_f32_16x16x32_bf16 v[8:11], v[160:163], v[202:205], v[8:11]
	v_mfma_f32_16x16x32_bf16 v[60:63], v[156:159], v[172:175], v[60:63]
	v_mfma_f32_16x16x32_bf16 v[56:59], v[164:167], v[172:175], v[56:59]
	v_mfma_f32_16x16x32_bf16 v[48:51], v[156:159], v[190:193], v[48:51]
	v_mfma_f32_16x16x32_bf16 v[40:43], v[164:167], v[190:193], v[40:43]
	v_mfma_f32_16x16x32_bf16 v[32:35], v[156:159], v[198:201], v[32:35]
	v_mfma_f32_16x16x32_bf16 v[24:27], v[164:167], v[198:201], v[24:27]
	v_mfma_f32_16x16x32_bf16 v[16:19], v[156:159], v[206:209], v[16:19]
	v_mfma_f32_16x16x32_bf16 v[8:11], v[164:167], v[206:209], v[8:11]
	v_mfma_f32_16x16x32_bf16 v[52:55], v[210:213], v[168:171], v[52:55]
	v_mfma_f32_16x16x32_bf16 v[44:47], v[218:221], v[168:171], v[44:47]
	v_mfma_f32_16x16x32_bf16 v[36:39], v[210:213], v[182:185], v[36:39]
	v_mfma_f32_16x16x32_bf16 v[28:31], v[218:221], v[182:185], v[28:31]
	v_mfma_f32_16x16x32_bf16 v[20:23], v[210:213], v[194:197], v[20:23]
	v_mfma_f32_16x16x32_bf16 v[12:15], v[218:221], v[194:197], v[12:15]
	v_mfma_f32_16x16x32_bf16 v[4:7], v[210:213], v[202:205], v[4:7]
	v_mfma_f32_16x16x32_bf16 v[0:3], v[218:221], v[202:205], v[0:3]
	v_mfma_f32_16x16x32_bf16 v[52:55], v[214:217], v[172:175], v[52:55]
	v_mfma_f32_16x16x32_bf16 v[44:47], v[222:225], v[172:175], v[44:47]
	v_mfma_f32_16x16x32_bf16 v[36:39], v[214:217], v[190:193], v[36:39]
	v_mfma_f32_16x16x32_bf16 v[28:31], v[222:225], v[190:193], v[28:31]
	v_mfma_f32_16x16x32_bf16 v[20:23], v[214:217], v[198:201], v[20:23]
	v_mfma_f32_16x16x32_bf16 v[12:15], v[222:225], v[198:201], v[12:15]
	v_mfma_f32_16x16x32_bf16 v[4:7], v[214:217], v[206:209], v[4:7]
	v_mfma_f32_16x16x32_bf16 v[0:3], v[222:225], v[206:209], v[0:3]
	s_barrier
	s_add_i32 s56, s56, 2
	s_add_u32 s24, s24, 0x100
	s_addc_u32 s25, s25, 0
	s_add_u32 s54, s54, 0x100
	s_addc_u32 s55, s55, 0
	s_cmp_gt_u32 s56, 13
	s_cbranch_scc0 .LBB0_1083
	v_lshl_add_u32 v152, s22, 8, v146
	v_lshl_or_b32 v144, s51, 8, v148
	v_ashrrev_i32_e32 v153, 31, v152
	v_ashrrev_i32_e32 v145, 31, v144
	v_lshlrev_b64 v[154:155], 11, v[152:153]
	v_lshl_add_u64 v[154:155], s[4:5], 0, v[154:155]
	v_lshlrev_b64 v[156:157], 1, v[144:145]
	v_lshl_add_u64 v[144:145], v[154:155], 0, v[156:157]
	v_pk_add_f32 v[126:127], v[126:127], 0 op_sel_hi:[1,0]
	v_pk_add_f32 v[124:125], v[124:125], 0 op_sel_hi:[1,0]
	v_pk_add_f32 v[154:155], v[122:123], 0 op_sel_hi:[1,0]
	v_pk_add_f32 v[122:123], v[120:121], 0 op_sel_hi:[1,0]
	v_cvt_pk_bf16_f32 v120, v124, v125
	v_cvt_pk_bf16_f32 v121, v126, v127
	v_pk_add_f32 v[116:117], v[116:117], 0 op_sel_hi:[1,0]
	v_cvt_pk_bf16_f32 v122, v122, v123
	v_cvt_pk_bf16_f32 v123, v154, v155
	global_store_dwordx4 v[144:145], v[120:123], off
	v_pk_add_f32 v[118:119], v[118:119], 0 op_sel_hi:[1,0]
	v_pk_add_f32 v[110:111], v[110:111], 0 op_sel_hi:[1,0]
	v_pk_add_f32 v[120:121], v[114:115], 0 op_sel_hi:[1,0]
	v_pk_add_f32 v[114:115], v[112:113], 0 op_sel_hi:[1,0]
	v_cvt_pk_bf16_f32 v112, v116, v117
	v_cvt_pk_bf16_f32 v113, v118, v119
	v_pk_add_f32 v[108:109], v[108:109], 0 op_sel_hi:[1,0]
	v_cvt_pk_bf16_f32 v114, v114, v115
	v_cvt_pk_bf16_f32 v115, v120, v121
	global_store_dwordx4 v[144:145], v[112:115], off offset:256
	v_pk_add_f32 v[100:101], v[100:101], 0 op_sel_hi:[1,0]
	v_pk_add_f32 v[102:103], v[102:103], 0 op_sel_hi:[1,0]
	v_or_b32_e32 v112, 16, v152
	v_ashrrev_i32_e32 v113, 31, v112
	v_lshlrev_b64 v[112:113], 11, v[112:113]
	v_lshl_add_u64 v[112:113], s[4:5], 0, v[112:113]
	v_lshl_add_u64 v[112:113], v[112:113], 0, v[156:157]
	v_pk_add_f32 v[114:115], v[106:107], 0 op_sel_hi:[1,0]
	v_pk_add_f32 v[106:107], v[104:105], 0 op_sel_hi:[1,0]
	v_cvt_pk_bf16_f32 v104, v108, v109
	v_cvt_pk_bf16_f32 v105, v110, v111
	v_pk_add_f32 v[94:95], v[94:95], 0 op_sel_hi:[1,0]
	v_cvt_pk_bf16_f32 v106, v106, v107
	v_cvt_pk_bf16_f32 v107, v114, v115
	global_store_dwordx4 v[112:113], v[104:107], off
	v_pk_add_f32 v[92:93], v[92:93], 0 op_sel_hi:[1,0]
	v_pk_add_f32 v[84:85], v[84:85], 0 op_sel_hi:[1,0]
	v_pk_add_f32 v[104:105], v[98:99], 0 op_sel_hi:[1,0]
	v_pk_add_f32 v[98:99], v[96:97], 0 op_sel_hi:[1,0]
	v_cvt_pk_bf16_f32 v96, v100, v101
	v_cvt_pk_bf16_f32 v97, v102, v103
	v_pk_add_f32 v[86:87], v[86:87], 0 op_sel_hi:[1,0]
; __device__ __forceinline__ unsigned cvt_pk_bf16(float lo, float hi) { unsigned r; asm volatile("v_cvt_pk_bf16_f32 %0, %1, %2" : "=v"(r) : "v"(lo), "v"(hi)); return r; }
;     __device__ __forceinline__ void operator()(const f32x4 (&acc)[2][2][4][2], const Unit& u, int wr, int wc, int fr, int fq) const {
;     ...
;         const int row0 = u.pm * BM + wr * 64 + fr, col0 = u.pn * BM + wc * 32 + 8 * fq, bcol0 = wc * 32 + 8 * fq;
;         f32x4 bv[2][2];
; #pragma unroll
;         for (int bj = 0; bj < 2; ++bj)
; #pragma unroll
;             for (int n = 0; n < 2; ++n) bv[bj][n] = bias ? *(const f32x4*)(bias + bcol0 + bj * HALF + 4 * n) : (f32x4){0.f, 0.f, 0.f, 0.f};
; #pragma unroll
;         for (int ai = 0; ai < 2; ++ai)
; #pragma unroll
;             for (int m = 0; m < 4; ++m) { bf16_t* rowp = O + (size_t)(row0 + ai * HALF + m * 16) * ldc + col0;
; #pragma unroll
;                 for (int bj = 0; bj < 2; ++bj) { f32x4 v0 = acc[ai][bj][m][0] + bv[bj][0], v1 = acc[ai][bj][m][1] + bv[bj][1];
;                     if (act == 1) {
; #pragma unroll
;                         for (int j = 0; j < 1; ++j) { v0 = v0 * sigmoid4(v0); v1 = v1 * sigmoid4(v1); } }
;                     else if (act == 2) {
; #pragma unroll
;                         for (int j = 0; j < 1; ++j) { v0 = sigmoid4(v0); v1 = sigmoid4(v1); } }
;                     else if (act == 3) {
; #pragma unroll
;                         for (int j = 0; j < 4; ++j) { v0[j] = flogsig16(v0[j]); v1[j] = flogsig16(v1[j]); } }
;                     u32x4 w; w.x = cvt_pk_bf16(v0[0], v0[1]); w.y = cvt_pk_bf16(v0[2], v0[3]); w.z = cvt_pk_bf16(v1[0], v1[1]); w.w = cvt_pk_bf16(v1[2], v1[3]);
;                     *(u32x4*)(rowp + bj * HALF) = w; } }
; template <class Epi, class Sched>
; __device__ __forceinline__ void gemm_phase(PG8_LAS unsigned char* lds, const Gemm g, const Sched& S, const Epi& E) {
;     ...
;         if constexpr (!Epi::AFTER_DRAIN) { E(acc, cur, wr, wc, fr, fq); S.done(cur); }
;         if (!has_next) break;
; #pragma unroll
;         for (int a = 0; a < 2; ++a)
; #pragma unroll
;             for (int b = 0; b < 2; ++b)
; #pragma unroll
;                 for (int m = 0; m < 4; ++m)
; #pragma unroll
;                     for (int n = 0; n < 2; ++n) acc[a][b][m][n] = (f32x4){0.f, 0.f, 0.f, 0.f};
;         cur = nxt; cA = nA; cB = nB; ++ui;
;     }
;     PG8_WAIT_V(0);
;     if (wr == 0) PG8_BAR;
;     PG8_BAR;
	v_cvt_pk_bf16_f32 v98, v98, v99
	v_cvt_pk_bf16_f32 v99, v104, v105
	global_store_dwordx4 v[112:113], v[96:99], off offset:256
	v_pk_add_f32 v[78:79], v[78:79], 0 op_sel_hi:[1,0]
	v_pk_add_f32 v[76:77], v[76:77], 0 op_sel_hi:[1,0]
	v_or_b32_e32 v96, 32, v152
	v_ashrrev_i32_e32 v97, 31, v96
	v_lshlrev_b64 v[96:97], 11, v[96:97]
	v_lshl_add_u64 v[96:97], s[4:5], 0, v[96:97]
	v_lshl_add_u64 v[96:97], v[96:97], 0, v[156:157]
	v_pk_add_f32 v[98:99], v[90:91], 0 op_sel_hi:[1,0]
	v_pk_add_f32 v[90:91], v[88:89], 0 op_sel_hi:[1,0]
	v_cvt_pk_bf16_f32 v88, v92, v93
	v_cvt_pk_bf16_f32 v89, v94, v95
	v_pk_add_f32 v[70:71], v[70:71], 0 op_sel_hi:[1,0]
	v_cvt_pk_bf16_f32 v90, v90, v91
	v_cvt_pk_bf16_f32 v91, v98, v99
	global_store_dwordx4 v[96:97], v[88:91], off
	v_pk_add_f32 v[68:69], v[68:69], 0 op_sel_hi:[1,0]
	v_pk_add_f32 v[60:61], v[60:61], 0 op_sel_hi:[1,0]
	v_pk_add_f32 v[88:89], v[82:83], 0 op_sel_hi:[1,0]
	v_pk_add_f32 v[82:83], v[80:81], 0 op_sel_hi:[1,0]
	v_cvt_pk_bf16_f32 v80, v84, v85
	v_cvt_pk_bf16_f32 v81, v86, v87
	v_pk_add_f32 v[62:63], v[62:63], 0 op_sel_hi:[1,0]
	v_cvt_pk_bf16_f32 v82, v82, v83
	v_cvt_pk_bf16_f32 v83, v88, v89
	global_store_dwordx4 v[96:97], v[80:83], off offset:256
	v_pk_add_f32 v[54:55], v[54:55], 0 op_sel_hi:[1,0]
	v_pk_add_f32 v[52:53], v[52:53], 0 op_sel_hi:[1,0]
	v_or_b32_e32 v80, 48, v152
	v_ashrrev_i32_e32 v81, 31, v80
	v_lshlrev_b64 v[80:81], 11, v[80:81]
	v_lshl_add_u64 v[80:81], s[4:5], 0, v[80:81]
	v_lshl_add_u64 v[80:81], v[80:81], 0, v[156:157]
	v_pk_add_f32 v[82:83], v[74:75], 0 op_sel_hi:[1,0]
	v_pk_add_f32 v[74:75], v[72:73], 0 op_sel_hi:[1,0]
	v_cvt_pk_bf16_f32 v72, v76, v77
	v_cvt_pk_bf16_f32 v73, v78, v79
	v_pk_add_f32 v[48:49], v[48:49], 0 op_sel_hi:[1,0]
	v_cvt_pk_bf16_f32 v74, v74, v75
	v_cvt_pk_bf16_f32 v75, v82, v83
	global_store_dwordx4 v[80:81], v[72:75], off
	v_pk_add_f32 v[38:39], v[38:39], 0 op_sel_hi:[1,0]
	v_pk_add_f32 v[36:37], v[36:37], 0 op_sel_hi:[1,0]
	v_pk_add_f32 v[72:73], v[66:67], 0 op_sel_hi:[1,0]
	v_pk_add_f32 v[66:67], v[64:65], 0 op_sel_hi:[1,0]
	v_cvt_pk_bf16_f32 v64, v68, v69
	v_cvt_pk_bf16_f32 v65, v70, v71
	v_pk_add_f32 v[32:33], v[32:33], 0 op_sel_hi:[1,0]
	v_cvt_pk_bf16_f32 v66, v66, v67
	v_cvt_pk_bf16_f32 v67, v72, v73
	global_store_dwordx4 v[80:81], v[64:67], off offset:256
	v_pk_add_f32 v[22:23], v[22:23], 0 op_sel_hi:[1,0]
	v_pk_add_f32 v[20:21], v[20:21], 0 op_sel_hi:[1,0]
	v_pk_add_f32 v[66:67], v[58:59], 0 op_sel_hi:[1,0]
	v_pk_add_f32 v[58:59], v[56:57], 0 op_sel_hi:[1,0]
	v_cvt_pk_bf16_f32 v56, v60, v61
	v_add_co_u32_e32 v60, vcc, s47, v144
	v_cvt_pk_bf16_f32 v57, v62, v63
	v_cvt_pk_bf16_f32 v58, v58, v59
	v_cvt_pk_bf16_f32 v59, v66, v67
	v_lshl_add_u64 v[64:65], v[144:145], 0, s[0:1]
	s_nop 0
	v_addc_co_u32_e32 v61, vcc, 0, v145, vcc
	global_store_dwordx4 v[60:61], v[56:59], off
	v_pk_add_f32 v[16:17], v[16:17], 0 op_sel_hi:[1,0]
	s_mov_b32 s51, s14
	v_pk_add_f32 v[56:57], v[46:47], 0 op_sel_hi:[1,0]
	v_pk_add_f32 v[46:47], v[44:45], 0 op_sel_hi:[1,0]
	v_cvt_pk_bf16_f32 v44, v52, v53
	v_cvt_pk_bf16_f32 v45, v54, v55
	s_mov_b32 s22, s16
	v_cvt_pk_bf16_f32 v46, v46, v47
	v_cvt_pk_bf16_f32 v47, v56, v57
	global_store_dwordx4 v[64:65], v[44:47], off offset:256
	s_mov_b64 s[26:27], s[20:21]
	s_mov_b64 s[24:25], s[18:19]
	v_pk_add_f32 v[46:47], v[50:51], 0 op_sel_hi:[1,0]
	v_pk_add_f32 v[50:51], v[42:43], 0 op_sel_hi:[1,0]
	v_pk_add_f32 v[42:43], v[40:41], 0 op_sel_hi:[1,0]
	v_cvt_pk_bf16_f32 v40, v48, v49
	v_cvt_pk_bf16_f32 v41, v46, v47
	v_add_co_u32_e32 v46, vcc, s48, v144
	v_cvt_pk_bf16_f32 v42, v42, v43
	v_cvt_pk_bf16_f32 v43, v50, v51
	v_lshl_add_u64 v[44:45], v[144:145], 0, s[8:9]
	s_nop 0
	v_addc_co_u32_e32 v47, vcc, 0, v145, vcc
	global_store_dwordx4 v[46:47], v[40:43], off
	v_pk_add_f32 v[6:7], v[6:7], 0 op_sel_hi:[1,0]
	v_pk_add_f32 v[4:5], v[4:5], 0 op_sel_hi:[1,0]
	v_pk_add_f32 v[40:41], v[30:31], 0 op_sel_hi:[1,0]
	v_pk_add_f32 v[30:31], v[28:29], 0 op_sel_hi:[1,0]
	v_cvt_pk_bf16_f32 v28, v36, v37
	v_cvt_pk_bf16_f32 v29, v38, v39
	s_nop 0
	v_cvt_pk_bf16_f32 v30, v30, v31
	v_cvt_pk_bf16_f32 v31, v40, v41
	global_store_dwordx4 v[44:45], v[28:31], off offset:256
	s_nop 1
	v_pk_add_f32 v[30:31], v[34:35], 0 op_sel_hi:[1,0]
	v_pk_add_f32 v[34:35], v[26:27], 0 op_sel_hi:[1,0]
	v_pk_add_f32 v[26:27], v[24:25], 0 op_sel_hi:[1,0]
	v_cvt_pk_bf16_f32 v24, v32, v33
	v_cvt_pk_bf16_f32 v25, v30, v31
	v_add_co_u32_e32 v30, vcc, s49, v144
	v_cvt_pk_bf16_f32 v26, v26, v27
	v_cvt_pk_bf16_f32 v27, v34, v35
	v_lshl_add_u64 v[28:29], v[144:145], 0, s[10:11]
	s_nop 0
	v_addc_co_u32_e32 v31, vcc, 0, v145, vcc
	global_store_dwordx4 v[30:31], v[24:27], off
	s_nop 1
	v_pk_add_f32 v[24:25], v[14:15], 0 op_sel_hi:[1,0]
	v_pk_add_f32 v[14:15], v[12:13], 0 op_sel_hi:[1,0]
	v_cvt_pk_bf16_f32 v12, v20, v21
	v_cvt_pk_bf16_f32 v13, v22, v23
	s_nop 0
	v_cvt_pk_bf16_f32 v14, v14, v15
	v_cvt_pk_bf16_f32 v15, v24, v25
	global_store_dwordx4 v[28:29], v[12:15], off offset:256
	s_nop 1
	v_pk_add_f32 v[14:15], v[18:19], 0 op_sel_hi:[1,0]
	v_pk_add_f32 v[18:19], v[10:11], 0 op_sel_hi:[1,0]
	v_pk_add_f32 v[10:11], v[8:9], 0 op_sel_hi:[1,0]
	v_cvt_pk_bf16_f32 v8, v16, v17
	v_cvt_pk_bf16_f32 v9, v14, v15
	v_add_co_u32_e32 v14, vcc, s50, v144
	v_lshl_add_u64 v[12:13], v[144:145], 0, s[12:13]
	s_nop 0
	v_addc_co_u32_e32 v15, vcc, 0, v145, vcc
	v_cvt_pk_bf16_f32 v10, v10, v11
	v_cvt_pk_bf16_f32 v11, v18, v19
	global_store_dwordx4 v[14:15], v[8:11], off
	s_and_b64 vcc, exec, s[2:3]
	s_nop 0
	v_pk_add_f32 v[8:9], v[2:3], 0 op_sel_hi:[1,0]
	v_pk_add_f32 v[2:3], v[0:1], 0 op_sel_hi:[1,0]
	v_cvt_pk_bf16_f32 v0, v4, v5
	v_cvt_pk_bf16_f32 v1, v6, v7
	s_nop 0
	v_cvt_pk_bf16_f32 v2, v2, v3
	v_cvt_pk_bf16_f32 v3, v8, v9
	global_store_dwordx4 v[12:13], v[0:3], off offset:256
	s_cbranch_vccz .LBB0_1076
	s_waitcnt vmcnt(0)
	s_cmpk_gt_u32 s31, 0xff
	s_cbranch_scc1 .LBB0_1087
	s_barrier

; #define PG8_STAGE(bufoff, gbase, voff) do { _Pragma("unroll") for (int _i = 0; _i < 2; ++_i) \
;         __builtin_amdgcn_global_load_lds((const unsigned*)((const char*)(gbase) + (voff)[_i]), (PG8_LAS unsigned*)(lds + (bufoff) + ldsw + _i * 8192), 16, 0, 0); } while (0)
; #define PG8_LDA(dst, b, h) do { _Pragma("unroll") for (int m = 0; m < 4; ++m) _Pragma("unroll") for (int k = 0; k < 2; ++k) dst[m][k] = *(const PG8_LAS bf16x8*)(lds + PG8_SA(b, h) + aoff + m * 2048 + k * 1024); } while (0)
; #define PG8_LDB(dst, b, h) do { _Pragma("unroll") for (int n = 0; n < 2; ++n) _Pragma("unroll") for (int k = 0; k < 2; ++k) dst[n][k] = *(const PG8_LAS bf16x8*)(lds + PG8_SB(b, h) + boff + n * 2048 + k * 1024); } while (0)
; #define PG8_WAIT_V(n) asm volatile("s_waitcnt vmcnt(" #n ")" ::: "memory")
; #define PG8_WAIT_L(n) asm volatile("s_waitcnt lgkmcnt(" #n ")" ::: "memory")
; #define PG8_BAR __builtin_amdgcn_s_barrier()
; #define PG8_SCHED __builtin_amdgcn_sched_barrier(0)
; template <class Epi, class Sched>
; __device__ __forceinline__ void gemm_phase(PG8_LAS unsigned char* lds, const Gemm g, const Sched& S, const Epi& E) {
;     ...
;         const bool has_next = S.next(ui + 1, nxt);
;         const char* nA = has_next ? (const char*)g.A + (size_t)nxt.pm * tstep : cA; const char* nB = has_next ? (const char*)g.Bt + (size_t)nxt.pn * tstep : cB;
;         for (int t = 0; t < nt; t += 2) {
;             const bool last = (t == nt - 2);
;             const char* a1 = cA + (size_t)(t + 1) * kstep;
;             const char* a2 = last ? nA : cA + (size_t)(t + 2) * kstep; const char* b2 = last ? nB : cB + (size_t)(t + 2) * kstep;
;             const char* a3 = a2 + kstep; const char* b3 = b2 + kstep;
;             if (last && has_next) S.a_ready(nxt);
;             PG8_LDB(B0, 0, 0); PG8_SCHED; PG8_LDA(At, 0, 0); PG8_STAGE(PG8_SA(1, 1), a1 + hstep, voffA);
;             PG8_WAIT_L(8); PG8_BAR; PG8_WAIT_L(0); PG8_MMA(0, 0, At, B0); PG8_BAR; PG8_SCHED;
;             PG8_LDB(B1, 0, 1); PG8_STAGE(PG8_SB(0, 0), b2, voffB);
;             PG8_BAR; PG8_WAIT_L(0); PG8_MMA(0, 1, At, B1); PG8_BAR;
;             PG8_LDA(At, 0, 1); PG8_STAGE(PG8_SA(0, 0), a2, voffA);
;             PG8_BAR; PG8_WAIT_L(0); PG8_MMA(1, 0, At, B0); PG8_BAR; PG8_SCHED;
;             PG8_STAGE(PG8_SB(0, 1), b2 + hstep, voffB);
;             PG8_WAIT_V(6); PG8_BAR; PG8_MMA(1, 1, At, B1); PG8_BAR;
.LBB0_1201:
	s_ashr_i32 s9, s8, 31
	v_cmp_lt_i64_e32 vcc, s[10:11], v[140:141]
	s_lshl_b64 s[10:11], s[8:9], 19
	s_add_u32 s10, s24, s10
	s_addc_u32 s11, s25, s11
	s_and_b64 s[12:13], vcc, exec
	s_cselect_b32 s9, s11, s17
	s_cselect_b32 s42, s10, s16
	s_ashr_i32 s7, s6, 31
	s_lshl_b64 s[12:13], s[6:7], 19
	s_add_u32 s12, s84, s12
	s_addc_u32 s13, s85, s13
	s_and_b64 s[20:21], vcc, exec
	s_cselect_b32 s7, s13, s19
	s_cselect_b32 s43, s12, s18
	s_add_u32 s16, s16, 0x40080
	s_addc_u32 s17, s17, 0
	s_add_u32 s44, s18, 0x100
	s_addc_u32 s45, s19, 0
	s_mov_b32 s46, -2
	ds_read_b128 v[144:147], v151
	ds_read_b128 v[154:157], v151 offset:1024
	ds_read_b128 v[158:161], v151 offset:2048
	ds_read_b128 v[162:165], v151 offset:3072
	s_add_u32 s18, s16, 0xfffc0080
	s_addc_u32 s19, s17, -1
	s_cmp_eq_u32 s46, 12
	s_cselect_b32 s21, s9, s19
	s_cselect_b32 s20, s42, s18
	s_cselect_b32 s19, s7, s45
	s_cselect_b32 s18, s43, s44
	s_add_i32 m0, s15, 0xc000
	ds_read_b128 v[166:169], v152
	ds_read_b128 v[170:173], v152 offset:1024
	ds_read_b128 v[182:185], v152 offset:2048
	ds_read_b128 v[190:193], v152 offset:3072
	ds_read_b128 v[194:197], v152 offset:4096
	ds_read_b128 v[198:201], v152 offset:5120
	ds_read_b128 v[202:205], v152 offset:6144
	ds_read_b128 v[206:209], v152 offset:7168
	global_load_lds_dwordx4 v136, s[16:17]
	s_nop 1
	s_add_i32 m0, s15, 0xe000
	s_nop 0
	global_load_lds_dwordx4 v138, s[16:17]
	s_waitcnt lgkmcnt(8)
	ds_read_b128 v[210:213], v153
	ds_read_b128 v[214:217], v153 offset:1024
	ds_read_b128 v[218:221], v153 offset:2048
	ds_read_b128 v[222:225], v153 offset:3072
	s_waitcnt vmcnt(8) lgkmcnt(0)
	s_barrier
	v_mfma_f32_16x16x32_bf16 v[124:127], v[144:147], v[166:169], 0
	v_mfma_f32_16x16x32_bf16 v[120:123], v[158:161], v[166:169], 0
	v_mfma_f32_16x16x32_bf16 v[108:111], v[144:147], v[182:185], 0
	v_mfma_f32_16x16x32_bf16 v[104:107], v[158:161], v[182:185], 0
	v_mfma_f32_16x16x32_bf16 v[92:95], v[144:147], v[194:197], 0
	v_mfma_f32_16x16x32_bf16 v[88:91], v[158:161], v[194:197], 0
	v_mfma_f32_16x16x32_bf16 v[76:79], v[144:147], v[202:205], 0
	v_mfma_f32_16x16x32_bf16 v[72:75], v[158:161], v[202:205], 0
	v_mfma_f32_16x16x32_bf16 v[124:127], v[154:157], v[170:173], v[124:127]
	v_mfma_f32_16x16x32_bf16 v[120:123], v[162:165], v[170:173], v[120:123]
	v_mfma_f32_16x16x32_bf16 v[108:111], v[154:157], v[190:193], v[108:111]
	v_mfma_f32_16x16x32_bf16 v[104:107], v[162:165], v[190:193], v[104:107]
	v_mfma_f32_16x16x32_bf16 v[92:95], v[154:157], v[198:201], v[92:95]
	v_mfma_f32_16x16x32_bf16 v[88:91], v[162:165], v[198:201], v[88:91]
	v_mfma_f32_16x16x32_bf16 v[76:79], v[154:157], v[206:209], v[76:79]
	v_mfma_f32_16x16x32_bf16 v[72:75], v[162:165], v[206:209], v[72:75]
	v_mfma_f32_16x16x32_bf16 v[116:119], v[210:213], v[166:169], 0
	v_mfma_f32_16x16x32_bf16 v[112:115], v[218:221], v[166:169], 0
	v_mfma_f32_16x16x32_bf16 v[100:103], v[210:213], v[182:185], 0
	v_mfma_f32_16x16x32_bf16 v[96:99], v[218:221], v[182:185], 0
	v_mfma_f32_16x16x32_bf16 v[84:87], v[210:213], v[194:197], 0
	v_mfma_f32_16x16x32_bf16 v[80:83], v[218:221], v[194:197], 0
	v_mfma_f32_16x16x32_bf16 v[68:71], v[210:213], v[202:205], 0
	v_mfma_f32_16x16x32_bf16 v[64:67], v[218:221], v[202:205], 0
	v_mfma_f32_16x16x32_bf16 v[116:119], v[214:217], v[170:173], v[116:119]
	v_mfma_f32_16x16x32_bf16 v[112:115], v[222:225], v[170:173], v[112:115]
	v_mfma_f32_16x16x32_bf16 v[100:103], v[214:217], v[190:193], v[100:103]
	v_mfma_f32_16x16x32_bf16 v[96:99], v[222:225], v[190:193], v[96:99]
	v_mfma_f32_16x16x32_bf16 v[84:87], v[214:217], v[198:201], v[84:87]
	v_mfma_f32_16x16x32_bf16 v[80:83], v[222:225], v[198:201], v[80:83]
	v_mfma_f32_16x16x32_bf16 v[68:71], v[214:217], v[206:209], v[68:71]
	v_mfma_f32_16x16x32_bf16 v[64:67], v[222:225], v[206:209], v[64:67]
	s_barrier
	ds_read_b128 v[166:169], v152 offset:16384
	ds_read_b128 v[170:173], v152 offset:17408
	ds_read_b128 v[182:185], v152 offset:18432
	ds_read_b128 v[190:193], v152 offset:19456
	ds_read_b128 v[194:197], v152 offset:20480
	ds_read_b128 v[198:201], v152 offset:21504
	ds_read_b128 v[202:205], v152 offset:22528
	ds_read_b128 v[206:209], v152 offset:23552
	s_add_i32 s47, s38, s26
	s_add_u32 s98, s18, s4
	s_addc_u32 s99, s19, s5
	s_mov_b32 m0, s47
	s_nop 0
	global_load_lds_dwordx4 v132, s[18:19]
	s_nop 1
	s_add_i32 m0, s47, 0x2000
	s_nop 0
	global_load_lds_dwordx4 v128, s[18:19]
	s_nop 1
	s_mov_b32 m0, s15
	s_add_u32 s100, s20, s4
	s_addc_u32 s101, s21, s5
	global_load_lds_dwordx4 v134, s[20:21]
	s_nop 1
	s_mov_b32 m0, s29
	s_nop 0
	global_load_lds_dwordx4 v130, s[20:21]
	s_add_u32 s48, s18, 0x40000
	s_addc_u32 s49, s19, 0
	s_add_i32 s47, s39, s26
	s_mov_b32 m0, s47
	s_nop 0
	global_load_lds_dwordx4 v132, s[48:49]
	s_nop 1
	s_add_i32 m0, s47, 0x2000
	s_nop 0
	global_load_lds_dwordx4 v128, s[48:49]
	s_waitcnt vmcnt(8) lgkmcnt(0)
	s_barrier
; #define PG8_STAGE(bufoff, gbase, voff) do { _Pragma("unroll") for (int _i = 0; _i < 2; ++_i) \
;         __builtin_amdgcn_global_load_lds((const unsigned*)((const char*)(gbase) + (voff)[_i]), (PG8_LAS unsigned*)(lds + (bufoff) + ldsw + _i * 8192), 16, 0, 0); } while (0)
; #define PG8_LDA(dst, b, h) do { _Pragma("unroll") for (int m = 0; m < 4; ++m) _Pragma("unroll") for (int k = 0; k < 2; ++k) dst[m][k] = *(const PG8_LAS bf16x8*)(lds + PG8_SA(b, h) + aoff + m * 2048 + k * 1024); } while (0)
; #define PG8_LDB(dst, b, h) do { _Pragma("unroll") for (int n = 0; n < 2; ++n) _Pragma("unroll") for (int k = 0; k < 2; ++k) dst[n][k] = *(const PG8_LAS bf16x8*)(lds + PG8_SB(b, h) + boff + n * 2048 + k * 1024); } while (0)
; template <class Epi, class Sched>
; __device__ __forceinline__ void gemm_phase(PG8_LAS unsigned char* lds, const Gemm g, const Sched& S, const Epi& E) {
;     ...
;         for (int t = 0; t < nt; t += 2) {
;             const bool last = (t == nt - 2);
;             const char* a1 = cA + (size_t)(t + 1) * kstep;
;             const char* a2 = last ? nA : cA + (size_t)(t + 2) * kstep; const char* b2 = last ? nB : cB + (size_t)(t + 2) * kstep;
;             const char* a3 = a2 + kstep; const char* b3 = b2 + kstep;
;             if (last && has_next) S.a_ready(nxt);
;             PG8_LDB(B0, 0, 0); PG8_SCHED; PG8_LDA(At, 0, 0); PG8_STAGE(PG8_SA(1, 1), a1 + hstep, voffA);
;             PG8_WAIT_L(8); PG8_BAR; PG8_WAIT_L(0); PG8_MMA(0, 0, At, B0); PG8_BAR; PG8_SCHED;
;             PG8_LDB(B1, 0, 1); PG8_STAGE(PG8_SB(0, 0), b2, voffB);
;             PG8_BAR; PG8_WAIT_L(0); PG8_MMA(0, 1, At, B1); PG8_BAR;
;             PG8_LDA(At, 0, 1); PG8_STAGE(PG8_SA(0, 0), a2, voffA);
;             PG8_BAR; PG8_WAIT_L(0); PG8_MMA(1, 0, At, B0); PG8_BAR; PG8_SCHED;
;             PG8_STAGE(PG8_SB(0, 1), b2 + hstep, voffB);
;             PG8_WAIT_V(6); PG8_BAR; PG8_MMA(1, 1, At, B1); PG8_BAR;
;             PG8_LDB(B0, 1, 0); PG8_SCHED; PG8_LDA(At, 1, 0); PG8_STAGE(PG8_SA(0, 1), a2 + hstep, voffA);
;             PG8_WAIT_L(8); PG8_BAR; PG8_WAIT_L(0); PG8_MMA(0, 0, At, B0); PG8_BAR; PG8_SCHED;
;             PG8_LDB(B1, 1, 1); PG8_STAGE(PG8_SB(1, 0), b3, voffB);
;             PG8_BAR; PG8_WAIT_L(0); PG8_MMA(0, 1, At, B1); PG8_BAR;
;             PG8_LDA(At, 1, 1); PG8_STAGE(PG8_SA(1, 0), a3, voffA);
;             PG8_BAR; PG8_WAIT_L(0); PG8_MMA(1, 0, At, B0); PG8_BAR; PG8_SCHED;
	v_mfma_f32_16x16x32_bf16 v[60:63], v[144:147], v[166:169], 0
	v_mfma_f32_16x16x32_bf16 v[56:59], v[158:161], v[166:169], 0
	v_mfma_f32_16x16x32_bf16 v[44:47], v[144:147], v[182:185], 0
	v_mfma_f32_16x16x32_bf16 v[40:43], v[158:161], v[182:185], 0
	v_mfma_f32_16x16x32_bf16 v[28:31], v[144:147], v[194:197], 0
	v_mfma_f32_16x16x32_bf16 v[24:27], v[158:161], v[194:197], 0
	v_mfma_f32_16x16x32_bf16 v[12:15], v[144:147], v[202:205], 0
	v_mfma_f32_16x16x32_bf16 v[8:11], v[158:161], v[202:205], 0
	v_mfma_f32_16x16x32_bf16 v[60:63], v[154:157], v[170:173], v[60:63]
	v_mfma_f32_16x16x32_bf16 v[56:59], v[162:165], v[170:173], v[56:59]
	v_mfma_f32_16x16x32_bf16 v[44:47], v[154:157], v[190:193], v[44:47]
	v_mfma_f32_16x16x32_bf16 v[40:43], v[162:165], v[190:193], v[40:43]
	v_mfma_f32_16x16x32_bf16 v[28:31], v[154:157], v[198:201], v[28:31]
	v_mfma_f32_16x16x32_bf16 v[24:27], v[162:165], v[198:201], v[24:27]
	v_mfma_f32_16x16x32_bf16 v[12:15], v[154:157], v[206:209], v[12:15]
	v_mfma_f32_16x16x32_bf16 v[8:11], v[162:165], v[206:209], v[8:11]
	v_mfma_f32_16x16x32_bf16 v[52:55], v[210:213], v[166:169], 0
	v_mfma_f32_16x16x32_bf16 v[48:51], v[218:221], v[166:169], 0
	v_mfma_f32_16x16x32_bf16 v[36:39], v[210:213], v[182:185], 0
	v_mfma_f32_16x16x32_bf16 v[32:35], v[218:221], v[182:185], 0
	v_mfma_f32_16x16x32_bf16 v[20:23], v[210:213], v[194:197], 0
	v_mfma_f32_16x16x32_bf16 v[16:19], v[218:221], v[194:197], 0
	v_mfma_f32_16x16x32_bf16 v[4:7], v[210:213], v[202:205], 0
	v_mfma_f32_16x16x32_bf16 v[0:3], v[218:221], v[202:205], 0
	v_mfma_f32_16x16x32_bf16 v[52:55], v[214:217], v[170:173], v[52:55]
	v_mfma_f32_16x16x32_bf16 v[48:51], v[222:225], v[170:173], v[48:51]
	v_mfma_f32_16x16x32_bf16 v[36:39], v[214:217], v[190:193], v[36:39]
	v_mfma_f32_16x16x32_bf16 v[32:35], v[222:225], v[190:193], v[32:35]
	v_mfma_f32_16x16x32_bf16 v[20:23], v[214:217], v[198:201], v[20:23]
	v_mfma_f32_16x16x32_bf16 v[16:19], v[222:225], v[198:201], v[16:19]
	v_mfma_f32_16x16x32_bf16 v[4:7], v[214:217], v[206:209], v[4:7]
	v_mfma_f32_16x16x32_bf16 v[0:3], v[222:225], v[206:209], v[0:3]
	s_barrier
	s_add_i32 s47, 0, 0x18000
	v_add_u32_e32 v162, s47, v149
	ds_read_b128 v[144:147], v162
	ds_read_b128 v[154:157], v162 offset:1024
	ds_read_b128 v[158:161], v162 offset:2048
	ds_read_b128 v[162:165], v162 offset:3072
	s_add_u32 s20, s20, 0x40000
	s_addc_u32 s21, s21, 0
	s_mov_b32 m0, s30
	ds_read_b128 v[166:169], v152 offset:32768
	ds_read_b128 v[170:173], v152 offset:33792
	ds_read_b128 v[182:185], v152 offset:34816
	ds_read_b128 v[190:193], v152 offset:35840
	ds_read_b128 v[194:197], v152 offset:36864
	ds_read_b128 v[198:201], v152 offset:37888
	ds_read_b128 v[202:205], v152 offset:38912
	ds_read_b128 v[206:209], v152 offset:39936
	global_load_lds_dwordx4 v134, s[20:21]
	s_nop 1
	s_mov_b32 m0, s31
	s_nop 0
	global_load_lds_dwordx4 v130, s[20:21]
	s_add_i32 s20, 0, 0x1c000
	v_add_u32_e32 v179, s20, v149
	s_waitcnt lgkmcnt(8)
	ds_read_b128 v[210:213], v179
	ds_read_b128 v[214:217], v179 offset:1024
	ds_read_b128 v[218:221], v179 offset:2048
	ds_read_b128 v[222:225], v179 offset:3072
	s_waitcnt vmcnt(8) lgkmcnt(0)
	s_barrier
	v_mfma_f32_16x16x32_bf16 v[124:127], v[144:147], v[166:169], v[124:127]
	v_mfma_f32_16x16x32_bf16 v[120:123], v[158:161], v[166:169], v[120:123]
	v_mfma_f32_16x16x32_bf16 v[108:111], v[144:147], v[182:185], v[108:111]
	v_mfma_f32_16x16x32_bf16 v[104:107], v[158:161], v[182:185], v[104:107]
	v_mfma_f32_16x16x32_bf16 v[92:95], v[144:147], v[194:197], v[92:95]
	v_mfma_f32_16x16x32_bf16 v[88:91], v[158:161], v[194:197], v[88:91]
	v_mfma_f32_16x16x32_bf16 v[76:79], v[144:147], v[202:205], v[76:79]
	v_mfma_f32_16x16x32_bf16 v[72:75], v[158:161], v[202:205], v[72:75]
	v_mfma_f32_16x16x32_bf16 v[124:127], v[154:157], v[170:173], v[124:127]
	v_mfma_f32_16x16x32_bf16 v[120:123], v[162:165], v[170:173], v[120:123]
	v_mfma_f32_16x16x32_bf16 v[108:111], v[154:157], v[190:193], v[108:111]
	v_mfma_f32_16x16x32_bf16 v[104:107], v[162:165], v[190:193], v[104:107]
	v_mfma_f32_16x16x32_bf16 v[92:95], v[154:157], v[198:201], v[92:95]
	v_mfma_f32_16x16x32_bf16 v[88:91], v[162:165], v[198:201], v[88:91]
	v_mfma_f32_16x16x32_bf16 v[76:79], v[154:157], v[206:209], v[76:79]
	v_mfma_f32_16x16x32_bf16 v[72:75], v[162:165], v[206:209], v[72:75]
	v_mfma_f32_16x16x32_bf16 v[116:119], v[210:213], v[166:169], v[116:119]
	v_mfma_f32_16x16x32_bf16 v[112:115], v[218:221], v[166:169], v[112:115]
	v_mfma_f32_16x16x32_bf16 v[100:103], v[210:213], v[182:185], v[100:103]
	v_mfma_f32_16x16x32_bf16 v[96:99], v[218:221], v[182:185], v[96:99]
	v_mfma_f32_16x16x32_bf16 v[84:87], v[210:213], v[194:197], v[84:87]
	v_mfma_f32_16x16x32_bf16 v[80:83], v[218:221], v[194:197], v[80:83]
	v_mfma_f32_16x16x32_bf16 v[68:71], v[210:213], v[202:205], v[68:71]
	v_mfma_f32_16x16x32_bf16 v[64:67], v[218:221], v[202:205], v[64:67]
	v_mfma_f32_16x16x32_bf16 v[116:119], v[214:217], v[170:173], v[116:119]
	v_mfma_f32_16x16x32_bf16 v[112:115], v[222:225], v[170:173], v[112:115]
	v_mfma_f32_16x16x32_bf16 v[100:103], v[214:217], v[190:193], v[100:103]
	v_mfma_f32_16x16x32_bf16 v[96:99], v[222:225], v[190:193], v[96:99]
	v_mfma_f32_16x16x32_bf16 v[84:87], v[214:217], v[198:201], v[84:87]
	v_mfma_f32_16x16x32_bf16 v[80:83], v[222:225], v[198:201], v[80:83]
	v_mfma_f32_16x16x32_bf16 v[68:71], v[214:217], v[206:209], v[68:71]
	v_mfma_f32_16x16x32_bf16 v[64:67], v[222:225], v[206:209], v[64:67]
	s_barrier
; #define PG8_STAGE(bufoff, gbase, voff) do { _Pragma("unroll") for (int _i = 0; _i < 2; ++_i) \
;         __builtin_amdgcn_global_load_lds((const unsigned*)((const char*)(gbase) + (voff)[_i]), (PG8_LAS unsigned*)(lds + (bufoff) + ldsw + _i * 8192), 16, 0, 0); } while (0)
; #define PG8_LDA(dst, b, h) do { _Pragma("unroll") for (int m = 0; m < 4; ++m) _Pragma("unroll") for (int k = 0; k < 2; ++k) dst[m][k] = *(const PG8_LAS bf16x8*)(lds + PG8_SA(b, h) + aoff + m * 2048 + k * 1024); } while (0)
; #define PG8_WAIT_V(n) asm volatile("s_waitcnt vmcnt(" #n ")" ::: "memory")
; template <class Epi, class Sched>
; __device__ __forceinline__ void gemm_phase(PG8_LAS unsigned char* lds, const Gemm g, const Sched& S, const Epi& E) {
;     ...
;         for (int t = 0; t < nt; t += 2) {
;             const bool last = (t == nt - 2);
;             const char* a1 = cA + (size_t)(t + 1) * kstep;
;             const char* a2 = last ? nA : cA + (size_t)(t + 2) * kstep; const char* b2 = last ? nB : cB + (size_t)(t + 2) * kstep;
;             const char* a3 = a2 + kstep; const char* b3 = b2 + kstep;
;             if (last && has_next) S.a_ready(nxt);
;             PG8_LDB(B0, 0, 0); PG8_SCHED; PG8_LDA(At, 0, 0); PG8_STAGE(PG8_SA(1, 1), a1 + hstep, voffA);
;             PG8_WAIT_L(8); PG8_BAR; PG8_WAIT_L(0); PG8_MMA(0, 0, At, B0); PG8_BAR; PG8_SCHED;
;             PG8_LDB(B1, 0, 1); PG8_STAGE(PG8_SB(0, 0), b2, voffB);
;             PG8_BAR; PG8_WAIT_L(0); PG8_MMA(0, 1, At, B1); PG8_BAR;
;             PG8_LDA(At, 0, 1); PG8_STAGE(PG8_SA(0, 0), a2, voffA);
;             PG8_BAR; PG8_WAIT_L(0); PG8_MMA(1, 0, At, B0); PG8_BAR; PG8_SCHED;
;             PG8_STAGE(PG8_SB(0, 1), b2 + hstep, voffB);
;             PG8_WAIT_V(6); PG8_BAR; PG8_MMA(1, 1, At, B1); PG8_BAR;
;             PG8_LDB(B0, 1, 0); PG8_SCHED; PG8_LDA(At, 1, 0); PG8_STAGE(PG8_SA(0, 1), a2 + hstep, voffA);
;             PG8_WAIT_L(8); PG8_BAR; PG8_WAIT_L(0); PG8_MMA(0, 0, At, B0); PG8_BAR; PG8_SCHED;
;             PG8_LDB(B1, 1, 1); PG8_STAGE(PG8_SB(1, 0), b3, voffB);
;             PG8_BAR; PG8_WAIT_L(0); PG8_MMA(0, 1, At, B1); PG8_BAR;
;             PG8_LDA(At, 1, 1); PG8_STAGE(PG8_SA(1, 0), a3, voffA);
;             PG8_BAR; PG8_WAIT_L(0); PG8_MMA(1, 0, At, B0); PG8_BAR; PG8_SCHED;
;             PG8_STAGE(PG8_SB(1, 1), b3 + hstep, voffB);
;             PG8_WAIT_V(6); PG8_BAR; PG8_MMA(1, 1, At, B1); PG8_BAR;
	ds_read_b128 v[166:169], v152 offset:49152
	ds_read_b128 v[170:173], v152 offset:50176
	ds_read_b128 v[182:185], v152 offset:51200
	ds_read_b128 v[190:193], v152 offset:52224
	ds_read_b128 v[194:197], v152 offset:53248
	ds_read_b128 v[198:201], v152 offset:54272
	ds_read_b128 v[202:205], v152 offset:55296
	ds_read_b128 v[206:209], v152 offset:56320
	s_add_i32 s21, s47, s26
	s_mov_b32 m0, s21
	s_nop 0
	global_load_lds_dwordx4 v132, s[98:99]
	s_nop 1
	s_add_i32 m0, s21, 0x2000
	s_nop 0
	global_load_lds_dwordx4 v128, s[98:99]
	s_nop 1
	s_mov_b32 m0, s35
	s_nop 0
	global_load_lds_dwordx4 v134, s[100:101]
	s_nop 1
	s_mov_b32 m0, s36
	s_nop 0
	global_load_lds_dwordx4 v130, s[100:101]
	s_add_u32 s18, s18, 0x40080
	s_addc_u32 s19, s19, 0
	s_add_i32 s20, s20, s26
	s_mov_b32 m0, s20
	s_nop 0
	global_load_lds_dwordx4 v132, s[18:19]
	s_nop 1
	s_add_i32 m0, s20, 0x2000
	s_nop 0
	global_load_lds_dwordx4 v128, s[18:19]
	s_waitcnt vmcnt(8) lgkmcnt(0)
	s_barrier
	v_mfma_f32_16x16x32_bf16 v[60:63], v[144:147], v[166:169], v[60:63]
	v_mfma_f32_16x16x32_bf16 v[56:59], v[158:161], v[166:169], v[56:59]
	v_mfma_f32_16x16x32_bf16 v[44:47], v[144:147], v[182:185], v[44:47]
	v_mfma_f32_16x16x32_bf16 v[40:43], v[158:161], v[182:185], v[40:43]
	v_mfma_f32_16x16x32_bf16 v[28:31], v[144:147], v[194:197], v[28:31]
	v_mfma_f32_16x16x32_bf16 v[24:27], v[158:161], v[194:197], v[24:27]
	v_mfma_f32_16x16x32_bf16 v[12:15], v[144:147], v[202:205], v[12:15]
	v_mfma_f32_16x16x32_bf16 v[8:11], v[158:161], v[202:205], v[8:11]
	v_mfma_f32_16x16x32_bf16 v[60:63], v[154:157], v[170:173], v[60:63]
	v_mfma_f32_16x16x32_bf16 v[56:59], v[162:165], v[170:173], v[56:59]
	v_mfma_f32_16x16x32_bf16 v[44:47], v[154:157], v[190:193], v[44:47]
	v_mfma_f32_16x16x32_bf16 v[40:43], v[162:165], v[190:193], v[40:43]
	v_mfma_f32_16x16x32_bf16 v[28:31], v[154:157], v[198:201], v[28:31]
	v_mfma_f32_16x16x32_bf16 v[24:27], v[162:165], v[198:201], v[24:27]
	v_mfma_f32_16x16x32_bf16 v[12:15], v[154:157], v[206:209], v[12:15]
	v_mfma_f32_16x16x32_bf16 v[8:11], v[162:165], v[206:209], v[8:11]
	v_mfma_f32_16x16x32_bf16 v[52:55], v[210:213], v[166:169], v[52:55]
	v_mfma_f32_16x16x32_bf16 v[48:51], v[218:221], v[166:169], v[48:51]
	v_mfma_f32_16x16x32_bf16 v[36:39], v[210:213], v[182:185], v[36:39]
	v_mfma_f32_16x16x32_bf16 v[32:35], v[218:221], v[182:185], v[32:35]
	v_mfma_f32_16x16x32_bf16 v[20:23], v[210:213], v[194:197], v[20:23]
	v_mfma_f32_16x16x32_bf16 v[16:19], v[218:221], v[194:197], v[16:19]
	v_mfma_f32_16x16x32_bf16 v[4:7], v[210:213], v[202:205], v[4:7]
	v_mfma_f32_16x16x32_bf16 v[0:3], v[218:221], v[202:205], v[0:3]
	v_mfma_f32_16x16x32_bf16 v[52:55], v[214:217], v[170:173], v[52:55]
	v_mfma_f32_16x16x32_bf16 v[48:51], v[222:225], v[170:173], v[48:51]
	v_mfma_f32_16x16x32_bf16 v[36:39], v[214:217], v[190:193], v[36:39]
	v_mfma_f32_16x16x32_bf16 v[32:35], v[222:225], v[190:193], v[32:35]
	v_mfma_f32_16x16x32_bf16 v[20:23], v[214:217], v[198:201], v[20:23]
	v_mfma_f32_16x16x32_bf16 v[16:19], v[222:225], v[198:201], v[16:19]
	v_mfma_f32_16x16x32_bf16 v[4:7], v[214:217], v[206:209], v[4:7]
	v_mfma_f32_16x16x32_bf16 v[0:3], v[222:225], v[206:209], v[0:3]
	s_barrier
	s_add_i32 s46, s46, 2
	s_add_u32 s16, s16, 0x100
	s_addc_u32 s17, s17, 0
	s_add_u32 s44, s44, 0x100
	s_addc_u32 s45, s45, 0
	s_cmp_gt_u32 s46, 13
.LBB0_1202:
	ds_read_b128 v[144:147], v151
	ds_read_b128 v[154:157], v151 offset:1024
	ds_read_b128 v[158:161], v151 offset:2048
	ds_read_b128 v[162:165], v151 offset:3072
	s_add_u32 s18, s16, 0xfffc0080
	s_addc_u32 s19, s17, -1
	s_cmp_eq_u32 s46, 12
	s_cselect_b32 s21, s9, s19
	s_cselect_b32 s20, s42, s18
	s_cselect_b32 s19, s7, s45
	s_cselect_b32 s18, s43, s44
	s_add_i32 m0, s15, 0xc000
	ds_read_b128 v[166:169], v152
	ds_read_b128 v[170:173], v152 offset:1024
	ds_read_b128 v[182:185], v152 offset:2048
	ds_read_b128 v[190:193], v152 offset:3072
	ds_read_b128 v[194:197], v152 offset:4096
	ds_read_b128 v[198:201], v152 offset:5120
	ds_read_b128 v[202:205], v152 offset:6144
	ds_read_b128 v[206:209], v152 offset:7168
	global_load_lds_dwordx4 v136, s[16:17]
	s_nop 1
	s_add_i32 m0, s15, 0xe000
	s_nop 0
	global_load_lds_dwordx4 v138, s[16:17]
	s_waitcnt lgkmcnt(8)
	ds_read_b128 v[210:213], v153
	ds_read_b128 v[214:217], v153 offset:1024
	ds_read_b128 v[218:221], v153 offset:2048
	ds_read_b128 v[222:225], v153 offset:3072
	s_waitcnt vmcnt(8) lgkmcnt(0)
	s_barrier
	v_mfma_f32_16x16x32_bf16 v[124:127], v[144:147], v[166:169], v[124:127]
	v_mfma_f32_16x16x32_bf16 v[120:123], v[158:161], v[166:169], v[120:123]
	v_mfma_f32_16x16x32_bf16 v[108:111], v[144:147], v[182:185], v[108:111]
	v_mfma_f32_16x16x32_bf16 v[104:107], v[158:161], v[182:185], v[104:107]
	v_mfma_f32_16x16x32_bf16 v[92:95], v[144:147], v[194:197], v[92:95]
	v_mfma_f32_16x16x32_bf16 v[88:91], v[158:161], v[194:197], v[88:91]
	v_mfma_f32_16x16x32_bf16 v[76:79], v[144:147], v[202:205], v[76:79]
	v_mfma_f32_16x16x32_bf16 v[72:75], v[158:161], v[202:205], v[72:75]
	v_mfma_f32_16x16x32_bf16 v[124:127], v[154:157], v[170:173], v[124:127]
	v_mfma_f32_16x16x32_bf16 v[120:123], v[162:165], v[170:173], v[120:123]
	v_mfma_f32_16x16x32_bf16 v[108:111], v[154:157], v[190:193], v[108:111]
	v_mfma_f32_16x16x32_bf16 v[104:107], v[162:165], v[190:193], v[104:107]
	v_mfma_f32_16x16x32_bf16 v[92:95], v[154:157], v[198:201], v[92:95]
	v_mfma_f32_16x16x32_bf16 v[88:91], v[162:165], v[198:201], v[88:91]
	v_mfma_f32_16x16x32_bf16 v[76:79], v[154:157], v[206:209], v[76:79]
	v_mfma_f32_16x16x32_bf16 v[72:75], v[162:165], v[206:209], v[72:75]
	v_mfma_f32_16x16x32_bf16 v[116:119], v[210:213], v[166:169], v[116:119]
	v_mfma_f32_16x16x32_bf16 v[112:115], v[218:221], v[166:169], v[112:115]
	v_mfma_f32_16x16x32_bf16 v[100:103], v[210:213], v[182:185], v[100:103]
	v_mfma_f32_16x16x32_bf16 v[96:99], v[218:221], v[182:185], v[96:99]
	v_mfma_f32_16x16x32_bf16 v[84:87], v[210:213], v[194:197], v[84:87]
	v_mfma_f32_16x16x32_bf16 v[80:83], v[218:221], v[194:197], v[80:83]
	v_mfma_f32_16x16x32_bf16 v[68:71], v[210:213], v[202:205], v[68:71]
	v_mfma_f32_16x16x32_bf16 v[64:67], v[218:221], v[202:205], v[64:67]
	v_mfma_f32_16x16x32_bf16 v[116:119], v[214:217], v[170:173], v[116:119]
	v_mfma_f32_16x16x32_bf16 v[112:115], v[222:225], v[170:173], v[112:115]
	v_mfma_f32_16x16x32_bf16 v[100:103], v[214:217], v[190:193], v[100:103]
	v_mfma_f32_16x16x32_bf16 v[96:99], v[222:225], v[190:193], v[96:99]
	v_mfma_f32_16x16x32_bf16 v[84:87], v[214:217], v[198:201], v[84:87]
	v_mfma_f32_16x16x32_bf16 v[80:83], v[222:225], v[198:201], v[80:83]
	v_mfma_f32_16x16x32_bf16 v[68:71], v[214:217], v[206:209], v[68:71]
	v_mfma_f32_16x16x32_bf16 v[64:67], v[222:225], v[206:209], v[64:67]
	s_barrier
; #define PG8_STAGE(bufoff, gbase, voff) do { _Pragma("unroll") for (int _i = 0; _i < 2; ++_i) \
;         __builtin_amdgcn_global_load_lds((const unsigned*)((const char*)(gbase) + (voff)[_i]), (PG8_LAS unsigned*)(lds + (bufoff) + ldsw + _i * 8192), 16, 0, 0); } while (0)
; #define PG8_LDA(dst, b, h) do { _Pragma("unroll") for (int m = 0; m < 4; ++m) _Pragma("unroll") for (int k = 0; k < 2; ++k) dst[m][k] = *(const PG8_LAS bf16x8*)(lds + PG8_SA(b, h) + aoff + m * 2048 + k * 1024); } while (0)
; #define PG8_WAIT_V(n) asm volatile("s_waitcnt vmcnt(" #n ")" ::: "memory")
; template <class Epi, class Sched>
; __device__ __forceinline__ void gemm_phase(PG8_LAS unsigned char* lds, const Gemm g, const Sched& S, const Epi& E) {
;     ...
;         for (int t = 0; t < nt; t += 2) {
;             const bool last = (t == nt - 2);
;             const char* a1 = cA + (size_t)(t + 1) * kstep;
;             const char* a2 = last ? nA : cA + (size_t)(t + 2) * kstep; const char* b2 = last ? nB : cB + (size_t)(t + 2) * kstep;
;             const char* a3 = a2 + kstep; const char* b3 = b2 + kstep;
;             if (last && has_next) S.a_ready(nxt);
;             PG8_LDB(B0, 0, 0); PG8_SCHED; PG8_LDA(At, 0, 0); PG8_STAGE(PG8_SA(1, 1), a1 + hstep, voffA);
;             PG8_WAIT_L(8); PG8_BAR; PG8_WAIT_L(0); PG8_MMA(0, 0, At, B0); PG8_BAR; PG8_SCHED;
;             PG8_LDB(B1, 0, 1); PG8_STAGE(PG8_SB(0, 0), b2, voffB);
;             PG8_BAR; PG8_WAIT_L(0); PG8_MMA(0, 1, At, B1); PG8_BAR;
;             PG8_LDA(At, 0, 1); PG8_STAGE(PG8_SA(0, 0), a2, voffA);
;             PG8_BAR; PG8_WAIT_L(0); PG8_MMA(1, 0, At, B0); PG8_BAR; PG8_SCHED;
;             PG8_STAGE(PG8_SB(0, 1), b2 + hstep, voffB);
;             PG8_WAIT_V(6); PG8_BAR; PG8_MMA(1, 1, At, B1); PG8_BAR;
;             PG8_LDB(B0, 1, 0); PG8_SCHED; PG8_LDA(At, 1, 0); PG8_STAGE(PG8_SA(0, 1), a2 + hstep, voffA);
;             PG8_WAIT_L(8); PG8_BAR; PG8_WAIT_L(0); PG8_MMA(0, 0, At, B0); PG8_BAR; PG8_SCHED;
;             PG8_LDB(B1, 1, 1); PG8_STAGE(PG8_SB(1, 0), b3, voffB);
;             PG8_BAR; PG8_WAIT_L(0); PG8_MMA(0, 1, At, B1); PG8_BAR;
;             PG8_LDA(At, 1, 1); PG8_STAGE(PG8_SA(1, 0), a3, voffA);
;             PG8_BAR; PG8_WAIT_L(0); PG8_MMA(1, 0, At, B0); PG8_BAR; PG8_SCHED;
;             PG8_STAGE(PG8_SB(1, 1), b3 + hstep, voffB);
;             PG8_WAIT_V(6); PG8_BAR; PG8_MMA(1, 1, At, B1); PG8_BAR;
	ds_read_b128 v[166:169], v152 offset:16384
	ds_read_b128 v[170:173], v152 offset:17408
	ds_read_b128 v[182:185], v152 offset:18432
	ds_read_b128 v[190:193], v152 offset:19456
	ds_read_b128 v[194:197], v152 offset:20480
	ds_read_b128 v[198:201], v152 offset:21504
	ds_read_b128 v[202:205], v152 offset:22528
	ds_read_b128 v[206:209], v152 offset:23552
	s_add_i32 s47, s38, s26
	s_add_u32 s98, s18, s4
	s_addc_u32 s99, s19, s5
	s_mov_b32 m0, s47
	s_nop 0
	global_load_lds_dwordx4 v132, s[18:19]
	s_nop 1
	s_add_i32 m0, s47, 0x2000
	s_nop 0
	global_load_lds_dwordx4 v128, s[18:19]
	s_nop 1
	s_mov_b32 m0, s15
	s_add_u32 s100, s20, s4
	s_addc_u32 s101, s21, s5
	global_load_lds_dwordx4 v134, s[20:21]
	s_nop 1
	s_mov_b32 m0, s29
	s_nop 0
	global_load_lds_dwordx4 v130, s[20:21]
	s_add_u32 s48, s18, 0x40000
	s_addc_u32 s49, s19, 0
	s_add_i32 s47, s39, s26
	s_mov_b32 m0, s47
	s_nop 0
	global_load_lds_dwordx4 v132, s[48:49]
	s_nop 1
	s_add_i32 m0, s47, 0x2000
	s_nop 0
	global_load_lds_dwordx4 v128, s[48:49]
	s_waitcnt vmcnt(8) lgkmcnt(0)
	s_barrier
	v_mfma_f32_16x16x32_bf16 v[60:63], v[144:147], v[166:169], v[60:63]
	v_mfma_f32_16x16x32_bf16 v[56:59], v[158:161], v[166:169], v[56:59]
	v_mfma_f32_16x16x32_bf16 v[44:47], v[144:147], v[182:185], v[44:47]
	v_mfma_f32_16x16x32_bf16 v[40:43], v[158:161], v[182:185], v[40:43]
	v_mfma_f32_16x16x32_bf16 v[28:31], v[144:147], v[194:197], v[28:31]
	v_mfma_f32_16x16x32_bf16 v[24:27], v[158:161], v[194:197], v[24:27]
	v_mfma_f32_16x16x32_bf16 v[12:15], v[144:147], v[202:205], v[12:15]
	v_mfma_f32_16x16x32_bf16 v[8:11], v[158:161], v[202:205], v[8:11]
	v_mfma_f32_16x16x32_bf16 v[60:63], v[154:157], v[170:173], v[60:63]
	v_mfma_f32_16x16x32_bf16 v[56:59], v[162:165], v[170:173], v[56:59]
	v_mfma_f32_16x16x32_bf16 v[44:47], v[154:157], v[190:193], v[44:47]
	v_mfma_f32_16x16x32_bf16 v[40:43], v[162:165], v[190:193], v[40:43]
	v_mfma_f32_16x16x32_bf16 v[28:31], v[154:157], v[198:201], v[28:31]
	v_mfma_f32_16x16x32_bf16 v[24:27], v[162:165], v[198:201], v[24:27]
	v_mfma_f32_16x16x32_bf16 v[12:15], v[154:157], v[206:209], v[12:15]
	v_mfma_f32_16x16x32_bf16 v[8:11], v[162:165], v[206:209], v[8:11]
	v_mfma_f32_16x16x32_bf16 v[52:55], v[210:213], v[166:169], v[52:55]
	v_mfma_f32_16x16x32_bf16 v[48:51], v[218:221], v[166:169], v[48:51]
	v_mfma_f32_16x16x32_bf16 v[36:39], v[210:213], v[182:185], v[36:39]
	v_mfma_f32_16x16x32_bf16 v[32:35], v[218:221], v[182:185], v[32:35]
	v_mfma_f32_16x16x32_bf16 v[20:23], v[210:213], v[194:197], v[20:23]
	v_mfma_f32_16x16x32_bf16 v[16:19], v[218:221], v[194:197], v[16:19]
	v_mfma_f32_16x16x32_bf16 v[4:7], v[210:213], v[202:205], v[4:7]
	v_mfma_f32_16x16x32_bf16 v[0:3], v[218:221], v[202:205], v[0:3]
	v_mfma_f32_16x16x32_bf16 v[52:55], v[214:217], v[170:173], v[52:55]
	v_mfma_f32_16x16x32_bf16 v[48:51], v[222:225], v[170:173], v[48:51]
	v_mfma_f32_16x16x32_bf16 v[36:39], v[214:217], v[190:193], v[36:39]
	v_mfma_f32_16x16x32_bf16 v[32:35], v[222:225], v[190:193], v[32:35]
	v_mfma_f32_16x16x32_bf16 v[20:23], v[214:217], v[198:201], v[20:23]
	v_mfma_f32_16x16x32_bf16 v[16:19], v[222:225], v[198:201], v[16:19]
	v_mfma_f32_16x16x32_bf16 v[4:7], v[214:217], v[206:209], v[4:7]
	v_mfma_f32_16x16x32_bf16 v[0:3], v[222:225], v[206:209], v[0:3]
	s_barrier
	s_add_i32 s47, 0, 0x18000
	v_add_u32_e32 v162, s47, v149
	ds_read_b128 v[144:147], v162
	ds_read_b128 v[154:157], v162 offset:1024
	ds_read_b128 v[158:161], v162 offset:2048
	ds_read_b128 v[162:165], v162 offset:3072
	s_add_u32 s20, s20, 0x40000
	s_addc_u32 s21, s21, 0
	s_mov_b32 m0, s30
	ds_read_b128 v[166:169], v152 offset:32768
	ds_read_b128 v[170:173], v152 offset:33792
	ds_read_b128 v[182:185], v152 offset:34816
	ds_read_b128 v[190:193], v152 offset:35840
	ds_read_b128 v[194:197], v152 offset:36864
	ds_read_b128 v[198:201], v152 offset:37888
	ds_read_b128 v[202:205], v152 offset:38912
	ds_read_b128 v[206:209], v152 offset:39936
	global_load_lds_dwordx4 v134, s[20:21]
	s_nop 1
	s_mov_b32 m0, s31
	s_nop 0
	global_load_lds_dwordx4 v130, s[20:21]
	s_add_i32 s20, 0, 0x1c000
	v_add_u32_e32 v179, s20, v149
	s_waitcnt lgkmcnt(8)
	ds_read_b128 v[210:213], v179
	ds_read_b128 v[214:217], v179 offset:1024
	ds_read_b128 v[218:221], v179 offset:2048
	ds_read_b128 v[222:225], v179 offset:3072
	s_waitcnt vmcnt(8) lgkmcnt(0)
	s_barrier
	v_mfma_f32_16x16x32_bf16 v[124:127], v[144:147], v[166:169], v[124:127]
	v_mfma_f32_16x16x32_bf16 v[120:123], v[158:161], v[166:169], v[120:123]
	v_mfma_f32_16x16x32_bf16 v[108:111], v[144:147], v[182:185], v[108:111]
	v_mfma_f32_16x16x32_bf16 v[104:107], v[158:161], v[182:185], v[104:107]
	v_mfma_f32_16x16x32_bf16 v[92:95], v[144:147], v[194:197], v[92:95]
	v_mfma_f32_16x16x32_bf16 v[88:91], v[158:161], v[194:197], v[88:91]
	v_mfma_f32_16x16x32_bf16 v[76:79], v[144:147], v[202:205], v[76:79]
	v_mfma_f32_16x16x32_bf16 v[72:75], v[158:161], v[202:205], v[72:75]
	v_mfma_f32_16x16x32_bf16 v[124:127], v[154:157], v[170:173], v[124:127]
	v_mfma_f32_16x16x32_bf16 v[120:123], v[162:165], v[170:173], v[120:123]
	v_mfma_f32_16x16x32_bf16 v[108:111], v[154:157], v[190:193], v[108:111]
	v_mfma_f32_16x16x32_bf16 v[104:107], v[162:165], v[190:193], v[104:107]
	v_mfma_f32_16x16x32_bf16 v[92:95], v[154:157], v[198:201], v[92:95]
	v_mfma_f32_16x16x32_bf16 v[88:91], v[162:165], v[198:201], v[88:91]
	v_mfma_f32_16x16x32_bf16 v[76:79], v[154:157], v[206:209], v[76:79]
	v_mfma_f32_16x16x32_bf16 v[72:75], v[162:165], v[206:209], v[72:75]
	v_mfma_f32_16x16x32_bf16 v[116:119], v[210:213], v[166:169], v[116:119]
	v_mfma_f32_16x16x32_bf16 v[112:115], v[218:221], v[166:169], v[112:115]
	v_mfma_f32_16x16x32_bf16 v[100:103], v[210:213], v[182:185], v[100:103]
	v_mfma_f32_16x16x32_bf16 v[96:99], v[218:221], v[182:185], v[96:99]
	v_mfma_f32_16x16x32_bf16 v[84:87], v[210:213], v[194:197], v[84:87]
	v_mfma_f32_16x16x32_bf16 v[80:83], v[218:221], v[194:197], v[80:83]
	v_mfma_f32_16x16x32_bf16 v[68:71], v[210:213], v[202:205], v[68:71]
	v_mfma_f32_16x16x32_bf16 v[64:67], v[218:221], v[202:205], v[64:67]
	v_mfma_f32_16x16x32_bf16 v[116:119], v[214:217], v[170:173], v[116:119]
	v_mfma_f32_16x16x32_bf16 v[112:115], v[222:225], v[170:173], v[112:115]
	v_mfma_f32_16x16x32_bf16 v[100:103], v[214:217], v[190:193], v[100:103]
	v_mfma_f32_16x16x32_bf16 v[96:99], v[222:225], v[190:193], v[96:99]
	v_mfma_f32_16x16x32_bf16 v[84:87], v[214:217], v[198:201], v[84:87]
	v_mfma_f32_16x16x32_bf16 v[80:83], v[222:225], v[198:201], v[80:83]
	v_mfma_f32_16x16x32_bf16 v[68:71], v[214:217], v[206:209], v[68:71]
	v_mfma_f32_16x16x32_bf16 v[64:67], v[222:225], v[206:209], v[64:67]
	s_barrier
; #define PG8_LDA(dst, b, h) do { _Pragma("unroll") for (int m = 0; m < 4; ++m) _Pragma("unroll") for (int k = 0; k < 2; ++k) dst[m][k] = *(const PG8_LAS bf16x8*)(lds + PG8_SA(b, h) + aoff + m * 2048 + k * 1024); } while (0)
; __device__ __forceinline__ f32x4 sigmoid4(f32x4 x) {
;     f32x4 d;
; #pragma unroll
;     for (int j = 0; j < 4; ++j) d[j] = 1.0f + __expf(-fmaxf(x[j], -20.0f));
;     const float p01 = d[0] * d[1], p23 = d[2] * d[3], r = __builtin_amdgcn_rcpf(p01 * p23), r01 = r * p23, r23 = r * p01;
;     return (f32x4){r01 * d[1], r01 * d[0], r23 * d[3], r23 * d[2]};
; }
; template <class Epi, class Sched>
; __device__ __forceinline__ void gemm_phase(PG8_LAS unsigned char* lds, const Gemm g, const Sched& S, const Epi& E) {
;     ...
;         for (int t = 0; t < nt; t += 2) {
;             const bool last = (t == nt - 2);
;             const char* a1 = cA + (size_t)(t + 1) * kstep;
;             const char* a2 = last ? nA : cA + (size_t)(t + 2) * kstep; const char* b2 = last ? nB : cB + (size_t)(t + 2) * kstep;
;             const char* a3 = a2 + kstep; const char* b3 = b2 + kstep;
;             if (last && has_next) S.a_ready(nxt);
;             PG8_LDB(B0, 0, 0); PG8_SCHED; PG8_LDA(At, 0, 0); PG8_STAGE(PG8_SA(1, 1), a1 + hstep, voffA);
;             PG8_WAIT_L(8); PG8_BAR; PG8_WAIT_L(0); PG8_MMA(0, 0, At, B0); PG8_BAR; PG8_SCHED;
;             PG8_LDB(B1, 0, 1); PG8_STAGE(PG8_SB(0, 0), b2, voffB);
;             PG8_BAR; PG8_WAIT_L(0); PG8_MMA(0, 1, At, B1); PG8_BAR;
;             PG8_LDA(At, 0, 1); PG8_STAGE(PG8_SA(0, 0), a2, voffA);
;             PG8_BAR; PG8_WAIT_L(0); PG8_MMA(1, 0, At, B0); PG8_BAR; PG8_SCHED;
;             PG8_STAGE(PG8_SB(0, 1), b2 + hstep, voffB);
;             PG8_WAIT_V(6); PG8_BAR; PG8_MMA(1, 1, At, B1); PG8_BAR;
;             PG8_LDB(B0, 1, 0); PG8_SCHED; PG8_LDA(At, 1, 0); PG8_STAGE(PG8_SA(0, 1), a2 + hstep, voffA);
;             PG8_WAIT_L(8); PG8_BAR; PG8_WAIT_L(0); PG8_MMA(0, 0, At, B0); PG8_BAR; PG8_SCHED;
;             PG8_LDB(B1, 1, 1); PG8_STAGE(PG8_SB(1, 0), b3, voffB);
;             PG8_BAR; PG8_WAIT_L(0); PG8_MMA(0, 1, At, B1); PG8_BAR;
;             PG8_LDA(At, 1, 1); PG8_STAGE(PG8_SA(1, 0), a3, voffA);
;             PG8_BAR; PG8_WAIT_L(0); PG8_MMA(1, 0, At, B0); PG8_BAR; PG8_SCHED;
;             PG8_STAGE(PG8_SB(1, 1), b3 + hstep, voffB);
;             PG8_WAIT_V(6); PG8_BAR; PG8_MMA(1, 1, At, B1); PG8_BAR;
	ds_read_b128 v[166:169], v152 offset:49152
	ds_read_b128 v[170:173], v152 offset:50176
	ds_read_b128 v[182:185], v152 offset:51200
	ds_read_b128 v[190:193], v152 offset:52224
	ds_read_b128 v[194:197], v152 offset:53248
	ds_read_b128 v[198:201], v152 offset:54272
	ds_read_b128 v[202:205], v152 offset:55296
	ds_read_b128 v[206:209], v152 offset:56320
	s_add_i32 s21, s47, s26
	s_mov_b32 m0, s21
	s_nop 0
	global_load_lds_dwordx4 v132, s[98:99]
	s_nop 1
	s_add_i32 m0, s21, 0x2000
	s_nop 0
	global_load_lds_dwordx4 v128, s[98:99]
	s_nop 1
	s_mov_b32 m0, s35
	s_nop 0
	global_load_lds_dwordx4 v134, s[100:101]
	s_nop 1
	s_mov_b32 m0, s36
	s_nop 0
	global_load_lds_dwordx4 v130, s[100:101]
	s_add_u32 s18, s18, 0x40080
	s_addc_u32 s19, s19, 0
	s_add_i32 s20, s20, s26
	s_mov_b32 m0, s20
	s_nop 0
	global_load_lds_dwordx4 v132, s[18:19]
	s_nop 1
	s_add_i32 m0, s20, 0x2000
	s_nop 0
	global_load_lds_dwordx4 v128, s[18:19]
	s_waitcnt vmcnt(8) lgkmcnt(0)
	s_barrier
	v_mfma_f32_16x16x32_bf16 v[60:63], v[144:147], v[166:169], v[60:63]
	v_mfma_f32_16x16x32_bf16 v[56:59], v[158:161], v[166:169], v[56:59]
	v_mfma_f32_16x16x32_bf16 v[44:47], v[144:147], v[182:185], v[44:47]
	v_mfma_f32_16x16x32_bf16 v[40:43], v[158:161], v[182:185], v[40:43]
	v_mfma_f32_16x16x32_bf16 v[28:31], v[144:147], v[194:197], v[28:31]
	v_mfma_f32_16x16x32_bf16 v[24:27], v[158:161], v[194:197], v[24:27]
	v_mfma_f32_16x16x32_bf16 v[12:15], v[144:147], v[202:205], v[12:15]
	v_mfma_f32_16x16x32_bf16 v[8:11], v[158:161], v[202:205], v[8:11]
	v_mfma_f32_16x16x32_bf16 v[60:63], v[154:157], v[170:173], v[60:63]
	v_mfma_f32_16x16x32_bf16 v[56:59], v[162:165], v[170:173], v[56:59]
	v_mfma_f32_16x16x32_bf16 v[44:47], v[154:157], v[190:193], v[44:47]
	v_mfma_f32_16x16x32_bf16 v[40:43], v[162:165], v[190:193], v[40:43]
	v_mfma_f32_16x16x32_bf16 v[28:31], v[154:157], v[198:201], v[28:31]
	v_mfma_f32_16x16x32_bf16 v[24:27], v[162:165], v[198:201], v[24:27]
	v_mfma_f32_16x16x32_bf16 v[12:15], v[154:157], v[206:209], v[12:15]
	v_mfma_f32_16x16x32_bf16 v[8:11], v[162:165], v[206:209], v[8:11]
	v_mfma_f32_16x16x32_bf16 v[52:55], v[210:213], v[166:169], v[52:55]
	v_mfma_f32_16x16x32_bf16 v[48:51], v[218:221], v[166:169], v[48:51]
	v_mfma_f32_16x16x32_bf16 v[36:39], v[210:213], v[182:185], v[36:39]
	v_mfma_f32_16x16x32_bf16 v[32:35], v[218:221], v[182:185], v[32:35]
	v_mfma_f32_16x16x32_bf16 v[20:23], v[210:213], v[194:197], v[20:23]
	v_mfma_f32_16x16x32_bf16 v[16:19], v[218:221], v[194:197], v[16:19]
	v_mfma_f32_16x16x32_bf16 v[4:7], v[210:213], v[202:205], v[4:7]
	v_mfma_f32_16x16x32_bf16 v[0:3], v[218:221], v[202:205], v[0:3]
	v_mfma_f32_16x16x32_bf16 v[52:55], v[214:217], v[170:173], v[52:55]
	v_mfma_f32_16x16x32_bf16 v[48:51], v[222:225], v[170:173], v[48:51]
	v_mfma_f32_16x16x32_bf16 v[36:39], v[214:217], v[190:193], v[36:39]
	v_mfma_f32_16x16x32_bf16 v[32:35], v[222:225], v[190:193], v[32:35]
	v_mfma_f32_16x16x32_bf16 v[20:23], v[214:217], v[198:201], v[20:23]
	v_mfma_f32_16x16x32_bf16 v[16:19], v[222:225], v[198:201], v[16:19]
	v_mfma_f32_16x16x32_bf16 v[4:7], v[214:217], v[206:209], v[4:7]
	v_mfma_f32_16x16x32_bf16 v[0:3], v[222:225], v[206:209], v[0:3]
	s_barrier
	s_add_i32 s46, s46, 2
	s_add_u32 s16, s16, 0x100
	s_addc_u32 s17, s17, 0
	s_add_u32 s44, s44, 0x100
	s_addc_u32 s45, s45, 0
	s_cmp_gt_u32 s46, 13
	s_cbranch_scc0 .LBB0_1202
	v_max_f32_e32 v144, 0xc1a00000, v124
	v_mul_f32_e32 v144, 0xbfb8aa3b, v144
	v_exp_f32_e32 v157, v144
	v_max_f32_e32 v144, 0xc1a00000, v125
	v_mul_f32_e32 v144, 0xbfb8aa3b, v144
	v_exp_f32_e32 v156, v144
	v_max_f32_e32 v144, 0xc1a00000, v126
	v_mul_f32_e32 v144, 0xbfb8aa3b, v144
	v_exp_f32_e32 v159, v144
	v_max_f32_e32 v144, 0xc1a00000, v127
	v_mul_f32_e32 v144, 0xbfb8aa3b, v144
	v_exp_f32_e32 v158, v144
	v_pk_add_f32 v[156:157], v[156:157], 1.0 op_sel_hi:[1,0]
	v_lshl_or_b32 v146, s41, 7, v150
	v_mov_b32_e32 v160, v157
	v_pk_add_f32 v[158:159], v[158:159], 1.0 op_sel_hi:[1,0]
	v_mov_b32_e32 v162, v156
	v_mov_b32_e32 v161, v159
	v_mov_b32_e32 v163, v158
	v_pk_mul_f32 v[160:161], v[160:161], v[162:163]
	v_lshl_add_u32 v154, s14, 8, v148
	v_mul_f32_e32 v155, v160, v161
	v_rcp_f32_e32 v155, v155
	v_ashrrev_i32_e32 v147, 31, v146
	v_mov_b64_e32 v[144:145], s[0:1]
	v_mad_i64_i32 v[162:163], s[16:17], v154, s40, v[144:145]
	v_mul_f32_e32 v164, v161, v155
	v_mul_f32_e32 v160, v160, v155
	v_max_f32_e32 v155, 0xc1a00000, v120
	v_mul_f32_e32 v155, 0xbfb8aa3b, v155
	v_pk_mul_f32 v[158:159], v[158:159], v[160:161] op_sel_hi:[1,0]
	v_exp_f32_e32 v161, v155
	v_max_f32_e32 v155, 0xc1a00000, v121
	v_mul_f32_e32 v155, 0xbfb8aa3b, v155
	v_exp_f32_e32 v160, v155
	v_max_f32_e32 v155, 0xc1a00000, v122
	v_mul_f32_e32 v155, 0xbfb8aa3b, v155
	v_exp_f32_e32 v167, v155
	v_max_f32_e32 v155, 0xc1a00000, v123
	v_mul_f32_e32 v155, 0xbfb8aa3b, v155
	v_exp_f32_e32 v166, v155
	v_pk_mul_f32 v[156:157], v[156:157], v[164:165] op_sel_hi:[1,0]
	v_pk_mul_f32 v[126:127], v[126:127], v[158:159]
	v_pk_mul_f32 v[124:125], v[124:125], v[156:157]
	v_pk_add_f32 v[156:157], v[160:161], 1.0 op_sel_hi:[1,0]
	v_pk_add_f32 v[160:161], v[166:167], 1.0 op_sel_hi:[1,0]
	v_mov_b32_e32 v164, v157
	v_mov_b32_e32 v165, v161
	v_mov_b32_e32 v166, v156
	v_mov_b32_e32 v167, v160
	v_pk_mul_f32 v[164:165], v[164:165], v[166:167]
	v_pk_mul_f32 v[118:119], v[126:127], v[118:119]
	v_mul_f32_e32 v155, v164, v165
	v_rcp_f32_e32 v155, v155
	v_pk_mul_f32 v[116:117], v[124:125], v[116:117]
	v_lshlrev_b64 v[146:147], 1, v[146:147]
	v_lshl_add_u64 v[162:163], v[162:163], 0, v[146:147]
	v_mul_f32_e32 v124, v165, v155
	v_mul_f32_e32 v126, v164, v155
	v_pk_mul_f32 v[126:127], v[160:161], v[126:127] op_sel_hi:[1,0]
; __device__ __forceinline__ unsigned cvt_pk_bf16(float lo, float hi) { unsigned r; asm volatile("v_cvt_pk_bf16_f32 %0, %1, %2" : "=v"(r) : "v"(lo), "v"(hi)); return r; }
; __device__ __forceinline__ f32x4 sigmoid4(f32x4 x) {
;     f32x4 d;
; #pragma unroll
;     for (int j = 0; j < 4; ++j) d[j] = 1.0f + __expf(-fmaxf(x[j], -20.0f));
;     const float p01 = d[0] * d[1], p23 = d[2] * d[3], r = __builtin_amdgcn_rcpf(p01 * p23), r01 = r * p23, r23 = r * p01;
;     return (f32x4){r01 * d[1], r01 * d[0], r23 * d[3], r23 * d[2]};
; }
;     __device__ __forceinline__ void operator()(const f32x4 (&acc)[2][2][4][2], const Unit& u, int wr, int wc, int fr, int fq) const {
;         const int row0 = u.pm * BM + wr * 64 + fr, col0 = u.pn * HALF + wc * 32 + 8 * fq;
; #pragma unroll
;         for (int ai = 0; ai < 2; ++ai)
; #pragma unroll
;             for (int m = 0; m < 4; ++m) { bf16_t* rowp = O + (size_t)(row0 + ai * HALF + m * 16) * ldc + col0;
;                 f32x4 v0, v1;
; #pragma unroll
;                 for (int j = 0; j < 1; ++j) { v0 = acc[ai][0][m][0] * sigmoid4(acc[ai][0][m][0]) * acc[ai][1][m][0]; v1 = acc[ai][0][m][1] * sigmoid4(acc[ai][0][m][1]) * acc[ai][1][m][1]; }
;                 u32x4 w; w.x = cvt_pk_bf16(v0[0], v0[1]); w.y = cvt_pk_bf16(v0[2], v0[3]); w.z = cvt_pk_bf16(v1[0], v1[1]); w.w = cvt_pk_bf16(v1[2], v1[3]);
;                 *(u32x4*)rowp = w; }
	v_pk_mul_f32 v[124:125], v[156:157], v[124:125] op_sel_hi:[1,0]
	v_pk_mul_f32 v[122:123], v[122:123], v[126:127]
	v_pk_mul_f32 v[120:121], v[120:121], v[124:125]
	v_pk_mul_f32 v[122:123], v[122:123], v[114:115]
	v_pk_mul_f32 v[114:115], v[120:121], v[112:113]
	v_cvt_pk_bf16_f32 v112, v116, v117
	v_cvt_pk_bf16_f32 v113, v118, v119
	v_max_f32_e32 v116, 0xc1a00000, v108
	v_max_f32_e32 v118, 0xc1a00000, v110
	v_mul_f32_e32 v116, 0xbfb8aa3b, v116
	v_mul_f32_e32 v118, 0xbfb8aa3b, v118
	v_exp_f32_e32 v117, v116
	v_exp_f32_e32 v119, v118
	v_max_f32_e32 v116, 0xc1a00000, v109
	v_max_f32_e32 v118, 0xc1a00000, v111
	v_mul_f32_e32 v116, 0xbfb8aa3b, v116
	v_mul_f32_e32 v118, 0xbfb8aa3b, v118
	v_exp_f32_e32 v116, v116
	v_exp_f32_e32 v118, v118
	v_cvt_pk_bf16_f32 v114, v114, v115
	v_cvt_pk_bf16_f32 v115, v122, v123
	global_store_dwordx4 v[162:163], v[112:115], off
	v_or_b32_e32 v120, 16, v154
	s_and_b64 vcc, exec, s[2:3]
	v_pk_add_f32 v[112:113], v[116:117], 1.0 op_sel_hi:[1,0]
	v_pk_add_f32 v[114:115], v[118:119], 1.0 op_sel_hi:[1,0]
	v_mov_b32_e32 v116, v113
	v_mov_b32_e32 v117, v115
	v_mov_b32_e32 v118, v112
	v_mov_b32_e32 v119, v114
	v_pk_mul_f32 v[116:117], v[116:117], v[118:119]
	s_mov_b32 s41, s6
	v_mul_f32_e32 v118, v116, v117
	v_rcp_f32_e32 v121, v118
	v_mad_i64_i32 v[118:119], s[16:17], v120, s40, v[144:145]
	v_lshl_add_u64 v[118:119], v[118:119], 0, v[146:147]
	v_mul_f32_e32 v116, v116, v121
	v_mul_f32_e32 v120, v117, v121
	v_pk_mul_f32 v[114:115], v[114:115], v[116:117] op_sel_hi:[1,0]
	v_max_f32_e32 v116, 0xc1a00000, v104
	v_max_f32_e32 v121, 0xc1a00000, v106
	v_mul_f32_e32 v116, 0xbfb8aa3b, v116
	v_mul_f32_e32 v121, 0xbfb8aa3b, v121
	v_exp_f32_e32 v117, v116
	v_exp_f32_e32 v123, v121
	v_max_f32_e32 v116, 0xc1a00000, v105
	v_max_f32_e32 v121, 0xc1a00000, v107
	v_mul_f32_e32 v116, 0xbfb8aa3b, v116
	v_mul_f32_e32 v121, 0xbfb8aa3b, v121
	v_exp_f32_e32 v116, v116
	v_exp_f32_e32 v122, v121
	v_pk_mul_f32 v[112:113], v[112:113], v[120:121] op_sel_hi:[1,0]
	v_pk_mul_f32 v[110:111], v[110:111], v[114:115]
	v_pk_mul_f32 v[108:109], v[108:109], v[112:113]
	v_pk_add_f32 v[112:113], v[116:117], 1.0 op_sel_hi:[1,0]
	v_pk_add_f32 v[116:117], v[122:123], 1.0 op_sel_hi:[1,0]
	v_mov_b32_e32 v120, v113
	v_mov_b32_e32 v121, v117
	v_mov_b32_e32 v122, v112
	v_mov_b32_e32 v123, v116
	v_pk_mul_f32 v[120:121], v[120:121], v[122:123]
	v_pk_mul_f32 v[102:103], v[110:111], v[102:103]
	v_mul_f32_e32 v122, v120, v121
	v_rcp_f32_e32 v122, v122
	v_pk_mul_f32 v[100:101], v[108:109], v[100:101]
	s_mov_b32 s14, s8
	s_mov_b64 s[18:19], s[12:13]
	v_mul_f32_e32 v108, v121, v122
	v_mul_f32_e32 v110, v120, v122
	v_pk_mul_f32 v[110:111], v[116:117], v[110:111] op_sel_hi:[1,0]
	v_pk_mul_f32 v[108:109], v[112:113], v[108:109] op_sel_hi:[1,0]
	v_pk_mul_f32 v[106:107], v[106:107], v[110:111]
	v_pk_mul_f32 v[104:105], v[104:105], v[108:109]
	v_pk_mul_f32 v[106:107], v[106:107], v[98:99]
	v_pk_mul_f32 v[98:99], v[104:105], v[96:97]
	v_cvt_pk_bf16_f32 v96, v100, v101
	v_cvt_pk_bf16_f32 v97, v102, v103
	v_max_f32_e32 v100, 0xc1a00000, v92
	v_max_f32_e32 v102, 0xc1a00000, v94
	v_mul_f32_e32 v100, 0xbfb8aa3b, v100
	v_mul_f32_e32 v102, 0xbfb8aa3b, v102
	v_exp_f32_e32 v101, v100
	v_exp_f32_e32 v103, v102
	v_max_f32_e32 v100, 0xc1a00000, v93
	v_max_f32_e32 v102, 0xc1a00000, v95
	v_mul_f32_e32 v100, 0xbfb8aa3b, v100
	v_mul_f32_e32 v102, 0xbfb8aa3b, v102
	v_exp_f32_e32 v100, v100
	v_exp_f32_e32 v102, v102
	v_cvt_pk_bf16_f32 v98, v98, v99
	v_cvt_pk_bf16_f32 v99, v106, v107
	global_store_dwordx4 v[118:119], v[96:99], off
	v_or_b32_e32 v104, 32, v154
	s_nop 0
	v_pk_add_f32 v[96:97], v[100:101], 1.0 op_sel_hi:[1,0]
	v_pk_add_f32 v[98:99], v[102:103], 1.0 op_sel_hi:[1,0]
	v_mov_b32_e32 v100, v97
	v_mov_b32_e32 v101, v99
	v_mov_b32_e32 v102, v96
	v_mov_b32_e32 v103, v98
	v_pk_mul_f32 v[100:101], v[100:101], v[102:103]
	s_nop 0
	v_mul_f32_e32 v102, v100, v101
	v_rcp_f32_e32 v105, v102
	v_mad_i64_i32 v[102:103], s[16:17], v104, s40, v[144:145]
	v_lshl_add_u64 v[102:103], v[102:103], 0, v[146:147]
	v_mul_f32_e32 v100, v100, v105
	v_mul_f32_e32 v104, v101, v105
	v_pk_mul_f32 v[98:99], v[98:99], v[100:101] op_sel_hi:[1,0]
	v_max_f32_e32 v100, 0xc1a00000, v88
	v_max_f32_e32 v105, 0xc1a00000, v90
	v_mul_f32_e32 v100, 0xbfb8aa3b, v100
	v_mul_f32_e32 v105, 0xbfb8aa3b, v105
	v_exp_f32_e32 v101, v100
	v_exp_f32_e32 v107, v105
	v_max_f32_e32 v100, 0xc1a00000, v89
	v_max_f32_e32 v105, 0xc1a00000, v91
	v_mul_f32_e32 v100, 0xbfb8aa3b, v100
	v_mul_f32_e32 v105, 0xbfb8aa3b, v105
	v_exp_f32_e32 v100, v100
	v_exp_f32_e32 v106, v105
	v_pk_mul_f32 v[96:97], v[96:97], v[104:105] op_sel_hi:[1,0]
	v_pk_mul_f32 v[94:95], v[94:95], v[98:99]
	v_pk_mul_f32 v[92:93], v[92:93], v[96:97]
	v_pk_add_f32 v[96:97], v[100:101], 1.0 op_sel_hi:[1,0]
	v_pk_add_f32 v[100:101], v[106:107], 1.0 op_sel_hi:[1,0]
	v_mov_b32_e32 v104, v97
	v_mov_b32_e32 v105, v101
	v_mov_b32_e32 v106, v96
	v_mov_b32_e32 v107, v100
	v_pk_mul_f32 v[104:105], v[104:105], v[106:107]
	v_pk_mul_f32 v[86:87], v[94:95], v[86:87]
	v_mul_f32_e32 v106, v104, v105
	v_rcp_f32_e32 v106, v106
	v_pk_mul_f32 v[84:85], v[92:93], v[84:85]
	v_mul_f32_e32 v92, v105, v106
	v_mul_f32_e32 v94, v104, v106
	v_pk_mul_f32 v[94:95], v[100:101], v[94:95] op_sel_hi:[1,0]
	v_pk_mul_f32 v[92:93], v[96:97], v[92:93] op_sel_hi:[1,0]
	v_pk_mul_f32 v[90:91], v[90:91], v[94:95]
	v_pk_mul_f32 v[88:89], v[88:89], v[92:93]
	v_pk_mul_f32 v[90:91], v[90:91], v[82:83]
	v_pk_mul_f32 v[82:83], v[88:89], v[80:81]
	v_cvt_pk_bf16_f32 v80, v84, v85
	v_cvt_pk_bf16_f32 v81, v86, v87
	v_max_f32_e32 v84, 0xc1a00000, v76
	v_max_f32_e32 v86, 0xc1a00000, v78
	v_mul_f32_e32 v84, 0xbfb8aa3b, v84
	v_mul_f32_e32 v86, 0xbfb8aa3b, v86
; __device__ __forceinline__ unsigned cvt_pk_bf16(float lo, float hi) { unsigned r; asm volatile("v_cvt_pk_bf16_f32 %0, %1, %2" : "=v"(r) : "v"(lo), "v"(hi)); return r; }
; __device__ __forceinline__ f32x4 sigmoid4(f32x4 x) {
;     f32x4 d;
; #pragma unroll
;     for (int j = 0; j < 4; ++j) d[j] = 1.0f + __expf(-fmaxf(x[j], -20.0f));
;     const float p01 = d[0] * d[1], p23 = d[2] * d[3], r = __builtin_amdgcn_rcpf(p01 * p23), r01 = r * p23, r23 = r * p01;
;     return (f32x4){r01 * d[1], r01 * d[0], r23 * d[3], r23 * d[2]};
; }
;     __device__ __forceinline__ void operator()(const f32x4 (&acc)[2][2][4][2], const Unit& u, int wr, int wc, int fr, int fq) const {
;         const int row0 = u.pm * BM + wr * 64 + fr, col0 = u.pn * HALF + wc * 32 + 8 * fq;
; #pragma unroll
;         for (int ai = 0; ai < 2; ++ai)
; #pragma unroll
;             for (int m = 0; m < 4; ++m) { bf16_t* rowp = O + (size_t)(row0 + ai * HALF + m * 16) * ldc + col0;
;                 f32x4 v0, v1;
; #pragma unroll
;                 for (int j = 0; j < 1; ++j) { v0 = acc[ai][0][m][0] * sigmoid4(acc[ai][0][m][0]) * acc[ai][1][m][0]; v1 = acc[ai][0][m][1] * sigmoid4(acc[ai][0][m][1]) * acc[ai][1][m][1]; }
;                 u32x4 w; w.x = cvt_pk_bf16(v0[0], v0[1]); w.y = cvt_pk_bf16(v0[2], v0[3]); w.z = cvt_pk_bf16(v1[0], v1[1]); w.w = cvt_pk_bf16(v1[2], v1[3]);
;                 *(u32x4*)rowp = w; }
	v_exp_f32_e32 v85, v84
	v_exp_f32_e32 v87, v86
	v_max_f32_e32 v84, 0xc1a00000, v77
	v_max_f32_e32 v86, 0xc1a00000, v79
	v_mul_f32_e32 v84, 0xbfb8aa3b, v84
	v_mul_f32_e32 v86, 0xbfb8aa3b, v86
	v_exp_f32_e32 v84, v84
	v_exp_f32_e32 v86, v86
	v_cvt_pk_bf16_f32 v82, v82, v83
	v_cvt_pk_bf16_f32 v83, v90, v91
	global_store_dwordx4 v[102:103], v[80:83], off
	v_or_b32_e32 v88, 48, v154
	s_nop 0
	v_pk_add_f32 v[80:81], v[84:85], 1.0 op_sel_hi:[1,0]
	v_pk_add_f32 v[82:83], v[86:87], 1.0 op_sel_hi:[1,0]
	v_mov_b32_e32 v84, v81
	v_mov_b32_e32 v85, v83
	v_mov_b32_e32 v86, v80
	v_mov_b32_e32 v87, v82
	v_pk_mul_f32 v[84:85], v[84:85], v[86:87]
	s_nop 0
	v_mul_f32_e32 v86, v84, v85
	v_rcp_f32_e32 v89, v86
	v_mad_i64_i32 v[86:87], s[16:17], v88, s40, v[144:145]
	v_lshl_add_u64 v[86:87], v[86:87], 0, v[146:147]
	v_mul_f32_e32 v84, v84, v89
	v_mul_f32_e32 v88, v85, v89
	v_pk_mul_f32 v[82:83], v[82:83], v[84:85] op_sel_hi:[1,0]
	v_max_f32_e32 v84, 0xc1a00000, v72
	v_max_f32_e32 v89, 0xc1a00000, v74
	v_mul_f32_e32 v84, 0xbfb8aa3b, v84
	v_mul_f32_e32 v89, 0xbfb8aa3b, v89
	v_exp_f32_e32 v85, v84
	v_exp_f32_e32 v91, v89
	v_max_f32_e32 v84, 0xc1a00000, v73
	v_max_f32_e32 v89, 0xc1a00000, v75
	v_mul_f32_e32 v84, 0xbfb8aa3b, v84
	v_mul_f32_e32 v89, 0xbfb8aa3b, v89
	v_exp_f32_e32 v84, v84
	v_exp_f32_e32 v90, v89
	v_pk_mul_f32 v[80:81], v[80:81], v[88:89] op_sel_hi:[1,0]
	v_pk_mul_f32 v[78:79], v[78:79], v[82:83]
	v_pk_mul_f32 v[76:77], v[76:77], v[80:81]
	v_pk_add_f32 v[80:81], v[84:85], 1.0 op_sel_hi:[1,0]
	v_pk_add_f32 v[84:85], v[90:91], 1.0 op_sel_hi:[1,0]
	v_mov_b32_e32 v88, v81
	v_mov_b32_e32 v89, v85
	v_mov_b32_e32 v90, v80
	v_mov_b32_e32 v91, v84
	v_pk_mul_f32 v[88:89], v[88:89], v[90:91]
	v_pk_mul_f32 v[70:71], v[78:79], v[70:71]
	v_mul_f32_e32 v90, v88, v89
	v_rcp_f32_e32 v90, v90
	v_pk_mul_f32 v[68:69], v[76:77], v[68:69]
	v_mul_f32_e32 v76, v89, v90
	v_mul_f32_e32 v78, v88, v90
	v_pk_mul_f32 v[78:79], v[84:85], v[78:79] op_sel_hi:[1,0]
	v_pk_mul_f32 v[76:77], v[80:81], v[76:77] op_sel_hi:[1,0]
	v_pk_mul_f32 v[74:75], v[74:75], v[78:79]
	v_pk_mul_f32 v[72:73], v[72:73], v[76:77]
	v_pk_mul_f32 v[74:75], v[74:75], v[66:67]
	v_pk_mul_f32 v[66:67], v[72:73], v[64:65]
	v_cvt_pk_bf16_f32 v64, v68, v69
	v_cvt_pk_bf16_f32 v65, v70, v71
	v_max_f32_e32 v68, 0xc1a00000, v60
	v_max_f32_e32 v70, 0xc1a00000, v62
	v_mul_f32_e32 v68, 0xbfb8aa3b, v68
	v_mul_f32_e32 v70, 0xbfb8aa3b, v70
	v_exp_f32_e32 v69, v68
	v_exp_f32_e32 v71, v70
	v_max_f32_e32 v68, 0xc1a00000, v61
	v_max_f32_e32 v70, 0xc1a00000, v63
	v_mul_f32_e32 v68, 0xbfb8aa3b, v68
	v_mul_f32_e32 v70, 0xbfb8aa3b, v70
	v_exp_f32_e32 v68, v68
	v_exp_f32_e32 v70, v70
	v_cvt_pk_bf16_f32 v66, v66, v67
	v_cvt_pk_bf16_f32 v67, v74, v75
	global_store_dwordx4 v[86:87], v[64:67], off
	v_add_u32_e32 v72, 0x80, v154
	s_nop 0
	v_pk_add_f32 v[64:65], v[68:69], 1.0 op_sel_hi:[1,0]
	v_pk_add_f32 v[66:67], v[70:71], 1.0 op_sel_hi:[1,0]
	v_mov_b32_e32 v68, v65
	v_mov_b32_e32 v69, v67
	v_mov_b32_e32 v70, v64
	v_mov_b32_e32 v71, v66
	v_pk_mul_f32 v[68:69], v[68:69], v[70:71]
	s_nop 0
	v_mul_f32_e32 v70, v68, v69
	v_rcp_f32_e32 v73, v70
	v_mad_i64_i32 v[70:71], s[16:17], v72, s40, v[144:145]
	v_lshl_add_u64 v[70:71], v[70:71], 0, v[146:147]
	v_mul_f32_e32 v68, v68, v73
	v_mul_f32_e32 v72, v69, v73
	v_pk_mul_f32 v[66:67], v[66:67], v[68:69] op_sel_hi:[1,0]
	v_max_f32_e32 v68, 0xc1a00000, v56
	v_max_f32_e32 v73, 0xc1a00000, v58
	v_mul_f32_e32 v68, 0xbfb8aa3b, v68
	v_mul_f32_e32 v73, 0xbfb8aa3b, v73
	v_exp_f32_e32 v69, v68
	v_exp_f32_e32 v75, v73
	v_max_f32_e32 v68, 0xc1a00000, v57
	v_max_f32_e32 v73, 0xc1a00000, v59
	v_mul_f32_e32 v68, 0xbfb8aa3b, v68
	v_mul_f32_e32 v73, 0xbfb8aa3b, v73
	v_exp_f32_e32 v68, v68
	v_exp_f32_e32 v74, v73
	v_pk_mul_f32 v[64:65], v[64:65], v[72:73] op_sel_hi:[1,0]
	v_pk_mul_f32 v[62:63], v[62:63], v[66:67]
	v_pk_mul_f32 v[60:61], v[60:61], v[64:65]
	v_pk_add_f32 v[64:65], v[68:69], 1.0 op_sel_hi:[1,0]
	v_pk_add_f32 v[68:69], v[74:75], 1.0 op_sel_hi:[1,0]
	v_mov_b32_e32 v72, v65
	v_mov_b32_e32 v73, v69
	v_mov_b32_e32 v74, v64
	v_mov_b32_e32 v75, v68
	v_pk_mul_f32 v[72:73], v[72:73], v[74:75]
	v_pk_mul_f32 v[54:55], v[62:63], v[54:55]
	v_mul_f32_e32 v74, v72, v73
	v_rcp_f32_e32 v74, v74
	v_pk_mul_f32 v[52:53], v[60:61], v[52:53]
	v_mul_f32_e32 v60, v73, v74
	v_mul_f32_e32 v62, v72, v74
	v_pk_mul_f32 v[62:63], v[68:69], v[62:63] op_sel_hi:[1,0]
	v_pk_mul_f32 v[60:61], v[64:65], v[60:61] op_sel_hi:[1,0]
	v_pk_mul_f32 v[58:59], v[58:59], v[62:63]
	v_pk_mul_f32 v[56:57], v[56:57], v[60:61]
	v_pk_mul_f32 v[58:59], v[58:59], v[50:51]
	v_pk_mul_f32 v[50:51], v[56:57], v[48:49]
	v_cvt_pk_bf16_f32 v48, v52, v53
	v_cvt_pk_bf16_f32 v49, v54, v55
	v_max_f32_e32 v52, 0xc1a00000, v44
	v_max_f32_e32 v54, 0xc1a00000, v46
	v_mul_f32_e32 v52, 0xbfb8aa3b, v52
	v_mul_f32_e32 v54, 0xbfb8aa3b, v54
	v_exp_f32_e32 v53, v52
	v_exp_f32_e32 v55, v54
	v_max_f32_e32 v52, 0xc1a00000, v45
	v_max_f32_e32 v54, 0xc1a00000, v47
	v_mul_f32_e32 v52, 0xbfb8aa3b, v52
	v_mul_f32_e32 v54, 0xbfb8aa3b, v54
	v_exp_f32_e32 v52, v52
	v_exp_f32_e32 v54, v54
	v_cvt_pk_bf16_f32 v50, v50, v51
	v_cvt_pk_bf16_f32 v51, v58, v59
	global_store_dwordx4 v[70:71], v[48:51], off
	v_add_u32_e32 v56, 0x90, v154
	s_nop 0
	v_pk_add_f32 v[48:49], v[52:53], 1.0 op_sel_hi:[1,0]
	v_pk_add_f32 v[50:51], v[54:55], 1.0 op_sel_hi:[1,0]
	v_mov_b32_e32 v52, v49
	v_mov_b32_e32 v53, v51
	v_mov_b32_e32 v54, v48
	v_mov_b32_e32 v55, v50
	v_pk_mul_f32 v[52:53], v[52:53], v[54:55]
	s_nop 0
	v_mul_f32_e32 v54, v52, v53
	v_rcp_f32_e32 v57, v54
	v_mad_i64_i32 v[54:55], s[16:17], v56, s40, v[144:145]
	v_lshl_add_u64 v[54:55], v[54:55], 0, v[146:147]
	v_mul_f32_e32 v52, v52, v57
; __device__ __forceinline__ unsigned cvt_pk_bf16(float lo, float hi) { unsigned r; asm volatile("v_cvt_pk_bf16_f32 %0, %1, %2" : "=v"(r) : "v"(lo), "v"(hi)); return r; }
; __device__ __forceinline__ f32x4 sigmoid4(f32x4 x) {
;     f32x4 d;
; #pragma unroll
;     for (int j = 0; j < 4; ++j) d[j] = 1.0f + __expf(-fmaxf(x[j], -20.0f));
;     const float p01 = d[0] * d[1], p23 = d[2] * d[3], r = __builtin_amdgcn_rcpf(p01 * p23), r01 = r * p23, r23 = r * p01;
;     return (f32x4){r01 * d[1], r01 * d[0], r23 * d[3], r23 * d[2]};
; }
;     __device__ __forceinline__ void operator()(const f32x4 (&acc)[2][2][4][2], const Unit& u, int wr, int wc, int fr, int fq) const {
;         const int row0 = u.pm * BM + wr * 64 + fr, col0 = u.pn * HALF + wc * 32 + 8 * fq;
; #pragma unroll
;         for (int ai = 0; ai < 2; ++ai)
; #pragma unroll
;             for (int m = 0; m < 4; ++m) { bf16_t* rowp = O + (size_t)(row0 + ai * HALF + m * 16) * ldc + col0;
;                 f32x4 v0, v1;
; #pragma unroll
;                 for (int j = 0; j < 1; ++j) { v0 = acc[ai][0][m][0] * sigmoid4(acc[ai][0][m][0]) * acc[ai][1][m][0]; v1 = acc[ai][0][m][1] * sigmoid4(acc[ai][0][m][1]) * acc[ai][1][m][1]; }
;                 u32x4 w; w.x = cvt_pk_bf16(v0[0], v0[1]); w.y = cvt_pk_bf16(v0[2], v0[3]); w.z = cvt_pk_bf16(v1[0], v1[1]); w.w = cvt_pk_bf16(v1[2], v1[3]);
;                 *(u32x4*)rowp = w; }
	v_mul_f32_e32 v56, v53, v57
	v_pk_mul_f32 v[50:51], v[50:51], v[52:53] op_sel_hi:[1,0]
	v_max_f32_e32 v52, 0xc1a00000, v40
	v_max_f32_e32 v57, 0xc1a00000, v42
	v_mul_f32_e32 v52, 0xbfb8aa3b, v52
	v_mul_f32_e32 v57, 0xbfb8aa3b, v57
	v_exp_f32_e32 v53, v52
	v_exp_f32_e32 v59, v57
	v_max_f32_e32 v52, 0xc1a00000, v41
	v_max_f32_e32 v57, 0xc1a00000, v43
	v_mul_f32_e32 v52, 0xbfb8aa3b, v52
	v_mul_f32_e32 v57, 0xbfb8aa3b, v57
	v_exp_f32_e32 v52, v52
	v_exp_f32_e32 v58, v57
	v_pk_mul_f32 v[48:49], v[48:49], v[56:57] op_sel_hi:[1,0]
	v_pk_mul_f32 v[46:47], v[46:47], v[50:51]
	v_pk_mul_f32 v[44:45], v[44:45], v[48:49]
	v_pk_add_f32 v[48:49], v[52:53], 1.0 op_sel_hi:[1,0]
	v_pk_add_f32 v[52:53], v[58:59], 1.0 op_sel_hi:[1,0]
	v_mov_b32_e32 v56, v49
	v_mov_b32_e32 v57, v53
	v_mov_b32_e32 v58, v48
	v_mov_b32_e32 v59, v52
	v_pk_mul_f32 v[56:57], v[56:57], v[58:59]
	v_pk_mul_f32 v[38:39], v[46:47], v[38:39]
	v_mul_f32_e32 v58, v56, v57
	v_rcp_f32_e32 v58, v58
	v_pk_mul_f32 v[36:37], v[44:45], v[36:37]
	v_mul_f32_e32 v44, v57, v58
	v_mul_f32_e32 v46, v56, v58
	v_pk_mul_f32 v[46:47], v[52:53], v[46:47] op_sel_hi:[1,0]
	v_pk_mul_f32 v[44:45], v[48:49], v[44:45] op_sel_hi:[1,0]
	v_pk_mul_f32 v[42:43], v[42:43], v[46:47]
	v_pk_mul_f32 v[40:41], v[40:41], v[44:45]
	v_pk_mul_f32 v[42:43], v[42:43], v[34:35]
	v_pk_mul_f32 v[34:35], v[40:41], v[32:33]
	v_cvt_pk_bf16_f32 v32, v36, v37
	v_cvt_pk_bf16_f32 v33, v38, v39
	v_max_f32_e32 v36, 0xc1a00000, v28
	v_max_f32_e32 v38, 0xc1a00000, v30
	v_mul_f32_e32 v36, 0xbfb8aa3b, v36
	v_mul_f32_e32 v38, 0xbfb8aa3b, v38
	v_exp_f32_e32 v37, v36
	v_exp_f32_e32 v39, v38
	v_max_f32_e32 v36, 0xc1a00000, v29
	v_max_f32_e32 v38, 0xc1a00000, v31
	v_mul_f32_e32 v36, 0xbfb8aa3b, v36
	v_mul_f32_e32 v38, 0xbfb8aa3b, v38
	v_exp_f32_e32 v36, v36
	v_exp_f32_e32 v38, v38
	v_cvt_pk_bf16_f32 v34, v34, v35
	v_cvt_pk_bf16_f32 v35, v42, v43
	global_store_dwordx4 v[54:55], v[32:35], off
	v_add_u32_e32 v40, 0xa0, v154
	s_nop 0
	v_pk_add_f32 v[32:33], v[36:37], 1.0 op_sel_hi:[1,0]
	v_pk_add_f32 v[34:35], v[38:39], 1.0 op_sel_hi:[1,0]
	v_mov_b32_e32 v36, v33
	v_mov_b32_e32 v37, v35
	v_mov_b32_e32 v38, v32
	v_mov_b32_e32 v39, v34
	v_pk_mul_f32 v[36:37], v[36:37], v[38:39]
	s_nop 0
	v_mul_f32_e32 v38, v36, v37
	v_rcp_f32_e32 v41, v38
	v_mad_i64_i32 v[38:39], s[16:17], v40, s40, v[144:145]
	v_lshl_add_u64 v[38:39], v[38:39], 0, v[146:147]
	v_mul_f32_e32 v36, v36, v41
	v_mul_f32_e32 v40, v37, v41
	v_pk_mul_f32 v[34:35], v[34:35], v[36:37] op_sel_hi:[1,0]
	v_max_f32_e32 v36, 0xc1a00000, v24
	v_max_f32_e32 v41, 0xc1a00000, v26
	v_mul_f32_e32 v36, 0xbfb8aa3b, v36
	v_mul_f32_e32 v41, 0xbfb8aa3b, v41
	v_exp_f32_e32 v37, v36
	v_exp_f32_e32 v43, v41
	v_max_f32_e32 v36, 0xc1a00000, v25
	v_max_f32_e32 v41, 0xc1a00000, v27
	v_mul_f32_e32 v36, 0xbfb8aa3b, v36
	v_mul_f32_e32 v41, 0xbfb8aa3b, v41
	v_exp_f32_e32 v36, v36
	v_exp_f32_e32 v42, v41
	v_pk_mul_f32 v[32:33], v[32:33], v[40:41] op_sel_hi:[1,0]
	v_pk_mul_f32 v[30:31], v[30:31], v[34:35]
	v_pk_mul_f32 v[28:29], v[28:29], v[32:33]
	v_pk_add_f32 v[32:33], v[36:37], 1.0 op_sel_hi:[1,0]
	v_pk_add_f32 v[36:37], v[42:43], 1.0 op_sel_hi:[1,0]
	v_mov_b32_e32 v40, v33
	v_mov_b32_e32 v41, v37
	v_mov_b32_e32 v42, v32
	v_mov_b32_e32 v43, v36
	v_pk_mul_f32 v[40:41], v[40:41], v[42:43]
	v_pk_mul_f32 v[22:23], v[30:31], v[22:23]
	v_mul_f32_e32 v42, v40, v41
	v_rcp_f32_e32 v42, v42
	v_pk_mul_f32 v[20:21], v[28:29], v[20:21]
	v_mul_f32_e32 v28, v41, v42
	v_mul_f32_e32 v30, v40, v42
	v_pk_mul_f32 v[30:31], v[36:37], v[30:31] op_sel_hi:[1,0]
	v_pk_mul_f32 v[28:29], v[32:33], v[28:29] op_sel_hi:[1,0]
	v_pk_mul_f32 v[26:27], v[26:27], v[30:31]
	v_pk_mul_f32 v[24:25], v[24:25], v[28:29]
	v_pk_mul_f32 v[26:27], v[26:27], v[18:19]
	v_pk_mul_f32 v[18:19], v[24:25], v[16:17]
	v_cvt_pk_bf16_f32 v16, v20, v21
	v_cvt_pk_bf16_f32 v17, v22, v23
	v_max_f32_e32 v20, 0xc1a00000, v12
	v_max_f32_e32 v22, 0xc1a00000, v14
	v_mul_f32_e32 v20, 0xbfb8aa3b, v20
	v_mul_f32_e32 v22, 0xbfb8aa3b, v22
	v_exp_f32_e32 v21, v20
	v_exp_f32_e32 v23, v22
	v_max_f32_e32 v20, 0xc1a00000, v13
	v_max_f32_e32 v22, 0xc1a00000, v15
	v_mul_f32_e32 v20, 0xbfb8aa3b, v20
	v_mul_f32_e32 v22, 0xbfb8aa3b, v22
	v_exp_f32_e32 v20, v20
	v_exp_f32_e32 v22, v22
	v_cvt_pk_bf16_f32 v18, v18, v19
	v_cvt_pk_bf16_f32 v19, v26, v27
	global_store_dwordx4 v[38:39], v[16:19], off
	v_add_u32_e32 v24, 0xb0, v154
	s_nop 0
	v_pk_add_f32 v[16:17], v[20:21], 1.0 op_sel_hi:[1,0]
	v_pk_add_f32 v[18:19], v[22:23], 1.0 op_sel_hi:[1,0]
	v_mov_b32_e32 v20, v17
	v_mov_b32_e32 v21, v19
	v_mov_b32_e32 v22, v16
	v_mov_b32_e32 v23, v18
	v_pk_mul_f32 v[20:21], v[20:21], v[22:23]
	s_nop 0
	v_mul_f32_e32 v22, v20, v21
	v_rcp_f32_e32 v25, v22
	v_mad_i64_i32 v[22:23], s[16:17], v24, s40, v[144:145]
	v_lshl_add_u64 v[22:23], v[22:23], 0, v[146:147]
	v_mul_f32_e32 v20, v20, v25
	v_mul_f32_e32 v24, v21, v25
	v_pk_mul_f32 v[18:19], v[18:19], v[20:21] op_sel_hi:[1,0]
	v_max_f32_e32 v20, 0xc1a00000, v8
	v_max_f32_e32 v25, 0xc1a00000, v10
	v_mul_f32_e32 v20, 0xbfb8aa3b, v20
	v_mul_f32_e32 v25, 0xbfb8aa3b, v25
	v_exp_f32_e32 v21, v20
	v_exp_f32_e32 v27, v25
	v_max_f32_e32 v20, 0xc1a00000, v9
	v_max_f32_e32 v25, 0xc1a00000, v11
	v_mul_f32_e32 v20, 0xbfb8aa3b, v20
	v_mul_f32_e32 v25, 0xbfb8aa3b, v25
	v_exp_f32_e32 v20, v20
	v_exp_f32_e32 v26, v25
	v_pk_mul_f32 v[16:17], v[16:17], v[24:25] op_sel_hi:[1,0]
	v_pk_mul_f32 v[14:15], v[14:15], v[18:19]
	v_pk_mul_f32 v[12:13], v[12:13], v[16:17]
	v_pk_add_f32 v[16:17], v[20:21], 1.0 op_sel_hi:[1,0]
	v_pk_add_f32 v[20:21], v[26:27], 1.0 op_sel_hi:[1,0]
	v_mov_b32_e32 v24, v17
	v_mov_b32_e32 v25, v21
	v_mov_b32_e32 v26, v16
	v_mov_b32_e32 v27, v20
	v_pk_mul_f32 v[24:25], v[24:25], v[26:27]
	v_pk_mul_f32 v[6:7], v[14:15], v[6:7]
	v_mul_f32_e32 v26, v24, v25
	v_rcp_f32_e32 v26, v26
	v_pk_mul_f32 v[4:5], v[12:13], v[4:5]
	s_mov_b64 s[16:17], s[10:11]
	v_mul_f32_e32 v12, v25, v26
	v_mul_f32_e32 v14, v24, v26
	v_pk_mul_f32 v[14:15], v[20:21], v[14:15] op_sel_hi:[1,0]
	v_pk_mul_f32 v[12:13], v[16:17], v[12:13] op_sel_hi:[1,0]
	v_pk_mul_f32 v[10:11], v[10:11], v[14:15]
	v_pk_mul_f32 v[8:9], v[8:9], v[12:13]
	v_pk_mul_f32 v[10:11], v[10:11], v[2:3]
	v_pk_mul_f32 v[2:3], v[8:9], v[0:1]
	v_cvt_pk_bf16_f32 v0, v4, v5
	v_cvt_pk_bf16_f32 v1, v6, v7
	s_nop 0
	v_cvt_pk_bf16_f32 v2, v2, v3
	v_cvt_pk_bf16_f32 v3, v10, v11
	global_store_dwordx4 v[22:23], v[0:3], off
	s_cbranch_vccz .LBB0_1199
	s_waitcnt vmcnt(0)
	s_cmpk_gt_u32 s23, 0xff
	s_cbranch_scc1 .LBB0_1206
	s_barrier

; #define PG8_STAGE(bufoff, gbase, voff) do { _Pragma("unroll") for (int _i = 0; _i < 2; ++_i) \
;         __builtin_amdgcn_global_load_lds((const unsigned*)((const char*)(gbase) + (voff)[_i]), (PG8_LAS unsigned*)(lds + (bufoff) + ldsw + _i * 8192), 16, 0, 0); } while (0)
; #define PG8_LDA(dst, b, h) do { _Pragma("unroll") for (int m = 0; m < 4; ++m) _Pragma("unroll") for (int k = 0; k < 2; ++k) dst[m][k] = *(const PG8_LAS bf16x8*)(lds + PG8_SA(b, h) + aoff + m * 2048 + k * 1024); } while (0)
; #define PG8_LDB(dst, b, h) do { _Pragma("unroll") for (int n = 0; n < 2; ++n) _Pragma("unroll") for (int k = 0; k < 2; ++k) dst[n][k] = *(const PG8_LAS bf16x8*)(lds + PG8_SB(b, h) + boff + n * 2048 + k * 1024); } while (0)
; #define PG8_MMA(ai, bj, At, Bt) do { __builtin_amdgcn_s_setprio(1); _Pragma("unroll") for (int m = 0; m < 4; ++m) _Pragma("unroll") for (int n = 0; n < 2; ++n) _Pragma("unroll") for (int k = 0; k < 2; ++k) \
;         acc[ai][bj][m][n] = __builtin_amdgcn_mfma_f32_16x16x32_bf16(Bt[n][k], At[m][k], acc[ai][bj][m][n], 0, 0, 0); __builtin_amdgcn_s_setprio(0); } while (0)
; #define PG8_WAIT_V(n) asm volatile("s_waitcnt vmcnt(" #n ")" ::: "memory")
; #define PG8_WAIT_L(n) asm volatile("s_waitcnt lgkmcnt(" #n ")" ::: "memory")
; #define PG8_BAR __builtin_amdgcn_s_barrier()
; #define PG8_SCHED __builtin_amdgcn_sched_barrier(0)
; template <class Epi, class Sched>
; __device__ __forceinline__ void gemm_phase(PG8_LAS unsigned char* lds, const Gemm g, const Sched& S, const Epi& E) {
;     ...
;             PG8_LDB(B0, 0, 0); PG8_SCHED; PG8_LDA(At, 0, 0); PG8_STAGE(PG8_SA(1, 1), a1 + hstep, voffA);
;             PG8_WAIT_L(8); PG8_BAR; PG8_WAIT_L(0); PG8_MMA(0, 0, At, B0); PG8_BAR; PG8_SCHED;
;             PG8_LDB(B1, 0, 1); PG8_STAGE(PG8_SB(0, 0), b2, voffB);
;             PG8_BAR; PG8_WAIT_L(0); PG8_MMA(0, 1, At, B1); PG8_BAR;
;             PG8_LDA(At, 0, 1); PG8_STAGE(PG8_SA(0, 0), a2, voffA);
;             PG8_BAR; PG8_WAIT_L(0); PG8_MMA(1, 0, At, B0); PG8_BAR; PG8_SCHED;
;             PG8_STAGE(PG8_SB(0, 1), b2 + hstep, voffB);
;             PG8_WAIT_V(6); PG8_BAR; PG8_MMA(1, 1, At, B1); PG8_BAR;
.LBB0_1277:
	s_add_u32 s52, s20, 0x100
	s_addc_u32 s53, s21, 0
	s_mov_b32 s54, -2
	ds_read_b128 v[152:155], v149
	ds_read_b128 v[156:159], v149 offset:1024
	ds_read_b128 v[160:163], v149 offset:2048
	ds_read_b128 v[164:167], v149 offset:3072
	s_add_u32 s20, s18, 0x100
	s_addc_u32 s21, s19, 0
	s_cmp_eq_u32 s54, 40
	s_cselect_b32 s25, s1, s21
	s_cselect_b32 s24, s0, s20
	s_cselect_b32 s23, s5, s53
	s_cselect_b32 s22, s4, s52
	s_add_i32 m0, s34, 0xc000
	ds_read_b128 v[168:171], v150
	ds_read_b128 v[172:175], v150 offset:1024
	ds_read_b128 v[182:185], v150 offset:2048
	ds_read_b128 v[190:193], v150 offset:3072
	ds_read_b128 v[194:197], v150 offset:4096
	ds_read_b128 v[198:201], v150 offset:5120
	ds_read_b128 v[202:205], v150 offset:6144
	ds_read_b128 v[206:209], v150 offset:7168
	global_load_lds_dwordx4 v136, s[18:19]
	s_nop 1
	s_add_i32 m0, s34, 0xe000
	s_nop 0
	global_load_lds_dwordx4 v138, s[18:19]
	s_waitcnt lgkmcnt(8)
	ds_read_b128 v[210:213], v151
	ds_read_b128 v[214:217], v151 offset:1024
	ds_read_b128 v[218:221], v151 offset:2048
	ds_read_b128 v[222:225], v151 offset:3072
	s_waitcnt vmcnt(8) lgkmcnt(0)
	s_barrier
	v_mfma_f32_16x16x32_bf16 v[124:127], v[152:155], v[168:171], 0
	v_mfma_f32_16x16x32_bf16 v[120:123], v[160:163], v[168:171], 0
	v_mfma_f32_16x16x32_bf16 v[108:111], v[152:155], v[182:185], 0
	v_mfma_f32_16x16x32_bf16 v[104:107], v[160:163], v[182:185], 0
	v_mfma_f32_16x16x32_bf16 v[92:95], v[152:155], v[194:197], 0
	v_mfma_f32_16x16x32_bf16 v[88:91], v[160:163], v[194:197], 0
	v_mfma_f32_16x16x32_bf16 v[76:79], v[152:155], v[202:205], 0
	v_mfma_f32_16x16x32_bf16 v[72:75], v[160:163], v[202:205], 0
	v_mfma_f32_16x16x32_bf16 v[124:127], v[156:159], v[172:175], v[124:127]
	v_mfma_f32_16x16x32_bf16 v[120:123], v[164:167], v[172:175], v[120:123]
	v_mfma_f32_16x16x32_bf16 v[108:111], v[156:159], v[190:193], v[108:111]
	v_mfma_f32_16x16x32_bf16 v[104:107], v[164:167], v[190:193], v[104:107]
	v_mfma_f32_16x16x32_bf16 v[92:95], v[156:159], v[198:201], v[92:95]
	v_mfma_f32_16x16x32_bf16 v[88:91], v[164:167], v[198:201], v[88:91]
	v_mfma_f32_16x16x32_bf16 v[76:79], v[156:159], v[206:209], v[76:79]
	v_mfma_f32_16x16x32_bf16 v[72:75], v[164:167], v[206:209], v[72:75]
	v_mfma_f32_16x16x32_bf16 v[116:119], v[210:213], v[168:171], 0
	v_mfma_f32_16x16x32_bf16 v[112:115], v[218:221], v[168:171], 0
	v_mfma_f32_16x16x32_bf16 v[100:103], v[210:213], v[182:185], 0
	v_mfma_f32_16x16x32_bf16 v[96:99], v[218:221], v[182:185], 0
	v_mfma_f32_16x16x32_bf16 v[84:87], v[210:213], v[194:197], 0
	v_mfma_f32_16x16x32_bf16 v[80:83], v[218:221], v[194:197], 0
	v_mfma_f32_16x16x32_bf16 v[68:71], v[210:213], v[202:205], 0
	v_mfma_f32_16x16x32_bf16 v[64:67], v[218:221], v[202:205], 0
	v_mfma_f32_16x16x32_bf16 v[116:119], v[214:217], v[172:175], v[116:119]
	v_mfma_f32_16x16x32_bf16 v[112:115], v[222:225], v[172:175], v[112:115]
	v_mfma_f32_16x16x32_bf16 v[100:103], v[214:217], v[190:193], v[100:103]
	v_mfma_f32_16x16x32_bf16 v[96:99], v[222:225], v[190:193], v[96:99]
	v_mfma_f32_16x16x32_bf16 v[84:87], v[214:217], v[198:201], v[84:87]
	v_mfma_f32_16x16x32_bf16 v[80:83], v[222:225], v[198:201], v[80:83]
	v_mfma_f32_16x16x32_bf16 v[68:71], v[214:217], v[206:209], v[68:71]
	v_mfma_f32_16x16x32_bf16 v[64:67], v[222:225], v[206:209], v[64:67]
	s_barrier
	ds_read_b128 v[168:171], v150 offset:16384
	ds_read_b128 v[172:175], v150 offset:17408
	ds_read_b128 v[182:185], v150 offset:18432
	ds_read_b128 v[190:193], v150 offset:19456
	ds_read_b128 v[194:197], v150 offset:20480
	ds_read_b128 v[198:201], v150 offset:21504
	ds_read_b128 v[202:205], v150 offset:22528
	ds_read_b128 v[206:209], v150 offset:23552
	s_add_i32 s18, s42, s31
	s_add_u32 s98, s22, s8
	s_addc_u32 s99, s23, s9
	s_mov_b32 m0, s18
	s_nop 0
	global_load_lds_dwordx4 v130, s[22:23]
	s_nop 1
	s_add_i32 m0, s18, 0x2000
	s_nop 0
	global_load_lds_dwordx4 v134, s[22:23]
	s_nop 1
	s_mov_b32 m0, s34
	s_add_u32 s100, s24, s8
	s_addc_u32 s101, s25, s9
	global_load_lds_dwordx4 v128, s[24:25]
	s_nop 1
	s_mov_b32 m0, s35
	s_nop 0
	global_load_lds_dwordx4 v132, s[24:25]
	s_add_u32 s18, s22, 0xb0000
	s_addc_u32 s19, s23, 0
	s_add_i32 s55, s43, s31
	s_mov_b32 m0, s55
	s_nop 0
	global_load_lds_dwordx4 v130, s[18:19]
	s_nop 1
	s_add_i32 m0, s55, 0x2000
	s_nop 0
	global_load_lds_dwordx4 v134, s[18:19]
	s_waitcnt vmcnt(8) lgkmcnt(0)
	s_barrier
	v_mfma_f32_16x16x32_bf16 v[60:63], v[152:155], v[168:171], 0
	v_mfma_f32_16x16x32_bf16 v[56:59], v[160:163], v[168:171], 0
	v_mfma_f32_16x16x32_bf16 v[48:51], v[152:155], v[182:185], 0
	v_mfma_f32_16x16x32_bf16 v[40:43], v[160:163], v[182:185], 0
	v_mfma_f32_16x16x32_bf16 v[32:35], v[152:155], v[194:197], 0
	v_mfma_f32_16x16x32_bf16 v[24:27], v[160:163], v[194:197], 0
	v_mfma_f32_16x16x32_bf16 v[16:19], v[152:155], v[202:205], 0
	v_mfma_f32_16x16x32_bf16 v[8:11], v[160:163], v[202:205], 0
	v_mfma_f32_16x16x32_bf16 v[60:63], v[156:159], v[172:175], v[60:63]
	v_mfma_f32_16x16x32_bf16 v[56:59], v[164:167], v[172:175], v[56:59]
	v_mfma_f32_16x16x32_bf16 v[48:51], v[156:159], v[190:193], v[48:51]
	v_mfma_f32_16x16x32_bf16 v[40:43], v[164:167], v[190:193], v[40:43]
	v_mfma_f32_16x16x32_bf16 v[32:35], v[156:159], v[198:201], v[32:35]
	v_mfma_f32_16x16x32_bf16 v[24:27], v[164:167], v[198:201], v[24:27]
	v_mfma_f32_16x16x32_bf16 v[16:19], v[156:159], v[206:209], v[16:19]
	v_mfma_f32_16x16x32_bf16 v[8:11], v[164:167], v[206:209], v[8:11]
	v_mfma_f32_16x16x32_bf16 v[52:55], v[210:213], v[168:171], 0
	v_mfma_f32_16x16x32_bf16 v[44:47], v[218:221], v[168:171], 0
	v_mfma_f32_16x16x32_bf16 v[36:39], v[210:213], v[182:185], 0
	v_mfma_f32_16x16x32_bf16 v[28:31], v[218:221], v[182:185], 0
	v_mfma_f32_16x16x32_bf16 v[20:23], v[210:213], v[194:197], 0
	v_mfma_f32_16x16x32_bf16 v[12:15], v[218:221], v[194:197], 0
	v_mfma_f32_16x16x32_bf16 v[4:7], v[210:213], v[202:205], 0
	v_mfma_f32_16x16x32_bf16 v[0:3], v[218:221], v[202:205], 0
	v_mfma_f32_16x16x32_bf16 v[52:55], v[214:217], v[172:175], v[52:55]
	v_mfma_f32_16x16x32_bf16 v[44:47], v[222:225], v[172:175], v[44:47]
	v_mfma_f32_16x16x32_bf16 v[36:39], v[214:217], v[190:193], v[36:39]
	v_mfma_f32_16x16x32_bf16 v[28:31], v[222:225], v[190:193], v[28:31]
	v_mfma_f32_16x16x32_bf16 v[20:23], v[214:217], v[198:201], v[20:23]
	v_mfma_f32_16x16x32_bf16 v[12:15], v[222:225], v[198:201], v[12:15]
	v_mfma_f32_16x16x32_bf16 v[4:7], v[214:217], v[206:209], v[4:7]
	v_mfma_f32_16x16x32_bf16 v[0:3], v[222:225], v[206:209], v[0:3]
	s_barrier
; #define PG8_STAGE(bufoff, gbase, voff) do { _Pragma("unroll") for (int _i = 0; _i < 2; ++_i) \
;         __builtin_amdgcn_global_load_lds((const unsigned*)((const char*)(gbase) + (voff)[_i]), (PG8_LAS unsigned*)(lds + (bufoff) + ldsw + _i * 8192), 16, 0, 0); } while (0)
; #define PG8_LDA(dst, b, h) do { _Pragma("unroll") for (int m = 0; m < 4; ++m) _Pragma("unroll") for (int k = 0; k < 2; ++k) dst[m][k] = *(const PG8_LAS bf16x8*)(lds + PG8_SA(b, h) + aoff + m * 2048 + k * 1024); } while (0)
; #define PG8_LDB(dst, b, h) do { _Pragma("unroll") for (int n = 0; n < 2; ++n) _Pragma("unroll") for (int k = 0; k < 2; ++k) dst[n][k] = *(const PG8_LAS bf16x8*)(lds + PG8_SB(b, h) + boff + n * 2048 + k * 1024); } while (0)
; #define PG8_MMA(ai, bj, At, Bt) do { __builtin_amdgcn_s_setprio(1); _Pragma("unroll") for (int m = 0; m < 4; ++m) _Pragma("unroll") for (int n = 0; n < 2; ++n) _Pragma("unroll") for (int k = 0; k < 2; ++k) \
;         acc[ai][bj][m][n] = __builtin_amdgcn_mfma_f32_16x16x32_bf16(Bt[n][k], At[m][k], acc[ai][bj][m][n], 0, 0, 0); __builtin_amdgcn_s_setprio(0); } while (0)
; #define PG8_WAIT_V(n) asm volatile("s_waitcnt vmcnt(" #n ")" ::: "memory")
; #define PG8_WAIT_L(n) asm volatile("s_waitcnt lgkmcnt(" #n ")" ::: "memory")
; #define PG8_BAR __builtin_amdgcn_s_barrier()
; template <class Epi, class Sched>
; __device__ __forceinline__ void gemm_phase(PG8_LAS unsigned char* lds, const Gemm g, const Sched& S, const Epi& E) {
;     ...
;             PG8_LDA(At, 0, 1); PG8_STAGE(PG8_SA(0, 0), a2, voffA);
;             PG8_BAR; PG8_WAIT_L(0); PG8_MMA(1, 0, At, B0); PG8_BAR; PG8_SCHED;
;             PG8_STAGE(PG8_SB(0, 1), b2 + hstep, voffB);
;             PG8_WAIT_V(6); PG8_BAR; PG8_MMA(1, 1, At, B1); PG8_BAR;
;             PG8_LDB(B0, 1, 0); PG8_SCHED; PG8_LDA(At, 1, 0); PG8_STAGE(PG8_SA(0, 1), a2 + hstep, voffA);
;             PG8_WAIT_L(8); PG8_BAR; PG8_WAIT_L(0); PG8_MMA(0, 0, At, B0); PG8_BAR; PG8_SCHED;
;             PG8_LDB(B1, 1, 1); PG8_STAGE(PG8_SB(1, 0), b3, voffB);
;             PG8_BAR; PG8_WAIT_L(0); PG8_MMA(0, 1, At, B1); PG8_BAR;
;             PG8_LDA(At, 1, 1); PG8_STAGE(PG8_SA(1, 0), a3, voffA);
;             PG8_BAR; PG8_WAIT_L(0); PG8_MMA(1, 0, At, B0); PG8_BAR; PG8_SCHED;
;             PG8_STAGE(PG8_SB(1, 1), b3 + hstep, voffB);
;             PG8_WAIT_V(6); PG8_BAR; PG8_MMA(1, 1, At, B1); PG8_BAR;
	s_add_i32 s55, 0, 0x18000
	v_add_u32_e32 v164, s55, v147
	ds_read_b128 v[152:155], v164
	ds_read_b128 v[156:159], v164 offset:1024
	ds_read_b128 v[160:163], v164 offset:2048
	ds_read_b128 v[164:167], v164 offset:3072
	s_add_u32 s18, s24, 0xb0000
	s_addc_u32 s19, s25, 0
	s_mov_b32 m0, s36
	ds_read_b128 v[168:171], v150 offset:32768
	ds_read_b128 v[172:175], v150 offset:33792
	ds_read_b128 v[182:185], v150 offset:34816
	ds_read_b128 v[190:193], v150 offset:35840
	ds_read_b128 v[194:197], v150 offset:36864
	ds_read_b128 v[198:201], v150 offset:37888
	ds_read_b128 v[202:205], v150 offset:38912
	ds_read_b128 v[206:209], v150 offset:39936
	global_load_lds_dwordx4 v128, s[18:19]
	s_nop 1
	s_mov_b32 m0, s37
	s_nop 0
	global_load_lds_dwordx4 v132, s[18:19]
	s_add_i32 s24, 0, 0x1c000
	v_add_u32_e32 v179, s24, v147
	s_waitcnt lgkmcnt(8)
	ds_read_b128 v[210:213], v179
	ds_read_b128 v[214:217], v179 offset:1024
	ds_read_b128 v[218:221], v179 offset:2048
	ds_read_b128 v[222:225], v179 offset:3072
	s_waitcnt vmcnt(8) lgkmcnt(0)
	s_barrier
	v_mfma_f32_16x16x32_bf16 v[124:127], v[152:155], v[168:171], v[124:127]
	v_mfma_f32_16x16x32_bf16 v[120:123], v[160:163], v[168:171], v[120:123]
	v_mfma_f32_16x16x32_bf16 v[108:111], v[152:155], v[182:185], v[108:111]
	v_mfma_f32_16x16x32_bf16 v[104:107], v[160:163], v[182:185], v[104:107]
	v_mfma_f32_16x16x32_bf16 v[92:95], v[152:155], v[194:197], v[92:95]
	v_mfma_f32_16x16x32_bf16 v[88:91], v[160:163], v[194:197], v[88:91]
	v_mfma_f32_16x16x32_bf16 v[76:79], v[152:155], v[202:205], v[76:79]
	v_mfma_f32_16x16x32_bf16 v[72:75], v[160:163], v[202:205], v[72:75]
	v_mfma_f32_16x16x32_bf16 v[124:127], v[156:159], v[172:175], v[124:127]
	v_mfma_f32_16x16x32_bf16 v[120:123], v[164:167], v[172:175], v[120:123]
	v_mfma_f32_16x16x32_bf16 v[108:111], v[156:159], v[190:193], v[108:111]
	v_mfma_f32_16x16x32_bf16 v[104:107], v[164:167], v[190:193], v[104:107]
	v_mfma_f32_16x16x32_bf16 v[92:95], v[156:159], v[198:201], v[92:95]
	v_mfma_f32_16x16x32_bf16 v[88:91], v[164:167], v[198:201], v[88:91]
	v_mfma_f32_16x16x32_bf16 v[76:79], v[156:159], v[206:209], v[76:79]
	v_mfma_f32_16x16x32_bf16 v[72:75], v[164:167], v[206:209], v[72:75]
	v_mfma_f32_16x16x32_bf16 v[116:119], v[210:213], v[168:171], v[116:119]
	v_mfma_f32_16x16x32_bf16 v[112:115], v[218:221], v[168:171], v[112:115]
	v_mfma_f32_16x16x32_bf16 v[100:103], v[210:213], v[182:185], v[100:103]
	v_mfma_f32_16x16x32_bf16 v[96:99], v[218:221], v[182:185], v[96:99]
	v_mfma_f32_16x16x32_bf16 v[84:87], v[210:213], v[194:197], v[84:87]
	v_mfma_f32_16x16x32_bf16 v[80:83], v[218:221], v[194:197], v[80:83]
	v_mfma_f32_16x16x32_bf16 v[68:71], v[210:213], v[202:205], v[68:71]
	v_mfma_f32_16x16x32_bf16 v[64:67], v[218:221], v[202:205], v[64:67]
	v_mfma_f32_16x16x32_bf16 v[116:119], v[214:217], v[172:175], v[116:119]
	v_mfma_f32_16x16x32_bf16 v[112:115], v[222:225], v[172:175], v[112:115]
	v_mfma_f32_16x16x32_bf16 v[100:103], v[214:217], v[190:193], v[100:103]
	v_mfma_f32_16x16x32_bf16 v[96:99], v[222:225], v[190:193], v[96:99]
	v_mfma_f32_16x16x32_bf16 v[84:87], v[214:217], v[198:201], v[84:87]
	v_mfma_f32_16x16x32_bf16 v[80:83], v[222:225], v[198:201], v[80:83]
	v_mfma_f32_16x16x32_bf16 v[68:71], v[214:217], v[206:209], v[68:71]
	v_mfma_f32_16x16x32_bf16 v[64:67], v[222:225], v[206:209], v[64:67]
	s_barrier
	ds_read_b128 v[168:171], v150 offset:49152
	ds_read_b128 v[172:175], v150 offset:50176
	ds_read_b128 v[182:185], v150 offset:51200
	ds_read_b128 v[190:193], v150 offset:52224
	ds_read_b128 v[194:197], v150 offset:53248
	ds_read_b128 v[198:201], v150 offset:54272
	ds_read_b128 v[202:205], v150 offset:55296
	ds_read_b128 v[206:209], v150 offset:56320
	s_add_i32 s18, s55, s31
	s_mov_b32 m0, s18
	s_nop 0
	global_load_lds_dwordx4 v130, s[98:99]
	s_nop 1
	s_add_i32 m0, s18, 0x2000
	s_nop 0
	global_load_lds_dwordx4 v134, s[98:99]
	s_nop 1
	s_mov_b32 m0, s39
	s_nop 0
	global_load_lds_dwordx4 v128, s[100:101]
	s_nop 1
	s_mov_b32 m0, s40
	s_nop 0
	global_load_lds_dwordx4 v132, s[100:101]
	s_add_u32 s18, s22, 0xb0080
	s_addc_u32 s19, s23, 0
	s_add_i32 s22, s24, s31
	s_mov_b32 m0, s22
	s_nop 0
	global_load_lds_dwordx4 v130, s[18:19]
	s_nop 1
	s_add_i32 m0, s22, 0x2000
	s_nop 0
	global_load_lds_dwordx4 v134, s[18:19]
	s_waitcnt vmcnt(8) lgkmcnt(0)
	s_barrier
	v_mfma_f32_16x16x32_bf16 v[60:63], v[152:155], v[168:171], v[60:63]
	v_mfma_f32_16x16x32_bf16 v[56:59], v[160:163], v[168:171], v[56:59]
	v_mfma_f32_16x16x32_bf16 v[48:51], v[152:155], v[182:185], v[48:51]
	v_mfma_f32_16x16x32_bf16 v[40:43], v[160:163], v[182:185], v[40:43]
	v_mfma_f32_16x16x32_bf16 v[32:35], v[152:155], v[194:197], v[32:35]
	v_mfma_f32_16x16x32_bf16 v[24:27], v[160:163], v[194:197], v[24:27]
	v_mfma_f32_16x16x32_bf16 v[16:19], v[152:155], v[202:205], v[16:19]
	v_mfma_f32_16x16x32_bf16 v[8:11], v[160:163], v[202:205], v[8:11]
	v_mfma_f32_16x16x32_bf16 v[60:63], v[156:159], v[172:175], v[60:63]
	v_mfma_f32_16x16x32_bf16 v[56:59], v[164:167], v[172:175], v[56:59]
	v_mfma_f32_16x16x32_bf16 v[48:51], v[156:159], v[190:193], v[48:51]
	v_mfma_f32_16x16x32_bf16 v[40:43], v[164:167], v[190:193], v[40:43]
	v_mfma_f32_16x16x32_bf16 v[32:35], v[156:159], v[198:201], v[32:35]
	v_mfma_f32_16x16x32_bf16 v[24:27], v[164:167], v[198:201], v[24:27]
	v_mfma_f32_16x16x32_bf16 v[16:19], v[156:159], v[206:209], v[16:19]
	v_mfma_f32_16x16x32_bf16 v[8:11], v[164:167], v[206:209], v[8:11]
	v_mfma_f32_16x16x32_bf16 v[52:55], v[210:213], v[168:171], v[52:55]
	v_mfma_f32_16x16x32_bf16 v[44:47], v[218:221], v[168:171], v[44:47]
	v_mfma_f32_16x16x32_bf16 v[36:39], v[210:213], v[182:185], v[36:39]
	v_mfma_f32_16x16x32_bf16 v[28:31], v[218:221], v[182:185], v[28:31]
	v_mfma_f32_16x16x32_bf16 v[20:23], v[210:213], v[194:197], v[20:23]
	v_mfma_f32_16x16x32_bf16 v[12:15], v[218:221], v[194:197], v[12:15]
	v_mfma_f32_16x16x32_bf16 v[4:7], v[210:213], v[202:205], v[4:7]
	v_mfma_f32_16x16x32_bf16 v[0:3], v[218:221], v[202:205], v[0:3]
	v_mfma_f32_16x16x32_bf16 v[52:55], v[214:217], v[172:175], v[52:55]
	v_mfma_f32_16x16x32_bf16 v[44:47], v[222:225], v[172:175], v[44:47]
	v_mfma_f32_16x16x32_bf16 v[36:39], v[214:217], v[190:193], v[36:39]
	v_mfma_f32_16x16x32_bf16 v[28:31], v[222:225], v[190:193], v[28:31]
	v_mfma_f32_16x16x32_bf16 v[20:23], v[214:217], v[198:201], v[20:23]
	v_mfma_f32_16x16x32_bf16 v[12:15], v[222:225], v[198:201], v[12:15]
	v_mfma_f32_16x16x32_bf16 v[4:7], v[214:217], v[206:209], v[4:7]
	v_mfma_f32_16x16x32_bf16 v[0:3], v[222:225], v[206:209], v[0:3]
	s_barrier
	s_add_i32 s54, s54, 2
	s_add_u32 s52, s52, 0x100
	s_addc_u32 s53, s53, 0
	s_cmp_gt_u32 s54, 41
	s_mov_b64 s[18:19], s[20:21]
; #define PG8_STAGE(bufoff, gbase, voff) do { _Pragma("unroll") for (int _i = 0; _i < 2; ++_i) \
;         __builtin_amdgcn_global_load_lds((const unsigned*)((const char*)(gbase) + (voff)[_i]), (PG8_LAS unsigned*)(lds + (bufoff) + ldsw + _i * 8192), 16, 0, 0); } while (0)
; #define PG8_LDA(dst, b, h) do { _Pragma("unroll") for (int m = 0; m < 4; ++m) _Pragma("unroll") for (int k = 0; k < 2; ++k) dst[m][k] = *(const PG8_LAS bf16x8*)(lds + PG8_SA(b, h) + aoff + m * 2048 + k * 1024); } while (0)
; #define PG8_LDB(dst, b, h) do { _Pragma("unroll") for (int n = 0; n < 2; ++n) _Pragma("unroll") for (int k = 0; k < 2; ++k) dst[n][k] = *(const PG8_LAS bf16x8*)(lds + PG8_SB(b, h) + boff + n * 2048 + k * 1024); } while (0)
; #define PG8_MMA(ai, bj, At, Bt) do { __builtin_amdgcn_s_setprio(1); _Pragma("unroll") for (int m = 0; m < 4; ++m) _Pragma("unroll") for (int n = 0; n < 2; ++n) _Pragma("unroll") for (int k = 0; k < 2; ++k) \
;         acc[ai][bj][m][n] = __builtin_amdgcn_mfma_f32_16x16x32_bf16(Bt[n][k], At[m][k], acc[ai][bj][m][n], 0, 0, 0); __builtin_amdgcn_s_setprio(0); } while (0)
; #define PG8_WAIT_V(n) asm volatile("s_waitcnt vmcnt(" #n ")" ::: "memory")
; #define PG8_WAIT_L(n) asm volatile("s_waitcnt lgkmcnt(" #n ")" ::: "memory")
; #define PG8_BAR __builtin_amdgcn_s_barrier()
; #define PG8_SCHED __builtin_amdgcn_sched_barrier(0)
; template <class Epi, class Sched>
; __device__ __forceinline__ void gemm_phase(PG8_LAS unsigned char* lds, const Gemm g, const Sched& S, const Epi& E) {
;     ...
;             PG8_LDB(B0, 0, 0); PG8_SCHED; PG8_LDA(At, 0, 0); PG8_STAGE(PG8_SA(1, 1), a1 + hstep, voffA);
;             PG8_WAIT_L(8); PG8_BAR; PG8_WAIT_L(0); PG8_MMA(0, 0, At, B0); PG8_BAR; PG8_SCHED;
;             PG8_LDB(B1, 0, 1); PG8_STAGE(PG8_SB(0, 0), b2, voffB);
;             PG8_BAR; PG8_WAIT_L(0); PG8_MMA(0, 1, At, B1); PG8_BAR;
;             PG8_LDA(At, 0, 1); PG8_STAGE(PG8_SA(0, 0), a2, voffA);
;             PG8_BAR; PG8_WAIT_L(0); PG8_MMA(1, 0, At, B0); PG8_BAR; PG8_SCHED;
;             PG8_STAGE(PG8_SB(0, 1), b2 + hstep, voffB);
;             PG8_WAIT_V(6); PG8_BAR; PG8_MMA(1, 1, At, B1); PG8_BAR;
.LBB0_1278:
	ds_read_b128 v[152:155], v149
	ds_read_b128 v[156:159], v149 offset:1024
	ds_read_b128 v[160:163], v149 offset:2048
	ds_read_b128 v[164:167], v149 offset:3072
	s_add_u32 s20, s18, 0x100
	s_addc_u32 s21, s19, 0
	s_cmp_eq_u32 s54, 40
	s_cselect_b32 s25, s1, s21
	s_cselect_b32 s24, s0, s20
	s_cselect_b32 s23, s5, s53
	s_cselect_b32 s22, s4, s52
	s_add_i32 m0, s34, 0xc000
	ds_read_b128 v[168:171], v150
	ds_read_b128 v[172:175], v150 offset:1024
	ds_read_b128 v[182:185], v150 offset:2048
	ds_read_b128 v[190:193], v150 offset:3072
	ds_read_b128 v[194:197], v150 offset:4096
	ds_read_b128 v[198:201], v150 offset:5120
	ds_read_b128 v[202:205], v150 offset:6144
	ds_read_b128 v[206:209], v150 offset:7168
	global_load_lds_dwordx4 v136, s[18:19]
	s_nop 1
	s_add_i32 m0, s34, 0xe000
	s_nop 0
	global_load_lds_dwordx4 v138, s[18:19]
	s_waitcnt lgkmcnt(8)
	ds_read_b128 v[210:213], v151
	ds_read_b128 v[214:217], v151 offset:1024
	ds_read_b128 v[218:221], v151 offset:2048
	ds_read_b128 v[222:225], v151 offset:3072
	s_waitcnt vmcnt(8) lgkmcnt(0)
	s_barrier
	v_mfma_f32_16x16x32_bf16 v[124:127], v[152:155], v[168:171], v[124:127]
	v_mfma_f32_16x16x32_bf16 v[120:123], v[160:163], v[168:171], v[120:123]
	v_mfma_f32_16x16x32_bf16 v[108:111], v[152:155], v[182:185], v[108:111]
	v_mfma_f32_16x16x32_bf16 v[104:107], v[160:163], v[182:185], v[104:107]
	v_mfma_f32_16x16x32_bf16 v[92:95], v[152:155], v[194:197], v[92:95]
	v_mfma_f32_16x16x32_bf16 v[88:91], v[160:163], v[194:197], v[88:91]
	v_mfma_f32_16x16x32_bf16 v[76:79], v[152:155], v[202:205], v[76:79]
	v_mfma_f32_16x16x32_bf16 v[72:75], v[160:163], v[202:205], v[72:75]
	v_mfma_f32_16x16x32_bf16 v[124:127], v[156:159], v[172:175], v[124:127]
	v_mfma_f32_16x16x32_bf16 v[120:123], v[164:167], v[172:175], v[120:123]
	v_mfma_f32_16x16x32_bf16 v[108:111], v[156:159], v[190:193], v[108:111]
	v_mfma_f32_16x16x32_bf16 v[104:107], v[164:167], v[190:193], v[104:107]
	v_mfma_f32_16x16x32_bf16 v[92:95], v[156:159], v[198:201], v[92:95]
	v_mfma_f32_16x16x32_bf16 v[88:91], v[164:167], v[198:201], v[88:91]
	v_mfma_f32_16x16x32_bf16 v[76:79], v[156:159], v[206:209], v[76:79]
	v_mfma_f32_16x16x32_bf16 v[72:75], v[164:167], v[206:209], v[72:75]
	v_mfma_f32_16x16x32_bf16 v[116:119], v[210:213], v[168:171], v[116:119]
	v_mfma_f32_16x16x32_bf16 v[112:115], v[218:221], v[168:171], v[112:115]
	v_mfma_f32_16x16x32_bf16 v[100:103], v[210:213], v[182:185], v[100:103]
	v_mfma_f32_16x16x32_bf16 v[96:99], v[218:221], v[182:185], v[96:99]
	v_mfma_f32_16x16x32_bf16 v[84:87], v[210:213], v[194:197], v[84:87]
	v_mfma_f32_16x16x32_bf16 v[80:83], v[218:221], v[194:197], v[80:83]
	v_mfma_f32_16x16x32_bf16 v[68:71], v[210:213], v[202:205], v[68:71]
	v_mfma_f32_16x16x32_bf16 v[64:67], v[218:221], v[202:205], v[64:67]
	v_mfma_f32_16x16x32_bf16 v[116:119], v[214:217], v[172:175], v[116:119]
	v_mfma_f32_16x16x32_bf16 v[112:115], v[222:225], v[172:175], v[112:115]
	v_mfma_f32_16x16x32_bf16 v[100:103], v[214:217], v[190:193], v[100:103]
	v_mfma_f32_16x16x32_bf16 v[96:99], v[222:225], v[190:193], v[96:99]
	v_mfma_f32_16x16x32_bf16 v[84:87], v[214:217], v[198:201], v[84:87]
	v_mfma_f32_16x16x32_bf16 v[80:83], v[222:225], v[198:201], v[80:83]
	v_mfma_f32_16x16x32_bf16 v[68:71], v[214:217], v[206:209], v[68:71]
	v_mfma_f32_16x16x32_bf16 v[64:67], v[222:225], v[206:209], v[64:67]
	s_barrier
	ds_read_b128 v[168:171], v150 offset:16384
	ds_read_b128 v[172:175], v150 offset:17408
	ds_read_b128 v[182:185], v150 offset:18432
	ds_read_b128 v[190:193], v150 offset:19456
	ds_read_b128 v[194:197], v150 offset:20480
	ds_read_b128 v[198:201], v150 offset:21504
	ds_read_b128 v[202:205], v150 offset:22528
	ds_read_b128 v[206:209], v150 offset:23552
	s_add_i32 s18, s42, s31
	s_add_u32 s98, s22, s8
	s_addc_u32 s99, s23, s9
	s_mov_b32 m0, s18
	s_nop 0
	global_load_lds_dwordx4 v130, s[22:23]
	s_nop 1
	s_add_i32 m0, s18, 0x2000
	s_nop 0
	global_load_lds_dwordx4 v134, s[22:23]
	s_nop 1
	s_mov_b32 m0, s34
	s_add_u32 s100, s24, s8
	s_addc_u32 s101, s25, s9
	global_load_lds_dwordx4 v128, s[24:25]
	s_nop 1
	s_mov_b32 m0, s35
	s_nop 0
	global_load_lds_dwordx4 v132, s[24:25]
	s_add_u32 s18, s22, 0xb0000
	s_addc_u32 s19, s23, 0
	s_add_i32 s55, s43, s31
	s_mov_b32 m0, s55
	s_nop 0
	global_load_lds_dwordx4 v130, s[18:19]
	s_nop 1
	s_add_i32 m0, s55, 0x2000
	s_nop 0
	global_load_lds_dwordx4 v134, s[18:19]
	s_waitcnt vmcnt(8) lgkmcnt(0)
	s_barrier
	v_mfma_f32_16x16x32_bf16 v[60:63], v[152:155], v[168:171], v[60:63]
	v_mfma_f32_16x16x32_bf16 v[56:59], v[160:163], v[168:171], v[56:59]
	v_mfma_f32_16x16x32_bf16 v[48:51], v[152:155], v[182:185], v[48:51]
	v_mfma_f32_16x16x32_bf16 v[40:43], v[160:163], v[182:185], v[40:43]
	v_mfma_f32_16x16x32_bf16 v[32:35], v[152:155], v[194:197], v[32:35]
	v_mfma_f32_16x16x32_bf16 v[24:27], v[160:163], v[194:197], v[24:27]
	v_mfma_f32_16x16x32_bf16 v[16:19], v[152:155], v[202:205], v[16:19]
	v_mfma_f32_16x16x32_bf16 v[8:11], v[160:163], v[202:205], v[8:11]
	v_mfma_f32_16x16x32_bf16 v[60:63], v[156:159], v[172:175], v[60:63]
	v_mfma_f32_16x16x32_bf16 v[56:59], v[164:167], v[172:175], v[56:59]
	v_mfma_f32_16x16x32_bf16 v[48:51], v[156:159], v[190:193], v[48:51]
	v_mfma_f32_16x16x32_bf16 v[40:43], v[164:167], v[190:193], v[40:43]
	v_mfma_f32_16x16x32_bf16 v[32:35], v[156:159], v[198:201], v[32:35]
	v_mfma_f32_16x16x32_bf16 v[24:27], v[164:167], v[198:201], v[24:27]
	v_mfma_f32_16x16x32_bf16 v[16:19], v[156:159], v[206:209], v[16:19]
	v_mfma_f32_16x16x32_bf16 v[8:11], v[164:167], v[206:209], v[8:11]
	v_mfma_f32_16x16x32_bf16 v[52:55], v[210:213], v[168:171], v[52:55]
	v_mfma_f32_16x16x32_bf16 v[44:47], v[218:221], v[168:171], v[44:47]
	v_mfma_f32_16x16x32_bf16 v[36:39], v[210:213], v[182:185], v[36:39]
	v_mfma_f32_16x16x32_bf16 v[28:31], v[218:221], v[182:185], v[28:31]
	v_mfma_f32_16x16x32_bf16 v[20:23], v[210:213], v[194:197], v[20:23]
	v_mfma_f32_16x16x32_bf16 v[12:15], v[218:221], v[194:197], v[12:15]
	v_mfma_f32_16x16x32_bf16 v[4:7], v[210:213], v[202:205], v[4:7]
	v_mfma_f32_16x16x32_bf16 v[0:3], v[218:221], v[202:205], v[0:3]
	v_mfma_f32_16x16x32_bf16 v[52:55], v[214:217], v[172:175], v[52:55]
	v_mfma_f32_16x16x32_bf16 v[44:47], v[222:225], v[172:175], v[44:47]
	v_mfma_f32_16x16x32_bf16 v[36:39], v[214:217], v[190:193], v[36:39]
	v_mfma_f32_16x16x32_bf16 v[28:31], v[222:225], v[190:193], v[28:31]
	v_mfma_f32_16x16x32_bf16 v[20:23], v[214:217], v[198:201], v[20:23]
	v_mfma_f32_16x16x32_bf16 v[12:15], v[222:225], v[198:201], v[12:15]
	v_mfma_f32_16x16x32_bf16 v[4:7], v[214:217], v[206:209], v[4:7]
	v_mfma_f32_16x16x32_bf16 v[0:3], v[222:225], v[206:209], v[0:3]
	s_barrier
; #define PG8_STAGE(bufoff, gbase, voff) do { _Pragma("unroll") for (int _i = 0; _i < 2; ++_i) \
;         __builtin_amdgcn_global_load_lds((const unsigned*)((const char*)(gbase) + (voff)[_i]), (PG8_LAS unsigned*)(lds + (bufoff) + ldsw + _i * 8192), 16, 0, 0); } while (0)
; #define PG8_LDA(dst, b, h) do { _Pragma("unroll") for (int m = 0; m < 4; ++m) _Pragma("unroll") for (int k = 0; k < 2; ++k) dst[m][k] = *(const PG8_LAS bf16x8*)(lds + PG8_SA(b, h) + aoff + m * 2048 + k * 1024); } while (0)
; #define PG8_LDB(dst, b, h) do { _Pragma("unroll") for (int n = 0; n < 2; ++n) _Pragma("unroll") for (int k = 0; k < 2; ++k) dst[n][k] = *(const PG8_LAS bf16x8*)(lds + PG8_SB(b, h) + boff + n * 2048 + k * 1024); } while (0)
; #define PG8_MMA(ai, bj, At, Bt) do { __builtin_amdgcn_s_setprio(1); _Pragma("unroll") for (int m = 0; m < 4; ++m) _Pragma("unroll") for (int n = 0; n < 2; ++n) _Pragma("unroll") for (int k = 0; k < 2; ++k) \
;         acc[ai][bj][m][n] = __builtin_amdgcn_mfma_f32_16x16x32_bf16(Bt[n][k], At[m][k], acc[ai][bj][m][n], 0, 0, 0); __builtin_amdgcn_s_setprio(0); } while (0)
; #define PG8_WAIT_V(n) asm volatile("s_waitcnt vmcnt(" #n ")" ::: "memory")
; #define PG8_WAIT_L(n) asm volatile("s_waitcnt lgkmcnt(" #n ")" ::: "memory")
; #define PG8_BAR __builtin_amdgcn_s_barrier()
; #define PG8_SCHED __builtin_amdgcn_sched_barrier(0)
; template <class Epi, class Sched>
; __device__ __forceinline__ void gemm_phase(PG8_LAS unsigned char* lds, const Gemm g, const Sched& S, const Epi& E) {
;     ...
;             PG8_LDB(B0, 1, 0); PG8_SCHED; PG8_LDA(At, 1, 0); PG8_STAGE(PG8_SA(0, 1), a2 + hstep, voffA);
;             PG8_WAIT_L(8); PG8_BAR; PG8_WAIT_L(0); PG8_MMA(0, 0, At, B0); PG8_BAR; PG8_SCHED;
;             PG8_LDB(B1, 1, 1); PG8_STAGE(PG8_SB(1, 0), b3, voffB);
;             PG8_BAR; PG8_WAIT_L(0); PG8_MMA(0, 1, At, B1); PG8_BAR;
;             PG8_LDA(At, 1, 1); PG8_STAGE(PG8_SA(1, 0), a3, voffA);
;             PG8_BAR; PG8_WAIT_L(0); PG8_MMA(1, 0, At, B0); PG8_BAR; PG8_SCHED;
;             PG8_STAGE(PG8_SB(1, 1), b3 + hstep, voffB);
;             PG8_WAIT_V(6); PG8_BAR; PG8_MMA(1, 1, At, B1); PG8_BAR;
	s_add_i32 s55, 0, 0x18000
	v_add_u32_e32 v164, s55, v147
	ds_read_b128 v[152:155], v164
	ds_read_b128 v[156:159], v164 offset:1024
	ds_read_b128 v[160:163], v164 offset:2048
	ds_read_b128 v[164:167], v164 offset:3072
	s_add_u32 s18, s24, 0xb0000
	s_addc_u32 s19, s25, 0
	s_mov_b32 m0, s36
	ds_read_b128 v[168:171], v150 offset:32768
	ds_read_b128 v[172:175], v150 offset:33792
	ds_read_b128 v[182:185], v150 offset:34816
	ds_read_b128 v[190:193], v150 offset:35840
	ds_read_b128 v[194:197], v150 offset:36864
	ds_read_b128 v[198:201], v150 offset:37888
	ds_read_b128 v[202:205], v150 offset:38912
	ds_read_b128 v[206:209], v150 offset:39936
	global_load_lds_dwordx4 v128, s[18:19]
	s_nop 1
	s_mov_b32 m0, s37
	s_nop 0
	global_load_lds_dwordx4 v132, s[18:19]
	s_add_i32 s24, 0, 0x1c000
	v_add_u32_e32 v179, s24, v147
	s_waitcnt lgkmcnt(8)
	ds_read_b128 v[210:213], v179
	ds_read_b128 v[214:217], v179 offset:1024
	ds_read_b128 v[218:221], v179 offset:2048
	ds_read_b128 v[222:225], v179 offset:3072
	s_waitcnt vmcnt(8) lgkmcnt(0)
	s_barrier
	v_mfma_f32_16x16x32_bf16 v[124:127], v[152:155], v[168:171], v[124:127]
	v_mfma_f32_16x16x32_bf16 v[120:123], v[160:163], v[168:171], v[120:123]
	v_mfma_f32_16x16x32_bf16 v[108:111], v[152:155], v[182:185], v[108:111]
	v_mfma_f32_16x16x32_bf16 v[104:107], v[160:163], v[182:185], v[104:107]
	v_mfma_f32_16x16x32_bf16 v[92:95], v[152:155], v[194:197], v[92:95]
	v_mfma_f32_16x16x32_bf16 v[88:91], v[160:163], v[194:197], v[88:91]
	v_mfma_f32_16x16x32_bf16 v[76:79], v[152:155], v[202:205], v[76:79]
	v_mfma_f32_16x16x32_bf16 v[72:75], v[160:163], v[202:205], v[72:75]
	v_mfma_f32_16x16x32_bf16 v[124:127], v[156:159], v[172:175], v[124:127]
	v_mfma_f32_16x16x32_bf16 v[120:123], v[164:167], v[172:175], v[120:123]
	v_mfma_f32_16x16x32_bf16 v[108:111], v[156:159], v[190:193], v[108:111]
	v_mfma_f32_16x16x32_bf16 v[104:107], v[164:167], v[190:193], v[104:107]
	v_mfma_f32_16x16x32_bf16 v[92:95], v[156:159], v[198:201], v[92:95]
	v_mfma_f32_16x16x32_bf16 v[88:91], v[164:167], v[198:201], v[88:91]
	v_mfma_f32_16x16x32_bf16 v[76:79], v[156:159], v[206:209], v[76:79]
	v_mfma_f32_16x16x32_bf16 v[72:75], v[164:167], v[206:209], v[72:75]
	v_mfma_f32_16x16x32_bf16 v[116:119], v[210:213], v[168:171], v[116:119]
	v_mfma_f32_16x16x32_bf16 v[112:115], v[218:221], v[168:171], v[112:115]
	v_mfma_f32_16x16x32_bf16 v[100:103], v[210:213], v[182:185], v[100:103]
	v_mfma_f32_16x16x32_bf16 v[96:99], v[218:221], v[182:185], v[96:99]
	v_mfma_f32_16x16x32_bf16 v[84:87], v[210:213], v[194:197], v[84:87]
	v_mfma_f32_16x16x32_bf16 v[80:83], v[218:221], v[194:197], v[80:83]
	v_mfma_f32_16x16x32_bf16 v[68:71], v[210:213], v[202:205], v[68:71]
	v_mfma_f32_16x16x32_bf16 v[64:67], v[218:221], v[202:205], v[64:67]
	v_mfma_f32_16x16x32_bf16 v[116:119], v[214:217], v[172:175], v[116:119]
	v_mfma_f32_16x16x32_bf16 v[112:115], v[222:225], v[172:175], v[112:115]
	v_mfma_f32_16x16x32_bf16 v[100:103], v[214:217], v[190:193], v[100:103]
	v_mfma_f32_16x16x32_bf16 v[96:99], v[222:225], v[190:193], v[96:99]
	v_mfma_f32_16x16x32_bf16 v[84:87], v[214:217], v[198:201], v[84:87]
	v_mfma_f32_16x16x32_bf16 v[80:83], v[222:225], v[198:201], v[80:83]
	v_mfma_f32_16x16x32_bf16 v[68:71], v[214:217], v[206:209], v[68:71]
	v_mfma_f32_16x16x32_bf16 v[64:67], v[222:225], v[206:209], v[64:67]
	s_barrier
	ds_read_b128 v[168:171], v150 offset:49152
	ds_read_b128 v[172:175], v150 offset:50176
	ds_read_b128 v[182:185], v150 offset:51200
	ds_read_b128 v[190:193], v150 offset:52224
	ds_read_b128 v[194:197], v150 offset:53248
	ds_read_b128 v[198:201], v150 offset:54272
	ds_read_b128 v[202:205], v150 offset:55296
	ds_read_b128 v[206:209], v150 offset:56320
	s_add_i32 s18, s55, s31
	s_mov_b32 m0, s18
	s_nop 0
	global_load_lds_dwordx4 v130, s[98:99]
	s_nop 1
	s_add_i32 m0, s18, 0x2000
	s_nop 0
	global_load_lds_dwordx4 v134, s[98:99]
	s_nop 1
	s_mov_b32 m0, s39
	s_nop 0
	global_load_lds_dwordx4 v128, s[100:101]
	s_nop 1
	s_mov_b32 m0, s40
	s_nop 0
	global_load_lds_dwordx4 v132, s[100:101]
	s_add_u32 s18, s22, 0xb0080
	s_addc_u32 s19, s23, 0
	s_add_i32 s22, s24, s31
	s_mov_b32 m0, s22
	s_nop 0
	global_load_lds_dwordx4 v130, s[18:19]
	s_nop 1
	s_add_i32 m0, s22, 0x2000
	s_nop 0
	global_load_lds_dwordx4 v134, s[18:19]
	s_waitcnt vmcnt(8) lgkmcnt(0)
	s_barrier
	v_mfma_f32_16x16x32_bf16 v[60:63], v[152:155], v[168:171], v[60:63]
	v_mfma_f32_16x16x32_bf16 v[56:59], v[160:163], v[168:171], v[56:59]
	v_mfma_f32_16x16x32_bf16 v[48:51], v[152:155], v[182:185], v[48:51]
	v_mfma_f32_16x16x32_bf16 v[40:43], v[160:163], v[182:185], v[40:43]
	v_mfma_f32_16x16x32_bf16 v[32:35], v[152:155], v[194:197], v[32:35]
	v_mfma_f32_16x16x32_bf16 v[24:27], v[160:163], v[194:197], v[24:27]
	v_mfma_f32_16x16x32_bf16 v[16:19], v[152:155], v[202:205], v[16:19]
	v_mfma_f32_16x16x32_bf16 v[8:11], v[160:163], v[202:205], v[8:11]
	v_mfma_f32_16x16x32_bf16 v[60:63], v[156:159], v[172:175], v[60:63]
	v_mfma_f32_16x16x32_bf16 v[56:59], v[164:167], v[172:175], v[56:59]
	v_mfma_f32_16x16x32_bf16 v[48:51], v[156:159], v[190:193], v[48:51]
	v_mfma_f32_16x16x32_bf16 v[40:43], v[164:167], v[190:193], v[40:43]
	v_mfma_f32_16x16x32_bf16 v[32:35], v[156:159], v[198:201], v[32:35]
	v_mfma_f32_16x16x32_bf16 v[24:27], v[164:167], v[198:201], v[24:27]
	v_mfma_f32_16x16x32_bf16 v[16:19], v[156:159], v[206:209], v[16:19]
	v_mfma_f32_16x16x32_bf16 v[8:11], v[164:167], v[206:209], v[8:11]
	v_mfma_f32_16x16x32_bf16 v[52:55], v[210:213], v[168:171], v[52:55]
	v_mfma_f32_16x16x32_bf16 v[44:47], v[218:221], v[168:171], v[44:47]
	v_mfma_f32_16x16x32_bf16 v[36:39], v[210:213], v[182:185], v[36:39]
	v_mfma_f32_16x16x32_bf16 v[28:31], v[218:221], v[182:185], v[28:31]
	v_mfma_f32_16x16x32_bf16 v[20:23], v[210:213], v[194:197], v[20:23]
	v_mfma_f32_16x16x32_bf16 v[12:15], v[218:221], v[194:197], v[12:15]
	v_mfma_f32_16x16x32_bf16 v[4:7], v[210:213], v[202:205], v[4:7]
	v_mfma_f32_16x16x32_bf16 v[0:3], v[218:221], v[202:205], v[0:3]
	v_mfma_f32_16x16x32_bf16 v[52:55], v[214:217], v[172:175], v[52:55]
	v_mfma_f32_16x16x32_bf16 v[44:47], v[222:225], v[172:175], v[44:47]
	v_mfma_f32_16x16x32_bf16 v[36:39], v[214:217], v[190:193], v[36:39]
	v_mfma_f32_16x16x32_bf16 v[28:31], v[222:225], v[190:193], v[28:31]
	v_mfma_f32_16x16x32_bf16 v[20:23], v[214:217], v[198:201], v[20:23]
	v_mfma_f32_16x16x32_bf16 v[12:15], v[222:225], v[198:201], v[12:15]
	v_mfma_f32_16x16x32_bf16 v[4:7], v[214:217], v[206:209], v[4:7]
	v_mfma_f32_16x16x32_bf16 v[0:3], v[222:225], v[206:209], v[0:3]
	s_barrier
; __device__ __forceinline__ unsigned cvt_pk_bf16(float lo, float hi) { unsigned r; asm volatile("v_cvt_pk_bf16_f32 %0, %1, %2" : "=v"(r) : "v"(lo), "v"(hi)); return r; }
; __device__ __forceinline__ float flogsig16(float x) { return (fminf(x, 0.f) - __logf(1.0f + __expf(-fabsf(x)))) * 0.0625f; }
;     __device__ __forceinline__ void operator()(const f32x4 (&acc)[2][2][4][2], const Unit& u, int wr, int wc, int fr, int fq) const {
;     ...
;         const int row0 = u.pm * BM + wr * 64 + fr, col0 = u.pn * BM + wc * 32 + 8 * fq, bcol0 = wc * 32 + 8 * fq;
;         f32x4 bv[2][2];
; #pragma unroll
;         for (int bj = 0; bj < 2; ++bj)
; #pragma unroll
;             for (int n = 0; n < 2; ++n) bv[bj][n] = bias ? *(const f32x4*)(bias + bcol0 + bj * HALF + 4 * n) : (f32x4){0.f, 0.f, 0.f, 0.f};
; #pragma unroll
;         for (int ai = 0; ai < 2; ++ai)
; #pragma unroll
;             for (int m = 0; m < 4; ++m) { bf16_t* rowp = O + (size_t)(row0 + ai * HALF + m * 16) * ldc + col0;
; #pragma unroll
;                 for (int bj = 0; bj < 2; ++bj) { f32x4 v0 = acc[ai][bj][m][0] + bv[bj][0], v1 = acc[ai][bj][m][1] + bv[bj][1];
;                     if (act == 1) {
; #pragma unroll
;                         for (int j = 0; j < 1; ++j) { v0 = v0 * sigmoid4(v0); v1 = v1 * sigmoid4(v1); } }
;                     else if (act == 2) {
; #pragma unroll
;                         for (int j = 0; j < 1; ++j) { v0 = sigmoid4(v0); v1 = sigmoid4(v1); } }
;                     else if (act == 3) {
; #pragma unroll
;                         for (int j = 0; j < 4; ++j) { v0[j] = flogsig16(v0[j]); v1[j] = flogsig16(v1[j]); } }
;                     u32x4 w; w.x = cvt_pk_bf16(v0[0], v0[1]); w.y = cvt_pk_bf16(v0[2], v0[3]); w.z = cvt_pk_bf16(v1[0], v1[1]); w.w = cvt_pk_bf16(v1[2], v1[3]);
;                     *(u32x4*)(rowp + bj * HALF) = w; } }
	s_add_i32 s54, s54, 2
	s_add_u32 s52, s52, 0x100
	s_addc_u32 s53, s53, 0
	s_cmp_gt_u32 s54, 41
	s_mov_b64 s[18:19], s[20:21]
	s_cbranch_scc0 .LBB0_1278
	v_lshl_add_u32 v152, s50, 8, v146
	v_lshl_or_b32 v144, s51, 8, v148
	v_ashrrev_i32_e32 v153, 31, v152
	v_ashrrev_i32_e32 v145, 31, v144
	v_lshlrev_b64 v[154:155], 11, v[152:153]
	v_lshl_add_u64 v[154:155], s[6:7], 0, v[154:155]
	v_lshlrev_b64 v[156:157], 1, v[144:145]
	v_lshl_add_u64 v[144:145], v[154:155], 0, v[156:157]
	v_pk_add_f32 v[126:127], v[126:127], 0 op_sel_hi:[1,0]
	v_pk_add_f32 v[124:125], v[124:125], 0 op_sel_hi:[1,0]
	v_pk_add_f32 v[154:155], v[122:123], 0 op_sel_hi:[1,0]
	v_pk_add_f32 v[122:123], v[120:121], 0 op_sel_hi:[1,0]
	v_cvt_pk_bf16_f32 v120, v124, v125
	v_cvt_pk_bf16_f32 v121, v126, v127
	v_pk_add_f32 v[116:117], v[116:117], 0 op_sel_hi:[1,0]
	v_cvt_pk_bf16_f32 v122, v122, v123
	v_cvt_pk_bf16_f32 v123, v154, v155
	global_store_dwordx4 v[144:145], v[120:123], off
	v_pk_add_f32 v[118:119], v[118:119], 0 op_sel_hi:[1,0]
	v_pk_add_f32 v[110:111], v[110:111], 0 op_sel_hi:[1,0]
	v_pk_add_f32 v[120:121], v[114:115], 0 op_sel_hi:[1,0]
	v_pk_add_f32 v[114:115], v[112:113], 0 op_sel_hi:[1,0]
	v_cvt_pk_bf16_f32 v112, v116, v117
	v_cvt_pk_bf16_f32 v113, v118, v119
	v_pk_add_f32 v[108:109], v[108:109], 0 op_sel_hi:[1,0]
	v_cvt_pk_bf16_f32 v114, v114, v115
	v_cvt_pk_bf16_f32 v115, v120, v121
	global_store_dwordx4 v[144:145], v[112:115], off offset:256
	v_pk_add_f32 v[100:101], v[100:101], 0 op_sel_hi:[1,0]
	v_pk_add_f32 v[102:103], v[102:103], 0 op_sel_hi:[1,0]
	v_or_b32_e32 v112, 16, v152
	v_ashrrev_i32_e32 v113, 31, v112
	v_lshlrev_b64 v[112:113], 11, v[112:113]
	v_lshl_add_u64 v[112:113], s[6:7], 0, v[112:113]
	v_lshl_add_u64 v[112:113], v[112:113], 0, v[156:157]
	v_pk_add_f32 v[114:115], v[106:107], 0 op_sel_hi:[1,0]
	v_pk_add_f32 v[106:107], v[104:105], 0 op_sel_hi:[1,0]
	v_cvt_pk_bf16_f32 v104, v108, v109
	v_cvt_pk_bf16_f32 v105, v110, v111
	v_pk_add_f32 v[94:95], v[94:95], 0 op_sel_hi:[1,0]
	v_cvt_pk_bf16_f32 v106, v106, v107
	v_cvt_pk_bf16_f32 v107, v114, v115
	global_store_dwordx4 v[112:113], v[104:107], off
	v_pk_add_f32 v[92:93], v[92:93], 0 op_sel_hi:[1,0]
	v_pk_add_f32 v[84:85], v[84:85], 0 op_sel_hi:[1,0]
	v_pk_add_f32 v[104:105], v[98:99], 0 op_sel_hi:[1,0]
	v_pk_add_f32 v[98:99], v[96:97], 0 op_sel_hi:[1,0]
	v_cvt_pk_bf16_f32 v96, v100, v101
	v_cvt_pk_bf16_f32 v97, v102, v103
	v_pk_add_f32 v[86:87], v[86:87], 0 op_sel_hi:[1,0]
	v_cvt_pk_bf16_f32 v98, v98, v99
	v_cvt_pk_bf16_f32 v99, v104, v105
	global_store_dwordx4 v[112:113], v[96:99], off offset:256
	v_pk_add_f32 v[78:79], v[78:79], 0 op_sel_hi:[1,0]
	v_pk_add_f32 v[76:77], v[76:77], 0 op_sel_hi:[1,0]
	v_or_b32_e32 v96, 32, v152
	v_ashrrev_i32_e32 v97, 31, v96
	v_lshlrev_b64 v[96:97], 11, v[96:97]
	v_lshl_add_u64 v[96:97], s[6:7], 0, v[96:97]
	v_lshl_add_u64 v[96:97], v[96:97], 0, v[156:157]
	v_pk_add_f32 v[98:99], v[90:91], 0 op_sel_hi:[1,0]
	v_pk_add_f32 v[90:91], v[88:89], 0 op_sel_hi:[1,0]
	v_cvt_pk_bf16_f32 v88, v92, v93
	v_cvt_pk_bf16_f32 v89, v94, v95
	v_pk_add_f32 v[70:71], v[70:71], 0 op_sel_hi:[1,0]
	v_cvt_pk_bf16_f32 v90, v90, v91
	v_cvt_pk_bf16_f32 v91, v98, v99
	global_store_dwordx4 v[96:97], v[88:91], off
	v_pk_add_f32 v[68:69], v[68:69], 0 op_sel_hi:[1,0]
	v_pk_add_f32 v[60:61], v[60:61], 0 op_sel_hi:[1,0]
	v_pk_add_f32 v[88:89], v[82:83], 0 op_sel_hi:[1,0]
	v_pk_add_f32 v[82:83], v[80:81], 0 op_sel_hi:[1,0]
	v_cvt_pk_bf16_f32 v80, v84, v85
	v_cvt_pk_bf16_f32 v81, v86, v87
	v_pk_add_f32 v[62:63], v[62:63], 0 op_sel_hi:[1,0]
	v_cvt_pk_bf16_f32 v82, v82, v83
	v_cvt_pk_bf16_f32 v83, v88, v89
	global_store_dwordx4 v[96:97], v[80:83], off offset:256
	v_pk_add_f32 v[54:55], v[54:55], 0 op_sel_hi:[1,0]
	v_pk_add_f32 v[52:53], v[52:53], 0 op_sel_hi:[1,0]
	v_or_b32_e32 v80, 48, v152
	v_ashrrev_i32_e32 v81, 31, v80
	v_lshlrev_b64 v[80:81], 11, v[80:81]
	v_lshl_add_u64 v[80:81], s[6:7], 0, v[80:81]
	v_lshl_add_u64 v[80:81], v[80:81], 0, v[156:157]
	v_pk_add_f32 v[82:83], v[74:75], 0 op_sel_hi:[1,0]
	v_pk_add_f32 v[74:75], v[72:73], 0 op_sel_hi:[1,0]
	v_cvt_pk_bf16_f32 v72, v76, v77
	v_cvt_pk_bf16_f32 v73, v78, v79
; __device__ __forceinline__ unsigned cvt_pk_bf16(float lo, float hi) { unsigned r; asm volatile("v_cvt_pk_bf16_f32 %0, %1, %2" : "=v"(r) : "v"(lo), "v"(hi)); return r; }
; __device__ __forceinline__ float flogsig16(float x) { return (fminf(x, 0.f) - __logf(1.0f + __expf(-fabsf(x)))) * 0.0625f; }
; #define PG8_WAIT_V(n) asm volatile("s_waitcnt vmcnt(" #n ")" ::: "memory")
; #define PG8_BAR __builtin_amdgcn_s_barrier()
;     __device__ __forceinline__ void operator()(const f32x4 (&acc)[2][2][4][2], const Unit& u, int wr, int wc, int fr, int fq) const {
;     ...
;             for (int m = 0; m < 4; ++m) { bf16_t* rowp = O + (size_t)(row0 + ai * HALF + m * 16) * ldc + col0;
; #pragma unroll
;                 for (int bj = 0; bj < 2; ++bj) { f32x4 v0 = acc[ai][bj][m][0] + bv[bj][0], v1 = acc[ai][bj][m][1] + bv[bj][1];
;                     if (act == 1) {
; #pragma unroll
;                         for (int j = 0; j < 1; ++j) { v0 = v0 * sigmoid4(v0); v1 = v1 * sigmoid4(v1); } }
;                     else if (act == 2) {
; #pragma unroll
;                         for (int j = 0; j < 1; ++j) { v0 = sigmoid4(v0); v1 = sigmoid4(v1); } }
;                     else if (act == 3) {
; #pragma unroll
;                         for (int j = 0; j < 4; ++j) { v0[j] = flogsig16(v0[j]); v1[j] = flogsig16(v1[j]); } }
;                     u32x4 w; w.x = cvt_pk_bf16(v0[0], v0[1]); w.y = cvt_pk_bf16(v0[2], v0[3]); w.z = cvt_pk_bf16(v1[0], v1[1]); w.w = cvt_pk_bf16(v1[2], v1[3]);
;                     *(u32x4*)(rowp + bj * HALF) = w; } }
; template <class Epi, class Sched>
; __device__ __forceinline__ void gemm_phase(PG8_LAS unsigned char* lds, const Gemm g, const Sched& S, const Epi& E) {
;     ...
;         if (!has_next) break;
; #pragma unroll
;         for (int a = 0; a < 2; ++a)
; #pragma unroll
;             for (int b = 0; b < 2; ++b)
; #pragma unroll
;                 for (int m = 0; m < 4; ++m)
; #pragma unroll
;                     for (int n = 0; n < 2; ++n) acc[a][b][m][n] = (f32x4){0.f, 0.f, 0.f, 0.f};
;         cur = nxt; cA = nA; cB = nB; ++ui;
;     }
;     PG8_WAIT_V(0);
;     if (wr == 0) PG8_BAR;
;     PG8_BAR;
	v_pk_add_f32 v[48:49], v[48:49], 0 op_sel_hi:[1,0]
	v_cvt_pk_bf16_f32 v74, v74, v75
	v_cvt_pk_bf16_f32 v75, v82, v83
	global_store_dwordx4 v[80:81], v[72:75], off
	v_pk_add_f32 v[38:39], v[38:39], 0 op_sel_hi:[1,0]
	v_pk_add_f32 v[36:37], v[36:37], 0 op_sel_hi:[1,0]
	v_pk_add_f32 v[72:73], v[66:67], 0 op_sel_hi:[1,0]
	v_pk_add_f32 v[66:67], v[64:65], 0 op_sel_hi:[1,0]
	v_cvt_pk_bf16_f32 v64, v68, v69
	v_cvt_pk_bf16_f32 v65, v70, v71
	v_pk_add_f32 v[32:33], v[32:33], 0 op_sel_hi:[1,0]
	v_cvt_pk_bf16_f32 v66, v66, v67
	v_cvt_pk_bf16_f32 v67, v72, v73
	global_store_dwordx4 v[80:81], v[64:67], off offset:256
	v_pk_add_f32 v[22:23], v[22:23], 0 op_sel_hi:[1,0]
	v_pk_add_f32 v[20:21], v[20:21], 0 op_sel_hi:[1,0]
	v_pk_add_f32 v[66:67], v[58:59], 0 op_sel_hi:[1,0]
	v_pk_add_f32 v[58:59], v[56:57], 0 op_sel_hi:[1,0]
	v_cvt_pk_bf16_f32 v56, v60, v61
	v_add_co_u32_e32 v60, vcc, s44, v144
	v_cvt_pk_bf16_f32 v57, v62, v63
	v_cvt_pk_bf16_f32 v58, v58, v59
	v_cvt_pk_bf16_f32 v59, v66, v67
	v_lshl_add_u64 v[64:65], v[144:145], 0, s[10:11]
	s_nop 0
	v_addc_co_u32_e32 v61, vcc, 0, v145, vcc
	global_store_dwordx4 v[60:61], v[56:59], off
	v_pk_add_f32 v[16:17], v[16:17], 0 op_sel_hi:[1,0]
	s_mov_b32 s51, s48
	v_pk_add_f32 v[56:57], v[46:47], 0 op_sel_hi:[1,0]
	v_pk_add_f32 v[46:47], v[44:45], 0 op_sel_hi:[1,0]
	v_cvt_pk_bf16_f32 v44, v52, v53
	v_cvt_pk_bf16_f32 v45, v54, v55
	s_mov_b32 s50, s49
	v_cvt_pk_bf16_f32 v46, v46, v47
	v_cvt_pk_bf16_f32 v47, v56, v57
	global_store_dwordx4 v[64:65], v[44:47], off offset:256
	s_mov_b64 s[20:21], s[4:5]
	s_mov_b64 s[18:19], s[0:1]
	v_pk_add_f32 v[46:47], v[50:51], 0 op_sel_hi:[1,0]
	v_pk_add_f32 v[50:51], v[42:43], 0 op_sel_hi:[1,0]
	v_pk_add_f32 v[42:43], v[40:41], 0 op_sel_hi:[1,0]
	v_cvt_pk_bf16_f32 v40, v48, v49
	v_cvt_pk_bf16_f32 v41, v46, v47
	v_add_co_u32_e32 v46, vcc, s45, v144
	v_cvt_pk_bf16_f32 v42, v42, v43
	v_cvt_pk_bf16_f32 v43, v50, v51
	v_lshl_add_u64 v[44:45], v[144:145], 0, s[12:13]
	s_nop 0
	v_addc_co_u32_e32 v47, vcc, 0, v145, vcc
	global_store_dwordx4 v[46:47], v[40:43], off
	v_pk_add_f32 v[6:7], v[6:7], 0 op_sel_hi:[1,0]
	v_pk_add_f32 v[4:5], v[4:5], 0 op_sel_hi:[1,0]
	v_pk_add_f32 v[40:41], v[30:31], 0 op_sel_hi:[1,0]
	v_pk_add_f32 v[30:31], v[28:29], 0 op_sel_hi:[1,0]
	v_cvt_pk_bf16_f32 v28, v36, v37
	v_cvt_pk_bf16_f32 v29, v38, v39
	s_nop 0
	v_cvt_pk_bf16_f32 v30, v30, v31
	v_cvt_pk_bf16_f32 v31, v40, v41
	global_store_dwordx4 v[44:45], v[28:31], off offset:256
	s_nop 1
	v_pk_add_f32 v[30:31], v[34:35], 0 op_sel_hi:[1,0]
	v_pk_add_f32 v[34:35], v[26:27], 0 op_sel_hi:[1,0]
	v_pk_add_f32 v[26:27], v[24:25], 0 op_sel_hi:[1,0]
	v_cvt_pk_bf16_f32 v24, v32, v33
	v_cvt_pk_bf16_f32 v25, v30, v31
	v_add_co_u32_e32 v30, vcc, s46, v144
	v_cvt_pk_bf16_f32 v26, v26, v27
	v_cvt_pk_bf16_f32 v27, v34, v35
	v_lshl_add_u64 v[28:29], v[144:145], 0, s[14:15]
	s_nop 0
	v_addc_co_u32_e32 v31, vcc, 0, v145, vcc
	global_store_dwordx4 v[30:31], v[24:27], off
	s_nop 1
	v_pk_add_f32 v[24:25], v[14:15], 0 op_sel_hi:[1,0]
	v_pk_add_f32 v[14:15], v[12:13], 0 op_sel_hi:[1,0]
	v_cvt_pk_bf16_f32 v12, v20, v21
	v_cvt_pk_bf16_f32 v13, v22, v23
	s_nop 0
	v_cvt_pk_bf16_f32 v14, v14, v15
	v_cvt_pk_bf16_f32 v15, v24, v25
	global_store_dwordx4 v[28:29], v[12:15], off offset:256
	s_nop 1
	v_pk_add_f32 v[14:15], v[18:19], 0 op_sel_hi:[1,0]
	v_pk_add_f32 v[18:19], v[10:11], 0 op_sel_hi:[1,0]
	v_pk_add_f32 v[10:11], v[8:9], 0 op_sel_hi:[1,0]
	v_cvt_pk_bf16_f32 v8, v16, v17
	v_cvt_pk_bf16_f32 v9, v14, v15
	v_add_co_u32_e32 v14, vcc, s47, v144
	v_lshl_add_u64 v[12:13], v[144:145], 0, s[16:17]
	s_nop 0
	v_addc_co_u32_e32 v15, vcc, 0, v145, vcc
	v_cvt_pk_bf16_f32 v10, v10, v11
	v_cvt_pk_bf16_f32 v11, v18, v19
	global_store_dwordx4 v[14:15], v[8:11], off
	s_and_b64 vcc, exec, s[2:3]
	s_nop 0
	v_pk_add_f32 v[8:9], v[2:3], 0 op_sel_hi:[1,0]
	v_pk_add_f32 v[2:3], v[0:1], 0 op_sel_hi:[1,0]
	v_cvt_pk_bf16_f32 v0, v4, v5
	v_cvt_pk_bf16_f32 v1, v6, v7
	s_nop 0
	v_cvt_pk_bf16_f32 v2, v2, v3
	v_cvt_pk_bf16_f32 v3, v8, v9
	global_store_dwordx4 v[12:13], v[0:3], off offset:256
	s_cbranch_vccz .LBB0_1267
	s_waitcnt vmcnt(0)
	s_cmpk_gt_u32 s27, 0xff
	s_cbranch_scc1 .LBB0_1282
	s_barrier

; __global__ void __launch_bounds__(512, 2) mk_fwd(Args a) {
	.amdhsa_kernel _ZN2mk6mk_fwdENS_4ArgsE
		.amdhsa_group_segment_fixed_size 0
		.amdhsa_private_segment_fixed_size 0
		.amdhsa_kernarg_size 456
		.amdhsa_user_sgpr_count 2
		.amdhsa_user_sgpr_dispatch_ptr 0
		.amdhsa_user_sgpr_queue_ptr 0
		.amdhsa_user_sgpr_kernarg_segment_ptr 1
		.amdhsa_user_sgpr_dispatch_id 0
		.amdhsa_user_sgpr_kernarg_preload_length 0
		.amdhsa_user_sgpr_kernarg_preload_offset 0
		.amdhsa_user_sgpr_private_segment_size 0
		.amdhsa_uses_dynamic_stack 0
		.amdhsa_enable_private_segment 0
		.amdhsa_system_sgpr_workgroup_id_x 1
		.amdhsa_system_sgpr_workgroup_id_y 0
		.amdhsa_system_sgpr_workgroup_id_z 0
		.amdhsa_system_sgpr_workgroup_info 0
		.amdhsa_system_vgpr_workitem_id 2
		.amdhsa_next_free_vgpr 248
		.amdhsa_next_free_sgpr 102
		.amdhsa_accum_offset 248
		.amdhsa_reserve_vcc 1
		.amdhsa_float_round_mode_32 0
		.amdhsa_float_round_mode_16_64 0
		.amdhsa_float_denorm_mode_32 3
		.amdhsa_float_denorm_mode_16_64 3
		.amdhsa_dx10_clamp 1
		.amdhsa_ieee_mode 1
		.amdhsa_fp16_overflow 0
		.amdhsa_tg_split 0
		.amdhsa_exception_fp_ieee_invalid_op 0
		.amdhsa_exception_fp_denorm_src 0
		.amdhsa_exception_fp_ieee_div_zero 0
		.amdhsa_exception_fp_ieee_overflow 0
		.amdhsa_exception_fp_ieee_underflow 0
		.amdhsa_exception_fp_ieee_inexact 0
		.amdhsa_exception_int_div_zero 0
	.end_amdhsa_kernel

; __global__ void __launch_bounds__(512, 2) mk_fwd(Args a) {
amdhsa.kernels:
  - .agpr_count:     0
    .args:
      - .offset:         0
        .size:           200
        .value_kind:     by_value
      - .offset:         200
        .size:           4
        .value_kind:     hidden_block_count_x
      - .offset:         204
        .size:           4
        .value_kind:     hidden_block_count_y
      - .offset:         208
        .size:           4
        .value_kind:     hidden_block_count_z
      - .offset:         212
        .size:           2
        .value_kind:     hidden_group_size_x
      - .offset:         214
        .size:           2
        .value_kind:     hidden_group_size_y
      - .offset:         216
        .size:           2
        .value_kind:     hidden_group_size_z
      - .offset:         218
        .size:           2
        .value_kind:     hidden_remainder_x
      - .offset:         220
        .size:           2
        .value_kind:     hidden_remainder_y
      - .offset:         222
        .size:           2
        .value_kind:     hidden_remainder_z
      - .offset:         240
        .size:           8
        .value_kind:     hidden_global_offset_x
      - .offset:         248
        .size:           8
        .value_kind:     hidden_global_offset_y
      - .offset:         256
        .size:           8
        .value_kind:     hidden_global_offset_z
      - .offset:         264
        .size:           2
        .value_kind:     hidden_grid_dims
      - .offset:         288
        .size:           8
        .value_kind:     hidden_multigrid_sync_arg
      - .offset:         320
        .size:           4
        .value_kind:     hidden_dynamic_lds_size
    .group_segment_fixed_size: 0
    .kernarg_segment_align: 8
    .kernarg_segment_size: 456
    .language:       OpenCL C
    .language_version:
      - 2
      - 0
    .max_flat_workgroup_size: 512
    .name:           _ZN2mk6mk_fwdENS_4ArgsE
    .private_segment_fixed_size: 0
    .sgpr_count:     108
    .sgpr_spill_count: 74
    .symbol:         _ZN2mk6mk_fwdENS_4ArgsE.kd
    .uniform_work_group_size: 1
    .uses_dynamic_stack: false
    .vgpr_count:     248
    .vgpr_spill_count: 0
    .wavefront_size: 64
